# flat_load/flat_store converted to global_load/global_store in GEMM epilogues (in-proj, up, down) and conv loop; same code size
# baseline (speedup 1.0000x reference)
; __device__ __forceinline__ void st8(bf16_t* p, f32x4 a, f32x4 b) { u32x4 w = {cvt_pk(a[0], a[1]), cvt_pk(a[2], a[3]), cvt_pk(b[0], b[1]), cvt_pk(b[2], b[3])}; *(u32x4*)p = w; }
; __device__ __forceinline__ float dot4(f32x4 a) { return (a[0] * a[0] + a[1] * a[1]) + (a[2] * a[2] + a[3] * a[3]); }
; #define FOR_AI_M _Pragma("unroll") for (int ai = 0; ai < 2; ++ai) if ((__builtin_amdgcn_sched_barrier(0), true)) _Pragma("unroll") for (int m = 0; m < 4; ++m)
;   __device__ __forceinline__ void ssq_store(const f32x4 (&acc)[2][2][4][2], bf16_t* dst, int ld, float* sq, int ns, int slot, int rbase, int c0, int fq) const {
;     FOR_AI_M { const int row = rbase + ai * 128 + m * 16; float s = 0.f;
; #pragma unroll
;       for (int bj = 0; bj < 2; ++bj) { const f32x4 v0 = acc[ai][bj][m][0], v1 = acc[ai][bj][m][1]; s += dot4(v0) + dot4(v1); st8(dst + (size_t)row * ld + bj * 128 + c0, v0, v1); }
;       s += __shfl_xor(s, 16); s += __shfl_xor(s, 32); if (fq == 0 && at) sq[(size_t)(b.g0 + row) * ns + slot] = s; }
;   }
;   __device__ __forceinline__ void operator()(EPI_ARGS) const {
;     const int pn = u.pn, rbase = u.pm * 256 + wr * 64 + fr, c0 = wc * 32 + fq * 8;
;     if (pn < 2) rope_store(acc, b.RQ, 1.f, pn, rbase, wc, fq);
;     else if (pn < 4) rope_store(acc, b.RK, 0.08838834764831845f, pn - 2, rbase, wc, fq);
;     else if (pn < 8) plain_store<0>(acc, b.RV, (pn - 4) * 256 + c0, rbase);
;     else if (pn < 12) plain_store<1>(acc, b.RG, (pn - 8) * 256 + c0, rbase);
;     else if (pn < 16) plain_store<2>(acc, b.GR, (pn - 12) * 256 + c0, rbase);
;     else if (pn < 20) plain_store<2>(acc, b.GA, (pn - 16) * 256 + c0, rbase);
;     else if (pn == 20) ssq_store(acc, b.CQ, 384, b.ssq_cq, 8, wc, rbase, c0, fq);
;     else if (pn == 22) ssq_store(acc, b.CKV, 256, b.ssq_ckv, 4, wc, rbase, c0, fq);
.LBB0_309:
	s_cmp_gt_u32 s47, 3
	s_cbranch_scc0 .LBB0_417
	s_cmp_gt_u32 s47, 7
	s_cbranch_scc0 .LBB0_414
	s_cmp_gt_u32 s47, 11
	s_cbranch_scc0 .LBB0_411
	s_cmp_gt_u32 s47, 15
	s_cbranch_scc0 .LBB0_408
	s_cmp_gt_u32 s47, 19
	s_cbranch_scc0 .LBB0_405
	v_ashrrev_i32_e32 v147, 31, v146
	s_mov_b64 s[78:79], -1
	s_mov_b64 s[44:45], 0
	s_cmp_lt_i32 s47, 22
	s_mov_b64 s[42:43], 0
	s_cbranch_scc1 .LBB0_334
	s_cmp_eq_u32 s47, 22
	s_mov_b64 s[42:43], -1
	s_cbranch_scc0 .LBB0_333
	v_readlane_b32 s10, v255, 38
	v_readlane_b32 s11, v255, 39
	v_cmp_eq_u32_e32 vcc, 0, v162
	s_waitcnt lgkmcnt(0)
	v_lshl_add_u64 v[128:129], v[146:147], 1, s[10:11]
	v_ashrrev_i32_e32 v145, 31, v144
	v_lshlrev_b64 v[130:131], 9, v[144:145]
	v_mul_f32_e32 v145, v125, v125
	v_mul_f32_e32 v148, v127, v127
	v_fmac_f32_e32 v145, v124, v124
	v_fmac_f32_e32 v148, v126, v126
	v_add_f32_e32 v145, v145, v148
	v_mul_f32_e32 v148, v121, v121
	v_mul_f32_e32 v149, v123, v123
	v_fmac_f32_e32 v148, v120, v120
	v_fmac_f32_e32 v149, v122, v122
	v_add_f32_e32 v148, v148, v149
	v_lshl_add_u64 v[130:131], v[128:129], 0, v[130:131]
	v_add_f32_e32 v145, v148, v145
	v_cvt_pk_bf16_f32 v148, v124, v125
	v_cvt_pk_bf16_f32 v149, v126, v127
	v_cvt_pk_bf16_f32 v150, v120, v121
	v_cvt_pk_bf16_f32 v151, v122, v123
	global_store_dwordx4 v[130:131], v[148:151], off
	s_nop 1
	v_mul_f32_e32 v148, v117, v117
	v_mul_f32_e32 v149, v119, v119
	v_fmac_f32_e32 v148, v116, v116
	v_fmac_f32_e32 v149, v118, v118
	v_add_f32_e32 v148, v148, v149
	v_mul_f32_e32 v149, v113, v113
	v_mul_f32_e32 v150, v115, v115
	v_fmac_f32_e32 v149, v112, v112
	v_fmac_f32_e32 v150, v114, v114
	v_add_f32_e32 v149, v149, v150
	v_add_f32_e32 v148, v149, v148
	v_add_f32_e32 v152, v148, v145
	v_cvt_pk_bf16_f32 v148, v116, v117
	v_cvt_pk_bf16_f32 v149, v118, v119
	v_cvt_pk_bf16_f32 v150, v112, v113
	v_cvt_pk_bf16_f32 v151, v114, v115
	global_store_dwordx4 v[130:131], v[148:151], off offset:256
	v_and_b32_e32 v131, 64, v233
	v_xor_b32_e32 v130, 16, v233
	v_add_u32_e32 v131, 64, v131
	v_cmp_lt_i32_e64 s[42:43], v130, v131
	v_xor_b32_e32 v148, 32, v233
	s_nop 0
	v_cndmask_b32_e64 v130, v233, v130, s[42:43]
	v_lshlrev_b32_e32 v145, 2, v130
	ds_bpermute_b32 v130, v145, v152
	v_cmp_lt_i32_e64 s[42:43], v148, v131
	s_waitcnt lgkmcnt(0)
	v_add_f32_e32 v130, v152, v130
	v_cndmask_b32_e64 v131, v233, v148, s[42:43]
	v_lshlrev_b32_e32 v148, 2, v131
	ds_bpermute_b32 v131, v148, v130
	s_and_saveexec_b64 s[42:43], vcc
	v_readlane_b32 s10, v255, 48
	v_readlane_b32 s11, v255, 49
	s_cbranch_execz .LBB0_318
	v_add_u32_e32 v150, s68, v144
	v_ashrrev_i32_e32 v151, 31, v150
	v_lshl_add_u64 v[150:151], v[150:151], 4, s[10:11]
	s_waitcnt lgkmcnt(0)
	v_add_f32_e32 v130, v130, v131
	global_store_dword v[150:151], v130, off
.LBB0_318:
	s_or_b64 exec, exec, s[42:43]
	v_add_u32_e32 v130, 16, v144
	s_waitcnt lgkmcnt(0)
	v_ashrrev_i32_e32 v131, 31, v130
	v_lshlrev_b64 v[150:151], 9, v[130:131]
	v_mul_f32_e32 v131, v109, v109
	v_mul_f32_e32 v149, v111, v111
	v_fmac_f32_e32 v131, v108, v108
	v_fmac_f32_e32 v149, v110, v110
	v_lshl_add_u64 v[154:155], v[128:129], 0, v[150:151]
	v_add_f32_e32 v131, v131, v149
	v_mul_f32_e32 v149, v105, v105
	v_mul_f32_e32 v150, v107, v107
	v_fmac_f32_e32 v149, v104, v104
	v_fmac_f32_e32 v150, v106, v106
	v_add_f32_e32 v149, v149, v150
	v_cvt_pk_bf16_f32 v150, v108, v109
	v_add_f32_e32 v131, v149, v131
	v_cvt_pk_bf16_f32 v151, v110, v111
	v_cvt_pk_bf16_f32 v152, v104, v105
	v_cvt_pk_bf16_f32 v153, v106, v107
	global_store_dwordx4 v[154:155], v[150:153], off
	v_mul_f32_e32 v149, v101, v101
	v_fmac_f32_e32 v149, v100, v100
	v_mul_f32_e32 v150, v103, v103
	v_fmac_f32_e32 v150, v102, v102
	v_add_f32_e32 v149, v149, v150
	v_mul_f32_e32 v150, v97, v97
	v_mul_f32_e32 v151, v99, v99
	v_fmac_f32_e32 v150, v96, v96
	v_fmac_f32_e32 v151, v98, v98
	v_add_f32_e32 v150, v150, v151
	v_add_f32_e32 v149, v150, v149
	v_add_f32_e32 v131, v149, v131
	ds_bpermute_b32 v149, v145, v131
	v_cvt_pk_bf16_f32 v150, v100, v101
	v_cvt_pk_bf16_f32 v151, v102, v103
	v_cvt_pk_bf16_f32 v152, v96, v97
	v_cvt_pk_bf16_f32 v153, v98, v99
	s_waitcnt lgkmcnt(0)
	v_add_f32_e32 v131, v131, v149
	ds_bpermute_b32 v149, v148, v131
	global_store_dwordx4 v[154:155], v[150:153], off offset:256
	s_and_saveexec_b64 s[42:43], vcc
	s_cbranch_execz .LBB0_320
	v_add_u32_e32 v150, s68, v130
	v_ashrrev_i32_e32 v151, 31, v150
	v_lshl_add_u64 v[150:151], v[150:151], 4, s[10:11]
	s_waitcnt lgkmcnt(0)
	v_add_f32_e32 v130, v131, v149
	global_store_dword v[150:151], v130, off
.LBB0_320:
	s_or_b64 exec, exec, s[42:43]
	v_add_u32_e32 v130, 32, v144
	v_ashrrev_i32_e32 v131, 31, v130
	v_lshlrev_b64 v[150:151], 9, v[130:131]
	v_mul_f32_e32 v131, v93, v93
	s_waitcnt lgkmcnt(0)
	v_mul_f32_e32 v149, v95, v95
	v_fmac_f32_e32 v131, v92, v92
	v_fmac_f32_e32 v149, v94, v94
	v_lshl_add_u64 v[154:155], v[128:129], 0, v[150:151]
	v_add_f32_e32 v131, v131, v149
	v_mul_f32_e32 v149, v89, v89
	v_mul_f32_e32 v150, v91, v91
	v_fmac_f32_e32 v149, v88, v88
	v_fmac_f32_e32 v150, v90, v90
	v_add_f32_e32 v149, v149, v150
	v_cvt_pk_bf16_f32 v150, v92, v93
	v_add_f32_e32 v131, v149, v131
	v_cvt_pk_bf16_f32 v151, v94, v95
	v_cvt_pk_bf16_f32 v152, v88, v89
	v_cvt_pk_bf16_f32 v153, v90, v91
	global_store_dwordx4 v[154:155], v[150:153], off
	v_mul_f32_e32 v149, v85, v85
	v_fmac_f32_e32 v149, v84, v84
	v_mul_f32_e32 v150, v87, v87
	v_fmac_f32_e32 v150, v86, v86
	v_add_f32_e32 v149, v149, v150
	v_mul_f32_e32 v150, v81, v81
	v_mul_f32_e32 v151, v83, v83
	v_fmac_f32_e32 v150, v80, v80
	v_fmac_f32_e32 v151, v82, v82
	v_add_f32_e32 v150, v150, v151
	v_add_f32_e32 v149, v150, v149
	v_add_f32_e32 v131, v149, v131
	ds_bpermute_b32 v149, v145, v131
	v_cvt_pk_bf16_f32 v150, v84, v85
	v_cvt_pk_bf16_f32 v151, v86, v87
	v_cvt_pk_bf16_f32 v152, v80, v81
	v_cvt_pk_bf16_f32 v153, v82, v83
	s_waitcnt lgkmcnt(0)
	v_add_f32_e32 v131, v131, v149
	ds_bpermute_b32 v149, v148, v131
	global_store_dwordx4 v[154:155], v[150:153], off offset:256
	s_and_saveexec_b64 s[42:43], vcc
	s_cbranch_execz .LBB0_322
	v_add_u32_e32 v150, s68, v130
	v_ashrrev_i32_e32 v151, 31, v150
	v_lshl_add_u64 v[150:151], v[150:151], 4, s[10:11]
	s_waitcnt lgkmcnt(0)
	v_add_f32_e32 v130, v131, v149
	global_store_dword v[150:151], v130, off
; __device__ __forceinline__ void st8(bf16_t* p, f32x4 a, f32x4 b) { u32x4 w = {cvt_pk(a[0], a[1]), cvt_pk(a[2], a[3]), cvt_pk(b[0], b[1]), cvt_pk(b[2], b[3])}; *(u32x4*)p = w; }
; __device__ __forceinline__ float dot4(f32x4 a) { return (a[0] * a[0] + a[1] * a[1]) + (a[2] * a[2] + a[3] * a[3]); }
; #define FOR_AI_M _Pragma("unroll") for (int ai = 0; ai < 2; ++ai) if ((__builtin_amdgcn_sched_barrier(0), true)) _Pragma("unroll") for (int m = 0; m < 4; ++m)
;   __device__ __forceinline__ void ssq_store(const f32x4 (&acc)[2][2][4][2], bf16_t* dst, int ld, float* sq, int ns, int slot, int rbase, int c0, int fq) const {
;     FOR_AI_M { const int row = rbase + ai * 128 + m * 16; float s = 0.f;
; #pragma unroll
;       for (int bj = 0; bj < 2; ++bj) { const f32x4 v0 = acc[ai][bj][m][0], v1 = acc[ai][bj][m][1]; s += dot4(v0) + dot4(v1); st8(dst + (size_t)row * ld + bj * 128 + c0, v0, v1); }
;       s += __shfl_xor(s, 16); s += __shfl_xor(s, 32); if (fq == 0 && at) sq[(size_t)(b.g0 + row) * ns + slot] = s; }
.LBB0_322:
	s_or_b64 exec, exec, s[42:43]
	v_add_u32_e32 v130, 48, v144
	v_ashrrev_i32_e32 v131, 31, v130
	v_lshlrev_b64 v[150:151], 9, v[130:131]
	v_mul_f32_e32 v131, v77, v77
	s_waitcnt lgkmcnt(0)
	v_mul_f32_e32 v149, v79, v79
	v_fmac_f32_e32 v131, v76, v76
	v_fmac_f32_e32 v149, v78, v78
	v_lshl_add_u64 v[154:155], v[128:129], 0, v[150:151]
	v_add_f32_e32 v131, v131, v149
	v_mul_f32_e32 v149, v73, v73
	v_mul_f32_e32 v150, v75, v75
	v_fmac_f32_e32 v149, v72, v72
	v_fmac_f32_e32 v150, v74, v74
	v_add_f32_e32 v149, v149, v150
	v_cvt_pk_bf16_f32 v150, v76, v77
	v_add_f32_e32 v131, v149, v131
	v_cvt_pk_bf16_f32 v151, v78, v79
	v_cvt_pk_bf16_f32 v152, v72, v73
	v_cvt_pk_bf16_f32 v153, v74, v75
	global_store_dwordx4 v[154:155], v[150:153], off
	v_mul_f32_e32 v149, v69, v69
	v_fmac_f32_e32 v149, v68, v68
	v_mul_f32_e32 v150, v71, v71
	v_fmac_f32_e32 v150, v70, v70
	v_add_f32_e32 v149, v149, v150
	v_mul_f32_e32 v150, v65, v65
	v_mul_f32_e32 v151, v67, v67
	v_fmac_f32_e32 v150, v64, v64
	v_fmac_f32_e32 v151, v66, v66
	v_add_f32_e32 v150, v150, v151
	v_add_f32_e32 v149, v150, v149
	v_add_f32_e32 v131, v149, v131
	ds_bpermute_b32 v149, v145, v131
	v_cvt_pk_bf16_f32 v150, v68, v69
	v_cvt_pk_bf16_f32 v151, v70, v71
	v_cvt_pk_bf16_f32 v152, v64, v65
	v_cvt_pk_bf16_f32 v153, v66, v67
	s_waitcnt lgkmcnt(0)
	v_add_f32_e32 v131, v131, v149
	ds_bpermute_b32 v149, v148, v131
	global_store_dwordx4 v[154:155], v[150:153], off offset:256
	s_and_saveexec_b64 s[42:43], vcc
	s_cbranch_execz .LBB0_324
	v_add_u32_e32 v150, s68, v130
	v_ashrrev_i32_e32 v151, 31, v150
	v_lshl_add_u64 v[150:151], v[150:151], 4, s[10:11]
	s_waitcnt lgkmcnt(0)
	v_add_f32_e32 v130, v131, v149
	global_store_dword v[150:151], v130, off
.LBB0_324:
	s_or_b64 exec, exec, s[42:43]
	v_add_u32_e32 v130, 0x80, v144
	v_ashrrev_i32_e32 v131, 31, v130
	v_lshlrev_b64 v[150:151], 9, v[130:131]
	v_mul_f32_e32 v131, v61, v61
	s_waitcnt lgkmcnt(0)
	v_mul_f32_e32 v149, v63, v63
	v_fmac_f32_e32 v131, v60, v60
	v_fmac_f32_e32 v149, v62, v62
	v_lshl_add_u64 v[154:155], v[128:129], 0, v[150:151]
	v_add_f32_e32 v131, v131, v149
	v_mul_f32_e32 v149, v57, v57
	v_mul_f32_e32 v150, v59, v59
	v_fmac_f32_e32 v149, v56, v56
	v_fmac_f32_e32 v150, v58, v58
	v_add_f32_e32 v149, v149, v150
	v_cvt_pk_bf16_f32 v150, v60, v61
	v_add_f32_e32 v131, v149, v131
	v_cvt_pk_bf16_f32 v151, v62, v63
	v_cvt_pk_bf16_f32 v152, v56, v57
	v_cvt_pk_bf16_f32 v153, v58, v59
	global_store_dwordx4 v[154:155], v[150:153], off
	v_mul_f32_e32 v149, v53, v53
	v_fmac_f32_e32 v149, v52, v52
	v_mul_f32_e32 v150, v55, v55
	v_fmac_f32_e32 v150, v54, v54
	v_add_f32_e32 v149, v149, v150
	v_mul_f32_e32 v150, v49, v49
	v_mul_f32_e32 v151, v51, v51
	v_fmac_f32_e32 v150, v48, v48
	v_fmac_f32_e32 v151, v50, v50
	v_add_f32_e32 v150, v150, v151
	v_add_f32_e32 v149, v150, v149
	v_add_f32_e32 v131, v149, v131
	ds_bpermute_b32 v149, v145, v131
	v_cvt_pk_bf16_f32 v150, v52, v53
	v_cvt_pk_bf16_f32 v151, v54, v55
	v_cvt_pk_bf16_f32 v152, v48, v49
	v_cvt_pk_bf16_f32 v153, v50, v51
	s_waitcnt lgkmcnt(0)
	v_add_f32_e32 v131, v131, v149
	ds_bpermute_b32 v149, v148, v131
	global_store_dwordx4 v[154:155], v[150:153], off offset:256
	s_and_saveexec_b64 s[42:43], vcc
	s_cbranch_execz .LBB0_326
	v_add_u32_e32 v150, s68, v130
	v_ashrrev_i32_e32 v151, 31, v150
	v_lshl_add_u64 v[150:151], v[150:151], 4, s[10:11]
	s_waitcnt lgkmcnt(0)
	v_add_f32_e32 v130, v131, v149
	global_store_dword v[150:151], v130, off
; __device__ __forceinline__ void st8(bf16_t* p, f32x4 a, f32x4 b) { u32x4 w = {cvt_pk(a[0], a[1]), cvt_pk(a[2], a[3]), cvt_pk(b[0], b[1]), cvt_pk(b[2], b[3])}; *(u32x4*)p = w; }
; __device__ __forceinline__ float dot4(f32x4 a) { return (a[0] * a[0] + a[1] * a[1]) + (a[2] * a[2] + a[3] * a[3]); }
; #define FOR_AI_M _Pragma("unroll") for (int ai = 0; ai < 2; ++ai) if ((__builtin_amdgcn_sched_barrier(0), true)) _Pragma("unroll") for (int m = 0; m < 4; ++m)
;   __device__ __forceinline__ void ssq_store(const f32x4 (&acc)[2][2][4][2], bf16_t* dst, int ld, float* sq, int ns, int slot, int rbase, int c0, int fq) const {
;     FOR_AI_M { const int row = rbase + ai * 128 + m * 16; float s = 0.f;
; #pragma unroll
;       for (int bj = 0; bj < 2; ++bj) { const f32x4 v0 = acc[ai][bj][m][0], v1 = acc[ai][bj][m][1]; s += dot4(v0) + dot4(v1); st8(dst + (size_t)row * ld + bj * 128 + c0, v0, v1); }
;       s += __shfl_xor(s, 16); s += __shfl_xor(s, 32); if (fq == 0 && at) sq[(size_t)(b.g0 + row) * ns + slot] = s; }
.LBB0_326:
	s_or_b64 exec, exec, s[42:43]
	v_add_u32_e32 v130, 0x90, v144
	v_ashrrev_i32_e32 v131, 31, v130
	v_lshlrev_b64 v[150:151], 9, v[130:131]
	v_mul_f32_e32 v131, v45, v45
	s_waitcnt lgkmcnt(0)
	v_mul_f32_e32 v149, v47, v47
	v_fmac_f32_e32 v131, v44, v44
	v_fmac_f32_e32 v149, v46, v46
	v_lshl_add_u64 v[154:155], v[128:129], 0, v[150:151]
	v_add_f32_e32 v131, v131, v149
	v_mul_f32_e32 v149, v41, v41
	v_mul_f32_e32 v150, v43, v43
	v_fmac_f32_e32 v149, v40, v40
	v_fmac_f32_e32 v150, v42, v42
	v_add_f32_e32 v149, v149, v150
	v_cvt_pk_bf16_f32 v150, v44, v45
	v_add_f32_e32 v131, v149, v131
	v_cvt_pk_bf16_f32 v151, v46, v47
	v_cvt_pk_bf16_f32 v152, v40, v41
	v_cvt_pk_bf16_f32 v153, v42, v43
	global_store_dwordx4 v[154:155], v[150:153], off
	v_mul_f32_e32 v149, v37, v37
	v_fmac_f32_e32 v149, v36, v36
	v_mul_f32_e32 v150, v39, v39
	v_fmac_f32_e32 v150, v38, v38
	v_add_f32_e32 v149, v149, v150
	v_mul_f32_e32 v150, v33, v33
	v_mul_f32_e32 v151, v35, v35
	v_fmac_f32_e32 v150, v32, v32
	v_fmac_f32_e32 v151, v34, v34
	v_add_f32_e32 v150, v150, v151
	v_add_f32_e32 v149, v150, v149
	v_add_f32_e32 v131, v149, v131
	ds_bpermute_b32 v149, v145, v131
	v_cvt_pk_bf16_f32 v150, v36, v37
	v_cvt_pk_bf16_f32 v151, v38, v39
	v_cvt_pk_bf16_f32 v152, v32, v33
	v_cvt_pk_bf16_f32 v153, v34, v35
	s_waitcnt lgkmcnt(0)
	v_add_f32_e32 v131, v131, v149
	ds_bpermute_b32 v149, v148, v131
	global_store_dwordx4 v[154:155], v[150:153], off offset:256
	s_and_saveexec_b64 s[42:43], vcc
	s_cbranch_execz .LBB0_328
	v_add_u32_e32 v150, s68, v130
	v_ashrrev_i32_e32 v151, 31, v150
	v_lshl_add_u64 v[150:151], v[150:151], 4, s[10:11]
	s_waitcnt lgkmcnt(0)
	v_add_f32_e32 v130, v131, v149
	global_store_dword v[150:151], v130, off
.LBB0_328:
	s_or_b64 exec, exec, s[42:43]
	v_add_u32_e32 v130, 0xa0, v144
	v_ashrrev_i32_e32 v131, 31, v130
	v_lshlrev_b64 v[150:151], 9, v[130:131]
	v_mul_f32_e32 v131, v29, v29
	s_waitcnt lgkmcnt(0)
	v_mul_f32_e32 v149, v31, v31
	v_fmac_f32_e32 v131, v28, v28
	v_fmac_f32_e32 v149, v30, v30
	v_lshl_add_u64 v[154:155], v[128:129], 0, v[150:151]
	v_add_f32_e32 v131, v131, v149
	v_mul_f32_e32 v149, v25, v25
	v_mul_f32_e32 v150, v27, v27
	v_fmac_f32_e32 v149, v24, v24
	v_fmac_f32_e32 v150, v26, v26
	v_add_f32_e32 v149, v149, v150
	v_cvt_pk_bf16_f32 v150, v28, v29
	v_add_f32_e32 v131, v149, v131
	v_cvt_pk_bf16_f32 v151, v30, v31
	v_cvt_pk_bf16_f32 v152, v24, v25
	v_cvt_pk_bf16_f32 v153, v26, v27
	global_store_dwordx4 v[154:155], v[150:153], off
	v_mul_f32_e32 v149, v21, v21
	v_fmac_f32_e32 v149, v20, v20
	v_mul_f32_e32 v150, v23, v23
	v_fmac_f32_e32 v150, v22, v22
	v_add_f32_e32 v149, v149, v150
	v_mul_f32_e32 v150, v17, v17
	v_mul_f32_e32 v151, v19, v19
	v_fmac_f32_e32 v150, v16, v16
	v_fmac_f32_e32 v151, v18, v18
	v_add_f32_e32 v150, v150, v151
	v_add_f32_e32 v149, v150, v149
	v_add_f32_e32 v131, v149, v131
	ds_bpermute_b32 v149, v145, v131
	v_cvt_pk_bf16_f32 v150, v20, v21
	v_cvt_pk_bf16_f32 v151, v22, v23
	v_cvt_pk_bf16_f32 v152, v16, v17
	v_cvt_pk_bf16_f32 v153, v18, v19
	s_waitcnt lgkmcnt(0)
	v_add_f32_e32 v131, v131, v149
	ds_bpermute_b32 v149, v148, v131
	global_store_dwordx4 v[154:155], v[150:153], off offset:256
	s_and_saveexec_b64 s[42:43], vcc
	s_cbranch_execz .LBB0_330
	v_add_u32_e32 v150, s68, v130
	v_ashrrev_i32_e32 v151, 31, v150
	v_lshl_add_u64 v[150:151], v[150:151], 4, s[10:11]
	s_waitcnt lgkmcnt(0)
	v_add_f32_e32 v130, v131, v149
	global_store_dword v[150:151], v130, off
.LBB0_330:
	s_or_b64 exec, exec, s[42:43]
	v_add_u32_e32 v130, 0xb0, v144
	v_ashrrev_i32_e32 v131, 31, v130
	v_lshlrev_b64 v[150:151], 9, v[130:131]
	v_mul_f32_e32 v131, v13, v13
	s_waitcnt lgkmcnt(0)
	v_mul_f32_e32 v149, v15, v15
	v_fmac_f32_e32 v131, v12, v12
	v_fmac_f32_e32 v149, v14, v14
	v_lshl_add_u64 v[128:129], v[128:129], 0, v[150:151]
	v_add_f32_e32 v131, v131, v149
	v_mul_f32_e32 v149, v9, v9
	v_mul_f32_e32 v150, v11, v11
	v_fmac_f32_e32 v149, v8, v8
	v_fmac_f32_e32 v150, v10, v10
	v_add_f32_e32 v149, v149, v150
	v_cvt_pk_bf16_f32 v150, v12, v13
	v_add_f32_e32 v131, v149, v131
	v_cvt_pk_bf16_f32 v151, v14, v15
	v_cvt_pk_bf16_f32 v152, v8, v9
	v_cvt_pk_bf16_f32 v153, v10, v11
	global_store_dwordx4 v[128:129], v[150:153], off
	v_mul_f32_e32 v149, v5, v5
	v_fmac_f32_e32 v149, v4, v4
	v_mul_f32_e32 v150, v7, v7
	v_fmac_f32_e32 v150, v6, v6
	v_add_f32_e32 v149, v149, v150
	v_mul_f32_e32 v150, v1, v1
	v_mul_f32_e32 v151, v3, v3
	v_fmac_f32_e32 v150, v0, v0
	v_fmac_f32_e32 v151, v2, v2
	v_add_f32_e32 v150, v150, v151
	v_add_f32_e32 v149, v150, v149
	v_add_f32_e32 v131, v149, v131
	v_cvt_pk_bf16_f32 v150, v4, v5
	v_cvt_pk_bf16_f32 v151, v6, v7
	v_cvt_pk_bf16_f32 v152, v0, v1
	v_cvt_pk_bf16_f32 v153, v2, v3
	global_store_dwordx4 v[128:129], v[150:153], off offset:256
	ds_bpermute_b32 v128, v145, v131
	s_waitcnt lgkmcnt(0)
	v_add_f32_e32 v128, v131, v128
	ds_bpermute_b32 v129, v148, v128
	s_and_saveexec_b64 s[42:43], vcc
	s_cbranch_execz .LBB0_332
	v_add_u32_e32 v130, s68, v130
	v_ashrrev_i32_e32 v131, 31, v130
	v_lshl_add_u64 v[130:131], v[130:131], 4, s[10:11]
	s_waitcnt lgkmcnt(0)
	v_add_f32_e32 v128, v128, v129
	global_store_dword v[130:131], v128, off

; __device__ __forceinline__ void st8(bf16_t* p, f32x4 a, f32x4 b) { u32x4 w = {cvt_pk(a[0], a[1]), cvt_pk(a[2], a[3]), cvt_pk(b[0], b[1]), cvt_pk(b[2], b[3])}; *(u32x4*)p = w; }
; __device__ __forceinline__ float dot4(f32x4 a) { return (a[0] * a[0] + a[1] * a[1]) + (a[2] * a[2] + a[3] * a[3]); }
; #define FOR_AI_M _Pragma("unroll") for (int ai = 0; ai < 2; ++ai) if ((__builtin_amdgcn_sched_barrier(0), true)) _Pragma("unroll") for (int m = 0; m < 4; ++m)
;   __device__ __forceinline__ void operator()(EPI_ARGS) const {
;     ...
;       FOR_AI_M { const int row = rbase + ai * 128 + m * 16, pos = (b.g0 + row) & b.slm;
;         { const f32x4 v0 = acc[ai][0][m][0], v1 = acc[ai][0][m][1]; float s = dot4(v0) + dot4(v1); st8(b.CQ + (size_t)row * 384 + 256 + c0, v0, v1);
;           s += __shfl_xor(s, 16); s += __shfl_xor(s, 32); if (fq == 0 && at) b.ssq_cq[(size_t)(b.g0 + row) * 8 + 4 + wc] = s; }
;         if (wc < 2) { f32x4 v0 = acc[ai][1][m][0], v1 = acc[ai][1][m][1]; const int j0 = wc * 16 + fq * 4;
;           const f32x2* tp = (const f32x2*)(b.rope + ((size_t)pos * 64 + 2 * j0) * 2); const f32x2 a0 = tp[0], a1 = tp[2], a2 = tp[4], a3 = tp[6];
;           rope4(v0, v1, (f32x4){a0[0], a0[1], a1[0], a1[1]}, (f32x4){a2[0], a2[1], a3[0], a3[1]});
;           float s = dot4(v0) + dot4(v1); st8(b.KR + (size_t)row * 64 + c0, v0, v1);
;           s += __shfl_xor(s, 16); s += __shfl_xor(s, 32); if (fq == 0 && at) b.ssq_kr[(size_t)(b.g0 + row) * 2 + wc] = s; } }
.LBB0_336:
	v_mul_f32_e32 v150, v125, v125
	v_mul_f32_e32 v151, v127, v127
	v_mul_f32_e32 v152, v121, v121
	v_mul_f32_e32 v153, v123, v123
	s_andn2_b64 vcc, exec, s[42:43]
	v_cmp_eq_u32_e64 s[42:43], 0, v162
	v_fmac_f32_e32 v150, v124, v124
	v_fmac_f32_e32 v151, v126, v126
	v_fmac_f32_e32 v152, v120, v120
	v_fmac_f32_e32 v153, v122, v122
	s_cbranch_vccnz .LBB0_386
	v_readlane_b32 s10, v255, 36
	v_add_f32_e32 v128, v150, v151
	s_waitcnt lgkmcnt(0)
	v_add_f32_e32 v129, v152, v153
	v_readlane_b32 s11, v255, 37
	v_add_f32_e32 v131, v129, v128
	s_movk_i32 s8, 0x300
	v_mov_b64_e32 v[128:129], s[10:11]
	v_mad_i64_i32 v[128:129], s[18:19], v144, s8, v[128:129]
	v_lshl_add_u64 v[128:129], v[146:147], 1, v[128:129]
	v_cvt_pk_bf16_f32 v154, v124, v125
	v_cvt_pk_bf16_f32 v155, v126, v127
	v_cvt_pk_bf16_f32 v156, v120, v121
	v_cvt_pk_bf16_f32 v157, v122, v123
	global_store_dwordx4 v[128:129], v[154:157], off offset:512
	v_and_b32_e32 v129, 64, v233
	v_xor_b32_e32 v128, 16, v233
	v_add_u32_e32 v129, 64, v129
	v_cmp_lt_i32_e32 vcc, v128, v129
	v_add_u32_e32 v130, s68, v144
	s_nop 0
	v_cndmask_b32_e32 v128, v233, v128, vcc
	v_lshlrev_b32_e32 v154, 2, v128
	ds_bpermute_b32 v128, v154, v131
	s_waitcnt lgkmcnt(0)
	v_add_f32_e32 v128, v131, v128
	v_xor_b32_e32 v131, 32, v233
	v_cmp_lt_i32_e32 vcc, v131, v129
	s_nop 1
	v_cndmask_b32_e32 v129, v233, v131, vcc
	v_lshlrev_b32_e32 v155, 2, v129
	ds_bpermute_b32 v129, v155, v128
	s_and_saveexec_b64 s[44:45], s[42:43]
	s_cbranch_execz .LBB0_339
	v_ashrrev_i32_e32 v131, 31, v130
	v_readlane_b32 s10, v255, 44
	v_lshlrev_b64 v[148:149], 5, v[130:131]
	v_readlane_b32 s11, v255, 45
	s_waitcnt lgkmcnt(0)
	v_add_f32_e32 v128, v128, v129
	v_lshl_add_u64 v[148:149], s[10:11], 0, v[148:149]
	global_store_dword v[148:149], v128, off offset:16
.LBB0_339:
	s_or_b64 exec, exec, s[44:45]
	v_readlane_b32 s10, v255, 42
	v_readlane_b32 s11, v255, 43
	s_andn2_b64 vcc, exec, s[10:11]
	s_nop 0
	v_cndmask_b32_e64 v128, 0, 1, s[10:11]
	v_cmp_ne_u32_e64 s[44:45], 1, v128
	s_waitcnt lgkmcnt(0)
	v_lshlrev_b64 v[128:129], 3, v[146:147]
	s_cbranch_vccnz .LBB0_343
	v_and_b32_e32 v131, s90, v144
	v_lshlrev_b32_e32 v188, 9, v131
	v_lshl_add_u64 v[148:149], s[96:97], 0, v[188:189]
	v_lshl_add_u64 v[148:149], v[148:149], 0, v[128:129]
	global_load_dwordx2 v[156:157], v[148:149], off
	global_load_dwordx2 v[164:165], v[148:149], off offset:16
	global_load_dwordx2 v[166:167], v[148:149], off offset:32
	s_nop 0
	global_load_dwordx2 v[148:149], v[148:149], off offset:48
	v_ashrrev_i32_e32 v145, 31, v144
	v_readlane_b32 s10, v255, 40
	v_readlane_b32 s11, v255, 41
	s_waitcnt vmcnt(0) lgkmcnt(0)
	v_pk_mul_f32 v[168:169], v[116:117], v[156:157]
	v_pk_mul_f32 v[156:157], v[116:117], v[156:157] op_sel:[0,1] op_sel_hi:[1,0]
	v_sub_f32_e32 v131, v168, v169
	v_add_f32_e32 v163, v156, v157
	v_pk_mul_f32 v[156:157], v[118:119], v[164:165]
	s_nop 0
	v_sub_f32_e32 v168, v156, v157
	v_pk_mul_f32 v[156:157], v[118:119], v[164:165] op_sel:[0,1] op_sel_hi:[1,0]
	v_mul_f32_e32 v164, v131, v131
	v_add_f32_e32 v165, v156, v157
	v_pk_mul_f32 v[156:157], v[112:113], v[166:167]
	v_fmac_f32_e32 v164, v163, v163
	v_sub_f32_e32 v169, v156, v157
	v_pk_mul_f32 v[156:157], v[112:113], v[166:167] op_sel:[0,1] op_sel_hi:[1,0]
	s_nop 0
	v_add_f32_e32 v166, v156, v157
	v_pk_mul_f32 v[156:157], v[114:115], v[148:149]
	v_pk_mul_f32 v[148:149], v[114:115], v[148:149] op_sel:[0,1] op_sel_hi:[1,0]
	v_sub_f32_e32 v156, v156, v157
	v_add_f32_e32 v157, v148, v149
	v_mul_f32_e32 v148, v156, v156
	v_mul_f32_e32 v149, v169, v169
	v_fmac_f32_e32 v148, v157, v157
	v_fmac_f32_e32 v149, v166, v166
	v_add_f32_e32 v148, v149, v148
	v_mul_f32_e32 v149, v168, v168
	v_fmac_f32_e32 v149, v165, v165
	v_add_f32_e32 v149, v164, v149
	v_add_f32_e32 v170, v149, v148
	v_cvt_pk_bf16_f32 v164, v131, v163
	ds_bpermute_b32 v131, v154, v170
	v_lshlrev_b64 v[148:149], 7, v[144:145]
	v_lshl_add_u64 v[148:149], s[10:11], 0, v[148:149]
	v_lshl_add_u64 v[148:149], v[146:147], 1, v[148:149]
	v_cvt_pk_bf16_f32 v165, v168, v165
	s_waitcnt lgkmcnt(0)
	v_add_f32_e32 v145, v170, v131
	v_cvt_pk_bf16_f32 v166, v169, v166
	v_cvt_pk_bf16_f32 v167, v156, v157
	global_store_dwordx4 v[148:149], v[164:167], off
	ds_bpermute_b32 v148, v155, v145
	s_and_saveexec_b64 s[78:79], s[42:43]
	s_cbranch_execz .LBB0_342
	v_readlane_b32 s10, v255, 46
	v_ashrrev_i32_e32 v131, 31, v130
	v_readlane_b32 s11, v255, 47
	s_waitcnt lgkmcnt(0)
	v_add_f32_e32 v145, v145, v148
	v_lshl_add_u64 v[130:131], v[130:131], 3, s[10:11]
	global_store_dword v[130:131], v145, off

; __device__ __forceinline__ void st8(bf16_t* p, f32x4 a, f32x4 b) { u32x4 w = {cvt_pk(a[0], a[1]), cvt_pk(a[2], a[3]), cvt_pk(b[0], b[1]), cvt_pk(b[2], b[3])}; *(u32x4*)p = w; }
; __device__ __forceinline__ float dot4(f32x4 a) { return (a[0] * a[0] + a[1] * a[1]) + (a[2] * a[2] + a[3] * a[3]); }
; #define FOR_AI_M _Pragma("unroll") for (int ai = 0; ai < 2; ++ai) if ((__builtin_amdgcn_sched_barrier(0), true)) _Pragma("unroll") for (int m = 0; m < 4; ++m)
;   __device__ __forceinline__ void operator()(EPI_ARGS) const {
;     ...
;       FOR_AI_M { const int row = rbase + ai * 128 + m * 16, pos = (b.g0 + row) & b.slm;
;         { const f32x4 v0 = acc[ai][0][m][0], v1 = acc[ai][0][m][1]; float s = dot4(v0) + dot4(v1); st8(b.CQ + (size_t)row * 384 + 256 + c0, v0, v1);
;           s += __shfl_xor(s, 16); s += __shfl_xor(s, 32); if (fq == 0 && at) b.ssq_cq[(size_t)(b.g0 + row) * 8 + 4 + wc] = s; }
;         if (wc < 2) { f32x4 v0 = acc[ai][1][m][0], v1 = acc[ai][1][m][1]; const int j0 = wc * 16 + fq * 4;
;           const f32x2* tp = (const f32x2*)(b.rope + ((size_t)pos * 64 + 2 * j0) * 2); const f32x2 a0 = tp[0], a1 = tp[2], a2 = tp[4], a3 = tp[6];
;           rope4(v0, v1, (f32x4){a0[0], a0[1], a1[0], a1[1]}, (f32x4){a2[0], a2[1], a3[0], a3[1]});
;           float s = dot4(v0) + dot4(v1); st8(b.KR + (size_t)row * 64 + c0, v0, v1);
;           s += __shfl_xor(s, 16); s += __shfl_xor(s, 32); if (fq == 0 && at) b.ssq_kr[(size_t)(b.g0 + row) * 2 + wc] = s; } }
.LBB0_343:
	v_mul_f32_e32 v131, v109, v109
	v_mul_f32_e32 v145, v111, v111
	v_fmac_f32_e32 v131, v108, v108
	v_fmac_f32_e32 v145, v110, v110
	v_add_f32_e32 v131, v131, v145
	v_mul_f32_e32 v145, v105, v105
	v_mul_f32_e32 v149, v107, v107
	v_fmac_f32_e32 v145, v104, v104
	v_fmac_f32_e32 v149, v106, v106
	v_add_f32_e32 v145, v145, v149
	v_add_f32_e32 v131, v145, v131
	ds_bpermute_b32 v145, v154, v131
	v_readlane_b32 s10, v255, 36
	v_readlane_b32 s11, v255, 37
	s_waitcnt lgkmcnt(0)
	v_add_u32_e32 v148, 16, v144
	v_add_u32_e32 v130, s68, v148
	v_add_f32_e32 v145, v131, v145
	ds_bpermute_b32 v149, v155, v145
	v_mov_b64_e32 v[156:157], s[10:11]
	v_mad_i64_i32 v[156:157], s[18:19], v148, s8, v[156:157]
	v_lshl_add_u64 v[156:157], v[146:147], 1, v[156:157]
	v_cvt_pk_bf16_f32 v164, v108, v109
	v_cvt_pk_bf16_f32 v165, v110, v111
	v_cvt_pk_bf16_f32 v166, v104, v105
	v_cvt_pk_bf16_f32 v167, v106, v107
	global_store_dwordx4 v[156:157], v[164:167], off offset:512
	s_and_saveexec_b64 s[78:79], s[42:43]
	s_cbranch_execz .LBB0_345
	v_ashrrev_i32_e32 v131, 31, v130
	v_readlane_b32 s10, v255, 44
	v_lshlrev_b64 v[156:157], 5, v[130:131]
	v_readlane_b32 s11, v255, 45
	s_waitcnt lgkmcnt(0)
	v_add_f32_e32 v131, v145, v149
	v_lshl_add_u64 v[156:157], s[10:11], 0, v[156:157]
	global_store_dword v[156:157], v131, off offset:16
.LBB0_345:
	s_or_b64 exec, exec, s[78:79]
	s_and_b64 vcc, exec, s[44:45]
	s_cbranch_vccnz .LBB0_349
	v_and_b32_e32 v131, s90, v148
	v_lshlrev_b32_e32 v188, 9, v131
	v_lshl_add_u64 v[156:157], s[96:97], 0, v[188:189]
	v_lshl_add_u64 v[156:157], v[156:157], 0, v[128:129]
	global_load_dwordx2 v[164:165], v[156:157], off
	global_load_dwordx2 v[166:167], v[156:157], off offset:16
	global_load_dwordx2 v[168:169], v[156:157], off offset:32
	s_nop 0
	global_load_dwordx2 v[156:157], v[156:157], off offset:48
	s_waitcnt lgkmcnt(0)
	v_ashrrev_i32_e32 v149, 31, v148
	v_readlane_b32 s10, v255, 40
	v_lshlrev_b64 v[148:149], 7, v[148:149]
	v_readlane_b32 s11, v255, 41
	s_waitcnt vmcnt(0)
	v_pk_mul_f32 v[170:171], v[100:101], v[164:165]
	v_pk_mul_f32 v[164:165], v[100:101], v[164:165] op_sel:[0,1] op_sel_hi:[1,0]
	v_sub_f32_e32 v131, v170, v171
	v_add_f32_e32 v145, v164, v165
	v_pk_mul_f32 v[164:165], v[102:103], v[166:167]
	v_lshl_add_u64 v[148:149], s[10:11], 0, v[148:149]
	v_sub_f32_e32 v163, v164, v165
	v_pk_mul_f32 v[164:165], v[102:103], v[166:167] op_sel:[0,1] op_sel_hi:[1,0]
	v_lshl_add_u64 v[148:149], v[146:147], 1, v[148:149]
	v_add_f32_e32 v166, v164, v165
	v_pk_mul_f32 v[164:165], v[96:97], v[168:169]
	s_nop 0
	v_sub_f32_e32 v167, v164, v165
	v_pk_mul_f32 v[164:165], v[96:97], v[168:169] op_sel:[0,1] op_sel_hi:[1,0]
	s_nop 0
	v_add_f32_e32 v168, v164, v165
	v_pk_mul_f32 v[164:165], v[98:99], v[156:157]
	v_pk_mul_f32 v[156:157], v[98:99], v[156:157] op_sel:[0,1] op_sel_hi:[1,0]
	v_sub_f32_e32 v169, v164, v165
	v_add_f32_e32 v156, v156, v157
	v_mul_f32_e32 v157, v169, v169
	v_mul_f32_e32 v164, v167, v167
	v_fmac_f32_e32 v157, v156, v156
	v_fmac_f32_e32 v164, v168, v168
	v_add_f32_e32 v157, v164, v157
	v_mul_f32_e32 v164, v163, v163
	v_mul_f32_e32 v165, v131, v131
	v_fmac_f32_e32 v164, v166, v166
	v_fmac_f32_e32 v165, v145, v145
	v_add_f32_e32 v164, v165, v164
	v_add_f32_e32 v157, v164, v157
	v_cvt_pk_bf16_f32 v164, v131, v145
	ds_bpermute_b32 v131, v154, v157
	v_cvt_pk_bf16_f32 v165, v163, v166
	v_cvt_pk_bf16_f32 v166, v167, v168
	v_cvt_pk_bf16_f32 v167, v169, v156
	global_store_dwordx4 v[148:149], v[164:167], off
	s_waitcnt lgkmcnt(0)
	v_add_f32_e32 v145, v157, v131
	ds_bpermute_b32 v148, v155, v145
	s_and_saveexec_b64 s[78:79], s[42:43]
	s_cbranch_execz .LBB0_348
	v_readlane_b32 s10, v255, 46
	v_ashrrev_i32_e32 v131, 31, v130
	v_readlane_b32 s11, v255, 47
	s_waitcnt lgkmcnt(0)
	v_add_f32_e32 v145, v145, v148
	v_lshl_add_u64 v[130:131], v[130:131], 3, s[10:11]
	global_store_dword v[130:131], v145, off

; __device__ __forceinline__ void st8(bf16_t* p, f32x4 a, f32x4 b) { u32x4 w = {cvt_pk(a[0], a[1]), cvt_pk(a[2], a[3]), cvt_pk(b[0], b[1]), cvt_pk(b[2], b[3])}; *(u32x4*)p = w; }
; __device__ __forceinline__ float dot4(f32x4 a) { return (a[0] * a[0] + a[1] * a[1]) + (a[2] * a[2] + a[3] * a[3]); }
; #define FOR_AI_M _Pragma("unroll") for (int ai = 0; ai < 2; ++ai) if ((__builtin_amdgcn_sched_barrier(0), true)) _Pragma("unroll") for (int m = 0; m < 4; ++m)
;   __device__ __forceinline__ void operator()(EPI_ARGS) const {
;     ...
;       FOR_AI_M { const int row = rbase + ai * 128 + m * 16, pos = (b.g0 + row) & b.slm;
;         { const f32x4 v0 = acc[ai][0][m][0], v1 = acc[ai][0][m][1]; float s = dot4(v0) + dot4(v1); st8(b.CQ + (size_t)row * 384 + 256 + c0, v0, v1);
;           s += __shfl_xor(s, 16); s += __shfl_xor(s, 32); if (fq == 0 && at) b.ssq_cq[(size_t)(b.g0 + row) * 8 + 4 + wc] = s; }
;         if (wc < 2) { f32x4 v0 = acc[ai][1][m][0], v1 = acc[ai][1][m][1]; const int j0 = wc * 16 + fq * 4;
;           const f32x2* tp = (const f32x2*)(b.rope + ((size_t)pos * 64 + 2 * j0) * 2); const f32x2 a0 = tp[0], a1 = tp[2], a2 = tp[4], a3 = tp[6];
;           rope4(v0, v1, (f32x4){a0[0], a0[1], a1[0], a1[1]}, (f32x4){a2[0], a2[1], a3[0], a3[1]});
;           float s = dot4(v0) + dot4(v1); st8(b.KR + (size_t)row * 64 + c0, v0, v1);
;           s += __shfl_xor(s, 16); s += __shfl_xor(s, 32); if (fq == 0 && at) b.ssq_kr[(size_t)(b.g0 + row) * 2 + wc] = s; } }
.LBB0_349:
	v_mul_f32_e32 v131, v93, v93
	v_mul_f32_e32 v145, v95, v95
	v_fmac_f32_e32 v131, v92, v92
	v_fmac_f32_e32 v145, v94, v94
	v_add_f32_e32 v131, v131, v145
	v_mul_f32_e32 v145, v89, v89
	s_waitcnt lgkmcnt(0)
	v_mul_f32_e32 v149, v91, v91
	v_fmac_f32_e32 v145, v88, v88
	v_fmac_f32_e32 v149, v90, v90
	v_add_f32_e32 v145, v145, v149
	v_add_f32_e32 v131, v145, v131
	ds_bpermute_b32 v145, v154, v131
	v_readlane_b32 s10, v255, 36
	v_readlane_b32 s11, v255, 37
	v_add_u32_e32 v148, 32, v144
	v_add_u32_e32 v130, s68, v148
	s_waitcnt lgkmcnt(0)
	v_add_f32_e32 v145, v131, v145
	ds_bpermute_b32 v149, v155, v145
	v_mov_b64_e32 v[156:157], s[10:11]
	v_mad_i64_i32 v[156:157], s[18:19], v148, s8, v[156:157]
	v_lshl_add_u64 v[156:157], v[146:147], 1, v[156:157]
	v_cvt_pk_bf16_f32 v164, v92, v93
	v_cvt_pk_bf16_f32 v165, v94, v95
	v_cvt_pk_bf16_f32 v166, v88, v89
	v_cvt_pk_bf16_f32 v167, v90, v91
	global_store_dwordx4 v[156:157], v[164:167], off offset:512
	s_and_saveexec_b64 s[78:79], s[42:43]
	s_cbranch_execz .LBB0_351
	v_ashrrev_i32_e32 v131, 31, v130
	v_readlane_b32 s10, v255, 44
	v_lshlrev_b64 v[156:157], 5, v[130:131]
	v_readlane_b32 s11, v255, 45
	s_waitcnt lgkmcnt(0)
	v_add_f32_e32 v131, v145, v149
	v_lshl_add_u64 v[156:157], s[10:11], 0, v[156:157]
	global_store_dword v[156:157], v131, off offset:16
.LBB0_351:
	s_or_b64 exec, exec, s[78:79]
	s_and_b64 vcc, exec, s[44:45]
	s_cbranch_vccnz .LBB0_355
	v_and_b32_e32 v131, s90, v148
	v_lshlrev_b32_e32 v188, 9, v131
	v_lshl_add_u64 v[156:157], s[96:97], 0, v[188:189]
	v_lshl_add_u64 v[156:157], v[156:157], 0, v[128:129]
	global_load_dwordx2 v[164:165], v[156:157], off
	global_load_dwordx2 v[166:167], v[156:157], off offset:16
	global_load_dwordx2 v[168:169], v[156:157], off offset:32
	s_nop 0
	global_load_dwordx2 v[156:157], v[156:157], off offset:48
	s_waitcnt lgkmcnt(0)
	v_ashrrev_i32_e32 v149, 31, v148
	v_readlane_b32 s10, v255, 40
	v_lshlrev_b64 v[148:149], 7, v[148:149]
	v_readlane_b32 s11, v255, 41
	s_waitcnt vmcnt(0)
	v_pk_mul_f32 v[170:171], v[84:85], v[164:165]
	v_pk_mul_f32 v[164:165], v[84:85], v[164:165] op_sel:[0,1] op_sel_hi:[1,0]
	v_sub_f32_e32 v131, v170, v171
	v_add_f32_e32 v145, v164, v165
	v_pk_mul_f32 v[164:165], v[86:87], v[166:167]
	v_lshl_add_u64 v[148:149], s[10:11], 0, v[148:149]
	v_sub_f32_e32 v163, v164, v165
	v_pk_mul_f32 v[164:165], v[86:87], v[166:167] op_sel:[0,1] op_sel_hi:[1,0]
	v_lshl_add_u64 v[148:149], v[146:147], 1, v[148:149]
	v_add_f32_e32 v166, v164, v165
	v_pk_mul_f32 v[164:165], v[80:81], v[168:169]
	s_nop 0
	v_sub_f32_e32 v167, v164, v165
	v_pk_mul_f32 v[164:165], v[80:81], v[168:169] op_sel:[0,1] op_sel_hi:[1,0]
	s_nop 0
	v_add_f32_e32 v168, v164, v165
	v_pk_mul_f32 v[164:165], v[82:83], v[156:157]
	v_pk_mul_f32 v[156:157], v[82:83], v[156:157] op_sel:[0,1] op_sel_hi:[1,0]
	v_sub_f32_e32 v169, v164, v165
	v_add_f32_e32 v156, v156, v157
	v_mul_f32_e32 v157, v169, v169
	v_mul_f32_e32 v164, v167, v167
	v_fmac_f32_e32 v157, v156, v156
	v_fmac_f32_e32 v164, v168, v168
	v_add_f32_e32 v157, v164, v157
	v_mul_f32_e32 v164, v163, v163
	v_mul_f32_e32 v165, v131, v131
	v_fmac_f32_e32 v164, v166, v166
	v_fmac_f32_e32 v165, v145, v145
	v_add_f32_e32 v164, v165, v164
	v_add_f32_e32 v157, v164, v157
	v_cvt_pk_bf16_f32 v164, v131, v145
	ds_bpermute_b32 v131, v154, v157
	v_cvt_pk_bf16_f32 v165, v163, v166
	v_cvt_pk_bf16_f32 v166, v167, v168
	v_cvt_pk_bf16_f32 v167, v169, v156
	global_store_dwordx4 v[148:149], v[164:167], off
	s_waitcnt lgkmcnt(0)
	v_add_f32_e32 v145, v157, v131
	ds_bpermute_b32 v148, v155, v145
	s_and_saveexec_b64 s[78:79], s[42:43]
	s_cbranch_execz .LBB0_354
	v_readlane_b32 s10, v255, 46
	v_ashrrev_i32_e32 v131, 31, v130
	v_readlane_b32 s11, v255, 47
	s_waitcnt lgkmcnt(0)
	v_add_f32_e32 v145, v145, v148
	v_lshl_add_u64 v[130:131], v[130:131], 3, s[10:11]
	global_store_dword v[130:131], v145, off

; __device__ __forceinline__ void st8(bf16_t* p, f32x4 a, f32x4 b) { u32x4 w = {cvt_pk(a[0], a[1]), cvt_pk(a[2], a[3]), cvt_pk(b[0], b[1]), cvt_pk(b[2], b[3])}; *(u32x4*)p = w; }
; __device__ __forceinline__ float dot4(f32x4 a) { return (a[0] * a[0] + a[1] * a[1]) + (a[2] * a[2] + a[3] * a[3]); }
; #define FOR_AI_M _Pragma("unroll") for (int ai = 0; ai < 2; ++ai) if ((__builtin_amdgcn_sched_barrier(0), true)) _Pragma("unroll") for (int m = 0; m < 4; ++m)
;   __device__ __forceinline__ void operator()(EPI_ARGS) const {
;     ...
;       FOR_AI_M { const int row = rbase + ai * 128 + m * 16, pos = (b.g0 + row) & b.slm;
;         { const f32x4 v0 = acc[ai][0][m][0], v1 = acc[ai][0][m][1]; float s = dot4(v0) + dot4(v1); st8(b.CQ + (size_t)row * 384 + 256 + c0, v0, v1);
;           s += __shfl_xor(s, 16); s += __shfl_xor(s, 32); if (fq == 0 && at) b.ssq_cq[(size_t)(b.g0 + row) * 8 + 4 + wc] = s; }
;         if (wc < 2) { f32x4 v0 = acc[ai][1][m][0], v1 = acc[ai][1][m][1]; const int j0 = wc * 16 + fq * 4;
;           const f32x2* tp = (const f32x2*)(b.rope + ((size_t)pos * 64 + 2 * j0) * 2); const f32x2 a0 = tp[0], a1 = tp[2], a2 = tp[4], a3 = tp[6];
;           rope4(v0, v1, (f32x4){a0[0], a0[1], a1[0], a1[1]}, (f32x4){a2[0], a2[1], a3[0], a3[1]});
;           float s = dot4(v0) + dot4(v1); st8(b.KR + (size_t)row * 64 + c0, v0, v1);
;           s += __shfl_xor(s, 16); s += __shfl_xor(s, 32); if (fq == 0 && at) b.ssq_kr[(size_t)(b.g0 + row) * 2 + wc] = s; } }
.LBB0_355:
	v_mul_f32_e32 v131, v77, v77
	v_mul_f32_e32 v145, v79, v79
	v_fmac_f32_e32 v131, v76, v76
	v_fmac_f32_e32 v145, v78, v78
	v_add_f32_e32 v131, v131, v145
	v_mul_f32_e32 v145, v73, v73
	s_waitcnt lgkmcnt(0)
	v_mul_f32_e32 v149, v75, v75
	v_fmac_f32_e32 v145, v72, v72
	v_fmac_f32_e32 v149, v74, v74
	v_add_f32_e32 v145, v145, v149
	v_add_f32_e32 v131, v145, v131
	ds_bpermute_b32 v145, v154, v131
	v_readlane_b32 s10, v255, 36
	v_readlane_b32 s11, v255, 37
	v_add_u32_e32 v148, 48, v144
	v_add_u32_e32 v130, s68, v148
	s_waitcnt lgkmcnt(0)
	v_add_f32_e32 v145, v131, v145
	ds_bpermute_b32 v149, v155, v145
	v_mov_b64_e32 v[156:157], s[10:11]
	v_mad_i64_i32 v[156:157], s[18:19], v148, s8, v[156:157]
	v_lshl_add_u64 v[156:157], v[146:147], 1, v[156:157]
	v_cvt_pk_bf16_f32 v164, v76, v77
	v_cvt_pk_bf16_f32 v165, v78, v79
	v_cvt_pk_bf16_f32 v166, v72, v73
	v_cvt_pk_bf16_f32 v167, v74, v75
	global_store_dwordx4 v[156:157], v[164:167], off offset:512
	s_and_saveexec_b64 s[78:79], s[42:43]
	s_cbranch_execz .LBB0_357
	v_ashrrev_i32_e32 v131, 31, v130
	v_readlane_b32 s10, v255, 44
	v_lshlrev_b64 v[156:157], 5, v[130:131]
	v_readlane_b32 s11, v255, 45
	s_waitcnt lgkmcnt(0)
	v_add_f32_e32 v131, v145, v149
	v_lshl_add_u64 v[156:157], s[10:11], 0, v[156:157]
	global_store_dword v[156:157], v131, off offset:16
.LBB0_357:
	s_or_b64 exec, exec, s[78:79]
	s_and_b64 vcc, exec, s[44:45]
	s_cbranch_vccnz .LBB0_361
	v_and_b32_e32 v131, s90, v148
	v_lshlrev_b32_e32 v188, 9, v131
	v_lshl_add_u64 v[156:157], s[96:97], 0, v[188:189]
	v_lshl_add_u64 v[156:157], v[156:157], 0, v[128:129]
	global_load_dwordx2 v[164:165], v[156:157], off
	global_load_dwordx2 v[166:167], v[156:157], off offset:16
	global_load_dwordx2 v[168:169], v[156:157], off offset:32
	s_nop 0
	global_load_dwordx2 v[156:157], v[156:157], off offset:48
	s_waitcnt lgkmcnt(0)
	v_ashrrev_i32_e32 v149, 31, v148
	v_readlane_b32 s10, v255, 40
	v_lshlrev_b64 v[148:149], 7, v[148:149]
	v_readlane_b32 s11, v255, 41
	s_waitcnt vmcnt(0)
	v_pk_mul_f32 v[170:171], v[68:69], v[164:165]
	v_pk_mul_f32 v[164:165], v[68:69], v[164:165] op_sel:[0,1] op_sel_hi:[1,0]
	v_sub_f32_e32 v131, v170, v171
	v_add_f32_e32 v145, v164, v165
	v_pk_mul_f32 v[164:165], v[70:71], v[166:167]
	v_lshl_add_u64 v[148:149], s[10:11], 0, v[148:149]
	v_sub_f32_e32 v163, v164, v165
	v_pk_mul_f32 v[164:165], v[70:71], v[166:167] op_sel:[0,1] op_sel_hi:[1,0]
	v_lshl_add_u64 v[148:149], v[146:147], 1, v[148:149]
	v_add_f32_e32 v166, v164, v165
	v_pk_mul_f32 v[164:165], v[64:65], v[168:169]
	s_nop 0
	v_sub_f32_e32 v167, v164, v165
	v_pk_mul_f32 v[164:165], v[64:65], v[168:169] op_sel:[0,1] op_sel_hi:[1,0]
	s_nop 0
	v_add_f32_e32 v168, v164, v165
	v_pk_mul_f32 v[164:165], v[66:67], v[156:157]
	v_pk_mul_f32 v[156:157], v[66:67], v[156:157] op_sel:[0,1] op_sel_hi:[1,0]
	v_sub_f32_e32 v169, v164, v165
	v_add_f32_e32 v156, v156, v157
	v_mul_f32_e32 v157, v169, v169
	v_mul_f32_e32 v164, v167, v167
	v_fmac_f32_e32 v157, v156, v156
	v_fmac_f32_e32 v164, v168, v168
	v_add_f32_e32 v157, v164, v157
	v_mul_f32_e32 v164, v163, v163
	v_mul_f32_e32 v165, v131, v131
	v_fmac_f32_e32 v164, v166, v166
	v_fmac_f32_e32 v165, v145, v145
	v_add_f32_e32 v164, v165, v164
	v_add_f32_e32 v157, v164, v157
	v_cvt_pk_bf16_f32 v164, v131, v145
	ds_bpermute_b32 v131, v154, v157
	v_cvt_pk_bf16_f32 v165, v163, v166
	v_cvt_pk_bf16_f32 v166, v167, v168
	v_cvt_pk_bf16_f32 v167, v169, v156
	global_store_dwordx4 v[148:149], v[164:167], off
	s_waitcnt lgkmcnt(0)
	v_add_f32_e32 v145, v157, v131
	ds_bpermute_b32 v148, v155, v145
	s_and_saveexec_b64 s[78:79], s[42:43]
	s_cbranch_execz .LBB0_360
	v_readlane_b32 s10, v255, 46
	v_ashrrev_i32_e32 v131, 31, v130
	v_readlane_b32 s11, v255, 47
	s_waitcnt lgkmcnt(0)
	v_add_f32_e32 v145, v145, v148
	v_lshl_add_u64 v[130:131], v[130:131], 3, s[10:11]
	global_store_dword v[130:131], v145, off

; __device__ __forceinline__ void st8(bf16_t* p, f32x4 a, f32x4 b) { u32x4 w = {cvt_pk(a[0], a[1]), cvt_pk(a[2], a[3]), cvt_pk(b[0], b[1]), cvt_pk(b[2], b[3])}; *(u32x4*)p = w; }
; __device__ __forceinline__ float dot4(f32x4 a) { return (a[0] * a[0] + a[1] * a[1]) + (a[2] * a[2] + a[3] * a[3]); }
; #define FOR_AI_M _Pragma("unroll") for (int ai = 0; ai < 2; ++ai) if ((__builtin_amdgcn_sched_barrier(0), true)) _Pragma("unroll") for (int m = 0; m < 4; ++m)
;   __device__ __forceinline__ void operator()(EPI_ARGS) const {
;     ...
;       FOR_AI_M { const int row = rbase + ai * 128 + m * 16, pos = (b.g0 + row) & b.slm;
;         { const f32x4 v0 = acc[ai][0][m][0], v1 = acc[ai][0][m][1]; float s = dot4(v0) + dot4(v1); st8(b.CQ + (size_t)row * 384 + 256 + c0, v0, v1);
;           s += __shfl_xor(s, 16); s += __shfl_xor(s, 32); if (fq == 0 && at) b.ssq_cq[(size_t)(b.g0 + row) * 8 + 4 + wc] = s; }
;         if (wc < 2) { f32x4 v0 = acc[ai][1][m][0], v1 = acc[ai][1][m][1]; const int j0 = wc * 16 + fq * 4;
;           const f32x2* tp = (const f32x2*)(b.rope + ((size_t)pos * 64 + 2 * j0) * 2); const f32x2 a0 = tp[0], a1 = tp[2], a2 = tp[4], a3 = tp[6];
;           rope4(v0, v1, (f32x4){a0[0], a0[1], a1[0], a1[1]}, (f32x4){a2[0], a2[1], a3[0], a3[1]});
;           float s = dot4(v0) + dot4(v1); st8(b.KR + (size_t)row * 64 + c0, v0, v1);
;           s += __shfl_xor(s, 16); s += __shfl_xor(s, 32); if (fq == 0 && at) b.ssq_kr[(size_t)(b.g0 + row) * 2 + wc] = s; } }
.LBB0_361:
	v_mul_f32_e32 v131, v61, v61
	v_mul_f32_e32 v145, v63, v63
	v_fmac_f32_e32 v131, v60, v60
	v_fmac_f32_e32 v145, v62, v62
	v_add_f32_e32 v131, v131, v145
	v_mul_f32_e32 v145, v57, v57
	s_waitcnt lgkmcnt(0)
	v_mul_f32_e32 v149, v59, v59
	v_fmac_f32_e32 v145, v56, v56
	v_fmac_f32_e32 v149, v58, v58
	v_add_f32_e32 v145, v145, v149
	v_add_f32_e32 v131, v145, v131
	ds_bpermute_b32 v145, v154, v131
	v_readlane_b32 s10, v255, 36
	v_readlane_b32 s11, v255, 37
	v_add_u32_e32 v148, 0x80, v144
	v_add_u32_e32 v130, s68, v148
	s_waitcnt lgkmcnt(0)
	v_add_f32_e32 v145, v131, v145
	ds_bpermute_b32 v149, v155, v145
	v_mov_b64_e32 v[156:157], s[10:11]
	v_mad_i64_i32 v[156:157], s[18:19], v148, s8, v[156:157]
	v_lshl_add_u64 v[156:157], v[146:147], 1, v[156:157]
	v_cvt_pk_bf16_f32 v164, v60, v61
	v_cvt_pk_bf16_f32 v165, v62, v63
	v_cvt_pk_bf16_f32 v166, v56, v57
	v_cvt_pk_bf16_f32 v167, v58, v59
	global_store_dwordx4 v[156:157], v[164:167], off offset:512
	s_and_saveexec_b64 s[78:79], s[42:43]
	s_cbranch_execz .LBB0_363
	v_ashrrev_i32_e32 v131, 31, v130
	v_readlane_b32 s10, v255, 44
	v_lshlrev_b64 v[156:157], 5, v[130:131]
	v_readlane_b32 s11, v255, 45
	s_waitcnt lgkmcnt(0)
	v_add_f32_e32 v131, v145, v149
	v_lshl_add_u64 v[156:157], s[10:11], 0, v[156:157]
	global_store_dword v[156:157], v131, off offset:16
.LBB0_363:
	s_or_b64 exec, exec, s[78:79]
	s_and_b64 vcc, exec, s[44:45]
	s_cbranch_vccnz .LBB0_367
	v_and_b32_e32 v131, s90, v148
	v_lshlrev_b32_e32 v188, 9, v131
	v_lshl_add_u64 v[156:157], s[96:97], 0, v[188:189]
	v_lshl_add_u64 v[156:157], v[156:157], 0, v[128:129]
	global_load_dwordx2 v[164:165], v[156:157], off
	global_load_dwordx2 v[166:167], v[156:157], off offset:16
	global_load_dwordx2 v[168:169], v[156:157], off offset:32
	s_nop 0
	global_load_dwordx2 v[156:157], v[156:157], off offset:48
	s_waitcnt lgkmcnt(0)
	v_ashrrev_i32_e32 v149, 31, v148
	v_readlane_b32 s10, v255, 40
	v_lshlrev_b64 v[148:149], 7, v[148:149]
	v_readlane_b32 s11, v255, 41
	s_waitcnt vmcnt(0)
	v_pk_mul_f32 v[170:171], v[52:53], v[164:165]
	v_pk_mul_f32 v[164:165], v[52:53], v[164:165] op_sel:[0,1] op_sel_hi:[1,0]
	v_sub_f32_e32 v131, v170, v171
	v_add_f32_e32 v145, v164, v165
	v_pk_mul_f32 v[164:165], v[54:55], v[166:167]
	v_lshl_add_u64 v[148:149], s[10:11], 0, v[148:149]
	v_sub_f32_e32 v163, v164, v165
	v_pk_mul_f32 v[164:165], v[54:55], v[166:167] op_sel:[0,1] op_sel_hi:[1,0]
	v_lshl_add_u64 v[148:149], v[146:147], 1, v[148:149]
	v_add_f32_e32 v166, v164, v165
	v_pk_mul_f32 v[164:165], v[48:49], v[168:169]
	s_nop 0
	v_sub_f32_e32 v167, v164, v165
	v_pk_mul_f32 v[164:165], v[48:49], v[168:169] op_sel:[0,1] op_sel_hi:[1,0]
	s_nop 0
	v_add_f32_e32 v168, v164, v165
	v_pk_mul_f32 v[164:165], v[50:51], v[156:157]
	v_pk_mul_f32 v[156:157], v[50:51], v[156:157] op_sel:[0,1] op_sel_hi:[1,0]
	v_sub_f32_e32 v169, v164, v165
	v_add_f32_e32 v156, v156, v157
	v_mul_f32_e32 v157, v169, v169
	v_mul_f32_e32 v164, v167, v167
	v_fmac_f32_e32 v157, v156, v156
	v_fmac_f32_e32 v164, v168, v168
	v_add_f32_e32 v157, v164, v157
	v_mul_f32_e32 v164, v163, v163
	v_mul_f32_e32 v165, v131, v131
	v_fmac_f32_e32 v164, v166, v166
	v_fmac_f32_e32 v165, v145, v145
	v_add_f32_e32 v164, v165, v164
	v_add_f32_e32 v157, v164, v157
	v_cvt_pk_bf16_f32 v164, v131, v145
	ds_bpermute_b32 v131, v154, v157
	v_cvt_pk_bf16_f32 v165, v163, v166
	v_cvt_pk_bf16_f32 v166, v167, v168
	v_cvt_pk_bf16_f32 v167, v169, v156
	global_store_dwordx4 v[148:149], v[164:167], off
	s_waitcnt lgkmcnt(0)
	v_add_f32_e32 v145, v157, v131
	ds_bpermute_b32 v148, v155, v145
	s_and_saveexec_b64 s[78:79], s[42:43]
	s_cbranch_execz .LBB0_366
	v_readlane_b32 s10, v255, 46
	v_ashrrev_i32_e32 v131, 31, v130
	v_readlane_b32 s11, v255, 47
	s_waitcnt lgkmcnt(0)
	v_add_f32_e32 v145, v145, v148
	v_lshl_add_u64 v[130:131], v[130:131], 3, s[10:11]
	global_store_dword v[130:131], v145, off

; __device__ __forceinline__ void st8(bf16_t* p, f32x4 a, f32x4 b) { u32x4 w = {cvt_pk(a[0], a[1]), cvt_pk(a[2], a[3]), cvt_pk(b[0], b[1]), cvt_pk(b[2], b[3])}; *(u32x4*)p = w; }
; __device__ __forceinline__ float dot4(f32x4 a) { return (a[0] * a[0] + a[1] * a[1]) + (a[2] * a[2] + a[3] * a[3]); }
; #define FOR_AI_M _Pragma("unroll") for (int ai = 0; ai < 2; ++ai) if ((__builtin_amdgcn_sched_barrier(0), true)) _Pragma("unroll") for (int m = 0; m < 4; ++m)
;   __device__ __forceinline__ void operator()(EPI_ARGS) const {
;     ...
;       FOR_AI_M { const int row = rbase + ai * 128 + m * 16, pos = (b.g0 + row) & b.slm;
;         { const f32x4 v0 = acc[ai][0][m][0], v1 = acc[ai][0][m][1]; float s = dot4(v0) + dot4(v1); st8(b.CQ + (size_t)row * 384 + 256 + c0, v0, v1);
;           s += __shfl_xor(s, 16); s += __shfl_xor(s, 32); if (fq == 0 && at) b.ssq_cq[(size_t)(b.g0 + row) * 8 + 4 + wc] = s; }
;         if (wc < 2) { f32x4 v0 = acc[ai][1][m][0], v1 = acc[ai][1][m][1]; const int j0 = wc * 16 + fq * 4;
;           const f32x2* tp = (const f32x2*)(b.rope + ((size_t)pos * 64 + 2 * j0) * 2); const f32x2 a0 = tp[0], a1 = tp[2], a2 = tp[4], a3 = tp[6];
;           rope4(v0, v1, (f32x4){a0[0], a0[1], a1[0], a1[1]}, (f32x4){a2[0], a2[1], a3[0], a3[1]});
;           float s = dot4(v0) + dot4(v1); st8(b.KR + (size_t)row * 64 + c0, v0, v1);
;           s += __shfl_xor(s, 16); s += __shfl_xor(s, 32); if (fq == 0 && at) b.ssq_kr[(size_t)(b.g0 + row) * 2 + wc] = s; } }
.LBB0_367:
	v_mul_f32_e32 v131, v45, v45
	v_mul_f32_e32 v145, v47, v47
	v_fmac_f32_e32 v131, v44, v44
	v_fmac_f32_e32 v145, v46, v46
	v_add_f32_e32 v131, v131, v145
	v_mul_f32_e32 v145, v41, v41
	s_waitcnt lgkmcnt(0)
	v_mul_f32_e32 v149, v43, v43
	v_fmac_f32_e32 v145, v40, v40
	v_fmac_f32_e32 v149, v42, v42
	v_add_f32_e32 v145, v145, v149
	v_add_f32_e32 v131, v145, v131
	ds_bpermute_b32 v145, v154, v131
	v_readlane_b32 s10, v255, 36
	v_readlane_b32 s11, v255, 37
	v_add_u32_e32 v148, 0x90, v144
	v_add_u32_e32 v130, s68, v148
	s_waitcnt lgkmcnt(0)
	v_add_f32_e32 v145, v131, v145
	ds_bpermute_b32 v149, v155, v145
	v_mov_b64_e32 v[156:157], s[10:11]
	v_mad_i64_i32 v[156:157], s[18:19], v148, s8, v[156:157]
	v_lshl_add_u64 v[156:157], v[146:147], 1, v[156:157]
	v_cvt_pk_bf16_f32 v164, v44, v45
	v_cvt_pk_bf16_f32 v165, v46, v47
	v_cvt_pk_bf16_f32 v166, v40, v41
	v_cvt_pk_bf16_f32 v167, v42, v43
	global_store_dwordx4 v[156:157], v[164:167], off offset:512
	s_and_saveexec_b64 s[78:79], s[42:43]
	s_cbranch_execz .LBB0_369
	v_ashrrev_i32_e32 v131, 31, v130
	v_readlane_b32 s10, v255, 44
	v_lshlrev_b64 v[156:157], 5, v[130:131]
	v_readlane_b32 s11, v255, 45
	s_waitcnt lgkmcnt(0)
	v_add_f32_e32 v131, v145, v149
	v_lshl_add_u64 v[156:157], s[10:11], 0, v[156:157]
	global_store_dword v[156:157], v131, off offset:16
.LBB0_369:
	s_or_b64 exec, exec, s[78:79]
	s_and_b64 vcc, exec, s[44:45]
	s_cbranch_vccnz .LBB0_373
	v_and_b32_e32 v131, s90, v148
	v_lshlrev_b32_e32 v188, 9, v131
	v_lshl_add_u64 v[156:157], s[96:97], 0, v[188:189]
	v_lshl_add_u64 v[156:157], v[156:157], 0, v[128:129]
	global_load_dwordx2 v[164:165], v[156:157], off
	global_load_dwordx2 v[166:167], v[156:157], off offset:16
	global_load_dwordx2 v[168:169], v[156:157], off offset:32
	s_nop 0
	global_load_dwordx2 v[156:157], v[156:157], off offset:48
	s_waitcnt lgkmcnt(0)
	v_ashrrev_i32_e32 v149, 31, v148
	v_readlane_b32 s10, v255, 40
	v_lshlrev_b64 v[148:149], 7, v[148:149]
	v_readlane_b32 s11, v255, 41
	s_waitcnt vmcnt(0)
	v_pk_mul_f32 v[170:171], v[36:37], v[164:165]
	v_pk_mul_f32 v[164:165], v[36:37], v[164:165] op_sel:[0,1] op_sel_hi:[1,0]
	v_sub_f32_e32 v131, v170, v171
	v_add_f32_e32 v145, v164, v165
	v_pk_mul_f32 v[164:165], v[38:39], v[166:167]
	v_lshl_add_u64 v[148:149], s[10:11], 0, v[148:149]
	v_sub_f32_e32 v163, v164, v165
	v_pk_mul_f32 v[164:165], v[38:39], v[166:167] op_sel:[0,1] op_sel_hi:[1,0]
	v_lshl_add_u64 v[148:149], v[146:147], 1, v[148:149]
	v_add_f32_e32 v166, v164, v165
	v_pk_mul_f32 v[164:165], v[32:33], v[168:169]
	s_nop 0
	v_sub_f32_e32 v167, v164, v165
	v_pk_mul_f32 v[164:165], v[32:33], v[168:169] op_sel:[0,1] op_sel_hi:[1,0]
	s_nop 0
	v_add_f32_e32 v168, v164, v165
	v_pk_mul_f32 v[164:165], v[34:35], v[156:157]
	v_pk_mul_f32 v[156:157], v[34:35], v[156:157] op_sel:[0,1] op_sel_hi:[1,0]
	v_sub_f32_e32 v169, v164, v165
	v_add_f32_e32 v156, v156, v157
	v_mul_f32_e32 v157, v169, v169
	v_mul_f32_e32 v164, v167, v167
	v_fmac_f32_e32 v157, v156, v156
	v_fmac_f32_e32 v164, v168, v168
	v_add_f32_e32 v157, v164, v157
	v_mul_f32_e32 v164, v163, v163
	v_mul_f32_e32 v165, v131, v131
	v_fmac_f32_e32 v164, v166, v166
	v_fmac_f32_e32 v165, v145, v145
	v_add_f32_e32 v164, v165, v164
	v_add_f32_e32 v157, v164, v157
	v_cvt_pk_bf16_f32 v164, v131, v145
	ds_bpermute_b32 v131, v154, v157
	v_cvt_pk_bf16_f32 v165, v163, v166
	v_cvt_pk_bf16_f32 v166, v167, v168
	v_cvt_pk_bf16_f32 v167, v169, v156
	global_store_dwordx4 v[148:149], v[164:167], off
	s_waitcnt lgkmcnt(0)
	v_add_f32_e32 v145, v157, v131
	ds_bpermute_b32 v148, v155, v145
	s_and_saveexec_b64 s[78:79], s[42:43]
	s_cbranch_execz .LBB0_372
	v_readlane_b32 s10, v255, 46
	v_ashrrev_i32_e32 v131, 31, v130
	v_readlane_b32 s11, v255, 47
	s_waitcnt lgkmcnt(0)
	v_add_f32_e32 v145, v145, v148
	v_lshl_add_u64 v[130:131], v[130:131], 3, s[10:11]
	global_store_dword v[130:131], v145, off

; __device__ __forceinline__ void st8(bf16_t* p, f32x4 a, f32x4 b) { u32x4 w = {cvt_pk(a[0], a[1]), cvt_pk(a[2], a[3]), cvt_pk(b[0], b[1]), cvt_pk(b[2], b[3])}; *(u32x4*)p = w; }
; __device__ __forceinline__ float dot4(f32x4 a) { return (a[0] * a[0] + a[1] * a[1]) + (a[2] * a[2] + a[3] * a[3]); }
; #define FOR_AI_M _Pragma("unroll") for (int ai = 0; ai < 2; ++ai) if ((__builtin_amdgcn_sched_barrier(0), true)) _Pragma("unroll") for (int m = 0; m < 4; ++m)
;   __device__ __forceinline__ void operator()(EPI_ARGS) const {
;     ...
;       FOR_AI_M { const int row = rbase + ai * 128 + m * 16, pos = (b.g0 + row) & b.slm;
;         { const f32x4 v0 = acc[ai][0][m][0], v1 = acc[ai][0][m][1]; float s = dot4(v0) + dot4(v1); st8(b.CQ + (size_t)row * 384 + 256 + c0, v0, v1);
;           s += __shfl_xor(s, 16); s += __shfl_xor(s, 32); if (fq == 0 && at) b.ssq_cq[(size_t)(b.g0 + row) * 8 + 4 + wc] = s; }
;         if (wc < 2) { f32x4 v0 = acc[ai][1][m][0], v1 = acc[ai][1][m][1]; const int j0 = wc * 16 + fq * 4;
;           const f32x2* tp = (const f32x2*)(b.rope + ((size_t)pos * 64 + 2 * j0) * 2); const f32x2 a0 = tp[0], a1 = tp[2], a2 = tp[4], a3 = tp[6];
;           rope4(v0, v1, (f32x4){a0[0], a0[1], a1[0], a1[1]}, (f32x4){a2[0], a2[1], a3[0], a3[1]});
;           float s = dot4(v0) + dot4(v1); st8(b.KR + (size_t)row * 64 + c0, v0, v1);
;           s += __shfl_xor(s, 16); s += __shfl_xor(s, 32); if (fq == 0 && at) b.ssq_kr[(size_t)(b.g0 + row) * 2 + wc] = s; } }
.LBB0_373:
	v_mul_f32_e32 v131, v29, v29
	v_mul_f32_e32 v145, v31, v31
	v_fmac_f32_e32 v131, v28, v28
	v_fmac_f32_e32 v145, v30, v30
	v_add_f32_e32 v131, v131, v145
	v_mul_f32_e32 v145, v25, v25
	s_waitcnt lgkmcnt(0)
	v_mul_f32_e32 v149, v27, v27
	v_fmac_f32_e32 v145, v24, v24
	v_fmac_f32_e32 v149, v26, v26
	v_add_f32_e32 v145, v145, v149
	v_add_f32_e32 v131, v145, v131
	ds_bpermute_b32 v145, v154, v131
	v_readlane_b32 s10, v255, 36
	v_readlane_b32 s11, v255, 37
	v_add_u32_e32 v148, 0xa0, v144
	v_add_u32_e32 v130, s68, v148
	s_waitcnt lgkmcnt(0)
	v_add_f32_e32 v145, v131, v145
	ds_bpermute_b32 v149, v155, v145
	v_mov_b64_e32 v[156:157], s[10:11]
	v_mad_i64_i32 v[156:157], s[18:19], v148, s8, v[156:157]
	v_lshl_add_u64 v[156:157], v[146:147], 1, v[156:157]
	v_cvt_pk_bf16_f32 v164, v28, v29
	v_cvt_pk_bf16_f32 v165, v30, v31
	v_cvt_pk_bf16_f32 v166, v24, v25
	v_cvt_pk_bf16_f32 v167, v26, v27
	global_store_dwordx4 v[156:157], v[164:167], off offset:512
	s_and_saveexec_b64 s[78:79], s[42:43]
	s_cbranch_execz .LBB0_375
	v_ashrrev_i32_e32 v131, 31, v130
	v_readlane_b32 s10, v255, 44
	v_lshlrev_b64 v[156:157], 5, v[130:131]
	v_readlane_b32 s11, v255, 45
	s_waitcnt lgkmcnt(0)
	v_add_f32_e32 v131, v145, v149
	v_lshl_add_u64 v[156:157], s[10:11], 0, v[156:157]
	global_store_dword v[156:157], v131, off offset:16
.LBB0_375:
	s_or_b64 exec, exec, s[78:79]
	s_and_b64 vcc, exec, s[44:45]
	s_cbranch_vccnz .LBB0_379
	v_and_b32_e32 v131, s90, v148
	v_lshlrev_b32_e32 v188, 9, v131
	v_lshl_add_u64 v[156:157], s[96:97], 0, v[188:189]
	v_lshl_add_u64 v[156:157], v[156:157], 0, v[128:129]
	global_load_dwordx2 v[164:165], v[156:157], off
	global_load_dwordx2 v[166:167], v[156:157], off offset:16
	global_load_dwordx2 v[168:169], v[156:157], off offset:32
	s_nop 0
	global_load_dwordx2 v[156:157], v[156:157], off offset:48
	s_waitcnt lgkmcnt(0)
	v_ashrrev_i32_e32 v149, 31, v148
	v_readlane_b32 s10, v255, 40
	v_lshlrev_b64 v[148:149], 7, v[148:149]
	v_readlane_b32 s11, v255, 41
	s_waitcnt vmcnt(0)
	v_pk_mul_f32 v[170:171], v[20:21], v[164:165]
	v_pk_mul_f32 v[164:165], v[20:21], v[164:165] op_sel:[0,1] op_sel_hi:[1,0]
	v_sub_f32_e32 v131, v170, v171
	v_add_f32_e32 v145, v164, v165
	v_pk_mul_f32 v[164:165], v[22:23], v[166:167]
	v_lshl_add_u64 v[148:149], s[10:11], 0, v[148:149]
	v_sub_f32_e32 v163, v164, v165
	v_pk_mul_f32 v[164:165], v[22:23], v[166:167] op_sel:[0,1] op_sel_hi:[1,0]
	v_lshl_add_u64 v[148:149], v[146:147], 1, v[148:149]
	v_add_f32_e32 v166, v164, v165
	v_pk_mul_f32 v[164:165], v[16:17], v[168:169]
	s_nop 0
	v_sub_f32_e32 v167, v164, v165
	v_pk_mul_f32 v[164:165], v[16:17], v[168:169] op_sel:[0,1] op_sel_hi:[1,0]
	s_nop 0
	v_add_f32_e32 v168, v164, v165
	v_pk_mul_f32 v[164:165], v[18:19], v[156:157]
	v_pk_mul_f32 v[156:157], v[18:19], v[156:157] op_sel:[0,1] op_sel_hi:[1,0]
	v_sub_f32_e32 v169, v164, v165
	v_add_f32_e32 v156, v156, v157
	v_mul_f32_e32 v157, v169, v169
	v_mul_f32_e32 v164, v167, v167
	v_fmac_f32_e32 v157, v156, v156
	v_fmac_f32_e32 v164, v168, v168
	v_add_f32_e32 v157, v164, v157
	v_mul_f32_e32 v164, v163, v163
	v_mul_f32_e32 v165, v131, v131
	v_fmac_f32_e32 v164, v166, v166
	v_fmac_f32_e32 v165, v145, v145
	v_add_f32_e32 v164, v165, v164
	v_add_f32_e32 v157, v164, v157
	v_cvt_pk_bf16_f32 v164, v131, v145
	ds_bpermute_b32 v131, v154, v157
	v_cvt_pk_bf16_f32 v165, v163, v166
	v_cvt_pk_bf16_f32 v166, v167, v168
	v_cvt_pk_bf16_f32 v167, v169, v156
	global_store_dwordx4 v[148:149], v[164:167], off
	s_waitcnt lgkmcnt(0)
	v_add_f32_e32 v145, v157, v131
	ds_bpermute_b32 v148, v155, v145
	s_and_saveexec_b64 s[78:79], s[42:43]
	s_cbranch_execz .LBB0_378
	v_readlane_b32 s10, v255, 46
	v_ashrrev_i32_e32 v131, 31, v130
	v_readlane_b32 s11, v255, 47
	s_waitcnt lgkmcnt(0)
	v_add_f32_e32 v145, v145, v148
	v_lshl_add_u64 v[130:131], v[130:131], 3, s[10:11]
	global_store_dword v[130:131], v145, off

; __device__ __forceinline__ void st8(bf16_t* p, f32x4 a, f32x4 b) { u32x4 w = {cvt_pk(a[0], a[1]), cvt_pk(a[2], a[3]), cvt_pk(b[0], b[1]), cvt_pk(b[2], b[3])}; *(u32x4*)p = w; }
; __device__ __forceinline__ float dot4(f32x4 a) { return (a[0] * a[0] + a[1] * a[1]) + (a[2] * a[2] + a[3] * a[3]); }
; #define FOR_AI_M _Pragma("unroll") for (int ai = 0; ai < 2; ++ai) if ((__builtin_amdgcn_sched_barrier(0), true)) _Pragma("unroll") for (int m = 0; m < 4; ++m)
;   __device__ __forceinline__ void operator()(EPI_ARGS) const {
;     ...
;       FOR_AI_M { const int row = rbase + ai * 128 + m * 16, pos = (b.g0 + row) & b.slm;
;         { const f32x4 v0 = acc[ai][0][m][0], v1 = acc[ai][0][m][1]; float s = dot4(v0) + dot4(v1); st8(b.CQ + (size_t)row * 384 + 256 + c0, v0, v1);
;           s += __shfl_xor(s, 16); s += __shfl_xor(s, 32); if (fq == 0 && at) b.ssq_cq[(size_t)(b.g0 + row) * 8 + 4 + wc] = s; }
;         if (wc < 2) { f32x4 v0 = acc[ai][1][m][0], v1 = acc[ai][1][m][1]; const int j0 = wc * 16 + fq * 4;
;           const f32x2* tp = (const f32x2*)(b.rope + ((size_t)pos * 64 + 2 * j0) * 2); const f32x2 a0 = tp[0], a1 = tp[2], a2 = tp[4], a3 = tp[6];
;           rope4(v0, v1, (f32x4){a0[0], a0[1], a1[0], a1[1]}, (f32x4){a2[0], a2[1], a3[0], a3[1]});
;           float s = dot4(v0) + dot4(v1); st8(b.KR + (size_t)row * 64 + c0, v0, v1);
;           s += __shfl_xor(s, 16); s += __shfl_xor(s, 32); if (fq == 0 && at) b.ssq_kr[(size_t)(b.g0 + row) * 2 + wc] = s; } }
.LBB0_379:
	v_mul_f32_e32 v131, v13, v13
	v_mul_f32_e32 v145, v15, v15
	v_fmac_f32_e32 v131, v12, v12
	v_fmac_f32_e32 v145, v14, v14
	v_add_f32_e32 v131, v131, v145
	v_mul_f32_e32 v145, v9, v9
	s_waitcnt lgkmcnt(0)
	v_mul_f32_e32 v149, v11, v11
	v_fmac_f32_e32 v145, v8, v8
	v_fmac_f32_e32 v149, v10, v10
	v_add_f32_e32 v145, v145, v149
	v_add_f32_e32 v131, v145, v131
	ds_bpermute_b32 v145, v154, v131
	v_readlane_b32 s10, v255, 36
	v_readlane_b32 s11, v255, 37
	v_add_u32_e32 v148, 0xb0, v144
	v_add_u32_e32 v130, s68, v148
	s_waitcnt lgkmcnt(0)
	v_add_f32_e32 v145, v131, v145
	ds_bpermute_b32 v149, v155, v145
	v_mov_b64_e32 v[156:157], s[10:11]
	v_mad_i64_i32 v[156:157], s[18:19], v148, s8, v[156:157]
	v_lshl_add_u64 v[156:157], v[146:147], 1, v[156:157]
	v_cvt_pk_bf16_f32 v164, v12, v13
	v_cvt_pk_bf16_f32 v165, v14, v15
	v_cvt_pk_bf16_f32 v166, v8, v9
	v_cvt_pk_bf16_f32 v167, v10, v11
	global_store_dwordx4 v[156:157], v[164:167], off offset:512
	s_and_saveexec_b64 s[78:79], s[42:43]
	s_cbranch_execz .LBB0_381
	v_ashrrev_i32_e32 v131, 31, v130
	v_readlane_b32 s10, v255, 44
	v_lshlrev_b64 v[156:157], 5, v[130:131]
	v_readlane_b32 s11, v255, 45
	s_waitcnt lgkmcnt(0)
	v_add_f32_e32 v131, v145, v149
	v_lshl_add_u64 v[156:157], s[10:11], 0, v[156:157]
	global_store_dword v[156:157], v131, off offset:16
.LBB0_381:
	s_or_b64 exec, exec, s[78:79]
	s_and_b64 vcc, exec, s[44:45]
	s_cbranch_vccnz .LBB0_385
	v_and_b32_e32 v131, s90, v148
	v_lshlrev_b32_e32 v188, 9, v131
	v_lshl_add_u64 v[156:157], s[96:97], 0, v[188:189]
	v_lshl_add_u64 v[128:129], v[156:157], 0, v[128:129]
	global_load_dwordx2 v[156:157], v[128:129], off
	global_load_dwordx2 v[164:165], v[128:129], off offset:16
	global_load_dwordx2 v[166:167], v[128:129], off offset:32
	s_nop 0
	global_load_dwordx2 v[128:129], v[128:129], off offset:48
	s_waitcnt lgkmcnt(0)
	v_ashrrev_i32_e32 v149, 31, v148
	v_readlane_b32 s10, v255, 40
	v_readlane_b32 s11, v255, 41
	s_waitcnt vmcnt(0)
	v_pk_mul_f32 v[168:169], v[4:5], v[156:157]
	v_pk_mul_f32 v[156:157], v[4:5], v[156:157] op_sel:[0,1] op_sel_hi:[1,0]
	v_sub_f32_e32 v131, v168, v169
	v_add_f32_e32 v145, v156, v157
	v_pk_mul_f32 v[156:157], v[6:7], v[164:165]
	s_nop 0
	v_sub_f32_e32 v163, v156, v157
	v_pk_mul_f32 v[156:157], v[6:7], v[164:165] op_sel:[0,1] op_sel_hi:[1,0]
	v_mul_f32_e32 v164, v131, v131
	v_add_f32_e32 v165, v156, v157
	v_pk_mul_f32 v[156:157], v[0:1], v[166:167]
	v_fmac_f32_e32 v164, v145, v145
	v_sub_f32_e32 v168, v156, v157
	v_pk_mul_f32 v[156:157], v[0:1], v[166:167] op_sel:[0,1] op_sel_hi:[1,0]
	s_nop 0
	v_add_f32_e32 v166, v156, v157
	v_pk_mul_f32 v[156:157], v[2:3], v[128:129]
	v_pk_mul_f32 v[128:129], v[2:3], v[128:129] op_sel:[0,1] op_sel_hi:[1,0]
	v_sub_f32_e32 v156, v156, v157
	v_add_f32_e32 v157, v128, v129
	v_mul_f32_e32 v128, v156, v156
	v_mul_f32_e32 v129, v168, v168
	v_fmac_f32_e32 v128, v157, v157
	v_fmac_f32_e32 v129, v166, v166
	v_add_f32_e32 v128, v129, v128
	v_mul_f32_e32 v129, v163, v163
	v_fmac_f32_e32 v129, v165, v165
	v_add_f32_e32 v129, v164, v129
	v_add_f32_e32 v169, v129, v128
	v_lshlrev_b64 v[128:129], 7, v[148:149]
	v_lshl_add_u64 v[128:129], s[10:11], 0, v[128:129]
	v_lshl_add_u64 v[128:129], v[146:147], 1, v[128:129]
	v_cvt_pk_bf16_f32 v164, v131, v145
	v_cvt_pk_bf16_f32 v165, v163, v165
	v_cvt_pk_bf16_f32 v166, v168, v166
	v_cvt_pk_bf16_f32 v167, v156, v157
	global_store_dwordx4 v[128:129], v[164:167], off
	ds_bpermute_b32 v128, v154, v169
	s_waitcnt lgkmcnt(0)
	v_add_f32_e32 v128, v169, v128
	ds_bpermute_b32 v129, v155, v128
	s_and_saveexec_b64 s[44:45], s[42:43]
	s_cbranch_execz .LBB0_384
	v_readlane_b32 s10, v255, 46
	v_ashrrev_i32_e32 v131, 31, v130
	v_readlane_b32 s11, v255, 47
	s_waitcnt lgkmcnt(0)
	v_add_f32_e32 v128, v128, v129
	v_lshl_add_u64 v[130:131], v[130:131], 3, s[10:11]
	global_store_dword v[130:131], v128, off

; __device__ __forceinline__ void st8(bf16_t* p, f32x4 a, f32x4 b) { u32x4 w = {cvt_pk(a[0], a[1]), cvt_pk(a[2], a[3]), cvt_pk(b[0], b[1]), cvt_pk(b[2], b[3])}; *(u32x4*)p = w; }
; __device__ __forceinline__ float dot4(f32x4 a) { return (a[0] * a[0] + a[1] * a[1]) + (a[2] * a[2] + a[3] * a[3]); }
; #define FOR_AI_M _Pragma("unroll") for (int ai = 0; ai < 2; ++ai) if ((__builtin_amdgcn_sched_barrier(0), true)) _Pragma("unroll") for (int m = 0; m < 4; ++m)
;   __device__ __forceinline__ void ssq_store(const f32x4 (&acc)[2][2][4][2], bf16_t* dst, int ld, float* sq, int ns, int slot, int rbase, int c0, int fq) const {
;     FOR_AI_M { const int row = rbase + ai * 128 + m * 16; float s = 0.f;
; #pragma unroll
;       for (int bj = 0; bj < 2; ++bj) { const f32x4 v0 = acc[ai][bj][m][0], v1 = acc[ai][bj][m][1]; s += dot4(v0) + dot4(v1); st8(dst + (size_t)row * ld + bj * 128 + c0, v0, v1); }
;       s += __shfl_xor(s, 16); s += __shfl_xor(s, 32); if (fq == 0 && at) sq[(size_t)(b.g0 + row) * ns + slot] = s; }
;   __device__ __forceinline__ void operator()(EPI_ARGS) const {
;     ...
;     else if (pn == 20) ssq_store(acc, b.CQ, 384, b.ssq_cq, 8, wc, rbase, c0, fq);
.LBB0_386:
	s_and_b64 vcc, exec, s[44:45]
	s_cbranch_vccz .LBB0_404
	v_readlane_b32 s10, v255, 36
	v_readlane_b32 s11, v255, 37
	v_cmp_eq_u32_e32 vcc, 0, v162
	s_waitcnt lgkmcnt(0)
	v_lshl_add_u64 v[128:129], v[146:147], 1, s[10:11]
	s_movk_i32 s8, 0x300
	v_mad_i64_i32 v[130:131], s[18:19], v144, s8, v[128:129]
	v_add_f32_e32 v145, v150, v151
	v_add_f32_e32 v147, v152, v153
	v_cvt_pk_bf16_f32 v148, v124, v125
	v_add_f32_e32 v145, v147, v145
	v_cvt_pk_bf16_f32 v149, v126, v127
	v_cvt_pk_bf16_f32 v150, v120, v121
	v_cvt_pk_bf16_f32 v151, v122, v123
	global_store_dwordx4 v[130:131], v[148:151], off
	v_mul_f32_e32 v147, v117, v117
	v_fmac_f32_e32 v147, v116, v116
	v_mul_f32_e32 v148, v119, v119
	v_fmac_f32_e32 v148, v118, v118
	v_add_f32_e32 v147, v147, v148
	v_mul_f32_e32 v148, v113, v113
	v_mul_f32_e32 v149, v115, v115
	v_fmac_f32_e32 v148, v112, v112
	v_fmac_f32_e32 v149, v114, v114
	v_add_f32_e32 v148, v148, v149
	v_add_f32_e32 v147, v148, v147
	v_cvt_pk_bf16_f32 v148, v116, v117
	v_cvt_pk_bf16_f32 v149, v118, v119
	v_cvt_pk_bf16_f32 v150, v112, v113
	v_cvt_pk_bf16_f32 v151, v114, v115
	global_store_dwordx4 v[130:131], v[148:151], off offset:256
	v_and_b32_e32 v131, 64, v233
	v_xor_b32_e32 v130, 16, v233
	v_add_u32_e32 v131, 64, v131
	v_cmp_lt_i32_e64 s[42:43], v130, v131
	v_add_f32_e32 v145, v147, v145
	s_nop 0
	v_cndmask_b32_e64 v130, v233, v130, s[42:43]
	v_lshlrev_b32_e32 v130, 2, v130
	ds_bpermute_b32 v147, v130, v145
	s_waitcnt lgkmcnt(0)
	v_add_f32_e32 v145, v145, v147
	v_xor_b32_e32 v147, 32, v233
	v_cmp_lt_i32_e64 s[42:43], v147, v131
	s_nop 1
	v_cndmask_b32_e64 v131, v233, v147, s[42:43]
	v_lshlrev_b32_e32 v131, 2, v131
	ds_bpermute_b32 v147, v131, v145
	s_and_saveexec_b64 s[42:43], vcc
	s_cbranch_execz .LBB0_389
	v_add_u32_e32 v148, s68, v144
	v_ashrrev_i32_e32 v149, 31, v148
	v_readlane_b32 s10, v255, 44
	v_lshlrev_b64 v[148:149], 5, v[148:149]
	v_readlane_b32 s11, v255, 45
	s_waitcnt lgkmcnt(0)
	v_add_f32_e32 v145, v145, v147
	v_lshl_add_u64 v[148:149], s[10:11], 0, v[148:149]
	global_store_dword v[148:149], v145, off
.LBB0_389:
	s_or_b64 exec, exec, s[42:43]
	s_waitcnt lgkmcnt(0)
	v_mul_f32_e32 v147, v109, v109
	v_mul_f32_e32 v148, v111, v111
	v_fmac_f32_e32 v147, v108, v108
	v_fmac_f32_e32 v148, v110, v110
	v_add_f32_e32 v147, v147, v148
	v_mul_f32_e32 v148, v105, v105
	v_mul_f32_e32 v149, v107, v107
	v_fmac_f32_e32 v148, v104, v104
	v_fmac_f32_e32 v149, v106, v106
	v_add_u32_e32 v145, 16, v144
	v_add_f32_e32 v148, v148, v149
	v_mad_i64_i32 v[152:153], s[18:19], v145, s8, v[128:129]
	v_add_f32_e32 v147, v148, v147
	v_cvt_pk_bf16_f32 v148, v108, v109
	v_cvt_pk_bf16_f32 v149, v110, v111
	v_cvt_pk_bf16_f32 v150, v104, v105
	v_cvt_pk_bf16_f32 v151, v106, v107
	global_store_dwordx4 v[152:153], v[148:151], off
	s_nop 1
	v_mul_f32_e32 v148, v101, v101
	v_mul_f32_e32 v149, v103, v103
	v_fmac_f32_e32 v148, v100, v100
	v_fmac_f32_e32 v149, v102, v102
	v_add_f32_e32 v148, v148, v149
	v_mul_f32_e32 v149, v97, v97
	v_mul_f32_e32 v150, v99, v99
	v_fmac_f32_e32 v149, v96, v96
	v_fmac_f32_e32 v150, v98, v98
	v_add_f32_e32 v149, v149, v150
	v_add_f32_e32 v148, v149, v148
	v_add_f32_e32 v147, v148, v147
	v_cvt_pk_bf16_f32 v148, v100, v101
	v_cvt_pk_bf16_f32 v149, v102, v103
	v_cvt_pk_bf16_f32 v150, v96, v97
	v_cvt_pk_bf16_f32 v151, v98, v99
	global_store_dwordx4 v[152:153], v[148:151], off offset:256
	ds_bpermute_b32 v148, v130, v147
	s_waitcnt lgkmcnt(0)
	v_add_f32_e32 v147, v147, v148
	ds_bpermute_b32 v148, v131, v147
	s_and_saveexec_b64 s[42:43], vcc
	s_cbranch_execz .LBB0_391
	v_add_u32_e32 v150, s68, v145
	v_ashrrev_i32_e32 v151, 31, v150
	v_readlane_b32 s10, v255, 44
	v_lshlrev_b64 v[150:151], 5, v[150:151]
	v_readlane_b32 s11, v255, 45
	s_waitcnt lgkmcnt(0)
	v_add_f32_e32 v145, v147, v148
	v_lshl_add_u64 v[150:151], s[10:11], 0, v[150:151]
	global_store_dword v[150:151], v145, off
.LBB0_391:
	s_or_b64 exec, exec, s[42:43]
	v_mul_f32_e32 v147, v93, v93
	s_waitcnt lgkmcnt(0)
	v_mul_f32_e32 v148, v95, v95
	v_fmac_f32_e32 v147, v92, v92
	v_fmac_f32_e32 v148, v94, v94
	v_add_f32_e32 v147, v147, v148
	v_mul_f32_e32 v148, v89, v89
	v_mul_f32_e32 v149, v91, v91
	v_fmac_f32_e32 v148, v88, v88
	v_fmac_f32_e32 v149, v90, v90
	v_add_u32_e32 v145, 32, v144
	v_add_f32_e32 v148, v148, v149
	v_mad_i64_i32 v[152:153], s[18:19], v145, s8, v[128:129]
	v_add_f32_e32 v147, v148, v147
	v_cvt_pk_bf16_f32 v148, v92, v93
	v_cvt_pk_bf16_f32 v149, v94, v95
	v_cvt_pk_bf16_f32 v150, v88, v89
	v_cvt_pk_bf16_f32 v151, v90, v91
	global_store_dwordx4 v[152:153], v[148:151], off
	s_nop 1
	v_mul_f32_e32 v148, v85, v85
	v_mul_f32_e32 v149, v87, v87
	v_fmac_f32_e32 v148, v84, v84
	v_fmac_f32_e32 v149, v86, v86
	v_add_f32_e32 v148, v148, v149
	v_mul_f32_e32 v149, v81, v81
	v_mul_f32_e32 v150, v83, v83
	v_fmac_f32_e32 v149, v80, v80
	v_fmac_f32_e32 v150, v82, v82
	v_add_f32_e32 v149, v149, v150
	v_add_f32_e32 v148, v149, v148
	v_add_f32_e32 v147, v148, v147
	v_cvt_pk_bf16_f32 v148, v84, v85
	v_cvt_pk_bf16_f32 v149, v86, v87
	v_cvt_pk_bf16_f32 v150, v80, v81
	v_cvt_pk_bf16_f32 v151, v82, v83
	global_store_dwordx4 v[152:153], v[148:151], off offset:256
	ds_bpermute_b32 v148, v130, v147
	s_waitcnt lgkmcnt(0)
	v_add_f32_e32 v147, v147, v148
	ds_bpermute_b32 v148, v131, v147
	s_and_saveexec_b64 s[42:43], vcc
	s_cbranch_execz .LBB0_393
	v_add_u32_e32 v150, s68, v145
	v_ashrrev_i32_e32 v151, 31, v150
	v_readlane_b32 s10, v255, 44
	v_lshlrev_b64 v[150:151], 5, v[150:151]
	v_readlane_b32 s11, v255, 45
	s_waitcnt lgkmcnt(0)
	v_add_f32_e32 v145, v147, v148
	v_lshl_add_u64 v[150:151], s[10:11], 0, v[150:151]
	global_store_dword v[150:151], v145, off
; __device__ __forceinline__ void st8(bf16_t* p, f32x4 a, f32x4 b) { u32x4 w = {cvt_pk(a[0], a[1]), cvt_pk(a[2], a[3]), cvt_pk(b[0], b[1]), cvt_pk(b[2], b[3])}; *(u32x4*)p = w; }
; __device__ __forceinline__ float dot4(f32x4 a) { return (a[0] * a[0] + a[1] * a[1]) + (a[2] * a[2] + a[3] * a[3]); }
; #define FOR_AI_M _Pragma("unroll") for (int ai = 0; ai < 2; ++ai) if ((__builtin_amdgcn_sched_barrier(0), true)) _Pragma("unroll") for (int m = 0; m < 4; ++m)
;   __device__ __forceinline__ void ssq_store(const f32x4 (&acc)[2][2][4][2], bf16_t* dst, int ld, float* sq, int ns, int slot, int rbase, int c0, int fq) const {
;     FOR_AI_M { const int row = rbase + ai * 128 + m * 16; float s = 0.f;
; #pragma unroll
;       for (int bj = 0; bj < 2; ++bj) { const f32x4 v0 = acc[ai][bj][m][0], v1 = acc[ai][bj][m][1]; s += dot4(v0) + dot4(v1); st8(dst + (size_t)row * ld + bj * 128 + c0, v0, v1); }
;       s += __shfl_xor(s, 16); s += __shfl_xor(s, 32); if (fq == 0 && at) sq[(size_t)(b.g0 + row) * ns + slot] = s; }
.LBB0_393:
	s_or_b64 exec, exec, s[42:43]
	v_mul_f32_e32 v147, v77, v77
	s_waitcnt lgkmcnt(0)
	v_mul_f32_e32 v148, v79, v79
	v_fmac_f32_e32 v147, v76, v76
	v_fmac_f32_e32 v148, v78, v78
	v_add_f32_e32 v147, v147, v148
	v_mul_f32_e32 v148, v73, v73
	v_mul_f32_e32 v149, v75, v75
	v_fmac_f32_e32 v148, v72, v72
	v_fmac_f32_e32 v149, v74, v74
	v_add_u32_e32 v145, 48, v144
	v_add_f32_e32 v148, v148, v149
	v_mad_i64_i32 v[152:153], s[18:19], v145, s8, v[128:129]
	v_add_f32_e32 v147, v148, v147
	v_cvt_pk_bf16_f32 v148, v76, v77
	v_cvt_pk_bf16_f32 v149, v78, v79
	v_cvt_pk_bf16_f32 v150, v72, v73
	v_cvt_pk_bf16_f32 v151, v74, v75
	global_store_dwordx4 v[152:153], v[148:151], off
	s_nop 1
	v_mul_f32_e32 v148, v69, v69
	v_mul_f32_e32 v149, v71, v71
	v_fmac_f32_e32 v148, v68, v68
	v_fmac_f32_e32 v149, v70, v70
	v_add_f32_e32 v148, v148, v149
	v_mul_f32_e32 v149, v65, v65
	v_mul_f32_e32 v150, v67, v67
	v_fmac_f32_e32 v149, v64, v64
	v_fmac_f32_e32 v150, v66, v66
	v_add_f32_e32 v149, v149, v150
	v_add_f32_e32 v148, v149, v148
	v_add_f32_e32 v147, v148, v147
	v_cvt_pk_bf16_f32 v148, v68, v69
	v_cvt_pk_bf16_f32 v149, v70, v71
	v_cvt_pk_bf16_f32 v150, v64, v65
	v_cvt_pk_bf16_f32 v151, v66, v67
	global_store_dwordx4 v[152:153], v[148:151], off offset:256
	ds_bpermute_b32 v148, v130, v147
	s_waitcnt lgkmcnt(0)
	v_add_f32_e32 v147, v147, v148
	ds_bpermute_b32 v148, v131, v147
	s_and_saveexec_b64 s[42:43], vcc
	s_cbranch_execz .LBB0_395
	v_add_u32_e32 v150, s68, v145
	v_ashrrev_i32_e32 v151, 31, v150
	v_readlane_b32 s10, v255, 44
	v_lshlrev_b64 v[150:151], 5, v[150:151]
	v_readlane_b32 s11, v255, 45
	s_waitcnt lgkmcnt(0)
	v_add_f32_e32 v145, v147, v148
	v_lshl_add_u64 v[150:151], s[10:11], 0, v[150:151]
	global_store_dword v[150:151], v145, off
.LBB0_395:
	s_or_b64 exec, exec, s[42:43]
	v_mul_f32_e32 v147, v61, v61
	s_waitcnt lgkmcnt(0)
	v_mul_f32_e32 v148, v63, v63
	v_fmac_f32_e32 v147, v60, v60
	v_fmac_f32_e32 v148, v62, v62
	v_add_f32_e32 v147, v147, v148
	v_mul_f32_e32 v148, v57, v57
	v_mul_f32_e32 v149, v59, v59
	v_fmac_f32_e32 v148, v56, v56
	v_fmac_f32_e32 v149, v58, v58
	v_add_u32_e32 v145, 0x80, v144
	v_add_f32_e32 v148, v148, v149
	v_mad_i64_i32 v[152:153], s[18:19], v145, s8, v[128:129]
	v_add_f32_e32 v147, v148, v147
	v_cvt_pk_bf16_f32 v148, v60, v61
	v_cvt_pk_bf16_f32 v149, v62, v63
	v_cvt_pk_bf16_f32 v150, v56, v57
	v_cvt_pk_bf16_f32 v151, v58, v59
	global_store_dwordx4 v[152:153], v[148:151], off
	s_nop 1
	v_mul_f32_e32 v148, v53, v53
	v_mul_f32_e32 v149, v55, v55
	v_fmac_f32_e32 v148, v52, v52
	v_fmac_f32_e32 v149, v54, v54
	v_add_f32_e32 v148, v148, v149
	v_mul_f32_e32 v149, v49, v49
	v_mul_f32_e32 v150, v51, v51
	v_fmac_f32_e32 v149, v48, v48
	v_fmac_f32_e32 v150, v50, v50
	v_add_f32_e32 v149, v149, v150
	v_add_f32_e32 v148, v149, v148
	v_add_f32_e32 v147, v148, v147
	v_cvt_pk_bf16_f32 v148, v52, v53
	v_cvt_pk_bf16_f32 v149, v54, v55
	v_cvt_pk_bf16_f32 v150, v48, v49
	v_cvt_pk_bf16_f32 v151, v50, v51
	global_store_dwordx4 v[152:153], v[148:151], off offset:256
	ds_bpermute_b32 v148, v130, v147
	s_waitcnt lgkmcnt(0)
	v_add_f32_e32 v147, v147, v148
	ds_bpermute_b32 v148, v131, v147
	s_and_saveexec_b64 s[42:43], vcc
	s_cbranch_execz .LBB0_397
	v_add_u32_e32 v150, s68, v145
	v_ashrrev_i32_e32 v151, 31, v150
	v_readlane_b32 s10, v255, 44
	v_lshlrev_b64 v[150:151], 5, v[150:151]
	v_readlane_b32 s11, v255, 45
	s_waitcnt lgkmcnt(0)
	v_add_f32_e32 v145, v147, v148
	v_lshl_add_u64 v[150:151], s[10:11], 0, v[150:151]
	global_store_dword v[150:151], v145, off
; __device__ __forceinline__ void st8(bf16_t* p, f32x4 a, f32x4 b) { u32x4 w = {cvt_pk(a[0], a[1]), cvt_pk(a[2], a[3]), cvt_pk(b[0], b[1]), cvt_pk(b[2], b[3])}; *(u32x4*)p = w; }
; __device__ __forceinline__ float dot4(f32x4 a) { return (a[0] * a[0] + a[1] * a[1]) + (a[2] * a[2] + a[3] * a[3]); }
; #define FOR_AI_M _Pragma("unroll") for (int ai = 0; ai < 2; ++ai) if ((__builtin_amdgcn_sched_barrier(0), true)) _Pragma("unroll") for (int m = 0; m < 4; ++m)
;   __device__ __forceinline__ void ssq_store(const f32x4 (&acc)[2][2][4][2], bf16_t* dst, int ld, float* sq, int ns, int slot, int rbase, int c0, int fq) const {
;     FOR_AI_M { const int row = rbase + ai * 128 + m * 16; float s = 0.f;
; #pragma unroll
;       for (int bj = 0; bj < 2; ++bj) { const f32x4 v0 = acc[ai][bj][m][0], v1 = acc[ai][bj][m][1]; s += dot4(v0) + dot4(v1); st8(dst + (size_t)row * ld + bj * 128 + c0, v0, v1); }
;       s += __shfl_xor(s, 16); s += __shfl_xor(s, 32); if (fq == 0 && at) sq[(size_t)(b.g0 + row) * ns + slot] = s; }
.LBB0_397:
	s_or_b64 exec, exec, s[42:43]
	v_mul_f32_e32 v147, v45, v45
	s_waitcnt lgkmcnt(0)
	v_mul_f32_e32 v148, v47, v47
	v_fmac_f32_e32 v147, v44, v44
	v_fmac_f32_e32 v148, v46, v46
	v_add_f32_e32 v147, v147, v148
	v_mul_f32_e32 v148, v41, v41
	v_mul_f32_e32 v149, v43, v43
	v_fmac_f32_e32 v148, v40, v40
	v_fmac_f32_e32 v149, v42, v42
	v_add_u32_e32 v145, 0x90, v144
	v_add_f32_e32 v148, v148, v149
	v_mad_i64_i32 v[152:153], s[18:19], v145, s8, v[128:129]
	v_add_f32_e32 v147, v148, v147
	v_cvt_pk_bf16_f32 v148, v44, v45
	v_cvt_pk_bf16_f32 v149, v46, v47
	v_cvt_pk_bf16_f32 v150, v40, v41
	v_cvt_pk_bf16_f32 v151, v42, v43
	global_store_dwordx4 v[152:153], v[148:151], off
	s_nop 1
	v_mul_f32_e32 v148, v37, v37
	v_mul_f32_e32 v149, v39, v39
	v_fmac_f32_e32 v148, v36, v36
	v_fmac_f32_e32 v149, v38, v38
	v_add_f32_e32 v148, v148, v149
	v_mul_f32_e32 v149, v33, v33
	v_mul_f32_e32 v150, v35, v35
	v_fmac_f32_e32 v149, v32, v32
	v_fmac_f32_e32 v150, v34, v34
	v_add_f32_e32 v149, v149, v150
	v_add_f32_e32 v148, v149, v148
	v_add_f32_e32 v147, v148, v147
	v_cvt_pk_bf16_f32 v148, v36, v37
	v_cvt_pk_bf16_f32 v149, v38, v39
	v_cvt_pk_bf16_f32 v150, v32, v33
	v_cvt_pk_bf16_f32 v151, v34, v35
	global_store_dwordx4 v[152:153], v[148:151], off offset:256
	ds_bpermute_b32 v148, v130, v147
	s_waitcnt lgkmcnt(0)
	v_add_f32_e32 v147, v147, v148
	ds_bpermute_b32 v148, v131, v147
	s_and_saveexec_b64 s[42:43], vcc
	s_cbranch_execz .LBB0_399
	v_add_u32_e32 v150, s68, v145
	v_ashrrev_i32_e32 v151, 31, v150
	v_readlane_b32 s10, v255, 44
	v_lshlrev_b64 v[150:151], 5, v[150:151]
	v_readlane_b32 s11, v255, 45
	s_waitcnt lgkmcnt(0)
	v_add_f32_e32 v145, v147, v148
	v_lshl_add_u64 v[150:151], s[10:11], 0, v[150:151]
	global_store_dword v[150:151], v145, off
.LBB0_399:
	s_or_b64 exec, exec, s[42:43]
	v_mul_f32_e32 v147, v29, v29
	s_waitcnt lgkmcnt(0)
	v_mul_f32_e32 v148, v31, v31
	v_fmac_f32_e32 v147, v28, v28
	v_fmac_f32_e32 v148, v30, v30
	v_add_f32_e32 v147, v147, v148
	v_mul_f32_e32 v148, v25, v25
	v_mul_f32_e32 v149, v27, v27
	v_fmac_f32_e32 v148, v24, v24
	v_fmac_f32_e32 v149, v26, v26
	v_add_u32_e32 v145, 0xa0, v144
	v_add_f32_e32 v148, v148, v149
	v_mad_i64_i32 v[152:153], s[18:19], v145, s8, v[128:129]
	v_add_f32_e32 v147, v148, v147
	v_cvt_pk_bf16_f32 v148, v28, v29
	v_cvt_pk_bf16_f32 v149, v30, v31
	v_cvt_pk_bf16_f32 v150, v24, v25
	v_cvt_pk_bf16_f32 v151, v26, v27
	global_store_dwordx4 v[152:153], v[148:151], off
	s_nop 1
	v_mul_f32_e32 v148, v21, v21
	v_mul_f32_e32 v149, v23, v23
	v_fmac_f32_e32 v148, v20, v20
	v_fmac_f32_e32 v149, v22, v22
	v_add_f32_e32 v148, v148, v149
	v_mul_f32_e32 v149, v17, v17
	v_mul_f32_e32 v150, v19, v19
	v_fmac_f32_e32 v149, v16, v16
	v_fmac_f32_e32 v150, v18, v18
	v_add_f32_e32 v149, v149, v150
	v_add_f32_e32 v148, v149, v148
	v_add_f32_e32 v147, v148, v147
	v_cvt_pk_bf16_f32 v148, v20, v21
	v_cvt_pk_bf16_f32 v149, v22, v23
	v_cvt_pk_bf16_f32 v150, v16, v17
	v_cvt_pk_bf16_f32 v151, v18, v19
	global_store_dwordx4 v[152:153], v[148:151], off offset:256
	ds_bpermute_b32 v148, v130, v147
	s_waitcnt lgkmcnt(0)
	v_add_f32_e32 v147, v147, v148
	ds_bpermute_b32 v148, v131, v147
	s_and_saveexec_b64 s[42:43], vcc
	s_cbranch_execz .LBB0_401
	v_add_u32_e32 v150, s68, v145
	v_ashrrev_i32_e32 v151, 31, v150
	v_readlane_b32 s10, v255, 44
	v_lshlrev_b64 v[150:151], 5, v[150:151]
	v_readlane_b32 s11, v255, 45
	s_waitcnt lgkmcnt(0)
	v_add_f32_e32 v145, v147, v148
	v_lshl_add_u64 v[150:151], s[10:11], 0, v[150:151]
	global_store_dword v[150:151], v145, off
.LBB0_401:
	s_or_b64 exec, exec, s[42:43]
	v_mul_f32_e32 v147, v13, v13
	s_waitcnt lgkmcnt(0)
	v_mul_f32_e32 v148, v15, v15
	v_fmac_f32_e32 v147, v12, v12
	v_fmac_f32_e32 v148, v14, v14
	v_add_f32_e32 v147, v147, v148
	v_mul_f32_e32 v148, v9, v9
	v_mul_f32_e32 v149, v11, v11
	v_fmac_f32_e32 v148, v8, v8
	v_fmac_f32_e32 v149, v10, v10
	v_add_u32_e32 v145, 0xb0, v144
	v_add_f32_e32 v148, v148, v149
	v_mad_i64_i32 v[128:129], s[18:19], v145, s8, v[128:129]
	v_add_f32_e32 v147, v148, v147
	v_cvt_pk_bf16_f32 v148, v12, v13
	v_cvt_pk_bf16_f32 v149, v14, v15
	v_cvt_pk_bf16_f32 v150, v8, v9
	v_cvt_pk_bf16_f32 v151, v10, v11
	global_store_dwordx4 v[128:129], v[148:151], off
	s_nop 1
	v_mul_f32_e32 v148, v5, v5
	v_mul_f32_e32 v149, v7, v7
	v_fmac_f32_e32 v148, v4, v4
	v_fmac_f32_e32 v149, v6, v6
	v_add_f32_e32 v148, v148, v149
	v_mul_f32_e32 v149, v1, v1
	v_mul_f32_e32 v150, v3, v3
	v_fmac_f32_e32 v149, v0, v0
	v_fmac_f32_e32 v150, v2, v2
	v_add_f32_e32 v149, v149, v150
	v_add_f32_e32 v148, v149, v148
	v_add_f32_e32 v147, v148, v147
	v_cvt_pk_bf16_f32 v148, v4, v5
	v_cvt_pk_bf16_f32 v149, v6, v7
	v_cvt_pk_bf16_f32 v150, v0, v1
	v_cvt_pk_bf16_f32 v151, v2, v3
	global_store_dwordx4 v[128:129], v[148:151], off offset:256
	ds_bpermute_b32 v128, v130, v147
	s_waitcnt lgkmcnt(0)
	v_add_f32_e32 v128, v147, v128
	ds_bpermute_b32 v129, v131, v128
	s_and_saveexec_b64 s[42:43], vcc
	s_cbranch_execz .LBB0_403
	v_add_u32_e32 v130, s68, v145
	v_ashrrev_i32_e32 v131, 31, v130
	v_readlane_b32 s10, v255, 44
	v_lshlrev_b64 v[130:131], 5, v[130:131]
	v_readlane_b32 s11, v255, 45
	s_waitcnt lgkmcnt(0)
	v_add_f32_e32 v128, v128, v129
	v_lshl_add_u64 v[130:131], s[10:11], 0, v[130:131]
	global_store_dword v[130:131], v128, off

; __device__ __forceinline__ void st8(bf16_t* p, f32x4 a, f32x4 b) { u32x4 w = {cvt_pk(a[0], a[1]), cvt_pk(a[2], a[3]), cvt_pk(b[0], b[1]), cvt_pk(b[2], b[3])}; *(u32x4*)p = w; }
; __device__ __forceinline__ float sigm(float x) { return __builtin_amdgcn_rcpf(1.f + __builtin_amdgcn_exp2f(x * -1.4426950408889634f)); }
; __device__ __forceinline__ void st8_s(bf16_t* p, f32x4 a, f32x4 b) { u32x4 w = {cvt_pk_s(a[0], a[1]), cvt_pk_s(a[2], a[3]), cvt_pk_s(b[0], b[1]), cvt_pk_s(b[2], b[3])}; *(u32x4*)p = w; }
; #define FOR_AI_M _Pragma("unroll") for (int ai = 0; ai < 2; ++ai) if ((__builtin_amdgcn_sched_barrier(0), true)) _Pragma("unroll") for (int m = 0; m < 4; ++m)
;   template <int ACT> __device__ __forceinline__ void plain_store(const f32x4 (&acc)[2][2][4][2], bf16_t* dst, int cbase, int rbase) const {
;     FOR_AI_M { const int row = rbase + ai * 128 + m * 16;
; #pragma unroll
;       for (int bj = 0; bj < 2; ++bj) { f32x4 v0 = acc[ai][bj][m][0], v1 = acc[ai][bj][m][1];
;         if (ACT == 1) {
; #pragma unroll
;           for (int e = 0; e < 4; ++e) { v0[e] = v0[e] * sigm(v0[e]); v1[e] = v1[e] * sigm(v1[e]); } }
;         if (ACT == 2) {
; #pragma unroll
;           for (int e = 0; e < 4; ++e) { v0[e] = sigm(v0[e]); v1[e] = sigm(v1[e]); } }
;         if (ACT == 0) st8(dst + (size_t)row * 1024 + cbase + bj * 128, v0, v1); else st8_s(dst + (size_t)row * 1024 + cbase + bj * 128, v0, v1); } }
;   }
;   __device__ __forceinline__ void operator()(EPI_ARGS) const {
;     ...
;     else if (pn < 20) plain_store<2>(acc, b.GA, (pn - 16) * 256 + c0, rbase);
.LBB0_405:
	s_and_b64 vcc, exec, s[42:43]
	s_cbranch_vccz .LBB0_407
	s_lshl_b32 s8, s47, 8
	s_addk_i32 s8, 0xf000
	v_add_u32_e32 v128, s8, v146
	v_readlane_b32 s10, v255, 34
	s_waitcnt lgkmcnt(0)
	v_ashrrev_i32_e32 v129, 31, v128
	v_readlane_b32 s11, v255, 35
	s_nop 1
	v_lshl_add_u64 v[128:129], v[128:129], 1, s[10:11]
	v_mul_f32_e32 v148, 0xbfb8aa3b, v126
	v_ashrrev_i32_e32 v145, 31, v144
	v_exp_f32_e32 v148, v148
	v_mul_f32_e32 v149, 0xbfb8aa3b, v122
	v_lshlrev_b64 v[130:131], 11, v[144:145]
	v_mul_f32_e32 v145, 0xbfb8aa3b, v124
	v_mul_f32_e32 v147, 0xbfb8aa3b, v120
	v_exp_f32_e32 v149, v149
	v_exp_f32_e32 v145, v145
	v_exp_f32_e32 v147, v147
	v_add_f32_e32 v148, 1.0, v148
	v_rcp_f32_e32 v150, v148
	v_add_f32_e32 v148, 1.0, v149
	v_mul_f32_e32 v149, 0xbfb8aa3b, v127
	v_lshl_add_u64 v[128:129], v[128:129], 0, v[130:131]
	v_add_f32_e32 v130, 1.0, v145
	v_add_f32_e32 v131, 1.0, v147
	v_mul_f32_e32 v145, 0xbfb8aa3b, v125
	v_mul_f32_e32 v147, 0xbfb8aa3b, v121
	v_exp_f32_e32 v149, v149
	v_mul_f32_e32 v151, 0xbfb8aa3b, v123
	v_exp_f32_e32 v145, v145
	v_exp_f32_e32 v147, v147
	v_exp_f32_e32 v151, v151
	v_rcp_f32_e32 v152, v148
	v_add_f32_e32 v148, 1.0, v149
	v_add_f32_e32 v145, 1.0, v145
	v_add_f32_e32 v147, 1.0, v147
	v_rcp_f32_e32 v149, v148
	v_add_f32_e32 v148, 1.0, v151
	v_rcp_f32_e32 v130, v130
	v_rcp_f32_e32 v131, v131
	v_rcp_f32_e32 v145, v145
	v_rcp_f32_e32 v147, v147
	v_rcp_f32_e32 v151, v148
	v_cvt_pk_bf16_f32 v149, v150, v149
	v_cvt_pk_bf16_f32 v148, v130, v145
	v_cvt_pk_bf16_f32 v150, v131, v147
	v_cvt_pk_bf16_f32 v151, v152, v151
	global_store_dwordx4 v[128:129], v[148:151], off
	v_mul_f32_e32 v130, 0xbfb8aa3b, v116
	v_mul_f32_e32 v131, 0xbfb8aa3b, v112
	v_mul_f32_e32 v148, 0xbfb8aa3b, v118
	v_exp_f32_e32 v148, v148
	v_mul_f32_e32 v149, 0xbfb8aa3b, v114
	v_exp_f32_e32 v149, v149
	v_mul_f32_e32 v145, 0xbfb8aa3b, v117
	v_add_f32_e32 v148, 1.0, v148
	v_rcp_f32_e32 v150, v148
	v_add_f32_e32 v148, 1.0, v149
	v_mul_f32_e32 v149, 0xbfb8aa3b, v119
	v_mul_f32_e32 v147, 0xbfb8aa3b, v113
	v_exp_f32_e32 v149, v149
	v_mul_f32_e32 v151, 0xbfb8aa3b, v115
	v_exp_f32_e32 v130, v130
	v_exp_f32_e32 v131, v131
	v_exp_f32_e32 v145, v145
	v_exp_f32_e32 v147, v147
	v_exp_f32_e32 v151, v151
	v_rcp_f32_e32 v152, v148
	v_add_f32_e32 v148, 1.0, v149
	v_add_f32_e32 v130, 1.0, v130
	v_add_f32_e32 v131, 1.0, v131
	v_add_f32_e32 v145, 1.0, v145
	v_add_f32_e32 v147, 1.0, v147
	v_rcp_f32_e32 v149, v148
	v_add_f32_e32 v148, 1.0, v151
	v_rcp_f32_e32 v130, v130
	v_rcp_f32_e32 v131, v131
	v_rcp_f32_e32 v145, v145
	v_rcp_f32_e32 v147, v147
	v_rcp_f32_e32 v151, v148
	v_cvt_pk_bf16_f32 v149, v150, v149
	v_cvt_pk_bf16_f32 v148, v130, v145
	v_cvt_pk_bf16_f32 v150, v131, v147
	v_cvt_pk_bf16_f32 v151, v152, v151
	global_store_dwordx4 v[128:129], v[148:151], off offset:256
	v_mul_f32_e32 v130, 0xbfb8aa3b, v108
	v_exp_f32_e32 v145, v130
	v_mul_f32_e32 v149, 0xbfb8aa3b, v105
	v_exp_f32_e32 v149, v149
	v_mul_f32_e32 v150, 0xbfb8aa3b, v110
	v_mul_f32_e32 v151, 0xbfb8aa3b, v106
	v_exp_f32_e32 v150, v150
	v_exp_f32_e32 v151, v151
	v_add_f32_e32 v149, 1.0, v149
	v_mul_f32_e32 v130, 0xbfb8aa3b, v104
	v_rcp_f32_e32 v152, v149
	v_add_f32_e32 v149, 1.0, v150
	v_add_f32_e32 v150, 1.0, v151
	v_mul_f32_e32 v151, 0xbfb8aa3b, v111
	v_exp_f32_e32 v147, v130
	v_mul_f32_e32 v148, 0xbfb8aa3b, v109
	v_exp_f32_e32 v151, v151
	v_mul_f32_e32 v153, 0xbfb8aa3b, v107
	v_exp_f32_e32 v148, v148
	v_exp_f32_e32 v153, v153
	v_add_f32_e32 v147, 1.0, v147
	v_rcp_f32_e32 v154, v150
	v_add_f32_e32 v150, 1.0, v151
	v_add_f32_e32 v145, 1.0, v145
	v_rcp_f32_e32 v147, v147
	v_add_f32_e32 v148, 1.0, v148
	v_rcp_f32_e32 v149, v149
	v_rcp_f32_e32 v150, v150
	v_add_f32_e32 v151, 1.0, v153
	v_rcp_f32_e32 v145, v145
	v_rcp_f32_e32 v148, v148
	v_rcp_f32_e32 v151, v151
	v_cvt_pk_bf16_f32 v149, v149, v150
	v_cvt_pk_bf16_f32 v150, v147, v152
	v_add_co_u32_e32 v152, vcc, s88, v128
	v_cvt_pk_bf16_f32 v148, v145, v148
	v_cvt_pk_bf16_f32 v151, v154, v151
	v_addc_co_u32_e32 v153, vcc, 0, v129, vcc
	global_store_dwordx4 v[152:153], v[148:151], off
	v_mul_f32_e32 v145, 0xbfb8aa3b, v100
	v_mul_f32_e32 v147, 0xbfb8aa3b, v96
	v_mul_f32_e32 v149, 0xbfb8aa3b, v97
	v_exp_f32_e32 v149, v149
	v_mul_f32_e32 v150, 0xbfb8aa3b, v102
	v_mul_f32_e32 v151, 0xbfb8aa3b, v98
	v_exp_f32_e32 v150, v150
	v_exp_f32_e32 v151, v151
	v_add_f32_e32 v149, 1.0, v149
	v_mul_f32_e32 v148, 0xbfb8aa3b, v101
	v_rcp_f32_e32 v152, v149
	v_add_f32_e32 v149, 1.0, v150
	v_add_f32_e32 v150, 1.0, v151
	v_mul_f32_e32 v151, 0xbfb8aa3b, v103
	v_mul_f32_e32 v153, 0xbfb8aa3b, v99
	v_exp_f32_e32 v145, v145
	v_exp_f32_e32 v147, v147
	v_exp_f32_e32 v148, v148
	v_exp_f32_e32 v151, v151
	v_exp_f32_e32 v153, v153
	v_add_f32_e32 v145, 1.0, v145
	v_add_f32_e32 v147, 1.0, v147
	v_add_f32_e32 v148, 1.0, v148
	v_rcp_f32_e32 v154, v150
	v_add_f32_e32 v150, 1.0, v151
	v_add_f32_e32 v151, 1.0, v153
	v_rcp_f32_e32 v145, v145
	v_rcp_f32_e32 v147, v147
	v_rcp_f32_e32 v148, v148
	v_rcp_f32_e32 v149, v149
	v_rcp_f32_e32 v150, v150
	v_rcp_f32_e32 v151, v151
	s_mov_b64 s[10:11], 0x8000
	v_lshl_add_u64 v[130:131], v[128:129], 0, s[10:11]
	v_cvt_pk_bf16_f32 v148, v145, v148
	v_cvt_pk_bf16_f32 v149, v149, v150
	v_cvt_pk_bf16_f32 v150, v147, v152
	v_cvt_pk_bf16_f32 v151, v154, v151
	global_store_dwordx4 v[130:131], v[148:151], off offset:256
	v_mul_f32_e32 v130, 0xbfb8aa3b, v92
	v_exp_f32_e32 v145, v130
	v_mul_f32_e32 v149, 0xbfb8aa3b, v89
	v_exp_f32_e32 v149, v149
	v_mul_f32_e32 v150, 0xbfb8aa3b, v94
	v_mul_f32_e32 v151, 0xbfb8aa3b, v90
	v_exp_f32_e32 v150, v150
	v_exp_f32_e32 v151, v151
	v_add_f32_e32 v149, 1.0, v149
	v_mul_f32_e32 v130, 0xbfb8aa3b, v88
	v_rcp_f32_e32 v152, v149
; __device__ __forceinline__ void st8(bf16_t* p, f32x4 a, f32x4 b) { u32x4 w = {cvt_pk(a[0], a[1]), cvt_pk(a[2], a[3]), cvt_pk(b[0], b[1]), cvt_pk(b[2], b[3])}; *(u32x4*)p = w; }
; __device__ __forceinline__ float sigm(float x) { return __builtin_amdgcn_rcpf(1.f + __builtin_amdgcn_exp2f(x * -1.4426950408889634f)); }
; __device__ __forceinline__ void st8_s(bf16_t* p, f32x4 a, f32x4 b) { u32x4 w = {cvt_pk_s(a[0], a[1]), cvt_pk_s(a[2], a[3]), cvt_pk_s(b[0], b[1]), cvt_pk_s(b[2], b[3])}; *(u32x4*)p = w; }
; #define FOR_AI_M _Pragma("unroll") for (int ai = 0; ai < 2; ++ai) if ((__builtin_amdgcn_sched_barrier(0), true)) _Pragma("unroll") for (int m = 0; m < 4; ++m)
;   template <int ACT> __device__ __forceinline__ void plain_store(const f32x4 (&acc)[2][2][4][2], bf16_t* dst, int cbase, int rbase) const {
;     FOR_AI_M { const int row = rbase + ai * 128 + m * 16;
; #pragma unroll
;       for (int bj = 0; bj < 2; ++bj) { f32x4 v0 = acc[ai][bj][m][0], v1 = acc[ai][bj][m][1];
;         if (ACT == 1) {
; #pragma unroll
;           for (int e = 0; e < 4; ++e) { v0[e] = v0[e] * sigm(v0[e]); v1[e] = v1[e] * sigm(v1[e]); } }
;         if (ACT == 2) {
; #pragma unroll
;           for (int e = 0; e < 4; ++e) { v0[e] = sigm(v0[e]); v1[e] = sigm(v1[e]); } }
;         if (ACT == 0) st8(dst + (size_t)row * 1024 + cbase + bj * 128, v0, v1); else st8_s(dst + (size_t)row * 1024 + cbase + bj * 128, v0, v1); } }
;   }
	v_add_f32_e32 v149, 1.0, v150
	v_add_f32_e32 v150, 1.0, v151
	v_mul_f32_e32 v151, 0xbfb8aa3b, v95
	v_exp_f32_e32 v147, v130
	v_mul_f32_e32 v148, 0xbfb8aa3b, v93
	v_exp_f32_e32 v151, v151
	v_mul_f32_e32 v153, 0xbfb8aa3b, v91
	v_exp_f32_e32 v148, v148
	v_exp_f32_e32 v153, v153
	v_add_f32_e32 v147, 1.0, v147
	v_rcp_f32_e32 v154, v150
	v_add_f32_e32 v150, 1.0, v151
	v_add_f32_e32 v145, 1.0, v145
	v_rcp_f32_e32 v147, v147
	v_add_f32_e32 v148, 1.0, v148
	v_rcp_f32_e32 v149, v149
	v_rcp_f32_e32 v150, v150
	v_add_f32_e32 v151, 1.0, v153
	v_rcp_f32_e32 v145, v145
	v_rcp_f32_e32 v148, v148
	v_rcp_f32_e32 v151, v151
	v_cvt_pk_bf16_f32 v149, v149, v150
	v_cvt_pk_bf16_f32 v150, v147, v152
	v_add_co_u32_e32 v152, vcc, s95, v128
	v_cvt_pk_bf16_f32 v148, v145, v148
	v_cvt_pk_bf16_f32 v151, v154, v151
	v_addc_co_u32_e32 v153, vcc, 0, v129, vcc
	global_store_dwordx4 v[152:153], v[148:151], off
	v_mul_f32_e32 v145, 0xbfb8aa3b, v84
	v_mul_f32_e32 v147, 0xbfb8aa3b, v80
	v_mul_f32_e32 v149, 0xbfb8aa3b, v81
	v_exp_f32_e32 v149, v149
	v_mul_f32_e32 v150, 0xbfb8aa3b, v86
	v_mul_f32_e32 v151, 0xbfb8aa3b, v82
	v_exp_f32_e32 v150, v150
	v_exp_f32_e32 v151, v151
	v_add_f32_e32 v149, 1.0, v149
	v_mul_f32_e32 v148, 0xbfb8aa3b, v85
	v_rcp_f32_e32 v152, v149
	v_add_f32_e32 v149, 1.0, v150
	v_add_f32_e32 v150, 1.0, v151
	v_mul_f32_e32 v151, 0xbfb8aa3b, v87
	v_mul_f32_e32 v153, 0xbfb8aa3b, v83
	v_exp_f32_e32 v145, v145
	v_exp_f32_e32 v147, v147
	v_exp_f32_e32 v148, v148
	v_exp_f32_e32 v151, v151
	v_exp_f32_e32 v153, v153
	v_add_f32_e32 v145, 1.0, v145
	v_add_f32_e32 v147, 1.0, v147
	v_add_f32_e32 v148, 1.0, v148
	v_rcp_f32_e32 v154, v150
	v_add_f32_e32 v150, 1.0, v151
	v_add_f32_e32 v151, 1.0, v153
	v_rcp_f32_e32 v145, v145
	v_rcp_f32_e32 v147, v147
	v_rcp_f32_e32 v148, v148
	v_rcp_f32_e32 v149, v149
	v_rcp_f32_e32 v150, v150
	v_rcp_f32_e32 v151, v151
	s_mov_b64 s[10:11], 0x10000
	v_lshl_add_u64 v[130:131], v[128:129], 0, s[10:11]
	v_cvt_pk_bf16_f32 v148, v145, v148
	v_cvt_pk_bf16_f32 v149, v149, v150
	v_cvt_pk_bf16_f32 v150, v147, v152
	v_cvt_pk_bf16_f32 v151, v154, v151
	global_store_dwordx4 v[130:131], v[148:151], off offset:256
	v_mul_f32_e32 v130, 0xbfb8aa3b, v76
	v_exp_f32_e32 v145, v130
	v_mul_f32_e32 v149, 0xbfb8aa3b, v73
	v_exp_f32_e32 v149, v149
	v_mul_f32_e32 v150, 0xbfb8aa3b, v78
	v_mul_f32_e32 v151, 0xbfb8aa3b, v74
	v_exp_f32_e32 v150, v150
	v_exp_f32_e32 v151, v151
	v_add_f32_e32 v149, 1.0, v149
	v_mul_f32_e32 v130, 0xbfb8aa3b, v72
	v_rcp_f32_e32 v152, v149
	v_add_f32_e32 v149, 1.0, v150
	v_add_f32_e32 v150, 1.0, v151
	v_mul_f32_e32 v151, 0xbfb8aa3b, v79
	v_exp_f32_e32 v147, v130
	v_mul_f32_e32 v148, 0xbfb8aa3b, v77
	v_exp_f32_e32 v151, v151
	v_mul_f32_e32 v153, 0xbfb8aa3b, v75
	v_exp_f32_e32 v148, v148
	v_exp_f32_e32 v153, v153
	v_add_f32_e32 v147, 1.0, v147
	v_rcp_f32_e32 v154, v150
	v_add_f32_e32 v150, 1.0, v151
	v_add_f32_e32 v145, 1.0, v145
	v_rcp_f32_e32 v147, v147
	v_add_f32_e32 v148, 1.0, v148
	v_rcp_f32_e32 v149, v149
	v_rcp_f32_e32 v150, v150
	v_add_f32_e32 v151, 1.0, v153
	v_rcp_f32_e32 v145, v145
	v_rcp_f32_e32 v148, v148
	v_rcp_f32_e32 v151, v151
	s_mov_b32 s8, 0x18000
	v_cvt_pk_bf16_f32 v149, v149, v150
	v_cvt_pk_bf16_f32 v150, v147, v152
	v_add_co_u32_e32 v152, vcc, s8, v128
	v_cvt_pk_bf16_f32 v148, v145, v148
	v_cvt_pk_bf16_f32 v151, v154, v151
	v_addc_co_u32_e32 v153, vcc, 0, v129, vcc
	global_store_dwordx4 v[152:153], v[148:151], off
	v_mul_f32_e32 v145, 0xbfb8aa3b, v68
	v_mul_f32_e32 v147, 0xbfb8aa3b, v64
	v_mul_f32_e32 v149, 0xbfb8aa3b, v65
	v_exp_f32_e32 v149, v149
	v_mul_f32_e32 v150, 0xbfb8aa3b, v70
	v_mul_f32_e32 v151, 0xbfb8aa3b, v66
	v_exp_f32_e32 v150, v150
	v_exp_f32_e32 v151, v151
	v_add_f32_e32 v149, 1.0, v149
	v_mul_f32_e32 v148, 0xbfb8aa3b, v69
	v_rcp_f32_e32 v152, v149
	v_add_f32_e32 v149, 1.0, v150
	v_add_f32_e32 v150, 1.0, v151
	v_mul_f32_e32 v151, 0xbfb8aa3b, v71
	v_mul_f32_e32 v153, 0xbfb8aa3b, v67
	v_exp_f32_e32 v145, v145
	v_exp_f32_e32 v147, v147
	v_exp_f32_e32 v148, v148
	v_exp_f32_e32 v151, v151
	v_exp_f32_e32 v153, v153
	v_add_f32_e32 v145, 1.0, v145
	v_add_f32_e32 v147, 1.0, v147
	v_add_f32_e32 v148, 1.0, v148
	v_rcp_f32_e32 v154, v150
	v_add_f32_e32 v150, 1.0, v151
	v_add_f32_e32 v151, 1.0, v153
	v_rcp_f32_e32 v145, v145
	v_rcp_f32_e32 v147, v147
	v_rcp_f32_e32 v148, v148
	v_rcp_f32_e32 v149, v149
	v_rcp_f32_e32 v150, v150
	v_rcp_f32_e32 v151, v151
	s_mov_b64 s[10:11], 0x18000
	v_lshl_add_u64 v[130:131], v[128:129], 0, s[10:11]
	v_cvt_pk_bf16_f32 v148, v145, v148
	v_cvt_pk_bf16_f32 v149, v149, v150
	v_cvt_pk_bf16_f32 v150, v147, v152
	v_cvt_pk_bf16_f32 v151, v154, v151
	global_store_dwordx4 v[130:131], v[148:151], off offset:256
	s_nop 1
	v_mul_f32_e32 v149, 0xbfb8aa3b, v57
	v_exp_f32_e32 v149, v149
	v_mul_f32_e32 v150, 0xbfb8aa3b, v62
	v_mul_f32_e32 v151, 0xbfb8aa3b, v58
	v_exp_f32_e32 v150, v150
	v_exp_f32_e32 v151, v151
	v_mul_f32_e32 v130, 0xbfb8aa3b, v60
	v_add_f32_e32 v149, 1.0, v149
	v_exp_f32_e32 v145, v130
	v_mul_f32_e32 v130, 0xbfb8aa3b, v56
	v_rcp_f32_e32 v152, v149
	v_add_f32_e32 v149, 1.0, v150
	v_add_f32_e32 v150, 1.0, v151
	v_mul_f32_e32 v151, 0xbfb8aa3b, v63
	v_exp_f32_e32 v147, v130
	v_mul_f32_e32 v148, 0xbfb8aa3b, v61
	v_exp_f32_e32 v151, v151
	v_mul_f32_e32 v153, 0xbfb8aa3b, v59
	v_exp_f32_e32 v148, v148
	v_exp_f32_e32 v153, v153
	v_add_f32_e32 v147, 1.0, v147
	v_rcp_f32_e32 v154, v150
	v_add_f32_e32 v150, 1.0, v151
	v_add_f32_e32 v145, 1.0, v145
	v_rcp_f32_e32 v147, v147
	v_add_f32_e32 v148, 1.0, v148
	v_rcp_f32_e32 v149, v149
	v_rcp_f32_e32 v150, v150
	v_add_f32_e32 v151, 1.0, v153
	v_rcp_f32_e32 v145, v145
	v_rcp_f32_e32 v148, v148
	v_rcp_f32_e32 v151, v151
	s_mov_b32 s8, 0x40000
; __device__ __forceinline__ void st8(bf16_t* p, f32x4 a, f32x4 b) { u32x4 w = {cvt_pk(a[0], a[1]), cvt_pk(a[2], a[3]), cvt_pk(b[0], b[1]), cvt_pk(b[2], b[3])}; *(u32x4*)p = w; }
; __device__ __forceinline__ float sigm(float x) { return __builtin_amdgcn_rcpf(1.f + __builtin_amdgcn_exp2f(x * -1.4426950408889634f)); }
; __device__ __forceinline__ void st8_s(bf16_t* p, f32x4 a, f32x4 b) { u32x4 w = {cvt_pk_s(a[0], a[1]), cvt_pk_s(a[2], a[3]), cvt_pk_s(b[0], b[1]), cvt_pk_s(b[2], b[3])}; *(u32x4*)p = w; }
; #define FOR_AI_M _Pragma("unroll") for (int ai = 0; ai < 2; ++ai) if ((__builtin_amdgcn_sched_barrier(0), true)) _Pragma("unroll") for (int m = 0; m < 4; ++m)
;   template <int ACT> __device__ __forceinline__ void plain_store(const f32x4 (&acc)[2][2][4][2], bf16_t* dst, int cbase, int rbase) const {
;     FOR_AI_M { const int row = rbase + ai * 128 + m * 16;
; #pragma unroll
;       for (int bj = 0; bj < 2; ++bj) { f32x4 v0 = acc[ai][bj][m][0], v1 = acc[ai][bj][m][1];
;         if (ACT == 1) {
; #pragma unroll
;           for (int e = 0; e < 4; ++e) { v0[e] = v0[e] * sigm(v0[e]); v1[e] = v1[e] * sigm(v1[e]); } }
;         if (ACT == 2) {
; #pragma unroll
;           for (int e = 0; e < 4; ++e) { v0[e] = sigm(v0[e]); v1[e] = sigm(v1[e]); } }
;         if (ACT == 0) st8(dst + (size_t)row * 1024 + cbase + bj * 128, v0, v1); else st8_s(dst + (size_t)row * 1024 + cbase + bj * 128, v0, v1); } }
;   }
	v_cvt_pk_bf16_f32 v149, v149, v150
	v_cvt_pk_bf16_f32 v150, v147, v152
	v_add_co_u32_e32 v152, vcc, s8, v128
	v_cvt_pk_bf16_f32 v148, v145, v148
	v_cvt_pk_bf16_f32 v151, v154, v151
	v_addc_co_u32_e32 v153, vcc, 0, v129, vcc
	global_store_dwordx4 v[152:153], v[148:151], off
	v_mul_f32_e32 v145, 0xbfb8aa3b, v52
	v_mul_f32_e32 v147, 0xbfb8aa3b, v48
	v_mul_f32_e32 v149, 0xbfb8aa3b, v49
	v_exp_f32_e32 v149, v149
	v_mul_f32_e32 v150, 0xbfb8aa3b, v54
	v_mul_f32_e32 v151, 0xbfb8aa3b, v50
	v_exp_f32_e32 v150, v150
	v_exp_f32_e32 v151, v151
	v_add_f32_e32 v149, 1.0, v149
	v_mul_f32_e32 v148, 0xbfb8aa3b, v53
	v_rcp_f32_e32 v152, v149
	v_add_f32_e32 v149, 1.0, v150
	v_add_f32_e32 v150, 1.0, v151
	v_mul_f32_e32 v151, 0xbfb8aa3b, v55
	v_mul_f32_e32 v153, 0xbfb8aa3b, v51
	v_exp_f32_e32 v145, v145
	v_exp_f32_e32 v147, v147
	v_exp_f32_e32 v148, v148
	v_exp_f32_e32 v151, v151
	v_exp_f32_e32 v153, v153
	v_add_f32_e32 v145, 1.0, v145
	v_add_f32_e32 v147, 1.0, v147
	v_add_f32_e32 v148, 1.0, v148
	v_rcp_f32_e32 v154, v150
	v_add_f32_e32 v150, 1.0, v151
	v_add_f32_e32 v151, 1.0, v153
	v_rcp_f32_e32 v145, v145
	v_rcp_f32_e32 v147, v147
	v_rcp_f32_e32 v148, v148
	v_rcp_f32_e32 v149, v149
	v_rcp_f32_e32 v150, v150
	v_rcp_f32_e32 v151, v151
	v_lshl_add_u64 v[130:131], v[128:129], 0, s[72:73]
	v_cvt_pk_bf16_f32 v148, v145, v148
	v_cvt_pk_bf16_f32 v149, v149, v150
	v_cvt_pk_bf16_f32 v150, v147, v152
	v_cvt_pk_bf16_f32 v151, v154, v151
	global_store_dwordx4 v[130:131], v[148:151], off offset:256
	v_mul_f32_e32 v130, 0xbfb8aa3b, v44
	v_exp_f32_e32 v145, v130
	v_mul_f32_e32 v149, 0xbfb8aa3b, v41
	v_exp_f32_e32 v149, v149
	v_mul_f32_e32 v150, 0xbfb8aa3b, v46
	v_mul_f32_e32 v151, 0xbfb8aa3b, v42
	v_exp_f32_e32 v150, v150
	v_exp_f32_e32 v151, v151
	v_add_f32_e32 v149, 1.0, v149
	v_mul_f32_e32 v130, 0xbfb8aa3b, v40
	v_rcp_f32_e32 v152, v149
	v_add_f32_e32 v149, 1.0, v150
	v_add_f32_e32 v150, 1.0, v151
	v_mul_f32_e32 v151, 0xbfb8aa3b, v47
	v_exp_f32_e32 v147, v130
	v_mul_f32_e32 v148, 0xbfb8aa3b, v45
	v_exp_f32_e32 v151, v151
	v_mul_f32_e32 v153, 0xbfb8aa3b, v43
	v_exp_f32_e32 v148, v148
	v_exp_f32_e32 v153, v153
	v_add_f32_e32 v147, 1.0, v147
	v_rcp_f32_e32 v154, v150
	v_add_f32_e32 v150, 1.0, v151
	v_add_f32_e32 v145, 1.0, v145
	v_rcp_f32_e32 v147, v147
	v_add_f32_e32 v148, 1.0, v148
	v_rcp_f32_e32 v149, v149
	v_rcp_f32_e32 v150, v150
	v_add_f32_e32 v151, 1.0, v153
	v_rcp_f32_e32 v145, v145
	v_rcp_f32_e32 v148, v148
	v_rcp_f32_e32 v151, v151
	s_mov_b32 s8, 0x48000
	v_cvt_pk_bf16_f32 v149, v149, v150
	v_cvt_pk_bf16_f32 v150, v147, v152
	v_add_co_u32_e32 v152, vcc, s8, v128
	v_cvt_pk_bf16_f32 v148, v145, v148
	v_cvt_pk_bf16_f32 v151, v154, v151
	v_addc_co_u32_e32 v153, vcc, 0, v129, vcc
	global_store_dwordx4 v[152:153], v[148:151], off
	v_mul_f32_e32 v145, 0xbfb8aa3b, v36
	v_mul_f32_e32 v147, 0xbfb8aa3b, v32
	v_mul_f32_e32 v149, 0xbfb8aa3b, v33
	v_exp_f32_e32 v149, v149
	v_mul_f32_e32 v150, 0xbfb8aa3b, v38
	v_mul_f32_e32 v151, 0xbfb8aa3b, v34
	v_exp_f32_e32 v150, v150
	v_exp_f32_e32 v151, v151
	v_add_f32_e32 v149, 1.0, v149
	v_mul_f32_e32 v148, 0xbfb8aa3b, v37
	v_rcp_f32_e32 v152, v149
	v_add_f32_e32 v149, 1.0, v150
	v_add_f32_e32 v150, 1.0, v151
	v_mul_f32_e32 v151, 0xbfb8aa3b, v39
	v_mul_f32_e32 v153, 0xbfb8aa3b, v35
	v_exp_f32_e32 v145, v145
	v_exp_f32_e32 v147, v147
	v_exp_f32_e32 v148, v148
	v_exp_f32_e32 v151, v151
	v_exp_f32_e32 v153, v153
	v_add_f32_e32 v145, 1.0, v145
	v_add_f32_e32 v147, 1.0, v147
	v_add_f32_e32 v148, 1.0, v148
	v_rcp_f32_e32 v154, v150
	v_add_f32_e32 v150, 1.0, v151
	v_add_f32_e32 v151, 1.0, v153
	v_rcp_f32_e32 v145, v145
	v_rcp_f32_e32 v147, v147
	v_rcp_f32_e32 v148, v148
	v_rcp_f32_e32 v149, v149
	v_rcp_f32_e32 v150, v150
	v_rcp_f32_e32 v151, v151
	s_mov_b64 s[10:11], 0x48000
	v_lshl_add_u64 v[130:131], v[128:129], 0, s[10:11]
	v_cvt_pk_bf16_f32 v148, v145, v148
	v_cvt_pk_bf16_f32 v149, v149, v150
	v_cvt_pk_bf16_f32 v150, v147, v152
	v_cvt_pk_bf16_f32 v151, v154, v151
	global_store_dwordx4 v[130:131], v[148:151], off offset:256
	v_mul_f32_e32 v130, 0xbfb8aa3b, v28
	v_exp_f32_e32 v145, v130
	v_mul_f32_e32 v149, 0xbfb8aa3b, v25
	v_exp_f32_e32 v149, v149
	v_mul_f32_e32 v150, 0xbfb8aa3b, v30
	v_mul_f32_e32 v151, 0xbfb8aa3b, v26
	v_exp_f32_e32 v150, v150
	v_exp_f32_e32 v151, v151
	v_add_f32_e32 v149, 1.0, v149
	v_mul_f32_e32 v130, 0xbfb8aa3b, v24
	v_rcp_f32_e32 v152, v149
	v_add_f32_e32 v149, 1.0, v150
	v_add_f32_e32 v150, 1.0, v151
	v_mul_f32_e32 v151, 0xbfb8aa3b, v31
	v_exp_f32_e32 v147, v130
	v_mul_f32_e32 v148, 0xbfb8aa3b, v29
; __device__ __forceinline__ void st8(bf16_t* p, f32x4 a, f32x4 b) { u32x4 w = {cvt_pk(a[0], a[1]), cvt_pk(a[2], a[3]), cvt_pk(b[0], b[1]), cvt_pk(b[2], b[3])}; *(u32x4*)p = w; }
; __device__ __forceinline__ float sigm(float x) { return __builtin_amdgcn_rcpf(1.f + __builtin_amdgcn_exp2f(x * -1.4426950408889634f)); }
; __device__ __forceinline__ void st8_s(bf16_t* p, f32x4 a, f32x4 b) { u32x4 w = {cvt_pk_s(a[0], a[1]), cvt_pk_s(a[2], a[3]), cvt_pk_s(b[0], b[1]), cvt_pk_s(b[2], b[3])}; *(u32x4*)p = w; }
; #define FOR_AI_M _Pragma("unroll") for (int ai = 0; ai < 2; ++ai) if ((__builtin_amdgcn_sched_barrier(0), true)) _Pragma("unroll") for (int m = 0; m < 4; ++m)
;   template <int ACT> __device__ __forceinline__ void plain_store(const f32x4 (&acc)[2][2][4][2], bf16_t* dst, int cbase, int rbase) const {
;     FOR_AI_M { const int row = rbase + ai * 128 + m * 16;
; #pragma unroll
;       for (int bj = 0; bj < 2; ++bj) { f32x4 v0 = acc[ai][bj][m][0], v1 = acc[ai][bj][m][1];
;         if (ACT == 1) {
; #pragma unroll
;           for (int e = 0; e < 4; ++e) { v0[e] = v0[e] * sigm(v0[e]); v1[e] = v1[e] * sigm(v1[e]); } }
;         if (ACT == 2) {
; #pragma unroll
;           for (int e = 0; e < 4; ++e) { v0[e] = sigm(v0[e]); v1[e] = sigm(v1[e]); } }
;         if (ACT == 0) st8(dst + (size_t)row * 1024 + cbase + bj * 128, v0, v1); else st8_s(dst + (size_t)row * 1024 + cbase + bj * 128, v0, v1); } }
;   }
	v_exp_f32_e32 v151, v151
	v_mul_f32_e32 v153, 0xbfb8aa3b, v27
	v_exp_f32_e32 v148, v148
	v_exp_f32_e32 v153, v153
	v_add_f32_e32 v147, 1.0, v147
	v_rcp_f32_e32 v154, v150
	v_add_f32_e32 v150, 1.0, v151
	v_add_f32_e32 v145, 1.0, v145
	v_rcp_f32_e32 v147, v147
	v_add_f32_e32 v148, 1.0, v148
	v_rcp_f32_e32 v149, v149
	v_rcp_f32_e32 v150, v150
	v_add_f32_e32 v151, 1.0, v153
	v_rcp_f32_e32 v145, v145
	v_rcp_f32_e32 v148, v148
	v_rcp_f32_e32 v151, v151
	s_mov_b32 s8, 0x50000
	v_cvt_pk_bf16_f32 v149, v149, v150
	v_cvt_pk_bf16_f32 v150, v147, v152
	v_add_co_u32_e32 v152, vcc, s8, v128
	v_cvt_pk_bf16_f32 v148, v145, v148
	v_cvt_pk_bf16_f32 v151, v154, v151
	v_addc_co_u32_e32 v153, vcc, 0, v129, vcc
	global_store_dwordx4 v[152:153], v[148:151], off
	v_mul_f32_e32 v145, 0xbfb8aa3b, v20
	v_mul_f32_e32 v147, 0xbfb8aa3b, v16
	v_mul_f32_e32 v149, 0xbfb8aa3b, v17
	v_exp_f32_e32 v149, v149
	v_mul_f32_e32 v150, 0xbfb8aa3b, v22
	v_mul_f32_e32 v151, 0xbfb8aa3b, v18
	v_exp_f32_e32 v150, v150
	v_exp_f32_e32 v151, v151
	v_add_f32_e32 v149, 1.0, v149
	v_mul_f32_e32 v148, 0xbfb8aa3b, v21
	v_rcp_f32_e32 v152, v149
	v_add_f32_e32 v149, 1.0, v150
	v_add_f32_e32 v150, 1.0, v151
	v_mul_f32_e32 v151, 0xbfb8aa3b, v23
	v_mul_f32_e32 v153, 0xbfb8aa3b, v19
	v_exp_f32_e32 v145, v145
	v_exp_f32_e32 v147, v147
	v_exp_f32_e32 v148, v148
	v_exp_f32_e32 v151, v151
	v_exp_f32_e32 v153, v153
	v_add_f32_e32 v145, 1.0, v145
	v_add_f32_e32 v147, 1.0, v147
	v_add_f32_e32 v148, 1.0, v148
	v_rcp_f32_e32 v154, v150
	v_add_f32_e32 v150, 1.0, v151
	v_add_f32_e32 v151, 1.0, v153
	v_rcp_f32_e32 v145, v145
	v_rcp_f32_e32 v147, v147
	v_rcp_f32_e32 v148, v148
	v_rcp_f32_e32 v149, v149
	v_rcp_f32_e32 v150, v150
	v_rcp_f32_e32 v151, v151
	s_mov_b64 s[10:11], 0x50000
	v_lshl_add_u64 v[130:131], v[128:129], 0, s[10:11]
	v_cvt_pk_bf16_f32 v148, v145, v148
	v_cvt_pk_bf16_f32 v149, v149, v150
	v_cvt_pk_bf16_f32 v150, v147, v152
	v_cvt_pk_bf16_f32 v151, v154, v151
	global_store_dwordx4 v[130:131], v[148:151], off offset:256
	v_mul_f32_e32 v130, 0xbfb8aa3b, v12
	v_mul_f32_e32 v131, 0xbfb8aa3b, v8
	v_mul_f32_e32 v148, 0xbfb8aa3b, v14
	v_exp_f32_e32 v148, v148
	v_mul_f32_e32 v149, 0xbfb8aa3b, v10
	v_exp_f32_e32 v149, v149
	v_mul_f32_e32 v145, 0xbfb8aa3b, v13
	v_add_f32_e32 v148, 1.0, v148
	v_mul_f32_e32 v147, 0xbfb8aa3b, v9
	v_rcp_f32_e32 v150, v148
	v_add_f32_e32 v148, 1.0, v149
	v_mul_f32_e32 v149, 0xbfb8aa3b, v15
	v_exp_f32_e32 v130, v130
	v_exp_f32_e32 v131, v131
	v_exp_f32_e32 v145, v145
	v_exp_f32_e32 v147, v147
	v_exp_f32_e32 v149, v149
	v_mul_f32_e32 v151, 0xbfb8aa3b, v11
	v_add_f32_e32 v130, 1.0, v130
	v_add_f32_e32 v131, 1.0, v131
	v_add_f32_e32 v145, 1.0, v145
	v_add_f32_e32 v147, 1.0, v147
	v_exp_f32_e32 v151, v151
	v_rcp_f32_e32 v154, v148
	v_add_f32_e32 v148, 1.0, v149
	v_rcp_f32_e32 v130, v130
	v_rcp_f32_e32 v131, v131
	v_rcp_f32_e32 v145, v145
	v_rcp_f32_e32 v147, v147
	v_rcp_f32_e32 v149, v148
	v_add_f32_e32 v148, 1.0, v151
	v_rcp_f32_e32 v151, v148
	v_cvt_pk_bf16_f32 v148, v130, v145
	v_cvt_pk_bf16_f32 v149, v150, v149
	v_cvt_pk_bf16_f32 v150, v131, v147
	v_mul_f32_e32 v130, 0xbfb8aa3b, v4
	v_mul_f32_e32 v131, 0xbfb8aa3b, v0
	v_exp_f32_e32 v130, v130
	v_exp_f32_e32 v131, v131
	s_mov_b64 s[10:11], 0x58000
	s_mov_b32 s8, 0x58000
	v_lshl_add_u64 v[152:153], v[128:129], 0, s[10:11]
	v_add_co_u32_e32 v128, vcc, s8, v128
	v_cvt_pk_bf16_f32 v151, v154, v151
	s_nop 0
	v_addc_co_u32_e32 v129, vcc, 0, v129, vcc
	global_store_dwordx4 v[128:129], v[148:151], off
	v_add_f32_e32 v128, 1.0, v130
	v_add_f32_e32 v129, 1.0, v131
	v_mul_f32_e32 v130, 0xbfb8aa3b, v5
	v_mul_f32_e32 v131, 0xbfb8aa3b, v1
	v_exp_f32_e32 v130, v130
	v_exp_f32_e32 v131, v131
	v_rcp_f32_e32 v145, v129
	v_mul_f32_e32 v147, 0xbfb8aa3b, v2
	v_add_f32_e32 v129, 1.0, v130
	v_add_f32_e32 v130, 1.0, v131
	v_mul_f32_e32 v131, 0xbfb8aa3b, v6
	v_mul_f32_e32 v148, 0xbfb8aa3b, v7
	v_mul_f32_e32 v149, 0xbfb8aa3b, v3
	v_exp_f32_e32 v131, v131
	v_exp_f32_e32 v147, v147
	v_exp_f32_e32 v148, v148
	v_exp_f32_e32 v149, v149
	v_add_f32_e32 v131, 1.0, v131
	v_add_f32_e32 v147, 1.0, v147
	v_add_f32_e32 v148, 1.0, v148
	v_add_f32_e32 v149, 1.0, v149
	v_rcp_f32_e32 v128, v128
	v_rcp_f32_e32 v129, v129
	v_rcp_f32_e32 v130, v130
	v_rcp_f32_e32 v131, v131
	v_rcp_f32_e32 v147, v147
	v_rcp_f32_e32 v148, v148
	v_rcp_f32_e32 v149, v149
	v_cvt_pk_bf16_f32 v128, v128, v129
	v_cvt_pk_bf16_f32 v130, v145, v130
	v_cvt_pk_bf16_f32 v129, v131, v148
	v_cvt_pk_bf16_f32 v131, v147, v149
	global_store_dwordx4 v[152:153], v[128:131], off offset:256

; __device__ __forceinline__ void st8(bf16_t* p, f32x4 a, f32x4 b) { u32x4 w = {cvt_pk(a[0], a[1]), cvt_pk(a[2], a[3]), cvt_pk(b[0], b[1]), cvt_pk(b[2], b[3])}; *(u32x4*)p = w; }
; __device__ __forceinline__ float sigm(float x) { return __builtin_amdgcn_rcpf(1.f + __builtin_amdgcn_exp2f(x * -1.4426950408889634f)); }
; __device__ __forceinline__ void st8_s(bf16_t* p, f32x4 a, f32x4 b) { u32x4 w = {cvt_pk_s(a[0], a[1]), cvt_pk_s(a[2], a[3]), cvt_pk_s(b[0], b[1]), cvt_pk_s(b[2], b[3])}; *(u32x4*)p = w; }
; #define FOR_AI_M _Pragma("unroll") for (int ai = 0; ai < 2; ++ai) if ((__builtin_amdgcn_sched_barrier(0), true)) _Pragma("unroll") for (int m = 0; m < 4; ++m)
;   template <int ACT> __device__ __forceinline__ void plain_store(const f32x4 (&acc)[2][2][4][2], bf16_t* dst, int cbase, int rbase) const {
;     FOR_AI_M { const int row = rbase + ai * 128 + m * 16;
; #pragma unroll
;       for (int bj = 0; bj < 2; ++bj) { f32x4 v0 = acc[ai][bj][m][0], v1 = acc[ai][bj][m][1];
;         if (ACT == 1) {
; #pragma unroll
;           for (int e = 0; e < 4; ++e) { v0[e] = v0[e] * sigm(v0[e]); v1[e] = v1[e] * sigm(v1[e]); } }
;         if (ACT == 2) {
; #pragma unroll
;           for (int e = 0; e < 4; ++e) { v0[e] = sigm(v0[e]); v1[e] = sigm(v1[e]); } }
;         if (ACT == 0) st8(dst + (size_t)row * 1024 + cbase + bj * 128, v0, v1); else st8_s(dst + (size_t)row * 1024 + cbase + bj * 128, v0, v1); } }
;   }
;   __device__ __forceinline__ void operator()(EPI_ARGS) const {
;     ...
;     else if (pn < 16) plain_store<2>(acc, b.GR, (pn - 12) * 256 + c0, rbase);
.LBB0_408:
	s_andn2_b64 vcc, exec, s[42:43]
	s_cbranch_vccnz .LBB0_410
	s_lshl_b32 s8, s47, 8
	s_addk_i32 s8, 0xf400
	v_add_u32_e32 v128, s8, v146
	v_readlane_b32 s10, v255, 32
	s_waitcnt lgkmcnt(0)
	v_ashrrev_i32_e32 v129, 31, v128
	v_readlane_b32 s11, v255, 33
	s_nop 1
	v_lshl_add_u64 v[128:129], v[128:129], 1, s[10:11]
	v_mul_f32_e32 v148, 0xbfb8aa3b, v126
	v_ashrrev_i32_e32 v145, 31, v144
	v_exp_f32_e32 v148, v148
	v_mul_f32_e32 v149, 0xbfb8aa3b, v122
	v_lshlrev_b64 v[130:131], 11, v[144:145]
	v_mul_f32_e32 v145, 0xbfb8aa3b, v124
	v_mul_f32_e32 v147, 0xbfb8aa3b, v120
	v_exp_f32_e32 v149, v149
	v_exp_f32_e32 v145, v145
	v_exp_f32_e32 v147, v147
	v_add_f32_e32 v148, 1.0, v148
	v_rcp_f32_e32 v150, v148
	v_add_f32_e32 v148, 1.0, v149
	v_mul_f32_e32 v149, 0xbfb8aa3b, v127
	v_lshl_add_u64 v[128:129], v[128:129], 0, v[130:131]
	v_add_f32_e32 v130, 1.0, v145
	v_add_f32_e32 v131, 1.0, v147
	v_mul_f32_e32 v145, 0xbfb8aa3b, v125
	v_mul_f32_e32 v147, 0xbfb8aa3b, v121
	v_exp_f32_e32 v149, v149
	v_mul_f32_e32 v151, 0xbfb8aa3b, v123
	v_exp_f32_e32 v145, v145
	v_exp_f32_e32 v147, v147
	v_exp_f32_e32 v151, v151
	v_rcp_f32_e32 v152, v148
	v_add_f32_e32 v148, 1.0, v149
	v_add_f32_e32 v145, 1.0, v145
	v_add_f32_e32 v147, 1.0, v147
	v_rcp_f32_e32 v149, v148
	v_add_f32_e32 v148, 1.0, v151
	v_rcp_f32_e32 v130, v130
	v_rcp_f32_e32 v131, v131
	v_rcp_f32_e32 v145, v145
	v_rcp_f32_e32 v147, v147
	v_rcp_f32_e32 v151, v148
	v_cvt_pk_bf16_f32 v149, v150, v149
	v_cvt_pk_bf16_f32 v148, v130, v145
	v_cvt_pk_bf16_f32 v150, v131, v147
	v_cvt_pk_bf16_f32 v151, v152, v151
	global_store_dwordx4 v[128:129], v[148:151], off
	v_mul_f32_e32 v130, 0xbfb8aa3b, v116
	v_mul_f32_e32 v131, 0xbfb8aa3b, v112
	v_mul_f32_e32 v148, 0xbfb8aa3b, v118
	v_exp_f32_e32 v148, v148
	v_mul_f32_e32 v149, 0xbfb8aa3b, v114
	v_exp_f32_e32 v149, v149
	v_mul_f32_e32 v145, 0xbfb8aa3b, v117
	v_add_f32_e32 v148, 1.0, v148
	v_rcp_f32_e32 v150, v148
	v_add_f32_e32 v148, 1.0, v149
	v_mul_f32_e32 v149, 0xbfb8aa3b, v119
	v_mul_f32_e32 v147, 0xbfb8aa3b, v113
	v_exp_f32_e32 v149, v149
	v_mul_f32_e32 v151, 0xbfb8aa3b, v115
	v_exp_f32_e32 v130, v130
	v_exp_f32_e32 v131, v131
	v_exp_f32_e32 v145, v145
	v_exp_f32_e32 v147, v147
	v_exp_f32_e32 v151, v151
	v_rcp_f32_e32 v152, v148
	v_add_f32_e32 v148, 1.0, v149
	v_add_f32_e32 v130, 1.0, v130
	v_add_f32_e32 v131, 1.0, v131
	v_add_f32_e32 v145, 1.0, v145
	v_add_f32_e32 v147, 1.0, v147
	v_rcp_f32_e32 v149, v148
	v_add_f32_e32 v148, 1.0, v151
	v_rcp_f32_e32 v130, v130
	v_rcp_f32_e32 v131, v131
	v_rcp_f32_e32 v145, v145
	v_rcp_f32_e32 v147, v147
	v_rcp_f32_e32 v151, v148
	v_cvt_pk_bf16_f32 v149, v150, v149
	v_cvt_pk_bf16_f32 v148, v130, v145
	v_cvt_pk_bf16_f32 v150, v131, v147
	v_cvt_pk_bf16_f32 v151, v152, v151
	global_store_dwordx4 v[128:129], v[148:151], off offset:256
	v_mul_f32_e32 v130, 0xbfb8aa3b, v108
	v_exp_f32_e32 v145, v130
	v_mul_f32_e32 v149, 0xbfb8aa3b, v105
	v_exp_f32_e32 v149, v149
	v_mul_f32_e32 v150, 0xbfb8aa3b, v110
	v_mul_f32_e32 v151, 0xbfb8aa3b, v106
	v_exp_f32_e32 v150, v150
	v_exp_f32_e32 v151, v151
	v_add_f32_e32 v149, 1.0, v149
	v_mul_f32_e32 v130, 0xbfb8aa3b, v104
	v_rcp_f32_e32 v152, v149
	v_add_f32_e32 v149, 1.0, v150
	v_add_f32_e32 v150, 1.0, v151
	v_mul_f32_e32 v151, 0xbfb8aa3b, v111
	v_exp_f32_e32 v147, v130
	v_mul_f32_e32 v148, 0xbfb8aa3b, v109
	v_exp_f32_e32 v151, v151
	v_mul_f32_e32 v153, 0xbfb8aa3b, v107
	v_exp_f32_e32 v148, v148
	v_exp_f32_e32 v153, v153
	v_add_f32_e32 v147, 1.0, v147
	v_rcp_f32_e32 v154, v150
	v_add_f32_e32 v150, 1.0, v151
	v_add_f32_e32 v145, 1.0, v145
	v_rcp_f32_e32 v147, v147
	v_add_f32_e32 v148, 1.0, v148
	v_rcp_f32_e32 v149, v149
	v_rcp_f32_e32 v150, v150
	v_add_f32_e32 v151, 1.0, v153
	v_rcp_f32_e32 v145, v145
	v_rcp_f32_e32 v148, v148
	v_rcp_f32_e32 v151, v151
	v_cvt_pk_bf16_f32 v149, v149, v150
	v_cvt_pk_bf16_f32 v150, v147, v152
	v_add_co_u32_e32 v152, vcc, s88, v128
	v_cvt_pk_bf16_f32 v148, v145, v148
	v_cvt_pk_bf16_f32 v151, v154, v151
	v_addc_co_u32_e32 v153, vcc, 0, v129, vcc
	global_store_dwordx4 v[152:153], v[148:151], off
	v_mul_f32_e32 v145, 0xbfb8aa3b, v100
	v_mul_f32_e32 v147, 0xbfb8aa3b, v96
	v_mul_f32_e32 v149, 0xbfb8aa3b, v97
	v_exp_f32_e32 v149, v149
	v_mul_f32_e32 v150, 0xbfb8aa3b, v102
	v_mul_f32_e32 v151, 0xbfb8aa3b, v98
	v_exp_f32_e32 v150, v150
	v_exp_f32_e32 v151, v151
	v_add_f32_e32 v149, 1.0, v149
	v_mul_f32_e32 v148, 0xbfb8aa3b, v101
	v_rcp_f32_e32 v152, v149
	v_add_f32_e32 v149, 1.0, v150
	v_add_f32_e32 v150, 1.0, v151
	v_mul_f32_e32 v151, 0xbfb8aa3b, v103
	v_mul_f32_e32 v153, 0xbfb8aa3b, v99
	v_exp_f32_e32 v145, v145
	v_exp_f32_e32 v147, v147
	v_exp_f32_e32 v148, v148
	v_exp_f32_e32 v151, v151
	v_exp_f32_e32 v153, v153
	v_add_f32_e32 v145, 1.0, v145
	v_add_f32_e32 v147, 1.0, v147
	v_add_f32_e32 v148, 1.0, v148
	v_rcp_f32_e32 v154, v150
	v_add_f32_e32 v150, 1.0, v151
	v_add_f32_e32 v151, 1.0, v153
	v_rcp_f32_e32 v145, v145
	v_rcp_f32_e32 v147, v147
	v_rcp_f32_e32 v148, v148
	v_rcp_f32_e32 v149, v149
	v_rcp_f32_e32 v150, v150
	v_rcp_f32_e32 v151, v151
	s_mov_b64 s[10:11], 0x8000
	v_lshl_add_u64 v[130:131], v[128:129], 0, s[10:11]
	v_cvt_pk_bf16_f32 v148, v145, v148
	v_cvt_pk_bf16_f32 v149, v149, v150
	v_cvt_pk_bf16_f32 v150, v147, v152
	v_cvt_pk_bf16_f32 v151, v154, v151
	global_store_dwordx4 v[130:131], v[148:151], off offset:256
	v_mul_f32_e32 v130, 0xbfb8aa3b, v92
	v_exp_f32_e32 v145, v130
	v_mul_f32_e32 v149, 0xbfb8aa3b, v89
	v_exp_f32_e32 v149, v149
	v_mul_f32_e32 v150, 0xbfb8aa3b, v94
	v_mul_f32_e32 v151, 0xbfb8aa3b, v90
	v_exp_f32_e32 v150, v150
	v_exp_f32_e32 v151, v151
	v_add_f32_e32 v149, 1.0, v149
	v_mul_f32_e32 v130, 0xbfb8aa3b, v88
	v_rcp_f32_e32 v152, v149
; __device__ __forceinline__ void st8(bf16_t* p, f32x4 a, f32x4 b) { u32x4 w = {cvt_pk(a[0], a[1]), cvt_pk(a[2], a[3]), cvt_pk(b[0], b[1]), cvt_pk(b[2], b[3])}; *(u32x4*)p = w; }
; __device__ __forceinline__ float sigm(float x) { return __builtin_amdgcn_rcpf(1.f + __builtin_amdgcn_exp2f(x * -1.4426950408889634f)); }
; __device__ __forceinline__ void st8_s(bf16_t* p, f32x4 a, f32x4 b) { u32x4 w = {cvt_pk_s(a[0], a[1]), cvt_pk_s(a[2], a[3]), cvt_pk_s(b[0], b[1]), cvt_pk_s(b[2], b[3])}; *(u32x4*)p = w; }
; #define FOR_AI_M _Pragma("unroll") for (int ai = 0; ai < 2; ++ai) if ((__builtin_amdgcn_sched_barrier(0), true)) _Pragma("unroll") for (int m = 0; m < 4; ++m)
;   template <int ACT> __device__ __forceinline__ void plain_store(const f32x4 (&acc)[2][2][4][2], bf16_t* dst, int cbase, int rbase) const {
;     FOR_AI_M { const int row = rbase + ai * 128 + m * 16;
; #pragma unroll
;       for (int bj = 0; bj < 2; ++bj) { f32x4 v0 = acc[ai][bj][m][0], v1 = acc[ai][bj][m][1];
;         if (ACT == 1) {
; #pragma unroll
;           for (int e = 0; e < 4; ++e) { v0[e] = v0[e] * sigm(v0[e]); v1[e] = v1[e] * sigm(v1[e]); } }
;         if (ACT == 2) {
; #pragma unroll
;           for (int e = 0; e < 4; ++e) { v0[e] = sigm(v0[e]); v1[e] = sigm(v1[e]); } }
;         if (ACT == 0) st8(dst + (size_t)row * 1024 + cbase + bj * 128, v0, v1); else st8_s(dst + (size_t)row * 1024 + cbase + bj * 128, v0, v1); } }
;   }
	v_add_f32_e32 v149, 1.0, v150
	v_add_f32_e32 v150, 1.0, v151
	v_mul_f32_e32 v151, 0xbfb8aa3b, v95
	v_exp_f32_e32 v147, v130
	v_mul_f32_e32 v148, 0xbfb8aa3b, v93
	v_exp_f32_e32 v151, v151
	v_mul_f32_e32 v153, 0xbfb8aa3b, v91
	v_exp_f32_e32 v148, v148
	v_exp_f32_e32 v153, v153
	v_add_f32_e32 v147, 1.0, v147
	v_rcp_f32_e32 v154, v150
	v_add_f32_e32 v150, 1.0, v151
	v_add_f32_e32 v145, 1.0, v145
	v_rcp_f32_e32 v147, v147
	v_add_f32_e32 v148, 1.0, v148
	v_rcp_f32_e32 v149, v149
	v_rcp_f32_e32 v150, v150
	v_add_f32_e32 v151, 1.0, v153
	v_rcp_f32_e32 v145, v145
	v_rcp_f32_e32 v148, v148
	v_rcp_f32_e32 v151, v151
	v_cvt_pk_bf16_f32 v149, v149, v150
	v_cvt_pk_bf16_f32 v150, v147, v152
	v_add_co_u32_e32 v152, vcc, s95, v128
	v_cvt_pk_bf16_f32 v148, v145, v148
	v_cvt_pk_bf16_f32 v151, v154, v151
	v_addc_co_u32_e32 v153, vcc, 0, v129, vcc
	global_store_dwordx4 v[152:153], v[148:151], off
	v_mul_f32_e32 v145, 0xbfb8aa3b, v84
	v_mul_f32_e32 v147, 0xbfb8aa3b, v80
	v_mul_f32_e32 v149, 0xbfb8aa3b, v81
	v_exp_f32_e32 v149, v149
	v_mul_f32_e32 v150, 0xbfb8aa3b, v86
	v_mul_f32_e32 v151, 0xbfb8aa3b, v82
	v_exp_f32_e32 v150, v150
	v_exp_f32_e32 v151, v151
	v_add_f32_e32 v149, 1.0, v149
	v_mul_f32_e32 v148, 0xbfb8aa3b, v85
	v_rcp_f32_e32 v152, v149
	v_add_f32_e32 v149, 1.0, v150
	v_add_f32_e32 v150, 1.0, v151
	v_mul_f32_e32 v151, 0xbfb8aa3b, v87
	v_mul_f32_e32 v153, 0xbfb8aa3b, v83
	v_exp_f32_e32 v145, v145
	v_exp_f32_e32 v147, v147
	v_exp_f32_e32 v148, v148
	v_exp_f32_e32 v151, v151
	v_exp_f32_e32 v153, v153
	v_add_f32_e32 v145, 1.0, v145
	v_add_f32_e32 v147, 1.0, v147
	v_add_f32_e32 v148, 1.0, v148
	v_rcp_f32_e32 v154, v150
	v_add_f32_e32 v150, 1.0, v151
	v_add_f32_e32 v151, 1.0, v153
	v_rcp_f32_e32 v145, v145
	v_rcp_f32_e32 v147, v147
	v_rcp_f32_e32 v148, v148
	v_rcp_f32_e32 v149, v149
	v_rcp_f32_e32 v150, v150
	v_rcp_f32_e32 v151, v151
	s_mov_b64 s[10:11], 0x10000
	v_lshl_add_u64 v[130:131], v[128:129], 0, s[10:11]
	v_cvt_pk_bf16_f32 v148, v145, v148
	v_cvt_pk_bf16_f32 v149, v149, v150
	v_cvt_pk_bf16_f32 v150, v147, v152
	v_cvt_pk_bf16_f32 v151, v154, v151
	global_store_dwordx4 v[130:131], v[148:151], off offset:256
	v_mul_f32_e32 v130, 0xbfb8aa3b, v76
	v_exp_f32_e32 v145, v130
	v_mul_f32_e32 v149, 0xbfb8aa3b, v73
	v_exp_f32_e32 v149, v149
	v_mul_f32_e32 v150, 0xbfb8aa3b, v78
	v_mul_f32_e32 v151, 0xbfb8aa3b, v74
	v_exp_f32_e32 v150, v150
	v_exp_f32_e32 v151, v151
	v_add_f32_e32 v149, 1.0, v149
	v_mul_f32_e32 v130, 0xbfb8aa3b, v72
	v_rcp_f32_e32 v152, v149
	v_add_f32_e32 v149, 1.0, v150
	v_add_f32_e32 v150, 1.0, v151
	v_mul_f32_e32 v151, 0xbfb8aa3b, v79
	v_exp_f32_e32 v147, v130
	v_mul_f32_e32 v148, 0xbfb8aa3b, v77
	v_exp_f32_e32 v151, v151
	v_mul_f32_e32 v153, 0xbfb8aa3b, v75
	v_exp_f32_e32 v148, v148
	v_exp_f32_e32 v153, v153
	v_add_f32_e32 v147, 1.0, v147
	v_rcp_f32_e32 v154, v150
	v_add_f32_e32 v150, 1.0, v151
	v_add_f32_e32 v145, 1.0, v145
	v_rcp_f32_e32 v147, v147
	v_add_f32_e32 v148, 1.0, v148
	v_rcp_f32_e32 v149, v149
	v_rcp_f32_e32 v150, v150
	v_add_f32_e32 v151, 1.0, v153
	v_rcp_f32_e32 v145, v145
	v_rcp_f32_e32 v148, v148
	v_rcp_f32_e32 v151, v151
	s_mov_b32 s8, 0x18000
	v_cvt_pk_bf16_f32 v149, v149, v150
	v_cvt_pk_bf16_f32 v150, v147, v152
	v_add_co_u32_e32 v152, vcc, s8, v128
	v_cvt_pk_bf16_f32 v148, v145, v148
	v_cvt_pk_bf16_f32 v151, v154, v151
	v_addc_co_u32_e32 v153, vcc, 0, v129, vcc
	global_store_dwordx4 v[152:153], v[148:151], off
	v_mul_f32_e32 v145, 0xbfb8aa3b, v68
	v_mul_f32_e32 v147, 0xbfb8aa3b, v64
	v_mul_f32_e32 v149, 0xbfb8aa3b, v65
	v_exp_f32_e32 v149, v149
	v_mul_f32_e32 v150, 0xbfb8aa3b, v70
	v_mul_f32_e32 v151, 0xbfb8aa3b, v66
	v_exp_f32_e32 v150, v150
	v_exp_f32_e32 v151, v151
	v_add_f32_e32 v149, 1.0, v149
	v_mul_f32_e32 v148, 0xbfb8aa3b, v69
	v_rcp_f32_e32 v152, v149
	v_add_f32_e32 v149, 1.0, v150
	v_add_f32_e32 v150, 1.0, v151
	v_mul_f32_e32 v151, 0xbfb8aa3b, v71
	v_mul_f32_e32 v153, 0xbfb8aa3b, v67
	v_exp_f32_e32 v145, v145
	v_exp_f32_e32 v147, v147
	v_exp_f32_e32 v148, v148
	v_exp_f32_e32 v151, v151
	v_exp_f32_e32 v153, v153
	v_add_f32_e32 v145, 1.0, v145
	v_add_f32_e32 v147, 1.0, v147
	v_add_f32_e32 v148, 1.0, v148
	v_rcp_f32_e32 v154, v150
	v_add_f32_e32 v150, 1.0, v151
	v_add_f32_e32 v151, 1.0, v153
	v_rcp_f32_e32 v145, v145
	v_rcp_f32_e32 v147, v147
	v_rcp_f32_e32 v148, v148
	v_rcp_f32_e32 v149, v149
	v_rcp_f32_e32 v150, v150
	v_rcp_f32_e32 v151, v151
	s_mov_b64 s[10:11], 0x18000
	v_lshl_add_u64 v[130:131], v[128:129], 0, s[10:11]
	v_cvt_pk_bf16_f32 v148, v145, v148
	v_cvt_pk_bf16_f32 v149, v149, v150
	v_cvt_pk_bf16_f32 v150, v147, v152
	v_cvt_pk_bf16_f32 v151, v154, v151
	global_store_dwordx4 v[130:131], v[148:151], off offset:256
	s_nop 1
	v_mul_f32_e32 v149, 0xbfb8aa3b, v57
	v_exp_f32_e32 v149, v149
	v_mul_f32_e32 v150, 0xbfb8aa3b, v62
	v_mul_f32_e32 v151, 0xbfb8aa3b, v58
	v_exp_f32_e32 v150, v150
	v_exp_f32_e32 v151, v151
	v_mul_f32_e32 v130, 0xbfb8aa3b, v60
	v_add_f32_e32 v149, 1.0, v149
	v_exp_f32_e32 v145, v130
	v_mul_f32_e32 v130, 0xbfb8aa3b, v56
	v_rcp_f32_e32 v152, v149
	v_add_f32_e32 v149, 1.0, v150
	v_add_f32_e32 v150, 1.0, v151
	v_mul_f32_e32 v151, 0xbfb8aa3b, v63
	v_exp_f32_e32 v147, v130
	v_mul_f32_e32 v148, 0xbfb8aa3b, v61
	v_exp_f32_e32 v151, v151
	v_mul_f32_e32 v153, 0xbfb8aa3b, v59
	v_exp_f32_e32 v148, v148
	v_exp_f32_e32 v153, v153
	v_add_f32_e32 v147, 1.0, v147
	v_rcp_f32_e32 v154, v150
	v_add_f32_e32 v150, 1.0, v151
	v_add_f32_e32 v145, 1.0, v145
	v_rcp_f32_e32 v147, v147
	v_add_f32_e32 v148, 1.0, v148
	v_rcp_f32_e32 v149, v149
	v_rcp_f32_e32 v150, v150
	v_add_f32_e32 v151, 1.0, v153
	v_rcp_f32_e32 v145, v145
	v_rcp_f32_e32 v148, v148
	v_rcp_f32_e32 v151, v151
	s_mov_b32 s8, 0x40000
; __device__ __forceinline__ void st8(bf16_t* p, f32x4 a, f32x4 b) { u32x4 w = {cvt_pk(a[0], a[1]), cvt_pk(a[2], a[3]), cvt_pk(b[0], b[1]), cvt_pk(b[2], b[3])}; *(u32x4*)p = w; }
; __device__ __forceinline__ float sigm(float x) { return __builtin_amdgcn_rcpf(1.f + __builtin_amdgcn_exp2f(x * -1.4426950408889634f)); }
; __device__ __forceinline__ void st8_s(bf16_t* p, f32x4 a, f32x4 b) { u32x4 w = {cvt_pk_s(a[0], a[1]), cvt_pk_s(a[2], a[3]), cvt_pk_s(b[0], b[1]), cvt_pk_s(b[2], b[3])}; *(u32x4*)p = w; }
; #define FOR_AI_M _Pragma("unroll") for (int ai = 0; ai < 2; ++ai) if ((__builtin_amdgcn_sched_barrier(0), true)) _Pragma("unroll") for (int m = 0; m < 4; ++m)
;   template <int ACT> __device__ __forceinline__ void plain_store(const f32x4 (&acc)[2][2][4][2], bf16_t* dst, int cbase, int rbase) const {
;     FOR_AI_M { const int row = rbase + ai * 128 + m * 16;
; #pragma unroll
;       for (int bj = 0; bj < 2; ++bj) { f32x4 v0 = acc[ai][bj][m][0], v1 = acc[ai][bj][m][1];
;         if (ACT == 1) {
; #pragma unroll
;           for (int e = 0; e < 4; ++e) { v0[e] = v0[e] * sigm(v0[e]); v1[e] = v1[e] * sigm(v1[e]); } }
;         if (ACT == 2) {
; #pragma unroll
;           for (int e = 0; e < 4; ++e) { v0[e] = sigm(v0[e]); v1[e] = sigm(v1[e]); } }
;         if (ACT == 0) st8(dst + (size_t)row * 1024 + cbase + bj * 128, v0, v1); else st8_s(dst + (size_t)row * 1024 + cbase + bj * 128, v0, v1); } }
;   }
	v_cvt_pk_bf16_f32 v149, v149, v150
	v_cvt_pk_bf16_f32 v150, v147, v152
	v_add_co_u32_e32 v152, vcc, s8, v128
	v_cvt_pk_bf16_f32 v148, v145, v148
	v_cvt_pk_bf16_f32 v151, v154, v151
	v_addc_co_u32_e32 v153, vcc, 0, v129, vcc
	global_store_dwordx4 v[152:153], v[148:151], off
	v_mul_f32_e32 v145, 0xbfb8aa3b, v52
	v_mul_f32_e32 v147, 0xbfb8aa3b, v48
	v_mul_f32_e32 v149, 0xbfb8aa3b, v49
	v_exp_f32_e32 v149, v149
	v_mul_f32_e32 v150, 0xbfb8aa3b, v54
	v_mul_f32_e32 v151, 0xbfb8aa3b, v50
	v_exp_f32_e32 v150, v150
	v_exp_f32_e32 v151, v151
	v_add_f32_e32 v149, 1.0, v149
	v_mul_f32_e32 v148, 0xbfb8aa3b, v53
	v_rcp_f32_e32 v152, v149
	v_add_f32_e32 v149, 1.0, v150
	v_add_f32_e32 v150, 1.0, v151
	v_mul_f32_e32 v151, 0xbfb8aa3b, v55
	v_mul_f32_e32 v153, 0xbfb8aa3b, v51
	v_exp_f32_e32 v145, v145
	v_exp_f32_e32 v147, v147
	v_exp_f32_e32 v148, v148
	v_exp_f32_e32 v151, v151
	v_exp_f32_e32 v153, v153
	v_add_f32_e32 v145, 1.0, v145
	v_add_f32_e32 v147, 1.0, v147
	v_add_f32_e32 v148, 1.0, v148
	v_rcp_f32_e32 v154, v150
	v_add_f32_e32 v150, 1.0, v151
	v_add_f32_e32 v151, 1.0, v153
	v_rcp_f32_e32 v145, v145
	v_rcp_f32_e32 v147, v147
	v_rcp_f32_e32 v148, v148
	v_rcp_f32_e32 v149, v149
	v_rcp_f32_e32 v150, v150
	v_rcp_f32_e32 v151, v151
	v_lshl_add_u64 v[130:131], v[128:129], 0, s[72:73]
	v_cvt_pk_bf16_f32 v148, v145, v148
	v_cvt_pk_bf16_f32 v149, v149, v150
	v_cvt_pk_bf16_f32 v150, v147, v152
	v_cvt_pk_bf16_f32 v151, v154, v151
	global_store_dwordx4 v[130:131], v[148:151], off offset:256
	v_mul_f32_e32 v130, 0xbfb8aa3b, v44
	v_exp_f32_e32 v145, v130
	v_mul_f32_e32 v149, 0xbfb8aa3b, v41
	v_exp_f32_e32 v149, v149
	v_mul_f32_e32 v150, 0xbfb8aa3b, v46
	v_mul_f32_e32 v151, 0xbfb8aa3b, v42
	v_exp_f32_e32 v150, v150
	v_exp_f32_e32 v151, v151
	v_add_f32_e32 v149, 1.0, v149
	v_mul_f32_e32 v130, 0xbfb8aa3b, v40
	v_rcp_f32_e32 v152, v149
	v_add_f32_e32 v149, 1.0, v150
	v_add_f32_e32 v150, 1.0, v151
	v_mul_f32_e32 v151, 0xbfb8aa3b, v47
	v_exp_f32_e32 v147, v130
	v_mul_f32_e32 v148, 0xbfb8aa3b, v45
	v_exp_f32_e32 v151, v151
	v_mul_f32_e32 v153, 0xbfb8aa3b, v43
	v_exp_f32_e32 v148, v148
	v_exp_f32_e32 v153, v153
	v_add_f32_e32 v147, 1.0, v147
	v_rcp_f32_e32 v154, v150
	v_add_f32_e32 v150, 1.0, v151
	v_add_f32_e32 v145, 1.0, v145
	v_rcp_f32_e32 v147, v147
	v_add_f32_e32 v148, 1.0, v148
	v_rcp_f32_e32 v149, v149
	v_rcp_f32_e32 v150, v150
	v_add_f32_e32 v151, 1.0, v153
	v_rcp_f32_e32 v145, v145
	v_rcp_f32_e32 v148, v148
	v_rcp_f32_e32 v151, v151
	s_mov_b32 s8, 0x48000
	v_cvt_pk_bf16_f32 v149, v149, v150
	v_cvt_pk_bf16_f32 v150, v147, v152
	v_add_co_u32_e32 v152, vcc, s8, v128
	v_cvt_pk_bf16_f32 v148, v145, v148
	v_cvt_pk_bf16_f32 v151, v154, v151
	v_addc_co_u32_e32 v153, vcc, 0, v129, vcc
	global_store_dwordx4 v[152:153], v[148:151], off
	v_mul_f32_e32 v145, 0xbfb8aa3b, v36
	v_mul_f32_e32 v147, 0xbfb8aa3b, v32
	v_mul_f32_e32 v149, 0xbfb8aa3b, v33
	v_exp_f32_e32 v149, v149
	v_mul_f32_e32 v150, 0xbfb8aa3b, v38
	v_mul_f32_e32 v151, 0xbfb8aa3b, v34
	v_exp_f32_e32 v150, v150
	v_exp_f32_e32 v151, v151
	v_add_f32_e32 v149, 1.0, v149
	v_mul_f32_e32 v148, 0xbfb8aa3b, v37
	v_rcp_f32_e32 v152, v149
	v_add_f32_e32 v149, 1.0, v150
	v_add_f32_e32 v150, 1.0, v151
	v_mul_f32_e32 v151, 0xbfb8aa3b, v39
	v_mul_f32_e32 v153, 0xbfb8aa3b, v35
	v_exp_f32_e32 v145, v145
	v_exp_f32_e32 v147, v147
	v_exp_f32_e32 v148, v148
	v_exp_f32_e32 v151, v151
	v_exp_f32_e32 v153, v153
	v_add_f32_e32 v145, 1.0, v145
	v_add_f32_e32 v147, 1.0, v147
	v_add_f32_e32 v148, 1.0, v148
	v_rcp_f32_e32 v154, v150
	v_add_f32_e32 v150, 1.0, v151
	v_add_f32_e32 v151, 1.0, v153
	v_rcp_f32_e32 v145, v145
	v_rcp_f32_e32 v147, v147
	v_rcp_f32_e32 v148, v148
	v_rcp_f32_e32 v149, v149
	v_rcp_f32_e32 v150, v150
	v_rcp_f32_e32 v151, v151
	s_mov_b64 s[10:11], 0x48000
	v_lshl_add_u64 v[130:131], v[128:129], 0, s[10:11]
	v_cvt_pk_bf16_f32 v148, v145, v148
	v_cvt_pk_bf16_f32 v149, v149, v150
	v_cvt_pk_bf16_f32 v150, v147, v152
	v_cvt_pk_bf16_f32 v151, v154, v151
	global_store_dwordx4 v[130:131], v[148:151], off offset:256
	v_mul_f32_e32 v130, 0xbfb8aa3b, v28
	v_exp_f32_e32 v145, v130
	v_mul_f32_e32 v149, 0xbfb8aa3b, v25
	v_exp_f32_e32 v149, v149
	v_mul_f32_e32 v150, 0xbfb8aa3b, v30
	v_mul_f32_e32 v151, 0xbfb8aa3b, v26
	v_exp_f32_e32 v150, v150
	v_exp_f32_e32 v151, v151
	v_add_f32_e32 v149, 1.0, v149
	v_mul_f32_e32 v130, 0xbfb8aa3b, v24
	v_rcp_f32_e32 v152, v149
	v_add_f32_e32 v149, 1.0, v150
	v_add_f32_e32 v150, 1.0, v151
	v_mul_f32_e32 v151, 0xbfb8aa3b, v31
	v_exp_f32_e32 v147, v130
	v_mul_f32_e32 v148, 0xbfb8aa3b, v29
; __device__ __forceinline__ void st8(bf16_t* p, f32x4 a, f32x4 b) { u32x4 w = {cvt_pk(a[0], a[1]), cvt_pk(a[2], a[3]), cvt_pk(b[0], b[1]), cvt_pk(b[2], b[3])}; *(u32x4*)p = w; }
; __device__ __forceinline__ float sigm(float x) { return __builtin_amdgcn_rcpf(1.f + __builtin_amdgcn_exp2f(x * -1.4426950408889634f)); }
; __device__ __forceinline__ void st8_s(bf16_t* p, f32x4 a, f32x4 b) { u32x4 w = {cvt_pk_s(a[0], a[1]), cvt_pk_s(a[2], a[3]), cvt_pk_s(b[0], b[1]), cvt_pk_s(b[2], b[3])}; *(u32x4*)p = w; }
; #define FOR_AI_M _Pragma("unroll") for (int ai = 0; ai < 2; ++ai) if ((__builtin_amdgcn_sched_barrier(0), true)) _Pragma("unroll") for (int m = 0; m < 4; ++m)
;   template <int ACT> __device__ __forceinline__ void plain_store(const f32x4 (&acc)[2][2][4][2], bf16_t* dst, int cbase, int rbase) const {
;     FOR_AI_M { const int row = rbase + ai * 128 + m * 16;
; #pragma unroll
;       for (int bj = 0; bj < 2; ++bj) { f32x4 v0 = acc[ai][bj][m][0], v1 = acc[ai][bj][m][1];
;         if (ACT == 1) {
; #pragma unroll
;           for (int e = 0; e < 4; ++e) { v0[e] = v0[e] * sigm(v0[e]); v1[e] = v1[e] * sigm(v1[e]); } }
;         if (ACT == 2) {
; #pragma unroll
;           for (int e = 0; e < 4; ++e) { v0[e] = sigm(v0[e]); v1[e] = sigm(v1[e]); } }
;         if (ACT == 0) st8(dst + (size_t)row * 1024 + cbase + bj * 128, v0, v1); else st8_s(dst + (size_t)row * 1024 + cbase + bj * 128, v0, v1); } }
;   }
	v_exp_f32_e32 v151, v151
	v_mul_f32_e32 v153, 0xbfb8aa3b, v27
	v_exp_f32_e32 v148, v148
	v_exp_f32_e32 v153, v153
	v_add_f32_e32 v147, 1.0, v147
	v_rcp_f32_e32 v154, v150
	v_add_f32_e32 v150, 1.0, v151
	v_add_f32_e32 v145, 1.0, v145
	v_rcp_f32_e32 v147, v147
	v_add_f32_e32 v148, 1.0, v148
	v_rcp_f32_e32 v149, v149
	v_rcp_f32_e32 v150, v150
	v_add_f32_e32 v151, 1.0, v153
	v_rcp_f32_e32 v145, v145
	v_rcp_f32_e32 v148, v148
	v_rcp_f32_e32 v151, v151
	s_mov_b32 s8, 0x50000
	v_cvt_pk_bf16_f32 v149, v149, v150
	v_cvt_pk_bf16_f32 v150, v147, v152
	v_add_co_u32_e32 v152, vcc, s8, v128
	v_cvt_pk_bf16_f32 v148, v145, v148
	v_cvt_pk_bf16_f32 v151, v154, v151
	v_addc_co_u32_e32 v153, vcc, 0, v129, vcc
	global_store_dwordx4 v[152:153], v[148:151], off
	v_mul_f32_e32 v145, 0xbfb8aa3b, v20
	v_mul_f32_e32 v147, 0xbfb8aa3b, v16
	v_mul_f32_e32 v149, 0xbfb8aa3b, v17
	v_exp_f32_e32 v149, v149
	v_mul_f32_e32 v150, 0xbfb8aa3b, v22
	v_mul_f32_e32 v151, 0xbfb8aa3b, v18
	v_exp_f32_e32 v150, v150
	v_exp_f32_e32 v151, v151
	v_add_f32_e32 v149, 1.0, v149
	v_mul_f32_e32 v148, 0xbfb8aa3b, v21
	v_rcp_f32_e32 v152, v149
	v_add_f32_e32 v149, 1.0, v150
	v_add_f32_e32 v150, 1.0, v151
	v_mul_f32_e32 v151, 0xbfb8aa3b, v23
	v_mul_f32_e32 v153, 0xbfb8aa3b, v19
	v_exp_f32_e32 v145, v145
	v_exp_f32_e32 v147, v147
	v_exp_f32_e32 v148, v148
	v_exp_f32_e32 v151, v151
	v_exp_f32_e32 v153, v153
	v_add_f32_e32 v145, 1.0, v145
	v_add_f32_e32 v147, 1.0, v147
	v_add_f32_e32 v148, 1.0, v148
	v_rcp_f32_e32 v154, v150
	v_add_f32_e32 v150, 1.0, v151
	v_add_f32_e32 v151, 1.0, v153
	v_rcp_f32_e32 v145, v145
	v_rcp_f32_e32 v147, v147
	v_rcp_f32_e32 v148, v148
	v_rcp_f32_e32 v149, v149
	v_rcp_f32_e32 v150, v150
	v_rcp_f32_e32 v151, v151
	s_mov_b64 s[10:11], 0x50000
	v_lshl_add_u64 v[130:131], v[128:129], 0, s[10:11]
	v_cvt_pk_bf16_f32 v148, v145, v148
	v_cvt_pk_bf16_f32 v149, v149, v150
	v_cvt_pk_bf16_f32 v150, v147, v152
	v_cvt_pk_bf16_f32 v151, v154, v151
	global_store_dwordx4 v[130:131], v[148:151], off offset:256
	v_mul_f32_e32 v130, 0xbfb8aa3b, v12
	v_mul_f32_e32 v131, 0xbfb8aa3b, v8
	v_mul_f32_e32 v148, 0xbfb8aa3b, v14
	v_exp_f32_e32 v148, v148
	v_mul_f32_e32 v149, 0xbfb8aa3b, v10
	v_exp_f32_e32 v149, v149
	v_mul_f32_e32 v145, 0xbfb8aa3b, v13
	v_add_f32_e32 v148, 1.0, v148
	v_mul_f32_e32 v147, 0xbfb8aa3b, v9
	v_rcp_f32_e32 v150, v148
	v_add_f32_e32 v148, 1.0, v149
	v_mul_f32_e32 v149, 0xbfb8aa3b, v15
	v_exp_f32_e32 v130, v130
	v_exp_f32_e32 v131, v131
	v_exp_f32_e32 v145, v145
	v_exp_f32_e32 v147, v147
	v_exp_f32_e32 v149, v149
	v_mul_f32_e32 v151, 0xbfb8aa3b, v11
	v_add_f32_e32 v130, 1.0, v130
	v_add_f32_e32 v131, 1.0, v131
	v_add_f32_e32 v145, 1.0, v145
	v_add_f32_e32 v147, 1.0, v147
	v_exp_f32_e32 v151, v151
	v_rcp_f32_e32 v154, v148
	v_add_f32_e32 v148, 1.0, v149
	v_rcp_f32_e32 v130, v130
	v_rcp_f32_e32 v131, v131
	v_rcp_f32_e32 v145, v145
	v_rcp_f32_e32 v147, v147
	v_rcp_f32_e32 v149, v148
	v_add_f32_e32 v148, 1.0, v151
	v_rcp_f32_e32 v151, v148
	v_cvt_pk_bf16_f32 v148, v130, v145
	v_cvt_pk_bf16_f32 v149, v150, v149
	v_cvt_pk_bf16_f32 v150, v131, v147
	v_mul_f32_e32 v130, 0xbfb8aa3b, v4
	v_mul_f32_e32 v131, 0xbfb8aa3b, v0
	v_exp_f32_e32 v130, v130
	v_exp_f32_e32 v131, v131
	s_mov_b64 s[10:11], 0x58000
	s_mov_b32 s8, 0x58000
	v_lshl_add_u64 v[152:153], v[128:129], 0, s[10:11]
	v_add_co_u32_e32 v128, vcc, s8, v128
	v_cvt_pk_bf16_f32 v151, v154, v151
	s_nop 0
	v_addc_co_u32_e32 v129, vcc, 0, v129, vcc
	global_store_dwordx4 v[128:129], v[148:151], off
	v_add_f32_e32 v128, 1.0, v130
	v_add_f32_e32 v129, 1.0, v131
	v_mul_f32_e32 v130, 0xbfb8aa3b, v5
	v_mul_f32_e32 v131, 0xbfb8aa3b, v1
	v_exp_f32_e32 v130, v130
	v_exp_f32_e32 v131, v131
	v_rcp_f32_e32 v145, v129
	v_mul_f32_e32 v147, 0xbfb8aa3b, v2
	v_add_f32_e32 v129, 1.0, v130
	v_add_f32_e32 v130, 1.0, v131
	v_mul_f32_e32 v131, 0xbfb8aa3b, v6
	v_mul_f32_e32 v148, 0xbfb8aa3b, v7
	v_mul_f32_e32 v149, 0xbfb8aa3b, v3
	v_exp_f32_e32 v131, v131
	v_exp_f32_e32 v147, v147
	v_exp_f32_e32 v148, v148
	v_exp_f32_e32 v149, v149
	v_add_f32_e32 v131, 1.0, v131
	v_add_f32_e32 v147, 1.0, v147
	v_add_f32_e32 v148, 1.0, v148
	v_add_f32_e32 v149, 1.0, v149
	v_rcp_f32_e32 v128, v128
	v_rcp_f32_e32 v129, v129
	v_rcp_f32_e32 v130, v130
	v_rcp_f32_e32 v131, v131
	v_rcp_f32_e32 v147, v147
	v_rcp_f32_e32 v148, v148
	v_rcp_f32_e32 v149, v149
	v_cvt_pk_bf16_f32 v128, v128, v129
	v_cvt_pk_bf16_f32 v130, v145, v130
	v_cvt_pk_bf16_f32 v129, v131, v148
	v_cvt_pk_bf16_f32 v131, v147, v149
	global_store_dwordx4 v[152:153], v[128:131], off offset:256

; __device__ __forceinline__ void st8(bf16_t* p, f32x4 a, f32x4 b) { u32x4 w = {cvt_pk(a[0], a[1]), cvt_pk(a[2], a[3]), cvt_pk(b[0], b[1]), cvt_pk(b[2], b[3])}; *(u32x4*)p = w; }
; __device__ __forceinline__ float sigm(float x) { return __builtin_amdgcn_rcpf(1.f + __builtin_amdgcn_exp2f(x * -1.4426950408889634f)); }
; __device__ __forceinline__ void st8_s(bf16_t* p, f32x4 a, f32x4 b) { u32x4 w = {cvt_pk_s(a[0], a[1]), cvt_pk_s(a[2], a[3]), cvt_pk_s(b[0], b[1]), cvt_pk_s(b[2], b[3])}; *(u32x4*)p = w; }
; #define FOR_AI_M _Pragma("unroll") for (int ai = 0; ai < 2; ++ai) if ((__builtin_amdgcn_sched_barrier(0), true)) _Pragma("unroll") for (int m = 0; m < 4; ++m)
;   template <int ACT> __device__ __forceinline__ void plain_store(const f32x4 (&acc)[2][2][4][2], bf16_t* dst, int cbase, int rbase) const {
;     FOR_AI_M { const int row = rbase + ai * 128 + m * 16;
; #pragma unroll
;       for (int bj = 0; bj < 2; ++bj) { f32x4 v0 = acc[ai][bj][m][0], v1 = acc[ai][bj][m][1];
;         if (ACT == 1) {
; #pragma unroll
;           for (int e = 0; e < 4; ++e) { v0[e] = v0[e] * sigm(v0[e]); v1[e] = v1[e] * sigm(v1[e]); } }
;         if (ACT == 2) {
; #pragma unroll
;           for (int e = 0; e < 4; ++e) { v0[e] = sigm(v0[e]); v1[e] = sigm(v1[e]); } }
;         if (ACT == 0) st8(dst + (size_t)row * 1024 + cbase + bj * 128, v0, v1); else st8_s(dst + (size_t)row * 1024 + cbase + bj * 128, v0, v1); } }
;   }
;   __device__ __forceinline__ void operator()(EPI_ARGS) const {
;     ...
;     else if (pn < 12) plain_store<1>(acc, b.RG, (pn - 8) * 256 + c0, rbase);
.LBB0_411:
	s_andn2_b64 vcc, exec, s[42:43]
	s_cbranch_vccnz .LBB0_413
	s_lshl_b32 s8, s47, 8
	s_addk_i32 s8, 0xf800
	v_add_u32_e32 v128, s8, v146
	v_readlane_b32 s10, v255, 30
	s_waitcnt lgkmcnt(0)
	v_ashrrev_i32_e32 v129, 31, v128
	v_readlane_b32 s11, v255, 31
	s_nop 1
	v_lshl_add_u64 v[128:129], v[128:129], 1, s[10:11]
	v_ashrrev_i32_e32 v145, 31, v144
	v_lshlrev_b64 v[130:131], 11, v[144:145]
	v_mul_f32_e32 v145, 0xbfb8aa3b, v124
	v_mul_f32_e32 v147, 0xbfb8aa3b, v120
	v_exp_f32_e32 v145, v145
	v_exp_f32_e32 v147, v147
	v_lshl_add_u64 v[128:129], v[128:129], 0, v[130:131]
	v_mul_f32_e32 v149, 0xbfb8aa3b, v122
	v_add_f32_e32 v130, 1.0, v145
	v_add_f32_e32 v131, 1.0, v147
	v_mul_f32_e32 v145, 0xbfb8aa3b, v125
	v_mul_f32_e32 v147, 0xbfb8aa3b, v121
	v_exp_f32_e32 v145, v145
	v_exp_f32_e32 v147, v147
	v_rcp_f32_e32 v148, v131
	v_exp_f32_e32 v151, v149
	v_add_f32_e32 v131, 1.0, v145
	v_add_f32_e32 v145, 1.0, v147
	v_mul_f32_e32 v147, 0xbfb8aa3b, v126
	v_exp_f32_e32 v147, v147
	v_rcp_f32_e32 v149, v145
	v_rcp_f32_e32 v130, v130
	v_rcp_f32_e32 v131, v131
	v_add_f32_e32 v145, 1.0, v147
	v_mul_f32_e32 v147, 0xbfb8aa3b, v127
	v_rcp_f32_e32 v150, v145
	v_add_f32_e32 v145, 1.0, v151
	v_exp_f32_e32 v147, v147
	v_mul_f32_e32 v151, 0xbfb8aa3b, v123
	v_exp_f32_e32 v153, v151
	v_rcp_f32_e32 v152, v145
	v_add_f32_e32 v145, 1.0, v147
	v_rcp_f32_e32 v151, v145
	v_add_f32_e32 v145, 1.0, v153
	v_pk_mul_f32 v[130:131], v[124:125], v[130:131]
	v_rcp_f32_e32 v153, v145
	v_pk_mul_f32 v[154:155], v[120:121], v[148:149]
	v_cvt_pk_bf16_f32 v148, v130, v131
	v_mul_f32_e32 v131, 0xbfb8aa3b, v112
	v_exp_f32_e32 v131, v131
	v_mul_f32_e32 v145, 0xbfb8aa3b, v117
	v_mul_f32_e32 v147, 0xbfb8aa3b, v113
	v_exp_f32_e32 v145, v145
	v_exp_f32_e32 v147, v147
	v_pk_mul_f32 v[150:151], v[126:127], v[150:151]
	v_pk_mul_f32 v[152:153], v[122:123], v[152:153]
	v_cvt_pk_bf16_f32 v149, v150, v151
	v_cvt_pk_bf16_f32 v150, v154, v155
	v_cvt_pk_bf16_f32 v151, v152, v153
	v_add_f32_e32 v131, 1.0, v131
	global_store_dwordx4 v[128:129], v[148:151], off
	v_mul_f32_e32 v130, 0xbfb8aa3b, v116
	v_exp_f32_e32 v130, v130
	v_rcp_f32_e32 v148, v131
	v_add_f32_e32 v131, 1.0, v145
	v_add_f32_e32 v145, 1.0, v147
	v_mul_f32_e32 v147, 0xbfb8aa3b, v118
	v_exp_f32_e32 v147, v147
	v_mul_f32_e32 v149, 0xbfb8aa3b, v114
	v_exp_f32_e32 v151, v149
	v_rcp_f32_e32 v149, v145
	v_add_f32_e32 v145, 1.0, v147
	v_mul_f32_e32 v147, 0xbfb8aa3b, v119
	v_add_f32_e32 v130, 1.0, v130
	v_rcp_f32_e32 v150, v145
	v_add_f32_e32 v145, 1.0, v151
	v_exp_f32_e32 v147, v147
	v_mul_f32_e32 v151, 0xbfb8aa3b, v115
	v_rcp_f32_e32 v130, v130
	v_rcp_f32_e32 v131, v131
	v_exp_f32_e32 v153, v151
	v_rcp_f32_e32 v152, v145
	v_add_f32_e32 v145, 1.0, v147
	v_rcp_f32_e32 v151, v145
	v_add_f32_e32 v145, 1.0, v153
	v_pk_mul_f32 v[130:131], v[116:117], v[130:131]
	v_rcp_f32_e32 v153, v145
	v_pk_mul_f32 v[154:155], v[112:113], v[148:149]
	v_cvt_pk_bf16_f32 v148, v130, v131
	v_mul_f32_e32 v130, 0xbfb8aa3b, v108
	v_exp_f32_e32 v145, v130
	v_mul_f32_e32 v130, 0xbfb8aa3b, v104
	v_exp_f32_e32 v147, v130
	v_pk_mul_f32 v[150:151], v[118:119], v[150:151]
	v_pk_mul_f32 v[152:153], v[114:115], v[152:153]
	v_cvt_pk_bf16_f32 v149, v150, v151
	v_cvt_pk_bf16_f32 v150, v154, v155
	v_cvt_pk_bf16_f32 v151, v152, v153
	v_add_f32_e32 v145, 1.0, v145
	global_store_dwordx4 v[128:129], v[148:151], off offset:256
	s_mov_b64 s[10:11], 0x8000
	v_lshl_add_u64 v[130:131], v[128:129], 0, s[10:11]
	v_rcp_f32_e32 v148, v145
	v_add_f32_e32 v145, 1.0, v147
	v_mul_f32_e32 v147, 0xbfb8aa3b, v109
	v_exp_f32_e32 v147, v147
	v_mul_f32_e32 v149, 0xbfb8aa3b, v105
	v_exp_f32_e32 v151, v149
	v_rcp_f32_e32 v150, v145
	v_add_f32_e32 v145, 1.0, v147
	v_mul_f32_e32 v147, 0xbfb8aa3b, v110
	v_rcp_f32_e32 v149, v145
	v_add_f32_e32 v145, 1.0, v151
	v_exp_f32_e32 v147, v147
	v_mul_f32_e32 v151, 0xbfb8aa3b, v106
	v_exp_f32_e32 v153, v151
	v_rcp_f32_e32 v151, v145
	v_add_f32_e32 v145, 1.0, v147
	v_mul_f32_e32 v147, 0xbfb8aa3b, v111
	v_rcp_f32_e32 v152, v145
	v_add_f32_e32 v145, 1.0, v153
	v_exp_f32_e32 v147, v147
	v_mul_f32_e32 v153, 0xbfb8aa3b, v107
	v_exp_f32_e32 v155, v153
	v_rcp_f32_e32 v154, v145
	v_add_f32_e32 v145, 1.0, v147
	v_rcp_f32_e32 v153, v145
	v_add_f32_e32 v145, 1.0, v155
	v_rcp_f32_e32 v155, v145
	v_mul_f32_e32 v145, 0xbfb8aa3b, v100
	v_exp_f32_e32 v145, v145
	v_mul_f32_e32 v147, 0xbfb8aa3b, v96
	v_exp_f32_e32 v147, v147
	v_pk_mul_f32 v[148:149], v[108:109], v[148:149]
	v_pk_mul_f32 v[152:153], v[110:111], v[152:153]
	v_pk_mul_f32 v[150:151], v[104:105], v[150:151]
	v_pk_mul_f32 v[154:155], v[106:107], v[154:155]
	v_cvt_pk_bf16_f32 v148, v148, v149
	v_cvt_pk_bf16_f32 v149, v152, v153
	v_add_co_u32_e32 v152, vcc, s88, v128
	v_cvt_pk_bf16_f32 v150, v150, v151
	v_cvt_pk_bf16_f32 v151, v154, v155
	v_addc_co_u32_e32 v153, vcc, 0, v129, vcc
	v_add_f32_e32 v145, 1.0, v145
	global_store_dwordx4 v[152:153], v[148:151], off
	s_mov_b64 s[10:11], 0x10000
	s_mov_b32 s8, 0x18000
	v_rcp_f32_e32 v148, v145
	v_add_f32_e32 v145, 1.0, v147
	v_mul_f32_e32 v147, 0xbfb8aa3b, v101
	v_exp_f32_e32 v147, v147
	v_mul_f32_e32 v149, 0xbfb8aa3b, v97
	v_exp_f32_e32 v151, v149
	v_rcp_f32_e32 v150, v145
	v_add_f32_e32 v145, 1.0, v147
	v_mul_f32_e32 v147, 0xbfb8aa3b, v102
	v_rcp_f32_e32 v149, v145
	v_add_f32_e32 v145, 1.0, v151
	v_exp_f32_e32 v147, v147
	v_mul_f32_e32 v151, 0xbfb8aa3b, v98
	v_exp_f32_e32 v153, v151
	v_rcp_f32_e32 v151, v145
	v_add_f32_e32 v145, 1.0, v147
	v_mul_f32_e32 v147, 0xbfb8aa3b, v103
	v_rcp_f32_e32 v152, v145
	v_add_f32_e32 v145, 1.0, v153
	v_exp_f32_e32 v147, v147
	v_mul_f32_e32 v153, 0xbfb8aa3b, v99
	v_exp_f32_e32 v155, v153
	v_rcp_f32_e32 v154, v145
	v_add_f32_e32 v145, 1.0, v147
; __device__ __forceinline__ void st8(bf16_t* p, f32x4 a, f32x4 b) { u32x4 w = {cvt_pk(a[0], a[1]), cvt_pk(a[2], a[3]), cvt_pk(b[0], b[1]), cvt_pk(b[2], b[3])}; *(u32x4*)p = w; }
; __device__ __forceinline__ float sigm(float x) { return __builtin_amdgcn_rcpf(1.f + __builtin_amdgcn_exp2f(x * -1.4426950408889634f)); }
; __device__ __forceinline__ void st8_s(bf16_t* p, f32x4 a, f32x4 b) { u32x4 w = {cvt_pk_s(a[0], a[1]), cvt_pk_s(a[2], a[3]), cvt_pk_s(b[0], b[1]), cvt_pk_s(b[2], b[3])}; *(u32x4*)p = w; }
; #define FOR_AI_M _Pragma("unroll") for (int ai = 0; ai < 2; ++ai) if ((__builtin_amdgcn_sched_barrier(0), true)) _Pragma("unroll") for (int m = 0; m < 4; ++m)
;   template <int ACT> __device__ __forceinline__ void plain_store(const f32x4 (&acc)[2][2][4][2], bf16_t* dst, int cbase, int rbase) const {
;     FOR_AI_M { const int row = rbase + ai * 128 + m * 16;
; #pragma unroll
;       for (int bj = 0; bj < 2; ++bj) { f32x4 v0 = acc[ai][bj][m][0], v1 = acc[ai][bj][m][1];
;         if (ACT == 1) {
; #pragma unroll
;           for (int e = 0; e < 4; ++e) { v0[e] = v0[e] * sigm(v0[e]); v1[e] = v1[e] * sigm(v1[e]); } }
;         if (ACT == 2) {
; #pragma unroll
;           for (int e = 0; e < 4; ++e) { v0[e] = sigm(v0[e]); v1[e] = sigm(v1[e]); } }
;         if (ACT == 0) st8(dst + (size_t)row * 1024 + cbase + bj * 128, v0, v1); else st8_s(dst + (size_t)row * 1024 + cbase + bj * 128, v0, v1); } }
;   }
	v_rcp_f32_e32 v153, v145
	v_add_f32_e32 v145, 1.0, v155
	v_rcp_f32_e32 v155, v145
	v_pk_mul_f32 v[148:149], v[100:101], v[148:149]
	v_pk_mul_f32 v[150:151], v[96:97], v[150:151]
	v_pk_mul_f32 v[152:153], v[102:103], v[152:153]
	v_pk_mul_f32 v[154:155], v[98:99], v[154:155]
	v_cvt_pk_bf16_f32 v148, v148, v149
	v_cvt_pk_bf16_f32 v149, v152, v153
	v_cvt_pk_bf16_f32 v150, v150, v151
	v_cvt_pk_bf16_f32 v151, v154, v155
	global_store_dwordx4 v[130:131], v[148:151], off offset:256
	v_mul_f32_e32 v130, 0xbfb8aa3b, v92
	v_exp_f32_e32 v145, v130
	v_mul_f32_e32 v130, 0xbfb8aa3b, v88
	v_exp_f32_e32 v147, v130
	v_mul_f32_e32 v149, 0xbfb8aa3b, v89
	v_add_f32_e32 v145, 1.0, v145
	v_rcp_f32_e32 v148, v145
	v_add_f32_e32 v145, 1.0, v147
	v_mul_f32_e32 v147, 0xbfb8aa3b, v93
	v_exp_f32_e32 v147, v147
	v_exp_f32_e32 v151, v149
	v_rcp_f32_e32 v150, v145
	v_lshl_add_u64 v[130:131], v[128:129], 0, s[10:11]
	v_add_f32_e32 v145, 1.0, v147
	v_mul_f32_e32 v147, 0xbfb8aa3b, v94
	v_rcp_f32_e32 v149, v145
	v_add_f32_e32 v145, 1.0, v151
	v_exp_f32_e32 v147, v147
	v_mul_f32_e32 v151, 0xbfb8aa3b, v90
	v_exp_f32_e32 v153, v151
	v_rcp_f32_e32 v151, v145
	v_add_f32_e32 v145, 1.0, v147
	v_mul_f32_e32 v147, 0xbfb8aa3b, v95
	v_rcp_f32_e32 v152, v145
	v_add_f32_e32 v145, 1.0, v153
	v_exp_f32_e32 v147, v147
	v_mul_f32_e32 v153, 0xbfb8aa3b, v91
	v_exp_f32_e32 v155, v153
	v_rcp_f32_e32 v154, v145
	v_add_f32_e32 v145, 1.0, v147
	v_rcp_f32_e32 v153, v145
	v_add_f32_e32 v145, 1.0, v155
	v_rcp_f32_e32 v155, v145
	v_mul_f32_e32 v145, 0xbfb8aa3b, v84
	v_exp_f32_e32 v145, v145
	v_mul_f32_e32 v147, 0xbfb8aa3b, v80
	v_exp_f32_e32 v147, v147
	v_pk_mul_f32 v[148:149], v[92:93], v[148:149]
	v_pk_mul_f32 v[152:153], v[94:95], v[152:153]
	v_pk_mul_f32 v[150:151], v[88:89], v[150:151]
	v_pk_mul_f32 v[154:155], v[90:91], v[154:155]
	v_cvt_pk_bf16_f32 v148, v148, v149
	v_cvt_pk_bf16_f32 v149, v152, v153
	v_add_co_u32_e32 v152, vcc, s95, v128
	v_cvt_pk_bf16_f32 v150, v150, v151
	v_cvt_pk_bf16_f32 v151, v154, v155
	v_addc_co_u32_e32 v153, vcc, 0, v129, vcc
	v_add_f32_e32 v145, 1.0, v145
	global_store_dwordx4 v[152:153], v[148:151], off
	s_mov_b64 s[10:11], 0x18000
	s_nop 0
	v_rcp_f32_e32 v148, v145
	v_add_f32_e32 v145, 1.0, v147
	v_mul_f32_e32 v147, 0xbfb8aa3b, v85
	v_exp_f32_e32 v147, v147
	v_mul_f32_e32 v149, 0xbfb8aa3b, v81
	v_exp_f32_e32 v151, v149
	v_rcp_f32_e32 v150, v145
	v_add_f32_e32 v145, 1.0, v147
	v_mul_f32_e32 v147, 0xbfb8aa3b, v86
	v_rcp_f32_e32 v149, v145
	v_add_f32_e32 v145, 1.0, v151
	v_exp_f32_e32 v147, v147
	v_mul_f32_e32 v151, 0xbfb8aa3b, v82
	v_exp_f32_e32 v153, v151
	v_rcp_f32_e32 v151, v145
	v_add_f32_e32 v145, 1.0, v147
	v_mul_f32_e32 v147, 0xbfb8aa3b, v87
	v_rcp_f32_e32 v152, v145
	v_add_f32_e32 v145, 1.0, v153
	v_exp_f32_e32 v147, v147
	v_mul_f32_e32 v153, 0xbfb8aa3b, v83
	v_exp_f32_e32 v155, v153
	v_rcp_f32_e32 v154, v145
	v_add_f32_e32 v145, 1.0, v147
	v_rcp_f32_e32 v153, v145
	v_add_f32_e32 v145, 1.0, v155
	v_rcp_f32_e32 v155, v145
	v_pk_mul_f32 v[148:149], v[84:85], v[148:149]
	v_pk_mul_f32 v[150:151], v[80:81], v[150:151]
	v_pk_mul_f32 v[152:153], v[86:87], v[152:153]
	v_pk_mul_f32 v[154:155], v[82:83], v[154:155]
	v_cvt_pk_bf16_f32 v148, v148, v149
	v_cvt_pk_bf16_f32 v149, v152, v153
	v_cvt_pk_bf16_f32 v150, v150, v151
	v_cvt_pk_bf16_f32 v151, v154, v155
	global_store_dwordx4 v[130:131], v[148:151], off offset:256
	v_mul_f32_e32 v130, 0xbfb8aa3b, v76
	v_exp_f32_e32 v145, v130
	v_mul_f32_e32 v130, 0xbfb8aa3b, v72
	v_exp_f32_e32 v147, v130
	v_mul_f32_e32 v149, 0xbfb8aa3b, v73
	v_add_f32_e32 v145, 1.0, v145
	v_rcp_f32_e32 v148, v145
	v_add_f32_e32 v145, 1.0, v147
	v_mul_f32_e32 v147, 0xbfb8aa3b, v77
	v_exp_f32_e32 v147, v147
	v_exp_f32_e32 v151, v149
	v_rcp_f32_e32 v150, v145
	v_lshl_add_u64 v[130:131], v[128:129], 0, s[10:11]
	v_add_f32_e32 v145, 1.0, v147
	v_mul_f32_e32 v147, 0xbfb8aa3b, v78
	v_rcp_f32_e32 v149, v145
	v_add_f32_e32 v145, 1.0, v151
	v_exp_f32_e32 v147, v147
	v_mul_f32_e32 v151, 0xbfb8aa3b, v74
	v_exp_f32_e32 v153, v151
	v_rcp_f32_e32 v151, v145
	v_add_f32_e32 v145, 1.0, v147
	v_mul_f32_e32 v147, 0xbfb8aa3b, v79
	v_rcp_f32_e32 v152, v145
	v_add_f32_e32 v145, 1.0, v153
	v_exp_f32_e32 v147, v147
	v_mul_f32_e32 v153, 0xbfb8aa3b, v75
	v_exp_f32_e32 v155, v153
	v_rcp_f32_e32 v154, v145
	v_add_f32_e32 v145, 1.0, v147
	v_rcp_f32_e32 v153, v145
	v_add_f32_e32 v145, 1.0, v155
	v_rcp_f32_e32 v155, v145
	v_mul_f32_e32 v145, 0xbfb8aa3b, v68
	v_exp_f32_e32 v145, v145
	v_mul_f32_e32 v147, 0xbfb8aa3b, v64
	v_exp_f32_e32 v147, v147
	v_pk_mul_f32 v[148:149], v[76:77], v[148:149]
	v_pk_mul_f32 v[152:153], v[78:79], v[152:153]
	v_pk_mul_f32 v[150:151], v[72:73], v[150:151]
	v_pk_mul_f32 v[154:155], v[74:75], v[154:155]
	v_cvt_pk_bf16_f32 v148, v148, v149
	v_cvt_pk_bf16_f32 v149, v152, v153
	v_add_co_u32_e32 v152, vcc, s8, v128
	v_cvt_pk_bf16_f32 v150, v150, v151
	v_cvt_pk_bf16_f32 v151, v154, v155
	v_addc_co_u32_e32 v153, vcc, 0, v129, vcc
	v_add_f32_e32 v145, 1.0, v145
	global_store_dwordx4 v[152:153], v[148:151], off
	s_nop 1
	v_rcp_f32_e32 v148, v145
	v_add_f32_e32 v145, 1.0, v147
	v_mul_f32_e32 v147, 0xbfb8aa3b, v69
	v_exp_f32_e32 v147, v147
	v_mul_f32_e32 v149, 0xbfb8aa3b, v65
	v_exp_f32_e32 v151, v149
	v_rcp_f32_e32 v150, v145
	v_add_f32_e32 v145, 1.0, v147
	v_mul_f32_e32 v147, 0xbfb8aa3b, v70
	v_rcp_f32_e32 v149, v145
	v_add_f32_e32 v145, 1.0, v151
	v_exp_f32_e32 v147, v147
	v_mul_f32_e32 v151, 0xbfb8aa3b, v66
	v_exp_f32_e32 v153, v151
	v_rcp_f32_e32 v151, v145
	v_add_f32_e32 v145, 1.0, v147
	v_mul_f32_e32 v147, 0xbfb8aa3b, v71
	v_rcp_f32_e32 v152, v145
	v_add_f32_e32 v145, 1.0, v153
	v_exp_f32_e32 v147, v147
	v_mul_f32_e32 v153, 0xbfb8aa3b, v67
	v_exp_f32_e32 v155, v153
; __device__ __forceinline__ void st8(bf16_t* p, f32x4 a, f32x4 b) { u32x4 w = {cvt_pk(a[0], a[1]), cvt_pk(a[2], a[3]), cvt_pk(b[0], b[1]), cvt_pk(b[2], b[3])}; *(u32x4*)p = w; }
; __device__ __forceinline__ void st8_s(bf16_t* p, f32x4 a, f32x4 b) { u32x4 w = {cvt_pk_s(a[0], a[1]), cvt_pk_s(a[2], a[3]), cvt_pk_s(b[0], b[1]), cvt_pk_s(b[2], b[3])}; *(u32x4*)p = w; }
; #define FOR_AI_M _Pragma("unroll") for (int ai = 0; ai < 2; ++ai) if ((__builtin_amdgcn_sched_barrier(0), true)) _Pragma("unroll") for (int m = 0; m < 4; ++m)
; __device__ __forceinline__ float sigm(float x) { return __builtin_amdgcn_rcpf(1.f + __builtin_amdgcn_exp2f(x * -1.4426950408889634f)); }
;   template <int ACT> __device__ __forceinline__ void plain_store(const f32x4 (&acc)[2][2][4][2], bf16_t* dst, int cbase, int rbase) const {
;     FOR_AI_M { const int row = rbase + ai * 128 + m * 16;
; #pragma unroll
;       for (int bj = 0; bj < 2; ++bj) { f32x4 v0 = acc[ai][bj][m][0], v1 = acc[ai][bj][m][1];
;         if (ACT == 1) {
; #pragma unroll
;           for (int e = 0; e < 4; ++e) { v0[e] = v0[e] * sigm(v0[e]); v1[e] = v1[e] * sigm(v1[e]); } }
;         if (ACT == 2) {
; #pragma unroll
;           for (int e = 0; e < 4; ++e) { v0[e] = sigm(v0[e]); v1[e] = sigm(v1[e]); } }
;         if (ACT == 0) st8(dst + (size_t)row * 1024 + cbase + bj * 128, v0, v1); else st8_s(dst + (size_t)row * 1024 + cbase + bj * 128, v0, v1); } }
	v_rcp_f32_e32 v154, v145
	v_add_f32_e32 v145, 1.0, v147
	v_rcp_f32_e32 v153, v145
	v_add_f32_e32 v145, 1.0, v155
	v_rcp_f32_e32 v155, v145
	v_pk_mul_f32 v[148:149], v[68:69], v[148:149]
	v_pk_mul_f32 v[150:151], v[64:65], v[150:151]
	v_pk_mul_f32 v[152:153], v[70:71], v[152:153]
	v_pk_mul_f32 v[154:155], v[66:67], v[154:155]
	v_cvt_pk_bf16_f32 v148, v148, v149
	v_cvt_pk_bf16_f32 v149, v152, v153
	v_cvt_pk_bf16_f32 v150, v150, v151
	v_cvt_pk_bf16_f32 v151, v154, v155
	global_store_dwordx4 v[130:131], v[148:151], off offset:256
	v_mul_f32_e32 v130, 0xbfb8aa3b, v60
	v_exp_f32_e32 v145, v130
	v_mul_f32_e32 v130, 0xbfb8aa3b, v56
	v_exp_f32_e32 v147, v130
	v_mul_f32_e32 v149, 0xbfb8aa3b, v57
	v_add_f32_e32 v145, 1.0, v145
	v_rcp_f32_e32 v148, v145
	v_add_f32_e32 v145, 1.0, v147
	v_mul_f32_e32 v147, 0xbfb8aa3b, v61
	v_exp_f32_e32 v147, v147
	v_exp_f32_e32 v151, v149
	v_rcp_f32_e32 v150, v145
	s_mov_b32 s8, 0x40000
	v_add_f32_e32 v145, 1.0, v147
	v_mul_f32_e32 v147, 0xbfb8aa3b, v62
	v_rcp_f32_e32 v149, v145
	v_add_f32_e32 v145, 1.0, v151
	v_exp_f32_e32 v147, v147
	v_mul_f32_e32 v151, 0xbfb8aa3b, v58
	v_exp_f32_e32 v153, v151
	v_rcp_f32_e32 v151, v145
	v_add_f32_e32 v145, 1.0, v147
	v_mul_f32_e32 v147, 0xbfb8aa3b, v63
	v_rcp_f32_e32 v152, v145
	v_add_f32_e32 v145, 1.0, v153
	v_exp_f32_e32 v147, v147
	v_mul_f32_e32 v153, 0xbfb8aa3b, v59
	v_exp_f32_e32 v155, v153
	v_rcp_f32_e32 v154, v145
	v_add_f32_e32 v145, 1.0, v147
	v_rcp_f32_e32 v153, v145
	v_add_f32_e32 v145, 1.0, v155
	v_rcp_f32_e32 v155, v145
	v_mul_f32_e32 v145, 0xbfb8aa3b, v52
	v_exp_f32_e32 v145, v145
	v_mul_f32_e32 v147, 0xbfb8aa3b, v48
	v_exp_f32_e32 v147, v147
	v_pk_mul_f32 v[148:149], v[60:61], v[148:149]
	v_pk_mul_f32 v[152:153], v[62:63], v[152:153]
	v_pk_mul_f32 v[150:151], v[56:57], v[150:151]
	v_pk_mul_f32 v[154:155], v[58:59], v[154:155]
	v_cvt_pk_bf16_f32 v148, v148, v149
	v_cvt_pk_bf16_f32 v149, v152, v153
	v_add_co_u32_e32 v152, vcc, s8, v128
	v_cvt_pk_bf16_f32 v150, v150, v151
	v_cvt_pk_bf16_f32 v151, v154, v155
	v_addc_co_u32_e32 v153, vcc, 0, v129, vcc
	v_add_f32_e32 v145, 1.0, v145
	global_store_dwordx4 v[152:153], v[148:151], off
	v_lshl_add_u64 v[130:131], v[128:129], 0, s[72:73]
	s_mov_b32 s8, 0x48000
	v_rcp_f32_e32 v148, v145
	v_add_f32_e32 v145, 1.0, v147
	v_mul_f32_e32 v147, 0xbfb8aa3b, v53
	v_exp_f32_e32 v147, v147
	v_mul_f32_e32 v149, 0xbfb8aa3b, v49
	v_exp_f32_e32 v151, v149
	v_rcp_f32_e32 v150, v145
	v_add_f32_e32 v145, 1.0, v147
	v_mul_f32_e32 v147, 0xbfb8aa3b, v54
	v_rcp_f32_e32 v149, v145
	v_add_f32_e32 v145, 1.0, v151
	v_exp_f32_e32 v147, v147
	v_mul_f32_e32 v151, 0xbfb8aa3b, v50
	v_exp_f32_e32 v153, v151
	v_rcp_f32_e32 v151, v145
	v_add_f32_e32 v145, 1.0, v147
	v_mul_f32_e32 v147, 0xbfb8aa3b, v55
	v_rcp_f32_e32 v152, v145
	v_add_f32_e32 v145, 1.0, v153
	v_exp_f32_e32 v147, v147
	v_mul_f32_e32 v153, 0xbfb8aa3b, v51
	v_exp_f32_e32 v155, v153
	v_rcp_f32_e32 v154, v145
	v_add_f32_e32 v145, 1.0, v147
	v_rcp_f32_e32 v153, v145
	v_add_f32_e32 v145, 1.0, v155
	v_rcp_f32_e32 v155, v145
	v_pk_mul_f32 v[148:149], v[52:53], v[148:149]
	v_pk_mul_f32 v[150:151], v[48:49], v[150:151]
	v_pk_mul_f32 v[152:153], v[54:55], v[152:153]
	v_pk_mul_f32 v[154:155], v[50:51], v[154:155]
	v_cvt_pk_bf16_f32 v148, v148, v149
	v_cvt_pk_bf16_f32 v149, v152, v153
	v_cvt_pk_bf16_f32 v150, v150, v151
	v_cvt_pk_bf16_f32 v151, v154, v155
	global_store_dwordx4 v[130:131], v[148:151], off offset:256
	v_mul_f32_e32 v130, 0xbfb8aa3b, v44
	v_exp_f32_e32 v145, v130
	v_mul_f32_e32 v130, 0xbfb8aa3b, v40
	v_exp_f32_e32 v147, v130
	v_mul_f32_e32 v149, 0xbfb8aa3b, v41
	v_add_f32_e32 v145, 1.0, v145
	v_rcp_f32_e32 v148, v145
	v_add_f32_e32 v145, 1.0, v147
	v_mul_f32_e32 v147, 0xbfb8aa3b, v45
	v_exp_f32_e32 v147, v147
	v_exp_f32_e32 v151, v149
	v_rcp_f32_e32 v150, v145
	s_mov_b64 s[10:11], 0x48000
	v_add_f32_e32 v145, 1.0, v147
	v_mul_f32_e32 v147, 0xbfb8aa3b, v46
	v_rcp_f32_e32 v149, v145
	v_add_f32_e32 v145, 1.0, v151
	v_exp_f32_e32 v147, v147
	v_mul_f32_e32 v151, 0xbfb8aa3b, v42
	v_exp_f32_e32 v153, v151
	v_rcp_f32_e32 v151, v145
	v_add_f32_e32 v145, 1.0, v147
	v_mul_f32_e32 v147, 0xbfb8aa3b, v47
	v_rcp_f32_e32 v152, v145
	v_add_f32_e32 v145, 1.0, v153
	v_exp_f32_e32 v147, v147
	v_mul_f32_e32 v153, 0xbfb8aa3b, v43
	v_exp_f32_e32 v155, v153
	v_rcp_f32_e32 v154, v145
	v_add_f32_e32 v145, 1.0, v147
	v_rcp_f32_e32 v153, v145
	v_add_f32_e32 v145, 1.0, v155
	v_rcp_f32_e32 v155, v145
	v_mul_f32_e32 v145, 0xbfb8aa3b, v36
	v_exp_f32_e32 v145, v145
	v_mul_f32_e32 v147, 0xbfb8aa3b, v32
	v_exp_f32_e32 v147, v147
	v_pk_mul_f32 v[148:149], v[44:45], v[148:149]
	v_pk_mul_f32 v[152:153], v[46:47], v[152:153]
	v_pk_mul_f32 v[150:151], v[40:41], v[150:151]
	v_pk_mul_f32 v[154:155], v[42:43], v[154:155]
	v_cvt_pk_bf16_f32 v148, v148, v149
	v_cvt_pk_bf16_f32 v149, v152, v153
	v_add_co_u32_e32 v152, vcc, s8, v128
	v_cvt_pk_bf16_f32 v150, v150, v151
	v_cvt_pk_bf16_f32 v151, v154, v155
	v_addc_co_u32_e32 v153, vcc, 0, v129, vcc
	v_add_f32_e32 v145, 1.0, v145
	global_store_dwordx4 v[152:153], v[148:151], off
	v_lshl_add_u64 v[130:131], v[128:129], 0, s[10:11]
	s_mov_b32 s8, 0x50000
	v_rcp_f32_e32 v148, v145
	v_add_f32_e32 v145, 1.0, v147
	v_mul_f32_e32 v147, 0xbfb8aa3b, v37
	v_exp_f32_e32 v147, v147
	v_mul_f32_e32 v149, 0xbfb8aa3b, v33
	v_exp_f32_e32 v151, v149
	v_rcp_f32_e32 v150, v145
	v_add_f32_e32 v145, 1.0, v147
	v_mul_f32_e32 v147, 0xbfb8aa3b, v38
	v_rcp_f32_e32 v149, v145
	v_add_f32_e32 v145, 1.0, v151
	v_exp_f32_e32 v147, v147
	v_mul_f32_e32 v151, 0xbfb8aa3b, v34
	v_exp_f32_e32 v153, v151
	v_rcp_f32_e32 v151, v145
	v_add_f32_e32 v145, 1.0, v147
	v_mul_f32_e32 v147, 0xbfb8aa3b, v39
	v_rcp_f32_e32 v152, v145
; __device__ __forceinline__ void st8(bf16_t* p, f32x4 a, f32x4 b) { u32x4 w = {cvt_pk(a[0], a[1]), cvt_pk(a[2], a[3]), cvt_pk(b[0], b[1]), cvt_pk(b[2], b[3])}; *(u32x4*)p = w; }
; __device__ __forceinline__ void st8_s(bf16_t* p, f32x4 a, f32x4 b) { u32x4 w = {cvt_pk_s(a[0], a[1]), cvt_pk_s(a[2], a[3]), cvt_pk_s(b[0], b[1]), cvt_pk_s(b[2], b[3])}; *(u32x4*)p = w; }
; #define FOR_AI_M _Pragma("unroll") for (int ai = 0; ai < 2; ++ai) if ((__builtin_amdgcn_sched_barrier(0), true)) _Pragma("unroll") for (int m = 0; m < 4; ++m)
; __device__ __forceinline__ float sigm(float x) { return __builtin_amdgcn_rcpf(1.f + __builtin_amdgcn_exp2f(x * -1.4426950408889634f)); }
;   template <int ACT> __device__ __forceinline__ void plain_store(const f32x4 (&acc)[2][2][4][2], bf16_t* dst, int cbase, int rbase) const {
;     FOR_AI_M { const int row = rbase + ai * 128 + m * 16;
; #pragma unroll
;       for (int bj = 0; bj < 2; ++bj) { f32x4 v0 = acc[ai][bj][m][0], v1 = acc[ai][bj][m][1];
;         if (ACT == 1) {
; #pragma unroll
;           for (int e = 0; e < 4; ++e) { v0[e] = v0[e] * sigm(v0[e]); v1[e] = v1[e] * sigm(v1[e]); } }
;         if (ACT == 2) {
; #pragma unroll
;           for (int e = 0; e < 4; ++e) { v0[e] = sigm(v0[e]); v1[e] = sigm(v1[e]); } }
;         if (ACT == 0) st8(dst + (size_t)row * 1024 + cbase + bj * 128, v0, v1); else st8_s(dst + (size_t)row * 1024 + cbase + bj * 128, v0, v1); } }
	v_add_f32_e32 v145, 1.0, v153
	v_exp_f32_e32 v147, v147
	v_mul_f32_e32 v153, 0xbfb8aa3b, v35
	v_exp_f32_e32 v155, v153
	v_rcp_f32_e32 v154, v145
	v_add_f32_e32 v145, 1.0, v147
	v_rcp_f32_e32 v153, v145
	v_add_f32_e32 v145, 1.0, v155
	v_rcp_f32_e32 v155, v145
	v_pk_mul_f32 v[148:149], v[36:37], v[148:149]
	v_pk_mul_f32 v[150:151], v[32:33], v[150:151]
	v_pk_mul_f32 v[152:153], v[38:39], v[152:153]
	v_pk_mul_f32 v[154:155], v[34:35], v[154:155]
	v_cvt_pk_bf16_f32 v148, v148, v149
	v_cvt_pk_bf16_f32 v149, v152, v153
	v_cvt_pk_bf16_f32 v150, v150, v151
	v_cvt_pk_bf16_f32 v151, v154, v155
	global_store_dwordx4 v[130:131], v[148:151], off offset:256
	v_mul_f32_e32 v130, 0xbfb8aa3b, v28
	v_exp_f32_e32 v145, v130
	v_mul_f32_e32 v130, 0xbfb8aa3b, v24
	v_exp_f32_e32 v147, v130
	v_mul_f32_e32 v149, 0xbfb8aa3b, v25
	v_add_f32_e32 v145, 1.0, v145
	v_rcp_f32_e32 v148, v145
	v_add_f32_e32 v145, 1.0, v147
	v_mul_f32_e32 v147, 0xbfb8aa3b, v29
	v_exp_f32_e32 v147, v147
	v_exp_f32_e32 v151, v149
	v_rcp_f32_e32 v150, v145
	s_mov_b64 s[10:11], 0x50000
	v_add_f32_e32 v145, 1.0, v147
	v_mul_f32_e32 v147, 0xbfb8aa3b, v30
	v_rcp_f32_e32 v149, v145
	v_add_f32_e32 v145, 1.0, v151
	v_exp_f32_e32 v147, v147
	v_mul_f32_e32 v151, 0xbfb8aa3b, v26
	v_exp_f32_e32 v153, v151
	v_rcp_f32_e32 v151, v145
	v_add_f32_e32 v145, 1.0, v147
	v_mul_f32_e32 v147, 0xbfb8aa3b, v31
	v_rcp_f32_e32 v152, v145
	v_add_f32_e32 v145, 1.0, v153
	v_exp_f32_e32 v147, v147
	v_mul_f32_e32 v153, 0xbfb8aa3b, v27
	v_exp_f32_e32 v155, v153
	v_rcp_f32_e32 v154, v145
	v_add_f32_e32 v145, 1.0, v147
	v_rcp_f32_e32 v153, v145
	v_add_f32_e32 v145, 1.0, v155
	v_rcp_f32_e32 v155, v145
	v_mul_f32_e32 v145, 0xbfb8aa3b, v20
	v_exp_f32_e32 v145, v145
	v_mul_f32_e32 v147, 0xbfb8aa3b, v16
	v_exp_f32_e32 v147, v147
	v_pk_mul_f32 v[148:149], v[28:29], v[148:149]
	v_pk_mul_f32 v[152:153], v[30:31], v[152:153]
	v_pk_mul_f32 v[150:151], v[24:25], v[150:151]
	v_pk_mul_f32 v[154:155], v[26:27], v[154:155]
	v_cvt_pk_bf16_f32 v148, v148, v149
	v_cvt_pk_bf16_f32 v149, v152, v153
	v_add_co_u32_e32 v152, vcc, s8, v128
	v_cvt_pk_bf16_f32 v150, v150, v151
	v_cvt_pk_bf16_f32 v151, v154, v155
	v_addc_co_u32_e32 v153, vcc, 0, v129, vcc
	v_add_f32_e32 v145, 1.0, v145
	global_store_dwordx4 v[152:153], v[148:151], off
	v_lshl_add_u64 v[130:131], v[128:129], 0, s[10:11]
	s_mov_b64 s[10:11], 0x58000
	v_rcp_f32_e32 v148, v145
	v_add_f32_e32 v145, 1.0, v147
	v_mul_f32_e32 v147, 0xbfb8aa3b, v21
	v_exp_f32_e32 v147, v147
	v_mul_f32_e32 v149, 0xbfb8aa3b, v17
	v_exp_f32_e32 v151, v149
	v_rcp_f32_e32 v150, v145
	v_add_f32_e32 v145, 1.0, v147
	v_mul_f32_e32 v147, 0xbfb8aa3b, v22
	v_rcp_f32_e32 v149, v145
	v_add_f32_e32 v145, 1.0, v151
	v_exp_f32_e32 v147, v147
	v_mul_f32_e32 v151, 0xbfb8aa3b, v18
	v_exp_f32_e32 v153, v151
	v_rcp_f32_e32 v151, v145
	v_add_f32_e32 v145, 1.0, v147
	v_mul_f32_e32 v147, 0xbfb8aa3b, v23
	v_rcp_f32_e32 v152, v145
	v_add_f32_e32 v145, 1.0, v153
	v_exp_f32_e32 v147, v147
	v_mul_f32_e32 v153, 0xbfb8aa3b, v19
	v_exp_f32_e32 v155, v153
	v_rcp_f32_e32 v154, v145
	v_add_f32_e32 v145, 1.0, v147
	v_rcp_f32_e32 v153, v145
	v_add_f32_e32 v145, 1.0, v155
	v_rcp_f32_e32 v155, v145
	v_pk_mul_f32 v[148:149], v[20:21], v[148:149]
	v_pk_mul_f32 v[150:151], v[16:17], v[150:151]
	v_pk_mul_f32 v[152:153], v[22:23], v[152:153]
	v_pk_mul_f32 v[154:155], v[18:19], v[154:155]
	v_cvt_pk_bf16_f32 v148, v148, v149
	v_cvt_pk_bf16_f32 v149, v152, v153
	v_cvt_pk_bf16_f32 v150, v150, v151
	v_cvt_pk_bf16_f32 v151, v154, v155
	global_store_dwordx4 v[130:131], v[148:151], off offset:256
	v_mul_f32_e32 v131, 0xbfb8aa3b, v8
	v_exp_f32_e32 v131, v131
	v_mul_f32_e32 v145, 0xbfb8aa3b, v13
	v_mul_f32_e32 v147, 0xbfb8aa3b, v9
	v_exp_f32_e32 v145, v145
	v_exp_f32_e32 v147, v147
	v_add_f32_e32 v131, 1.0, v131
	v_rcp_f32_e32 v148, v131
	v_add_f32_e32 v131, 1.0, v145
	v_add_f32_e32 v145, 1.0, v147
	v_mul_f32_e32 v147, 0xbfb8aa3b, v14
	v_exp_f32_e32 v147, v147
	v_mul_f32_e32 v149, 0xbfb8aa3b, v10
	v_mul_f32_e32 v130, 0xbfb8aa3b, v12
	v_exp_f32_e32 v151, v149
	v_exp_f32_e32 v130, v130
	v_rcp_f32_e32 v149, v145
	v_add_f32_e32 v145, 1.0, v147
	v_mul_f32_e32 v147, 0xbfb8aa3b, v15
	v_rcp_f32_e32 v150, v145
	v_add_f32_e32 v145, 1.0, v151
	v_exp_f32_e32 v147, v147
	v_mul_f32_e32 v151, 0xbfb8aa3b, v11
	v_add_f32_e32 v130, 1.0, v130
	v_exp_f32_e32 v155, v151
	v_rcp_f32_e32 v130, v130
	v_rcp_f32_e32 v131, v131
	v_rcp_f32_e32 v154, v145
	v_add_f32_e32 v145, 1.0, v147
	v_rcp_f32_e32 v151, v145
	v_add_f32_e32 v145, 1.0, v155
	v_rcp_f32_e32 v155, v145
	v_pk_mul_f32 v[130:131], v[12:13], v[130:131]
	v_pk_mul_f32 v[156:157], v[8:9], v[148:149]
	v_cvt_pk_bf16_f32 v148, v130, v131
	v_mul_f32_e32 v130, 0xbfb8aa3b, v4
	v_exp_f32_e32 v130, v130
	v_mul_f32_e32 v131, 0xbfb8aa3b, v0
	s_mov_b32 s8, 0x58000
	v_exp_f32_e32 v131, v131
	v_lshl_add_u64 v[152:153], v[128:129], 0, s[10:11]
	v_pk_mul_f32 v[150:151], v[14:15], v[150:151]
	v_pk_mul_f32 v[154:155], v[10:11], v[154:155]
	v_add_co_u32_e32 v128, vcc, s8, v128
	v_cvt_pk_bf16_f32 v149, v150, v151
	v_cvt_pk_bf16_f32 v150, v156, v157
	v_cvt_pk_bf16_f32 v151, v154, v155
	v_addc_co_u32_e32 v129, vcc, 0, v129, vcc
	global_store_dwordx4 v[128:129], v[148:151], off
	v_add_f32_e32 v128, 1.0, v130
	v_mul_f32_e32 v130, 0xbfb8aa3b, v5
	v_add_f32_e32 v129, 1.0, v131
	v_exp_f32_e32 v131, v130
	v_mul_f32_e32 v130, 0xbfb8aa3b, v1
	v_exp_f32_e32 v145, v130
	v_rcp_f32_e32 v130, v129
	v_add_f32_e32 v129, 1.0, v131
	v_mul_f32_e32 v147, 0xbfb8aa3b, v2
	v_add_f32_e32 v131, 1.0, v145
	v_mul_f32_e32 v145, 0xbfb8aa3b, v6
	v_exp_f32_e32 v145, v145
	v_exp_f32_e32 v147, v147
	v_mul_f32_e32 v149, 0xbfb8aa3b, v3
	v_exp_f32_e32 v151, v149
	v_add_f32_e32 v145, 1.0, v145
	v_rcp_f32_e32 v148, v145
	v_add_f32_e32 v145, 1.0, v147
	v_mul_f32_e32 v147, 0xbfb8aa3b, v7
	v_exp_f32_e32 v147, v147
	v_rcp_f32_e32 v150, v145
	v_rcp_f32_e32 v128, v128
	v_rcp_f32_e32 v129, v129
	v_add_f32_e32 v145, 1.0, v147
	v_rcp_f32_e32 v149, v145
	v_add_f32_e32 v145, 1.0, v151
	v_rcp_f32_e32 v131, v131
	v_rcp_f32_e32 v151, v145
	v_pk_mul_f32 v[128:129], v[4:5], v[128:129]
	v_pk_mul_f32 v[148:149], v[6:7], v[148:149]
	v_pk_mul_f32 v[130:131], v[0:1], v[130:131]
	v_pk_mul_f32 v[150:151], v[2:3], v[150:151]
	v_cvt_pk_bf16_f32 v128, v128, v129
	v_cvt_pk_bf16_f32 v129, v148, v149
	v_cvt_pk_bf16_f32 v130, v130, v131
	v_cvt_pk_bf16_f32 v131, v150, v151
	global_store_dwordx4 v[152:153], v[128:131], off offset:256

; __device__ __forceinline__ void st8(bf16_t* p, f32x4 a, f32x4 b) { u32x4 w = {cvt_pk(a[0], a[1]), cvt_pk(a[2], a[3]), cvt_pk(b[0], b[1]), cvt_pk(b[2], b[3])}; *(u32x4*)p = w; }
; __device__ __forceinline__ float sigm(float x) { return __builtin_amdgcn_rcpf(1.f + __builtin_amdgcn_exp2f(x * -1.4426950408889634f)); }
; __device__ __forceinline__ void st8_s(bf16_t* p, f32x4 a, f32x4 b) { u32x4 w = {cvt_pk_s(a[0], a[1]), cvt_pk_s(a[2], a[3]), cvt_pk_s(b[0], b[1]), cvt_pk_s(b[2], b[3])}; *(u32x4*)p = w; }
; #define FOR_AI_M _Pragma("unroll") for (int ai = 0; ai < 2; ++ai) if ((__builtin_amdgcn_sched_barrier(0), true)) _Pragma("unroll") for (int m = 0; m < 4; ++m)
;   template <int ACT> __device__ __forceinline__ void plain_store(const f32x4 (&acc)[2][2][4][2], bf16_t* dst, int cbase, int rbase) const {
;     FOR_AI_M { const int row = rbase + ai * 128 + m * 16;
; #pragma unroll
;       for (int bj = 0; bj < 2; ++bj) { f32x4 v0 = acc[ai][bj][m][0], v1 = acc[ai][bj][m][1];
;         if (ACT == 1) {
; #pragma unroll
;           for (int e = 0; e < 4; ++e) { v0[e] = v0[e] * sigm(v0[e]); v1[e] = v1[e] * sigm(v1[e]); } }
;         if (ACT == 2) {
; #pragma unroll
;           for (int e = 0; e < 4; ++e) { v0[e] = sigm(v0[e]); v1[e] = sigm(v1[e]); } }
;         if (ACT == 0) st8(dst + (size_t)row * 1024 + cbase + bj * 128, v0, v1); else st8_s(dst + (size_t)row * 1024 + cbase + bj * 128, v0, v1); } }
.LBB0_414:
	s_andn2_b64 vcc, exec, s[42:43]
	s_cbranch_vccnz .LBB0_416
	s_lshl_b32 s8, s47, 8
	s_addk_i32 s8, 0xfc00
	v_add_u32_e32 v128, s8, v146
	s_waitcnt lgkmcnt(0)
	v_ashrrev_i32_e32 v129, 31, v128
	v_lshl_add_u64 v[128:129], v[128:129], 1, s[34:35]
	v_ashrrev_i32_e32 v145, 31, v144
	v_lshlrev_b64 v[130:131], 11, v[144:145]
	v_lshl_add_u64 v[128:129], v[128:129], 0, v[130:131]
	v_cvt_pk_bf16_f32 v148, v124, v125
	v_cvt_pk_bf16_f32 v149, v126, v127
	v_cvt_pk_bf16_f32 v150, v120, v121
	v_cvt_pk_bf16_f32 v151, v122, v123
	global_store_dwordx4 v[128:129], v[148:151], off
	v_add_co_u32_e32 v152, vcc, s88, v128
	s_nop 0
	v_cvt_pk_bf16_f32 v148, v116, v117
	v_cvt_pk_bf16_f32 v149, v118, v119
	v_cvt_pk_bf16_f32 v150, v112, v113
	v_cvt_pk_bf16_f32 v151, v114, v115
	global_store_dwordx4 v[128:129], v[148:151], off offset:256
	s_mov_b64 s[10:11], 0x8000
	v_addc_co_u32_e32 v153, vcc, 0, v129, vcc
	v_cvt_pk_bf16_f32 v148, v108, v109
	v_cvt_pk_bf16_f32 v149, v110, v111
	v_cvt_pk_bf16_f32 v150, v104, v105
	v_cvt_pk_bf16_f32 v151, v106, v107
	v_lshl_add_u64 v[130:131], v[128:129], 0, s[10:11]
	global_store_dwordx4 v[152:153], v[148:151], off
	v_add_co_u32_e32 v152, vcc, s95, v128
	s_nop 0
	v_cvt_pk_bf16_f32 v148, v100, v101
	v_cvt_pk_bf16_f32 v149, v102, v103
	v_cvt_pk_bf16_f32 v150, v96, v97
	v_cvt_pk_bf16_f32 v151, v98, v99
	global_store_dwordx4 v[130:131], v[148:151], off offset:256
	s_mov_b64 s[10:11], 0x10000
	v_addc_co_u32_e32 v153, vcc, 0, v129, vcc
	v_cvt_pk_bf16_f32 v148, v92, v93
	v_cvt_pk_bf16_f32 v149, v94, v95
	v_cvt_pk_bf16_f32 v150, v88, v89
	v_cvt_pk_bf16_f32 v151, v90, v91
	s_mov_b32 s8, 0x18000
	v_lshl_add_u64 v[130:131], v[128:129], 0, s[10:11]
	global_store_dwordx4 v[152:153], v[148:151], off
	s_mov_b64 s[10:11], 0x18000
	v_add_co_u32_e32 v152, vcc, s8, v128
	v_cvt_pk_bf16_f32 v148, v84, v85
	v_cvt_pk_bf16_f32 v149, v86, v87
	v_cvt_pk_bf16_f32 v150, v80, v81
	v_cvt_pk_bf16_f32 v151, v82, v83
	global_store_dwordx4 v[130:131], v[148:151], off offset:256
	v_lshl_add_u64 v[130:131], v[128:129], 0, s[10:11]
	v_addc_co_u32_e32 v153, vcc, 0, v129, vcc
	v_cvt_pk_bf16_f32 v148, v76, v77
	v_cvt_pk_bf16_f32 v149, v78, v79
	v_cvt_pk_bf16_f32 v150, v72, v73
	v_cvt_pk_bf16_f32 v151, v74, v75
	global_store_dwordx4 v[152:153], v[148:151], off
	s_nop 1
	v_cvt_pk_bf16_f32 v148, v68, v69
	v_cvt_pk_bf16_f32 v149, v70, v71
	v_cvt_pk_bf16_f32 v150, v64, v65
	v_cvt_pk_bf16_f32 v151, v66, v67
	global_store_dwordx4 v[130:131], v[148:151], off offset:256
	s_mov_b32 s8, 0x40000
	v_add_co_u32_e32 v152, vcc, s8, v128
	s_mov_b32 s8, 0x48000
	s_nop 0
	v_addc_co_u32_e32 v153, vcc, 0, v129, vcc
	v_cvt_pk_bf16_f32 v148, v60, v61
	v_cvt_pk_bf16_f32 v149, v62, v63
	v_cvt_pk_bf16_f32 v150, v56, v57
	v_cvt_pk_bf16_f32 v151, v58, v59
	global_store_dwordx4 v[152:153], v[148:151], off
	v_add_co_u32_e32 v152, vcc, s8, v128
	v_lshl_add_u64 v[130:131], v[128:129], 0, s[72:73]
	v_cvt_pk_bf16_f32 v148, v52, v53
	v_cvt_pk_bf16_f32 v149, v54, v55
	v_cvt_pk_bf16_f32 v150, v48, v49
	v_cvt_pk_bf16_f32 v151, v50, v51
	s_mov_b64 s[10:11], 0x48000
	v_addc_co_u32_e32 v153, vcc, 0, v129, vcc
	s_mov_b32 s8, 0x50000
	global_store_dwordx4 v[130:131], v[148:151], off offset:256
	v_lshl_add_u64 v[130:131], v[128:129], 0, s[10:11]
	s_mov_b64 s[10:11], 0x50000
	v_cvt_pk_bf16_f32 v148, v44, v45
	v_cvt_pk_bf16_f32 v149, v46, v47
	v_cvt_pk_bf16_f32 v150, v40, v41
	v_cvt_pk_bf16_f32 v151, v42, v43
	global_store_dwordx4 v[152:153], v[148:151], off
	v_add_co_u32_e32 v152, vcc, s8, v128
	s_nop 0
	v_cvt_pk_bf16_f32 v148, v36, v37
	v_cvt_pk_bf16_f32 v149, v38, v39
	v_cvt_pk_bf16_f32 v150, v32, v33
	v_cvt_pk_bf16_f32 v151, v34, v35
	global_store_dwordx4 v[130:131], v[148:151], off offset:256
	v_lshl_add_u64 v[130:131], v[128:129], 0, s[10:11]
	v_addc_co_u32_e32 v153, vcc, 0, v129, vcc
	s_mov_b64 s[10:11], 0x58000
	s_mov_b32 s8, 0x58000
	v_cvt_pk_bf16_f32 v148, v28, v29
	v_cvt_pk_bf16_f32 v149, v30, v31
	v_cvt_pk_bf16_f32 v150, v24, v25
	v_cvt_pk_bf16_f32 v151, v26, v27
	global_store_dwordx4 v[152:153], v[148:151], off
	v_lshl_add_u64 v[152:153], v[128:129], 0, s[10:11]
	v_add_co_u32_e32 v128, vcc, s8, v128
	v_cvt_pk_bf16_f32 v148, v20, v21
	v_cvt_pk_bf16_f32 v149, v22, v23
	v_cvt_pk_bf16_f32 v150, v16, v17
	v_cvt_pk_bf16_f32 v151, v18, v19
	s_nop 1
	v_addc_co_u32_e32 v129, vcc, 0, v129, vcc
	global_store_dwordx4 v[130:131], v[148:151], off offset:256
	s_nop 1
	v_cvt_pk_bf16_f32 v148, v12, v13
	v_cvt_pk_bf16_f32 v149, v14, v15
	v_cvt_pk_bf16_f32 v150, v8, v9
	v_cvt_pk_bf16_f32 v151, v10, v11
	global_store_dwordx4 v[128:129], v[148:151], off
	v_cvt_pk_bf16_f32 v128, v4, v5
	v_cvt_pk_bf16_f32 v129, v6, v7
	v_cvt_pk_bf16_f32 v130, v0, v1
	v_cvt_pk_bf16_f32 v131, v2, v3
	global_store_dwordx4 v[152:153], v[128:131], off offset:256

; __device__ __forceinline__ void st8(bf16_t* p, f32x4 a, f32x4 b) { u32x4 w = {cvt_pk(a[0], a[1]), cvt_pk(a[2], a[3]), cvt_pk(b[0], b[1]), cvt_pk(b[2], b[3])}; *(u32x4*)p = w; }
; #define FOR_AI_M _Pragma("unroll") for (int ai = 0; ai < 2; ++ai) if ((__builtin_amdgcn_sched_barrier(0), true)) _Pragma("unroll") for (int m = 0; m < 4; ++m)
;   __device__ __forceinline__ void rope_store(const f32x4 (&acc)[2][2][4][2], bf16_t* dst, float sc, int hsel, int rbase, int wc, int fq) const {
;     const int c0 = wc * 32 + fq * 8, i0 = wc * 16 + fq * 4;
;     FOR_AI_M { const int row = rbase + ai * 128 + m * 16, pos = (b.g0 + row) & b.slm;
;       const f32x4* tp = (const f32x4*)(b.rope + ((size_t)pos * 64 + i0) * 2); const f32x4 t0 = tp[0], t1 = tp[1];
; #pragma unroll
;       for (int bj = 0; bj < 2; ++bj) { f32x4 v0 = acc[ai][bj][m][0], v1 = acc[ai][bj][m][1]; rope4(v0, v1, t0, t1);
;         st8(dst + (size_t)row * 512 + (hsel * 2 + bj) * 128 + c0, v0 * sc, v1 * sc); } }
.LBB0_417:
	s_andn2_b64 vcc, exec, s[42:43]
	s_cbranch_vccnz .LBB0_419
	v_lshl_add_u32 v128, v162, 2, s66
	s_waitcnt lgkmcnt(0)
	v_ashrrev_i32_e32 v129, 31, v128
	s_lshl_b32 s8, s47, 8
	v_ashrrev_i32_e32 v147, 31, v146
	v_lshlrev_b64 v[150:151], 3, v[128:129]
	s_add_i32 s62, s8, 0xfffffe00
	v_lshl_add_u64 v[148:149], v[146:147], 1, s[30:31]
	v_and_b32_e32 v128, s90, v144
	v_lshlrev_b32_e32 v188, 9, v128
	v_lshl_add_u64 v[128:129], s[96:97], 0, v[188:189]
	v_lshl_add_u64 v[152:153], v[128:129], 0, v[150:151]
	global_load_dwordx4 v[128:131], v[152:153], off
	s_nop 0
	global_load_dwordx4 v[152:155], v[152:153], off offset:16
	v_ashrrev_i32_e32 v145, 31, v144
	v_lshlrev_b64 v[156:157], 10, v[144:145]
	v_lshl_add_u64 v[156:157], v[148:149], 0, v[156:157]
	s_lshl_b64 s[42:43], s[62:63], 1
	v_lshl_add_u64 v[156:157], v[156:157], 0, s[42:43]
	s_waitcnt vmcnt(0) lgkmcnt(0)
	v_pk_mul_f32 v[164:165], v[124:125], v[128:129] op_sel:[1,1] op_sel_hi:[1,0]
	s_nop 0
	v_pk_fma_f32 v[166:167], v[124:125], v[128:129], v[164:165] op_sel_hi:[0,1,1] neg_lo:[0,0,1] neg_hi:[0,0,1]
	v_pk_fma_f32 v[164:165], v[124:125], v[128:129], v[164:165] op_sel_hi:[0,1,1]
	v_mov_b32_e32 v164, v127
	v_pk_mul_f32 v[168:169], v[164:165], v[130:131] op_sel:[0,1] op_sel_hi:[0,0]
	v_pk_mul_f32 v[172:173], v[120:121], v[152:153] op_sel:[1,1] op_sel_hi:[1,0]
	v_mov_b32_e32 v164, v123
	v_pk_fma_f32 v[170:171], v[126:127], v[130:131], v[168:169] op_sel_hi:[0,1,1] neg_lo:[0,0,1] neg_hi:[0,0,1]
	v_pk_fma_f32 v[168:169], v[126:127], v[130:131], v[168:169] op_sel_hi:[0,1,1]
	v_pk_fma_f32 v[174:175], v[120:121], v[152:153], v[172:173] op_sel_hi:[0,1,1] neg_lo:[0,0,1] neg_hi:[0,0,1]
	v_pk_fma_f32 v[172:173], v[120:121], v[152:153], v[172:173] op_sel_hi:[0,1,1]
	v_pk_mul_f32 v[176:177], v[164:165], v[154:155] op_sel:[0,1] op_sel_hi:[0,0]
	v_mov_b32_e32 v167, v165
	v_pk_fma_f32 v[178:179], v[122:123], v[154:155], v[176:177] op_sel_hi:[0,1,1] neg_lo:[0,0,1] neg_hi:[0,0,1]
	v_pk_fma_f32 v[176:177], v[122:123], v[154:155], v[176:177] op_sel_hi:[0,1,1]
	v_mov_b32_e32 v171, v169
	v_pk_mul_f32 v[164:165], v[166:167], s[16:17] op_sel_hi:[1,0]
	v_mov_b32_e32 v175, v173
	v_pk_mul_f32 v[168:169], v[170:171], s[16:17] op_sel_hi:[1,0]
	v_mov_b32_e32 v179, v177
	v_pk_mul_f32 v[166:167], v[174:175], s[16:17] op_sel_hi:[1,0]
	v_cvt_pk_bf16_f32 v164, v164, v165
	v_cvt_pk_bf16_f32 v165, v168, v169
	v_pk_mul_f32 v[170:171], v[178:179], s[16:17] op_sel_hi:[1,0]
	v_cvt_pk_bf16_f32 v166, v166, v167
	s_nop 0
	v_cvt_pk_bf16_f32 v167, v170, v171
	global_store_dwordx4 v[156:157], v[164:167], off
	s_nop 1
	v_pk_mul_f32 v[164:165], v[116:117], v[128:129] op_sel:[1,1] op_sel_hi:[1,0]
	s_nop 0
	v_pk_fma_f32 v[166:167], v[116:117], v[128:129], v[164:165] op_sel_hi:[0,1,1] neg_lo:[0,0,1] neg_hi:[0,0,1]
	v_pk_fma_f32 v[128:129], v[116:117], v[128:129], v[164:165] op_sel_hi:[0,1,1]
	v_mov_b32_e32 v128, v119
	v_pk_mul_f32 v[164:165], v[128:129], v[130:131] op_sel:[0,1] op_sel_hi:[0,0]
	v_pk_fma_f32 v[168:169], v[118:119], v[130:131], v[164:165] op_sel_hi:[0,1,1] neg_lo:[0,0,1] neg_hi:[0,0,1]
	v_pk_fma_f32 v[130:131], v[118:119], v[130:131], v[164:165] op_sel_hi:[0,1,1]
	v_pk_mul_f32 v[164:165], v[112:113], v[152:153] op_sel:[1,1] op_sel_hi:[1,0]
	v_mov_b32_e32 v128, v115
	v_pk_fma_f32 v[170:171], v[112:113], v[152:153], v[164:165] op_sel_hi:[0,1,1] neg_lo:[0,0,1] neg_hi:[0,0,1]
	v_pk_fma_f32 v[152:153], v[112:113], v[152:153], v[164:165] op_sel_hi:[0,1,1]
	v_pk_mul_f32 v[164:165], v[128:129], v[154:155] op_sel:[0,1] op_sel_hi:[0,0]
	v_pk_fma_f32 v[172:173], v[114:115], v[154:155], v[164:165] op_sel_hi:[0,1,1] neg_lo:[0,0,1] neg_hi:[0,0,1]
	v_pk_fma_f32 v[154:155], v[114:115], v[154:155], v[164:165] op_sel_hi:[0,1,1]
	v_mov_b32_e32 v169, v131
	v_mov_b32_e32 v167, v129
	v_pk_mul_f32 v[130:131], v[168:169], s[16:17] op_sel_hi:[1,0]
	v_pk_mul_f32 v[128:129], v[166:167], s[16:17] op_sel_hi:[1,0]
	v_mov_b32_e32 v173, v155
	v_mov_b32_e32 v171, v153
	v_pk_mul_f32 v[154:155], v[172:173], s[16:17] op_sel_hi:[1,0]
	v_pk_mul_f32 v[152:153], v[170:171], s[16:17] op_sel_hi:[1,0]
	v_cvt_pk_bf16_f32 v128, v128, v129
	v_cvt_pk_bf16_f32 v129, v130, v131
	s_nop 0
	v_cvt_pk_bf16_f32 v130, v152, v153
	v_cvt_pk_bf16_f32 v131, v154, v155
	global_store_dwordx4 v[156:157], v[128:131], off offset:256
	v_add_u32_e32 v156, 16, v144
	v_ashrrev_i32_e32 v157, 31, v156
	v_and_b32_e32 v128, s90, v156
	v_lshlrev_b32_e32 v188, 9, v128
	v_lshl_add_u64 v[128:129], s[96:97], 0, v[188:189]
	v_lshl_add_u64 v[152:153], v[128:129], 0, v[150:151]
	global_load_dwordx4 v[128:131], v[152:153], off
	s_nop 0
	global_load_dwordx4 v[152:155], v[152:153], off offset:16
	v_lshlrev_b64 v[156:157], 10, v[156:157]
	v_lshl_add_u64 v[156:157], v[148:149], 0, v[156:157]
	v_lshl_add_u64 v[156:157], v[156:157], 0, s[42:43]
	s_waitcnt vmcnt(0) lgkmcnt(0)
; __device__ __forceinline__ void st8(bf16_t* p, f32x4 a, f32x4 b) { u32x4 w = {cvt_pk(a[0], a[1]), cvt_pk(a[2], a[3]), cvt_pk(b[0], b[1]), cvt_pk(b[2], b[3])}; *(u32x4*)p = w; }
; #define FOR_AI_M _Pragma("unroll") for (int ai = 0; ai < 2; ++ai) if ((__builtin_amdgcn_sched_barrier(0), true)) _Pragma("unroll") for (int m = 0; m < 4; ++m)
;   __device__ __forceinline__ void rope_store(const f32x4 (&acc)[2][2][4][2], bf16_t* dst, float sc, int hsel, int rbase, int wc, int fq) const {
;     const int c0 = wc * 32 + fq * 8, i0 = wc * 16 + fq * 4;
;     FOR_AI_M { const int row = rbase + ai * 128 + m * 16, pos = (b.g0 + row) & b.slm;
;       const f32x4* tp = (const f32x4*)(b.rope + ((size_t)pos * 64 + i0) * 2); const f32x4 t0 = tp[0], t1 = tp[1];
; #pragma unroll
;       for (int bj = 0; bj < 2; ++bj) { f32x4 v0 = acc[ai][bj][m][0], v1 = acc[ai][bj][m][1]; rope4(v0, v1, t0, t1);
;         st8(dst + (size_t)row * 512 + (hsel * 2 + bj) * 128 + c0, v0 * sc, v1 * sc); } }
	v_pk_mul_f32 v[164:165], v[108:109], v[128:129] op_sel:[1,1] op_sel_hi:[1,0]
	s_nop 0
	v_pk_fma_f32 v[166:167], v[108:109], v[128:129], v[164:165] op_sel_hi:[0,1,1] neg_lo:[0,0,1] neg_hi:[0,0,1]
	v_pk_fma_f32 v[164:165], v[108:109], v[128:129], v[164:165] op_sel_hi:[0,1,1]
	v_mov_b32_e32 v164, v111
	v_pk_mul_f32 v[168:169], v[164:165], v[130:131] op_sel:[0,1] op_sel_hi:[0,0]
	v_pk_mul_f32 v[172:173], v[104:105], v[152:153] op_sel:[1,1] op_sel_hi:[1,0]
	v_mov_b32_e32 v164, v107
	v_pk_fma_f32 v[170:171], v[110:111], v[130:131], v[168:169] op_sel_hi:[0,1,1] neg_lo:[0,0,1] neg_hi:[0,0,1]
	v_pk_fma_f32 v[168:169], v[110:111], v[130:131], v[168:169] op_sel_hi:[0,1,1]
	v_pk_fma_f32 v[174:175], v[104:105], v[152:153], v[172:173] op_sel_hi:[0,1,1] neg_lo:[0,0,1] neg_hi:[0,0,1]
	v_pk_fma_f32 v[172:173], v[104:105], v[152:153], v[172:173] op_sel_hi:[0,1,1]
	v_pk_mul_f32 v[176:177], v[164:165], v[154:155] op_sel:[0,1] op_sel_hi:[0,0]
	v_mov_b32_e32 v167, v165
	v_pk_fma_f32 v[178:179], v[106:107], v[154:155], v[176:177] op_sel_hi:[0,1,1] neg_lo:[0,0,1] neg_hi:[0,0,1]
	v_pk_fma_f32 v[176:177], v[106:107], v[154:155], v[176:177] op_sel_hi:[0,1,1]
	v_mov_b32_e32 v171, v169
	v_pk_mul_f32 v[164:165], v[166:167], s[16:17] op_sel_hi:[1,0]
	v_mov_b32_e32 v175, v173
	v_pk_mul_f32 v[168:169], v[170:171], s[16:17] op_sel_hi:[1,0]
	v_mov_b32_e32 v179, v177
	v_pk_mul_f32 v[166:167], v[174:175], s[16:17] op_sel_hi:[1,0]
	v_cvt_pk_bf16_f32 v164, v164, v165
	v_cvt_pk_bf16_f32 v165, v168, v169
	v_pk_mul_f32 v[170:171], v[178:179], s[16:17] op_sel_hi:[1,0]
	v_cvt_pk_bf16_f32 v166, v166, v167
	s_nop 0
	v_cvt_pk_bf16_f32 v167, v170, v171
	global_store_dwordx4 v[156:157], v[164:167], off
	s_nop 1
	v_pk_mul_f32 v[164:165], v[100:101], v[128:129] op_sel:[1,1] op_sel_hi:[1,0]
	s_nop 0
	v_pk_fma_f32 v[166:167], v[100:101], v[128:129], v[164:165] op_sel_hi:[0,1,1] neg_lo:[0,0,1] neg_hi:[0,0,1]
	v_pk_fma_f32 v[128:129], v[100:101], v[128:129], v[164:165] op_sel_hi:[0,1,1]
	v_mov_b32_e32 v128, v103
	v_pk_mul_f32 v[164:165], v[128:129], v[130:131] op_sel:[0,1] op_sel_hi:[0,0]
	v_pk_fma_f32 v[168:169], v[102:103], v[130:131], v[164:165] op_sel_hi:[0,1,1] neg_lo:[0,0,1] neg_hi:[0,0,1]
	v_pk_fma_f32 v[130:131], v[102:103], v[130:131], v[164:165] op_sel_hi:[0,1,1]
	v_pk_mul_f32 v[164:165], v[96:97], v[152:153] op_sel:[1,1] op_sel_hi:[1,0]
	v_mov_b32_e32 v128, v99
	v_pk_fma_f32 v[170:171], v[96:97], v[152:153], v[164:165] op_sel_hi:[0,1,1] neg_lo:[0,0,1] neg_hi:[0,0,1]
	v_pk_fma_f32 v[152:153], v[96:97], v[152:153], v[164:165] op_sel_hi:[0,1,1]
	v_pk_mul_f32 v[164:165], v[128:129], v[154:155] op_sel:[0,1] op_sel_hi:[0,0]
	v_pk_fma_f32 v[172:173], v[98:99], v[154:155], v[164:165] op_sel_hi:[0,1,1] neg_lo:[0,0,1] neg_hi:[0,0,1]
	v_pk_fma_f32 v[154:155], v[98:99], v[154:155], v[164:165] op_sel_hi:[0,1,1]
	v_mov_b32_e32 v169, v131
	v_mov_b32_e32 v167, v129
	v_pk_mul_f32 v[130:131], v[168:169], s[16:17] op_sel_hi:[1,0]
	v_pk_mul_f32 v[128:129], v[166:167], s[16:17] op_sel_hi:[1,0]
	v_mov_b32_e32 v173, v155
	v_mov_b32_e32 v171, v153
	v_pk_mul_f32 v[154:155], v[172:173], s[16:17] op_sel_hi:[1,0]
	v_pk_mul_f32 v[152:153], v[170:171], s[16:17] op_sel_hi:[1,0]
	v_cvt_pk_bf16_f32 v128, v128, v129
	v_cvt_pk_bf16_f32 v129, v130, v131
	s_nop 0
	v_cvt_pk_bf16_f32 v130, v152, v153
	v_cvt_pk_bf16_f32 v131, v154, v155
	global_store_dwordx4 v[156:157], v[128:131], off offset:256
	v_add_u32_e32 v156, 32, v144
	v_ashrrev_i32_e32 v157, 31, v156
	v_and_b32_e32 v128, s90, v156
	v_lshlrev_b32_e32 v188, 9, v128
	v_lshl_add_u64 v[128:129], s[96:97], 0, v[188:189]
	v_lshl_add_u64 v[152:153], v[128:129], 0, v[150:151]
	global_load_dwordx4 v[128:131], v[152:153], off
	s_nop 0
	global_load_dwordx4 v[152:155], v[152:153], off offset:16
	v_lshlrev_b64 v[156:157], 10, v[156:157]
	v_lshl_add_u64 v[156:157], v[148:149], 0, v[156:157]
	v_lshl_add_u64 v[156:157], v[156:157], 0, s[42:43]
	s_waitcnt vmcnt(0) lgkmcnt(0)
	v_pk_mul_f32 v[164:165], v[92:93], v[128:129] op_sel:[1,1] op_sel_hi:[1,0]
	s_nop 0
	v_pk_fma_f32 v[166:167], v[92:93], v[128:129], v[164:165] op_sel_hi:[0,1,1] neg_lo:[0,0,1] neg_hi:[0,0,1]
	v_pk_fma_f32 v[164:165], v[92:93], v[128:129], v[164:165] op_sel_hi:[0,1,1]
	v_mov_b32_e32 v164, v95
	v_pk_mul_f32 v[168:169], v[164:165], v[130:131] op_sel:[0,1] op_sel_hi:[0,0]
	v_pk_mul_f32 v[172:173], v[88:89], v[152:153] op_sel:[1,1] op_sel_hi:[1,0]
	v_mov_b32_e32 v164, v91
	v_pk_fma_f32 v[170:171], v[94:95], v[130:131], v[168:169] op_sel_hi:[0,1,1] neg_lo:[0,0,1] neg_hi:[0,0,1]
	v_pk_fma_f32 v[168:169], v[94:95], v[130:131], v[168:169] op_sel_hi:[0,1,1]
	v_pk_fma_f32 v[174:175], v[88:89], v[152:153], v[172:173] op_sel_hi:[0,1,1] neg_lo:[0,0,1] neg_hi:[0,0,1]
	v_pk_fma_f32 v[172:173], v[88:89], v[152:153], v[172:173] op_sel_hi:[0,1,1]
	v_pk_mul_f32 v[176:177], v[164:165], v[154:155] op_sel:[0,1] op_sel_hi:[0,0]
	v_mov_b32_e32 v167, v165
	v_pk_fma_f32 v[178:179], v[90:91], v[154:155], v[176:177] op_sel_hi:[0,1,1] neg_lo:[0,0,1] neg_hi:[0,0,1]
	v_pk_fma_f32 v[176:177], v[90:91], v[154:155], v[176:177] op_sel_hi:[0,1,1]
	v_mov_b32_e32 v171, v169
	v_pk_mul_f32 v[164:165], v[166:167], s[16:17] op_sel_hi:[1,0]
	v_mov_b32_e32 v175, v173
	v_pk_mul_f32 v[168:169], v[170:171], s[16:17] op_sel_hi:[1,0]
	v_mov_b32_e32 v179, v177
	v_pk_mul_f32 v[166:167], v[174:175], s[16:17] op_sel_hi:[1,0]
	v_cvt_pk_bf16_f32 v164, v164, v165
	v_cvt_pk_bf16_f32 v165, v168, v169
	v_pk_mul_f32 v[170:171], v[178:179], s[16:17] op_sel_hi:[1,0]
	v_cvt_pk_bf16_f32 v166, v166, v167
	s_nop 0
	v_cvt_pk_bf16_f32 v167, v170, v171
	global_store_dwordx4 v[156:157], v[164:167], off
	s_nop 1
	v_pk_mul_f32 v[164:165], v[84:85], v[128:129] op_sel:[1,1] op_sel_hi:[1,0]
; __device__ __forceinline__ void st8(bf16_t* p, f32x4 a, f32x4 b) { u32x4 w = {cvt_pk(a[0], a[1]), cvt_pk(a[2], a[3]), cvt_pk(b[0], b[1]), cvt_pk(b[2], b[3])}; *(u32x4*)p = w; }
; #define FOR_AI_M _Pragma("unroll") for (int ai = 0; ai < 2; ++ai) if ((__builtin_amdgcn_sched_barrier(0), true)) _Pragma("unroll") for (int m = 0; m < 4; ++m)
;   __device__ __forceinline__ void rope_store(const f32x4 (&acc)[2][2][4][2], bf16_t* dst, float sc, int hsel, int rbase, int wc, int fq) const {
;     const int c0 = wc * 32 + fq * 8, i0 = wc * 16 + fq * 4;
;     FOR_AI_M { const int row = rbase + ai * 128 + m * 16, pos = (b.g0 + row) & b.slm;
;       const f32x4* tp = (const f32x4*)(b.rope + ((size_t)pos * 64 + i0) * 2); const f32x4 t0 = tp[0], t1 = tp[1];
; #pragma unroll
;       for (int bj = 0; bj < 2; ++bj) { f32x4 v0 = acc[ai][bj][m][0], v1 = acc[ai][bj][m][1]; rope4(v0, v1, t0, t1);
;         st8(dst + (size_t)row * 512 + (hsel * 2 + bj) * 128 + c0, v0 * sc, v1 * sc); } }
	s_nop 0
	v_pk_fma_f32 v[166:167], v[84:85], v[128:129], v[164:165] op_sel_hi:[0,1,1] neg_lo:[0,0,1] neg_hi:[0,0,1]
	v_pk_fma_f32 v[128:129], v[84:85], v[128:129], v[164:165] op_sel_hi:[0,1,1]
	v_mov_b32_e32 v128, v87
	v_pk_mul_f32 v[164:165], v[128:129], v[130:131] op_sel:[0,1] op_sel_hi:[0,0]
	v_pk_fma_f32 v[168:169], v[86:87], v[130:131], v[164:165] op_sel_hi:[0,1,1] neg_lo:[0,0,1] neg_hi:[0,0,1]
	v_pk_fma_f32 v[130:131], v[86:87], v[130:131], v[164:165] op_sel_hi:[0,1,1]
	v_pk_mul_f32 v[164:165], v[80:81], v[152:153] op_sel:[1,1] op_sel_hi:[1,0]
	v_mov_b32_e32 v128, v83
	v_pk_fma_f32 v[170:171], v[80:81], v[152:153], v[164:165] op_sel_hi:[0,1,1] neg_lo:[0,0,1] neg_hi:[0,0,1]
	v_pk_fma_f32 v[152:153], v[80:81], v[152:153], v[164:165] op_sel_hi:[0,1,1]
	v_pk_mul_f32 v[164:165], v[128:129], v[154:155] op_sel:[0,1] op_sel_hi:[0,0]
	v_mov_b32_e32 v169, v131
	v_mov_b32_e32 v167, v129
	v_mov_b32_e32 v171, v153
	v_pk_fma_f32 v[172:173], v[82:83], v[154:155], v[164:165] op_sel_hi:[0,1,1] neg_lo:[0,0,1] neg_hi:[0,0,1]
	v_pk_fma_f32 v[154:155], v[82:83], v[154:155], v[164:165] op_sel_hi:[0,1,1]
	v_pk_mul_f32 v[130:131], v[168:169], s[16:17] op_sel_hi:[1,0]
	v_pk_mul_f32 v[128:129], v[166:167], s[16:17] op_sel_hi:[1,0]
	v_pk_mul_f32 v[152:153], v[170:171], s[16:17] op_sel_hi:[1,0]
	v_mov_b32_e32 v173, v155
	v_cvt_pk_bf16_f32 v128, v128, v129
	v_cvt_pk_bf16_f32 v129, v130, v131
	v_cvt_pk_bf16_f32 v130, v152, v153
	v_add_u32_e32 v152, 48, v144
	v_pk_mul_f32 v[154:155], v[172:173], s[16:17] op_sel_hi:[1,0]
	v_ashrrev_i32_e32 v153, 31, v152
	v_cvt_pk_bf16_f32 v131, v154, v155
	global_store_dwordx4 v[156:157], v[128:131], off offset:256
	s_nop 1
	v_and_b32_e32 v128, s90, v152
	v_lshlrev_b32_e32 v188, 9, v128
	v_lshl_add_u64 v[128:129], s[96:97], 0, v[188:189]
	v_lshl_add_u64 v[128:129], v[128:129], 0, v[150:151]
	global_load_dwordx4 v[164:167], v[128:129], off
	s_nop 0
	global_load_dwordx4 v[128:131], v[128:129], off offset:16
	v_lshlrev_b64 v[152:153], 10, v[152:153]
	v_lshl_add_u64 v[152:153], v[148:149], 0, v[152:153]
	v_lshl_add_u64 v[152:153], v[152:153], 0, s[42:43]
	s_waitcnt vmcnt(0) lgkmcnt(0)
	v_pk_mul_f32 v[154:155], v[76:77], v[164:165] op_sel:[1,1] op_sel_hi:[1,0]
	s_nop 0
	v_pk_fma_f32 v[156:157], v[76:77], v[164:165], v[154:155] op_sel_hi:[0,1,1] neg_lo:[0,0,1] neg_hi:[0,0,1]
	v_pk_fma_f32 v[154:155], v[76:77], v[164:165], v[154:155] op_sel_hi:[0,1,1]
	v_mov_b32_e32 v154, v79
	v_pk_mul_f32 v[168:169], v[154:155], v[166:167] op_sel:[0,1] op_sel_hi:[0,0]
	v_pk_mul_f32 v[172:173], v[72:73], v[128:129] op_sel:[1,1] op_sel_hi:[1,0]
	v_mov_b32_e32 v154, v75
	v_pk_fma_f32 v[174:175], v[72:73], v[128:129], v[172:173] op_sel_hi:[0,1,1] neg_lo:[0,0,1] neg_hi:[0,0,1]
	v_pk_fma_f32 v[172:173], v[72:73], v[128:129], v[172:173] op_sel_hi:[0,1,1]
	v_pk_mul_f32 v[176:177], v[154:155], v[130:131] op_sel:[0,1] op_sel_hi:[0,0]
	v_pk_fma_f32 v[170:171], v[78:79], v[166:167], v[168:169] op_sel_hi:[0,1,1] neg_lo:[0,0,1] neg_hi:[0,0,1]
	v_pk_fma_f32 v[168:169], v[78:79], v[166:167], v[168:169] op_sel_hi:[0,1,1]
	v_pk_fma_f32 v[178:179], v[74:75], v[130:131], v[176:177] op_sel_hi:[0,1,1] neg_lo:[0,0,1] neg_hi:[0,0,1]
	v_pk_fma_f32 v[176:177], v[74:75], v[130:131], v[176:177] op_sel_hi:[0,1,1]
	v_mov_b32_e32 v157, v155
	v_mov_b32_e32 v175, v173
	v_mov_b32_e32 v171, v169
	v_pk_mul_f32 v[154:155], v[156:157], s[16:17] op_sel_hi:[1,0]
	v_mov_b32_e32 v179, v177
	v_pk_mul_f32 v[156:157], v[174:175], s[16:17] op_sel_hi:[1,0]
	v_pk_mul_f32 v[168:169], v[170:171], s[16:17] op_sel_hi:[1,0]
	v_pk_mul_f32 v[170:171], v[178:179], s[16:17] op_sel_hi:[1,0]
	v_cvt_pk_bf16_f32 v154, v154, v155
	v_cvt_pk_bf16_f32 v155, v168, v169
	v_cvt_pk_bf16_f32 v156, v156, v157
	s_nop 0
	v_cvt_pk_bf16_f32 v157, v170, v171
	global_store_dwordx4 v[152:153], v[154:157], off
	s_nop 1
	v_pk_mul_f32 v[156:157], v[68:69], v[164:165] op_sel:[1,1] op_sel_hi:[1,0]
	s_nop 0
	v_pk_fma_f32 v[154:155], v[68:69], v[164:165], v[156:157] op_sel_hi:[0,1,1] neg_lo:[0,0,1] neg_hi:[0,0,1]
	v_pk_fma_f32 v[156:157], v[68:69], v[164:165], v[156:157] op_sel_hi:[0,1,1]
	v_mov_b32_e32 v156, v71
	v_pk_mul_f32 v[164:165], v[156:157], v[166:167] op_sel:[0,1] op_sel_hi:[0,0]
	v_pk_fma_f32 v[168:169], v[70:71], v[166:167], v[164:165] op_sel_hi:[0,1,1] neg_lo:[0,0,1] neg_hi:[0,0,1]
	v_pk_fma_f32 v[164:165], v[70:71], v[166:167], v[164:165] op_sel_hi:[0,1,1]
	v_pk_mul_f32 v[166:167], v[64:65], v[128:129] op_sel:[1,1] op_sel_hi:[1,0]
	v_mov_b32_e32 v169, v165
	v_pk_fma_f32 v[170:171], v[64:65], v[128:129], v[166:167] op_sel_hi:[0,1,1] neg_lo:[0,0,1] neg_hi:[0,0,1]
	v_pk_fma_f32 v[128:129], v[64:65], v[128:129], v[166:167] op_sel_hi:[0,1,1]
	v_mov_b32_e32 v128, v67
	v_pk_mul_f32 v[166:167], v[128:129], v[130:131] op_sel:[0,1] op_sel_hi:[0,0]
	v_pk_fma_f32 v[172:173], v[66:67], v[130:131], v[166:167] op_sel_hi:[0,1,1] neg_lo:[0,0,1] neg_hi:[0,0,1]
	v_pk_fma_f32 v[130:131], v[66:67], v[130:131], v[166:167] op_sel_hi:[0,1,1]
	v_mov_b32_e32 v171, v129
	v_mov_b32_e32 v155, v157
	v_mov_b32_e32 v173, v131
	v_pk_mul_f32 v[130:131], v[170:171], s[16:17] op_sel_hi:[1,0]
	v_pk_mul_f32 v[164:165], v[168:169], s[16:17] op_sel_hi:[1,0]
	v_pk_mul_f32 v[154:155], v[154:155], s[16:17] op_sel_hi:[1,0]
	v_pk_mul_f32 v[156:157], v[172:173], s[16:17] op_sel_hi:[1,0]
	v_cvt_pk_bf16_f32 v128, v154, v155
	v_cvt_pk_bf16_f32 v129, v164, v165
	v_cvt_pk_bf16_f32 v130, v130, v131
	s_nop 0
	v_cvt_pk_bf16_f32 v131, v156, v157
	global_store_dwordx4 v[152:153], v[128:131], off offset:256
	v_add_u32_e32 v156, 0x80, v144
	s_nop 0
	v_and_b32_e32 v128, s90, v156
	v_lshlrev_b32_e32 v188, 9, v128
	v_lshl_add_u64 v[128:129], s[96:97], 0, v[188:189]
	v_lshl_add_u64 v[152:153], v[128:129], 0, v[150:151]
	global_load_dwordx4 v[128:131], v[152:153], off
	s_nop 0
	global_load_dwordx4 v[152:155], v[152:153], off offset:16
	v_ashrrev_i32_e32 v157, 31, v156
	v_lshlrev_b64 v[156:157], 10, v[156:157]
	v_lshl_add_u64 v[156:157], v[148:149], 0, v[156:157]
	v_lshl_add_u64 v[156:157], v[156:157], 0, s[42:43]
	s_waitcnt vmcnt(0) lgkmcnt(0)
; __device__ __forceinline__ void st8(bf16_t* p, f32x4 a, f32x4 b) { u32x4 w = {cvt_pk(a[0], a[1]), cvt_pk(a[2], a[3]), cvt_pk(b[0], b[1]), cvt_pk(b[2], b[3])}; *(u32x4*)p = w; }
; #define FOR_AI_M _Pragma("unroll") for (int ai = 0; ai < 2; ++ai) if ((__builtin_amdgcn_sched_barrier(0), true)) _Pragma("unroll") for (int m = 0; m < 4; ++m)
;   __device__ __forceinline__ void rope_store(const f32x4 (&acc)[2][2][4][2], bf16_t* dst, float sc, int hsel, int rbase, int wc, int fq) const {
;     const int c0 = wc * 32 + fq * 8, i0 = wc * 16 + fq * 4;
;     FOR_AI_M { const int row = rbase + ai * 128 + m * 16, pos = (b.g0 + row) & b.slm;
;       const f32x4* tp = (const f32x4*)(b.rope + ((size_t)pos * 64 + i0) * 2); const f32x4 t0 = tp[0], t1 = tp[1];
; #pragma unroll
;       for (int bj = 0; bj < 2; ++bj) { f32x4 v0 = acc[ai][bj][m][0], v1 = acc[ai][bj][m][1]; rope4(v0, v1, t0, t1);
;         st8(dst + (size_t)row * 512 + (hsel * 2 + bj) * 128 + c0, v0 * sc, v1 * sc); } }
	v_pk_mul_f32 v[164:165], v[60:61], v[128:129] op_sel:[1,1] op_sel_hi:[1,0]
	s_nop 0
	v_pk_fma_f32 v[166:167], v[60:61], v[128:129], v[164:165] op_sel_hi:[0,1,1] neg_lo:[0,0,1] neg_hi:[0,0,1]
	v_pk_fma_f32 v[164:165], v[60:61], v[128:129], v[164:165] op_sel_hi:[0,1,1]
	v_mov_b32_e32 v164, v63
	v_pk_mul_f32 v[168:169], v[164:165], v[130:131] op_sel:[0,1] op_sel_hi:[0,0]
	v_pk_mul_f32 v[172:173], v[56:57], v[152:153] op_sel:[1,1] op_sel_hi:[1,0]
	v_mov_b32_e32 v164, v59
	v_pk_fma_f32 v[170:171], v[62:63], v[130:131], v[168:169] op_sel_hi:[0,1,1] neg_lo:[0,0,1] neg_hi:[0,0,1]
	v_pk_fma_f32 v[168:169], v[62:63], v[130:131], v[168:169] op_sel_hi:[0,1,1]
	v_pk_fma_f32 v[174:175], v[56:57], v[152:153], v[172:173] op_sel_hi:[0,1,1] neg_lo:[0,0,1] neg_hi:[0,0,1]
	v_pk_fma_f32 v[172:173], v[56:57], v[152:153], v[172:173] op_sel_hi:[0,1,1]
	v_pk_mul_f32 v[176:177], v[164:165], v[154:155] op_sel:[0,1] op_sel_hi:[0,0]
	v_mov_b32_e32 v167, v165
	v_pk_fma_f32 v[178:179], v[58:59], v[154:155], v[176:177] op_sel_hi:[0,1,1] neg_lo:[0,0,1] neg_hi:[0,0,1]
	v_pk_fma_f32 v[176:177], v[58:59], v[154:155], v[176:177] op_sel_hi:[0,1,1]
	v_mov_b32_e32 v171, v169
	v_pk_mul_f32 v[164:165], v[166:167], s[16:17] op_sel_hi:[1,0]
	v_mov_b32_e32 v175, v173
	v_pk_mul_f32 v[168:169], v[170:171], s[16:17] op_sel_hi:[1,0]
	v_mov_b32_e32 v179, v177
	v_pk_mul_f32 v[166:167], v[174:175], s[16:17] op_sel_hi:[1,0]
	v_cvt_pk_bf16_f32 v164, v164, v165
	v_cvt_pk_bf16_f32 v165, v168, v169
	v_pk_mul_f32 v[170:171], v[178:179], s[16:17] op_sel_hi:[1,0]
	v_cvt_pk_bf16_f32 v166, v166, v167
	s_nop 0
	v_cvt_pk_bf16_f32 v167, v170, v171
	global_store_dwordx4 v[156:157], v[164:167], off
	s_nop 1
	v_pk_mul_f32 v[164:165], v[52:53], v[128:129] op_sel:[1,1] op_sel_hi:[1,0]
	s_nop 0
	v_pk_fma_f32 v[166:167], v[52:53], v[128:129], v[164:165] op_sel_hi:[0,1,1] neg_lo:[0,0,1] neg_hi:[0,0,1]
	v_pk_fma_f32 v[128:129], v[52:53], v[128:129], v[164:165] op_sel_hi:[0,1,1]
	v_mov_b32_e32 v128, v55
	v_pk_mul_f32 v[164:165], v[128:129], v[130:131] op_sel:[0,1] op_sel_hi:[0,0]
	v_pk_fma_f32 v[168:169], v[54:55], v[130:131], v[164:165] op_sel_hi:[0,1,1] neg_lo:[0,0,1] neg_hi:[0,0,1]
	v_pk_fma_f32 v[130:131], v[54:55], v[130:131], v[164:165] op_sel_hi:[0,1,1]
	v_pk_mul_f32 v[164:165], v[48:49], v[152:153] op_sel:[1,1] op_sel_hi:[1,0]
	v_mov_b32_e32 v128, v51
	v_pk_fma_f32 v[170:171], v[48:49], v[152:153], v[164:165] op_sel_hi:[0,1,1] neg_lo:[0,0,1] neg_hi:[0,0,1]
	v_pk_fma_f32 v[152:153], v[48:49], v[152:153], v[164:165] op_sel_hi:[0,1,1]
	v_pk_mul_f32 v[164:165], v[128:129], v[154:155] op_sel:[0,1] op_sel_hi:[0,0]
	v_pk_fma_f32 v[172:173], v[50:51], v[154:155], v[164:165] op_sel_hi:[0,1,1] neg_lo:[0,0,1] neg_hi:[0,0,1]
	v_pk_fma_f32 v[154:155], v[50:51], v[154:155], v[164:165] op_sel_hi:[0,1,1]
	v_mov_b32_e32 v169, v131
	v_mov_b32_e32 v167, v129
	v_pk_mul_f32 v[130:131], v[168:169], s[16:17] op_sel_hi:[1,0]
	v_pk_mul_f32 v[128:129], v[166:167], s[16:17] op_sel_hi:[1,0]
	v_mov_b32_e32 v173, v155
	v_mov_b32_e32 v171, v153
	v_pk_mul_f32 v[154:155], v[172:173], s[16:17] op_sel_hi:[1,0]
	v_pk_mul_f32 v[152:153], v[170:171], s[16:17] op_sel_hi:[1,0]
	v_cvt_pk_bf16_f32 v128, v128, v129
	v_cvt_pk_bf16_f32 v129, v130, v131
	s_nop 0
	v_cvt_pk_bf16_f32 v130, v152, v153
	v_cvt_pk_bf16_f32 v131, v154, v155
	global_store_dwordx4 v[156:157], v[128:131], off offset:256
	v_add_u32_e32 v156, 0x90, v144
	v_ashrrev_i32_e32 v157, 31, v156
	v_and_b32_e32 v128, s90, v156
	v_lshlrev_b32_e32 v188, 9, v128
	v_lshl_add_u64 v[128:129], s[96:97], 0, v[188:189]
	v_lshl_add_u64 v[152:153], v[128:129], 0, v[150:151]
	global_load_dwordx4 v[128:131], v[152:153], off
	s_nop 0
	global_load_dwordx4 v[152:155], v[152:153], off offset:16
	v_lshlrev_b64 v[156:157], 10, v[156:157]
	v_lshl_add_u64 v[156:157], v[148:149], 0, v[156:157]
	v_lshl_add_u64 v[156:157], v[156:157], 0, s[42:43]
	s_waitcnt vmcnt(0) lgkmcnt(0)
	v_pk_mul_f32 v[164:165], v[44:45], v[128:129] op_sel:[1,1] op_sel_hi:[1,0]
	s_nop 0
	v_pk_fma_f32 v[166:167], v[44:45], v[128:129], v[164:165] op_sel_hi:[0,1,1] neg_lo:[0,0,1] neg_hi:[0,0,1]
	v_pk_fma_f32 v[164:165], v[44:45], v[128:129], v[164:165] op_sel_hi:[0,1,1]
	v_mov_b32_e32 v164, v47
	v_pk_mul_f32 v[168:169], v[164:165], v[130:131] op_sel:[0,1] op_sel_hi:[0,0]
	v_pk_mul_f32 v[172:173], v[40:41], v[152:153] op_sel:[1,1] op_sel_hi:[1,0]
	v_mov_b32_e32 v164, v43
	v_pk_fma_f32 v[170:171], v[46:47], v[130:131], v[168:169] op_sel_hi:[0,1,1] neg_lo:[0,0,1] neg_hi:[0,0,1]
	v_pk_fma_f32 v[168:169], v[46:47], v[130:131], v[168:169] op_sel_hi:[0,1,1]
	v_pk_fma_f32 v[174:175], v[40:41], v[152:153], v[172:173] op_sel_hi:[0,1,1] neg_lo:[0,0,1] neg_hi:[0,0,1]
	v_pk_fma_f32 v[172:173], v[40:41], v[152:153], v[172:173] op_sel_hi:[0,1,1]
	v_pk_mul_f32 v[176:177], v[164:165], v[154:155] op_sel:[0,1] op_sel_hi:[0,0]
	v_mov_b32_e32 v167, v165
	v_pk_fma_f32 v[178:179], v[42:43], v[154:155], v[176:177] op_sel_hi:[0,1,1] neg_lo:[0,0,1] neg_hi:[0,0,1]
	v_pk_fma_f32 v[176:177], v[42:43], v[154:155], v[176:177] op_sel_hi:[0,1,1]
	v_mov_b32_e32 v171, v169
	v_pk_mul_f32 v[164:165], v[166:167], s[16:17] op_sel_hi:[1,0]
	v_mov_b32_e32 v175, v173
	v_pk_mul_f32 v[168:169], v[170:171], s[16:17] op_sel_hi:[1,0]
	v_mov_b32_e32 v179, v177
	v_pk_mul_f32 v[166:167], v[174:175], s[16:17] op_sel_hi:[1,0]
	v_cvt_pk_bf16_f32 v164, v164, v165
	v_cvt_pk_bf16_f32 v165, v168, v169
	v_pk_mul_f32 v[170:171], v[178:179], s[16:17] op_sel_hi:[1,0]
	v_cvt_pk_bf16_f32 v166, v166, v167
	s_nop 0
	v_cvt_pk_bf16_f32 v167, v170, v171
	global_store_dwordx4 v[156:157], v[164:167], off
	s_nop 1
	v_pk_mul_f32 v[164:165], v[36:37], v[128:129] op_sel:[1,1] op_sel_hi:[1,0]
	s_nop 0
; __device__ __forceinline__ void st8(bf16_t* p, f32x4 a, f32x4 b) { u32x4 w = {cvt_pk(a[0], a[1]), cvt_pk(a[2], a[3]), cvt_pk(b[0], b[1]), cvt_pk(b[2], b[3])}; *(u32x4*)p = w; }
; #define FOR_AI_M _Pragma("unroll") for (int ai = 0; ai < 2; ++ai) if ((__builtin_amdgcn_sched_barrier(0), true)) _Pragma("unroll") for (int m = 0; m < 4; ++m)
;   __device__ __forceinline__ void rope_store(const f32x4 (&acc)[2][2][4][2], bf16_t* dst, float sc, int hsel, int rbase, int wc, int fq) const {
;     const int c0 = wc * 32 + fq * 8, i0 = wc * 16 + fq * 4;
;     FOR_AI_M { const int row = rbase + ai * 128 + m * 16, pos = (b.g0 + row) & b.slm;
;       const f32x4* tp = (const f32x4*)(b.rope + ((size_t)pos * 64 + i0) * 2); const f32x4 t0 = tp[0], t1 = tp[1];
; #pragma unroll
;       for (int bj = 0; bj < 2; ++bj) { f32x4 v0 = acc[ai][bj][m][0], v1 = acc[ai][bj][m][1]; rope4(v0, v1, t0, t1);
;         st8(dst + (size_t)row * 512 + (hsel * 2 + bj) * 128 + c0, v0 * sc, v1 * sc); } }
	v_pk_fma_f32 v[166:167], v[36:37], v[128:129], v[164:165] op_sel_hi:[0,1,1] neg_lo:[0,0,1] neg_hi:[0,0,1]
	v_pk_fma_f32 v[128:129], v[36:37], v[128:129], v[164:165] op_sel_hi:[0,1,1]
	v_mov_b32_e32 v128, v39
	v_pk_mul_f32 v[164:165], v[128:129], v[130:131] op_sel:[0,1] op_sel_hi:[0,0]
	v_pk_fma_f32 v[168:169], v[38:39], v[130:131], v[164:165] op_sel_hi:[0,1,1] neg_lo:[0,0,1] neg_hi:[0,0,1]
	v_pk_fma_f32 v[130:131], v[38:39], v[130:131], v[164:165] op_sel_hi:[0,1,1]
	v_pk_mul_f32 v[164:165], v[32:33], v[152:153] op_sel:[1,1] op_sel_hi:[1,0]
	v_mov_b32_e32 v128, v35
	v_pk_fma_f32 v[170:171], v[32:33], v[152:153], v[164:165] op_sel_hi:[0,1,1] neg_lo:[0,0,1] neg_hi:[0,0,1]
	v_pk_fma_f32 v[152:153], v[32:33], v[152:153], v[164:165] op_sel_hi:[0,1,1]
	v_pk_mul_f32 v[164:165], v[128:129], v[154:155] op_sel:[0,1] op_sel_hi:[0,0]
	v_pk_fma_f32 v[172:173], v[34:35], v[154:155], v[164:165] op_sel_hi:[0,1,1] neg_lo:[0,0,1] neg_hi:[0,0,1]
	v_pk_fma_f32 v[154:155], v[34:35], v[154:155], v[164:165] op_sel_hi:[0,1,1]
	v_mov_b32_e32 v169, v131
	v_mov_b32_e32 v167, v129
	v_pk_mul_f32 v[130:131], v[168:169], s[16:17] op_sel_hi:[1,0]
	v_pk_mul_f32 v[128:129], v[166:167], s[16:17] op_sel_hi:[1,0]
	v_mov_b32_e32 v173, v155
	v_mov_b32_e32 v171, v153
	v_pk_mul_f32 v[154:155], v[172:173], s[16:17] op_sel_hi:[1,0]
	v_pk_mul_f32 v[152:153], v[170:171], s[16:17] op_sel_hi:[1,0]
	v_cvt_pk_bf16_f32 v128, v128, v129
	v_cvt_pk_bf16_f32 v129, v130, v131
	s_nop 0
	v_cvt_pk_bf16_f32 v130, v152, v153
	v_cvt_pk_bf16_f32 v131, v154, v155
	global_store_dwordx4 v[156:157], v[128:131], off offset:256
	v_add_u32_e32 v156, 0xa0, v144
	v_ashrrev_i32_e32 v157, 31, v156
	v_and_b32_e32 v128, s90, v156
	v_lshlrev_b32_e32 v188, 9, v128
	v_lshl_add_u64 v[128:129], s[96:97], 0, v[188:189]
	v_lshl_add_u64 v[152:153], v[128:129], 0, v[150:151]
	global_load_dwordx4 v[128:131], v[152:153], off
	s_nop 0
	global_load_dwordx4 v[152:155], v[152:153], off offset:16
	v_lshlrev_b64 v[156:157], 10, v[156:157]
	v_lshl_add_u64 v[156:157], v[148:149], 0, v[156:157]
	v_lshl_add_u64 v[156:157], v[156:157], 0, s[42:43]
	s_waitcnt vmcnt(0) lgkmcnt(0)
	v_pk_mul_f32 v[164:165], v[28:29], v[128:129] op_sel:[1,1] op_sel_hi:[1,0]
	s_nop 0
	v_pk_fma_f32 v[166:167], v[28:29], v[128:129], v[164:165] op_sel_hi:[0,1,1] neg_lo:[0,0,1] neg_hi:[0,0,1]
	v_pk_fma_f32 v[164:165], v[28:29], v[128:129], v[164:165] op_sel_hi:[0,1,1]
	v_mov_b32_e32 v164, v31
	v_pk_mul_f32 v[168:169], v[164:165], v[130:131] op_sel:[0,1] op_sel_hi:[0,0]
	v_pk_mul_f32 v[172:173], v[24:25], v[152:153] op_sel:[1,1] op_sel_hi:[1,0]
	v_mov_b32_e32 v164, v27
	v_pk_fma_f32 v[170:171], v[30:31], v[130:131], v[168:169] op_sel_hi:[0,1,1] neg_lo:[0,0,1] neg_hi:[0,0,1]
	v_pk_fma_f32 v[168:169], v[30:31], v[130:131], v[168:169] op_sel_hi:[0,1,1]
	v_pk_fma_f32 v[174:175], v[24:25], v[152:153], v[172:173] op_sel_hi:[0,1,1] neg_lo:[0,0,1] neg_hi:[0,0,1]
	v_pk_fma_f32 v[172:173], v[24:25], v[152:153], v[172:173] op_sel_hi:[0,1,1]
	v_pk_mul_f32 v[176:177], v[164:165], v[154:155] op_sel:[0,1] op_sel_hi:[0,0]
	v_mov_b32_e32 v167, v165
	v_pk_fma_f32 v[178:179], v[26:27], v[154:155], v[176:177] op_sel_hi:[0,1,1] neg_lo:[0,0,1] neg_hi:[0,0,1]
	v_pk_fma_f32 v[176:177], v[26:27], v[154:155], v[176:177] op_sel_hi:[0,1,1]
	v_mov_b32_e32 v171, v169
	v_pk_mul_f32 v[164:165], v[166:167], s[16:17] op_sel_hi:[1,0]
	v_mov_b32_e32 v175, v173
	v_pk_mul_f32 v[168:169], v[170:171], s[16:17] op_sel_hi:[1,0]
	v_mov_b32_e32 v179, v177
	v_pk_mul_f32 v[166:167], v[174:175], s[16:17] op_sel_hi:[1,0]
	v_cvt_pk_bf16_f32 v164, v164, v165
	v_cvt_pk_bf16_f32 v165, v168, v169
	v_pk_mul_f32 v[170:171], v[178:179], s[16:17] op_sel_hi:[1,0]
	v_cvt_pk_bf16_f32 v166, v166, v167
	s_nop 0
	v_cvt_pk_bf16_f32 v167, v170, v171
	global_store_dwordx4 v[156:157], v[164:167], off
	s_nop 1
	v_pk_mul_f32 v[164:165], v[20:21], v[128:129] op_sel:[1,1] op_sel_hi:[1,0]
	s_nop 0
	v_pk_fma_f32 v[166:167], v[20:21], v[128:129], v[164:165] op_sel_hi:[0,1,1] neg_lo:[0,0,1] neg_hi:[0,0,1]
	v_pk_fma_f32 v[128:129], v[20:21], v[128:129], v[164:165] op_sel_hi:[0,1,1]
	v_mov_b32_e32 v128, v23
	v_pk_mul_f32 v[164:165], v[128:129], v[130:131] op_sel:[0,1] op_sel_hi:[0,0]
	v_pk_fma_f32 v[168:169], v[22:23], v[130:131], v[164:165] op_sel_hi:[0,1,1] neg_lo:[0,0,1] neg_hi:[0,0,1]
	v_pk_fma_f32 v[130:131], v[22:23], v[130:131], v[164:165] op_sel_hi:[0,1,1]
	v_pk_mul_f32 v[164:165], v[16:17], v[152:153] op_sel:[1,1] op_sel_hi:[1,0]
	v_mov_b32_e32 v128, v19
	v_pk_fma_f32 v[170:171], v[16:17], v[152:153], v[164:165] op_sel_hi:[0,1,1] neg_lo:[0,0,1] neg_hi:[0,0,1]
	v_pk_fma_f32 v[152:153], v[16:17], v[152:153], v[164:165] op_sel_hi:[0,1,1]
	v_pk_mul_f32 v[164:165], v[128:129], v[154:155] op_sel:[0,1] op_sel_hi:[0,0]
	v_pk_fma_f32 v[172:173], v[18:19], v[154:155], v[164:165] op_sel_hi:[0,1,1] neg_lo:[0,0,1] neg_hi:[0,0,1]
	v_pk_fma_f32 v[154:155], v[18:19], v[154:155], v[164:165] op_sel_hi:[0,1,1]
	v_mov_b32_e32 v169, v131
	v_mov_b32_e32 v167, v129
	v_pk_mul_f32 v[130:131], v[168:169], s[16:17] op_sel_hi:[1,0]
	v_pk_mul_f32 v[128:129], v[166:167], s[16:17] op_sel_hi:[1,0]
	v_mov_b32_e32 v173, v155
	v_mov_b32_e32 v171, v153
	v_pk_mul_f32 v[154:155], v[172:173], s[16:17] op_sel_hi:[1,0]
	v_pk_mul_f32 v[152:153], v[170:171], s[16:17] op_sel_hi:[1,0]
	v_cvt_pk_bf16_f32 v128, v128, v129
	v_cvt_pk_bf16_f32 v129, v130, v131
	s_nop 0
	v_cvt_pk_bf16_f32 v130, v152, v153
	v_cvt_pk_bf16_f32 v131, v154, v155
	global_store_dwordx4 v[156:157], v[128:131], off offset:256
	v_add_u32_e32 v156, 0xb0, v144
	v_ashrrev_i32_e32 v157, 31, v156
	v_and_b32_e32 v128, s90, v156
	v_lshlrev_b32_e32 v188, 9, v128
	v_lshl_add_u64 v[128:129], s[96:97], 0, v[188:189]
	v_lshl_add_u64 v[128:129], v[128:129], 0, v[150:151]
	global_load_dwordx4 v[152:155], v[128:129], off
	s_nop 0
	global_load_dwordx4 v[128:131], v[128:129], off offset:16
	v_lshlrev_b64 v[150:151], 10, v[156:157]
	v_lshl_add_u64 v[148:149], v[148:149], 0, v[150:151]
	v_lshl_add_u64 v[148:149], v[148:149], 0, s[42:43]
	s_waitcnt vmcnt(0) lgkmcnt(0)
; __device__ __forceinline__ void st8(bf16_t* p, f32x4 a, f32x4 b) { u32x4 w = {cvt_pk(a[0], a[1]), cvt_pk(a[2], a[3]), cvt_pk(b[0], b[1]), cvt_pk(b[2], b[3])}; *(u32x4*)p = w; }
; #define FOR_AI_M _Pragma("unroll") for (int ai = 0; ai < 2; ++ai) if ((__builtin_amdgcn_sched_barrier(0), true)) _Pragma("unroll") for (int m = 0; m < 4; ++m)
;   __device__ __forceinline__ void rope_store(const f32x4 (&acc)[2][2][4][2], bf16_t* dst, float sc, int hsel, int rbase, int wc, int fq) const {
;     const int c0 = wc * 32 + fq * 8, i0 = wc * 16 + fq * 4;
;     FOR_AI_M { const int row = rbase + ai * 128 + m * 16, pos = (b.g0 + row) & b.slm;
;       const f32x4* tp = (const f32x4*)(b.rope + ((size_t)pos * 64 + i0) * 2); const f32x4 t0 = tp[0], t1 = tp[1];
; #pragma unroll
;       for (int bj = 0; bj < 2; ++bj) { f32x4 v0 = acc[ai][bj][m][0], v1 = acc[ai][bj][m][1]; rope4(v0, v1, t0, t1);
;         st8(dst + (size_t)row * 512 + (hsel * 2 + bj) * 128 + c0, v0 * sc, v1 * sc); } }
	v_pk_mul_f32 v[150:151], v[12:13], v[152:153] op_sel:[1,1] op_sel_hi:[1,0]
	s_nop 0
	v_pk_fma_f32 v[156:157], v[12:13], v[152:153], v[150:151] op_sel_hi:[0,1,1] neg_lo:[0,0,1] neg_hi:[0,0,1]
	v_pk_fma_f32 v[150:151], v[12:13], v[152:153], v[150:151] op_sel_hi:[0,1,1]
	v_mov_b32_e32 v150, v15
	v_pk_mul_f32 v[164:165], v[150:151], v[154:155] op_sel:[0,1] op_sel_hi:[0,0]
	v_mov_b32_e32 v150, v11
	v_pk_mul_f32 v[172:173], v[150:151], v[130:131] op_sel:[0,1] op_sel_hi:[0,0]
	v_pk_fma_f32 v[166:167], v[14:15], v[154:155], v[164:165] op_sel_hi:[0,1,1] neg_lo:[0,0,1] neg_hi:[0,0,1]
	v_pk_fma_f32 v[164:165], v[14:15], v[154:155], v[164:165] op_sel_hi:[0,1,1]
	v_pk_mul_f32 v[168:169], v[8:9], v[128:129] op_sel:[1,1] op_sel_hi:[1,0]
	v_pk_fma_f32 v[174:175], v[10:11], v[130:131], v[172:173] op_sel_hi:[0,1,1] neg_lo:[0,0,1] neg_hi:[0,0,1]
	v_pk_fma_f32 v[172:173], v[10:11], v[130:131], v[172:173] op_sel_hi:[0,1,1]
	v_pk_fma_f32 v[170:171], v[8:9], v[128:129], v[168:169] op_sel_hi:[0,1,1] neg_lo:[0,0,1] neg_hi:[0,0,1]
	v_pk_fma_f32 v[168:169], v[8:9], v[128:129], v[168:169] op_sel_hi:[0,1,1]
	v_mov_b32_e32 v167, v165
	v_mov_b32_e32 v157, v151
	v_mov_b32_e32 v175, v173
	v_pk_mul_f32 v[166:167], v[166:167], s[16:17] op_sel_hi:[1,0]
	v_pk_mul_f32 v[150:151], v[156:157], s[16:17] op_sel_hi:[1,0]
	v_pk_mul_f32 v[156:157], v[174:175], s[16:17] op_sel_hi:[1,0]
	v_mov_b32_e32 v171, v169
	v_pk_mul_f32 v[168:169], v[170:171], s[16:17] op_sel_hi:[1,0]
	v_cvt_pk_bf16_f32 v164, v150, v151
	v_cvt_pk_bf16_f32 v165, v166, v167
	s_nop 0
	v_cvt_pk_bf16_f32 v166, v168, v169
	v_cvt_pk_bf16_f32 v167, v156, v157
	v_pk_mul_f32 v[156:157], v[4:5], v[152:153] op_sel:[1,1] op_sel_hi:[1,0]
	global_store_dwordx4 v[148:149], v[164:167], off
	v_pk_fma_f32 v[150:151], v[4:5], v[152:153], v[156:157] op_sel_hi:[0,1,1] neg_lo:[0,0,1] neg_hi:[0,0,1]
	v_pk_fma_f32 v[152:153], v[4:5], v[152:153], v[156:157] op_sel_hi:[0,1,1]
	v_mov_b32_e32 v152, v7
	v_pk_mul_f32 v[156:157], v[152:153], v[154:155] op_sel:[0,1] op_sel_hi:[0,0]
	v_pk_fma_f32 v[164:165], v[6:7], v[154:155], v[156:157] op_sel_hi:[0,1,1] neg_lo:[0,0,1] neg_hi:[0,0,1]
	v_pk_fma_f32 v[154:155], v[6:7], v[154:155], v[156:157] op_sel_hi:[0,1,1]
	v_pk_mul_f32 v[156:157], v[0:1], v[128:129] op_sel:[1,1] op_sel_hi:[1,0]
	v_mov_b32_e32 v165, v155
	v_pk_fma_f32 v[166:167], v[0:1], v[128:129], v[156:157] op_sel_hi:[0,1,1] neg_lo:[0,0,1] neg_hi:[0,0,1]
	v_pk_fma_f32 v[128:129], v[0:1], v[128:129], v[156:157] op_sel_hi:[0,1,1]
	v_mov_b32_e32 v128, v3
	v_pk_mul_f32 v[156:157], v[128:129], v[130:131] op_sel:[0,1] op_sel_hi:[0,0]
	v_pk_fma_f32 v[168:169], v[2:3], v[130:131], v[156:157] op_sel_hi:[0,1,1] neg_lo:[0,0,1] neg_hi:[0,0,1]
	v_pk_fma_f32 v[130:131], v[2:3], v[130:131], v[156:157] op_sel_hi:[0,1,1]
	v_mov_b32_e32 v167, v129
	v_mov_b32_e32 v151, v153
	v_mov_b32_e32 v169, v131
	v_pk_mul_f32 v[130:131], v[166:167], s[16:17] op_sel_hi:[1,0]
	v_pk_mul_f32 v[154:155], v[164:165], s[16:17] op_sel_hi:[1,0]
	v_pk_mul_f32 v[150:151], v[150:151], s[16:17] op_sel_hi:[1,0]
	v_pk_mul_f32 v[152:153], v[168:169], s[16:17] op_sel_hi:[1,0]
	v_cvt_pk_bf16_f32 v128, v150, v151
	v_cvt_pk_bf16_f32 v129, v154, v155
	v_cvt_pk_bf16_f32 v130, v130, v131
	s_nop 0
	v_cvt_pk_bf16_f32 v131, v152, v153
	global_store_dwordx4 v[148:149], v[128:131], off offset:256

; __device__ __forceinline__ void st8(bf16_t* p, f32x4 a, f32x4 b) { u32x4 w = {cvt_pk(a[0], a[1]), cvt_pk(a[2], a[3]), cvt_pk(b[0], b[1]), cvt_pk(b[2], b[3])}; *(u32x4*)p = w; }
; #define FOR_AI_M _Pragma("unroll") for (int ai = 0; ai < 2; ++ai) if ((__builtin_amdgcn_sched_barrier(0), true)) _Pragma("unroll") for (int m = 0; m < 4; ++m)
;   __device__ __forceinline__ void rope_store(const f32x4 (&acc)[2][2][4][2], bf16_t* dst, float sc, int hsel, int rbase, int wc, int fq) const {
;     const int c0 = wc * 32 + fq * 8, i0 = wc * 16 + fq * 4;
;     FOR_AI_M { const int row = rbase + ai * 128 + m * 16, pos = (b.g0 + row) & b.slm;
;       const f32x4* tp = (const f32x4*)(b.rope + ((size_t)pos * 64 + i0) * 2); const f32x4 t0 = tp[0], t1 = tp[1];
; #pragma unroll
;       for (int bj = 0; bj < 2; ++bj) { f32x4 v0 = acc[ai][bj][m][0], v1 = acc[ai][bj][m][1]; rope4(v0, v1, t0, t1);
;         st8(dst + (size_t)row * 512 + (hsel * 2 + bj) * 128 + c0, v0 * sc, v1 * sc); } }
.LBB0_420:
	s_nop 0
	v_lshl_add_u32 v128, v162, 2, s66
	s_waitcnt lgkmcnt(0)
	v_ashrrev_i32_e32 v129, 31, v128
	v_ashrrev_i32_e32 v147, 31, v146
	v_lshlrev_b64 v[130:131], 3, v[128:129]
	s_lshl_b32 s42, s47, 8
	v_lshl_add_u64 v[128:129], v[146:147], 1, s[58:59]
	v_and_b32_e32 v145, s90, v144
	v_lshlrev_b32_e32 v188, 9, v145
	v_lshl_add_u64 v[146:147], s[96:97], 0, v[188:189]
	v_lshl_add_u64 v[150:151], v[146:147], 0, v[130:131]
	global_load_dwordx4 v[146:149], v[150:151], off
	s_nop 0
	global_load_dwordx4 v[150:153], v[150:151], off offset:16
	v_ashrrev_i32_e32 v145, 31, v144
	v_lshlrev_b64 v[154:155], 10, v[144:145]
	s_ashr_i32 s43, s42, 31
	v_lshl_add_u64 v[154:155], v[128:129], 0, v[154:155]
	s_lshl_b64 s[42:43], s[42:43], 1
	s_waitcnt vmcnt(0) lgkmcnt(0)
	v_pk_mul_f32 v[156:157], v[124:125], v[146:147]
	v_pk_mul_f32 v[124:125], v[124:125], v[146:147] op_sel:[0,1] op_sel_hi:[1,0]
	v_sub_f32_e32 v145, v156, v157
	v_add_f32_e32 v156, v124, v125
	v_pk_mul_f32 v[124:125], v[126:127], v[148:149]
	s_nop 0
	v_sub_f32_e32 v157, v124, v125
	v_pk_mul_f32 v[124:125], v[126:127], v[148:149] op_sel:[0,1] op_sel_hi:[1,0]
	s_nop 0
	v_add_f32_e32 v126, v124, v125
	v_pk_mul_f32 v[124:125], v[120:121], v[150:151]
	v_pk_mul_f32 v[120:121], v[120:121], v[150:151] op_sel:[0,1] op_sel_hi:[1,0]
	v_sub_f32_e32 v127, v124, v125
	v_add_f32_e32 v162, v120, v121
	v_pk_mul_f32 v[120:121], v[122:123], v[152:153]
	v_lshl_add_u64 v[124:125], v[154:155], 0, s[42:43]
	v_sub_f32_e32 v163, v120, v121
	v_pk_mul_f32 v[120:121], v[122:123], v[152:153] op_sel:[0,1] op_sel_hi:[1,0]
	s_nop 0
	v_add_f32_e32 v123, v120, v121
	v_cvt_pk_bf16_f32 v120, v145, v156
	v_cvt_pk_bf16_f32 v121, v157, v126
	v_cvt_pk_bf16_f32 v122, v127, v162
	v_cvt_pk_bf16_f32 v123, v163, v123
	global_store_dwordx4 v[124:125], v[120:123], off
	s_nop 1
	v_pk_mul_f32 v[120:121], v[116:117], v[146:147]
	v_pk_mul_f32 v[116:117], v[116:117], v[146:147] op_sel:[0,1] op_sel_hi:[1,0]
	v_sub_f32_e32 v120, v120, v121
	v_add_f32_e32 v121, v116, v117
	v_pk_mul_f32 v[116:117], v[118:119], v[148:149]
	s_nop 0
	v_sub_f32_e32 v122, v116, v117
	v_pk_mul_f32 v[116:117], v[118:119], v[148:149] op_sel:[0,1] op_sel_hi:[1,0]
	s_nop 0
	v_add_f32_e32 v118, v116, v117
	v_pk_mul_f32 v[116:117], v[112:113], v[150:151]
	v_pk_mul_f32 v[112:113], v[112:113], v[150:151] op_sel:[0,1] op_sel_hi:[1,0]
	v_sub_f32_e32 v116, v116, v117
	v_add_f32_e32 v117, v112, v113
	v_pk_mul_f32 v[112:113], v[114:115], v[152:153]
	s_nop 0
	v_sub_f32_e32 v119, v112, v113
	v_pk_mul_f32 v[112:113], v[114:115], v[152:153] op_sel:[0,1] op_sel_hi:[1,0]
	s_nop 0
	v_add_f32_e32 v115, v112, v113
	v_cvt_pk_bf16_f32 v112, v120, v121
	v_add_u32_e32 v120, 16, v144
	v_cvt_pk_bf16_f32 v113, v122, v118
	v_cvt_pk_bf16_f32 v114, v116, v117
	v_cvt_pk_bf16_f32 v115, v119, v115
	global_store_dwordx4 v[124:125], v[112:115], off offset:256
	v_ashrrev_i32_e32 v121, 31, v120
	s_nop 0
	v_and_b32_e32 v112, s90, v120
	v_lshlrev_b32_e32 v188, 9, v112
	v_lshl_add_u64 v[112:113], s[96:97], 0, v[188:189]
	v_lshl_add_u64 v[116:117], v[112:113], 0, v[130:131]
	global_load_dwordx4 v[112:115], v[116:117], off
	s_nop 0
	global_load_dwordx4 v[116:119], v[116:117], off offset:16
	v_lshlrev_b64 v[120:121], 10, v[120:121]
	v_lshl_add_u64 v[120:121], v[128:129], 0, v[120:121]
	s_waitcnt vmcnt(0) lgkmcnt(0)
	v_pk_mul_f32 v[122:123], v[108:109], v[112:113]
	v_pk_mul_f32 v[108:109], v[108:109], v[112:113] op_sel:[0,1] op_sel_hi:[1,0]
	v_sub_f32_e32 v122, v122, v123
	v_add_f32_e32 v123, v108, v109
	v_pk_mul_f32 v[108:109], v[110:111], v[114:115]
	s_nop 0
	v_sub_f32_e32 v124, v108, v109
	v_pk_mul_f32 v[108:109], v[110:111], v[114:115] op_sel:[0,1] op_sel_hi:[1,0]
	s_nop 0
	v_add_f32_e32 v110, v108, v109
	v_pk_mul_f32 v[108:109], v[104:105], v[116:117]
	v_pk_mul_f32 v[104:105], v[104:105], v[116:117] op_sel:[0,1] op_sel_hi:[1,0]
	v_sub_f32_e32 v111, v108, v109
	v_add_f32_e32 v125, v104, v105
	v_pk_mul_f32 v[104:105], v[106:107], v[118:119]
	v_lshl_add_u64 v[108:109], v[120:121], 0, s[42:43]
	v_sub_f32_e32 v126, v104, v105
	v_pk_mul_f32 v[104:105], v[106:107], v[118:119] op_sel:[0,1] op_sel_hi:[1,0]
	s_nop 0
	v_add_f32_e32 v107, v104, v105
	v_cvt_pk_bf16_f32 v104, v122, v123
	v_cvt_pk_bf16_f32 v105, v124, v110
	v_cvt_pk_bf16_f32 v106, v111, v125
	v_cvt_pk_bf16_f32 v107, v126, v107
	global_store_dwordx4 v[108:109], v[104:107], off
	s_nop 1
	v_pk_mul_f32 v[104:105], v[100:101], v[112:113]
	v_pk_mul_f32 v[100:101], v[100:101], v[112:113] op_sel:[0,1] op_sel_hi:[1,0]
	v_sub_f32_e32 v104, v104, v105
	v_add_f32_e32 v105, v100, v101
	v_pk_mul_f32 v[100:101], v[102:103], v[114:115]
	s_nop 0
	v_sub_f32_e32 v106, v100, v101
	v_pk_mul_f32 v[100:101], v[102:103], v[114:115] op_sel:[0,1] op_sel_hi:[1,0]
	s_nop 0
	v_add_f32_e32 v102, v100, v101
	v_pk_mul_f32 v[100:101], v[96:97], v[116:117]
	v_pk_mul_f32 v[96:97], v[96:97], v[116:117] op_sel:[0,1] op_sel_hi:[1,0]
	v_sub_f32_e32 v100, v100, v101
	v_add_f32_e32 v101, v96, v97
	v_pk_mul_f32 v[96:97], v[98:99], v[118:119]
	s_nop 0
	v_sub_f32_e32 v103, v96, v97
	v_pk_mul_f32 v[96:97], v[98:99], v[118:119] op_sel:[0,1] op_sel_hi:[1,0]
	s_nop 0
	v_add_f32_e32 v99, v96, v97
	v_cvt_pk_bf16_f32 v96, v104, v105
	v_add_u32_e32 v104, 32, v144
	v_cvt_pk_bf16_f32 v97, v106, v102
	v_cvt_pk_bf16_f32 v98, v100, v101
	v_cvt_pk_bf16_f32 v99, v103, v99
	global_store_dwordx4 v[108:109], v[96:99], off offset:256
	v_ashrrev_i32_e32 v105, 31, v104
	s_nop 0
	v_and_b32_e32 v96, s90, v104
	v_lshlrev_b32_e32 v188, 9, v96
	v_lshl_add_u64 v[96:97], s[96:97], 0, v[188:189]
	v_lshl_add_u64 v[100:101], v[96:97], 0, v[130:131]
	global_load_dwordx4 v[96:99], v[100:101], off
	s_nop 0
	global_load_dwordx4 v[100:103], v[100:101], off offset:16
	v_lshlrev_b64 v[104:105], 10, v[104:105]
	v_lshl_add_u64 v[104:105], v[128:129], 0, v[104:105]
	s_waitcnt vmcnt(0) lgkmcnt(0)
; __device__ __forceinline__ void st8(bf16_t* p, f32x4 a, f32x4 b) { u32x4 w = {cvt_pk(a[0], a[1]), cvt_pk(a[2], a[3]), cvt_pk(b[0], b[1]), cvt_pk(b[2], b[3])}; *(u32x4*)p = w; }
; #define FOR_AI_M _Pragma("unroll") for (int ai = 0; ai < 2; ++ai) if ((__builtin_amdgcn_sched_barrier(0), true)) _Pragma("unroll") for (int m = 0; m < 4; ++m)
;   __device__ __forceinline__ void rope_store(const f32x4 (&acc)[2][2][4][2], bf16_t* dst, float sc, int hsel, int rbase, int wc, int fq) const {
;     const int c0 = wc * 32 + fq * 8, i0 = wc * 16 + fq * 4;
;     FOR_AI_M { const int row = rbase + ai * 128 + m * 16, pos = (b.g0 + row) & b.slm;
;       const f32x4* tp = (const f32x4*)(b.rope + ((size_t)pos * 64 + i0) * 2); const f32x4 t0 = tp[0], t1 = tp[1];
; #pragma unroll
;       for (int bj = 0; bj < 2; ++bj) { f32x4 v0 = acc[ai][bj][m][0], v1 = acc[ai][bj][m][1]; rope4(v0, v1, t0, t1);
;         st8(dst + (size_t)row * 512 + (hsel * 2 + bj) * 128 + c0, v0 * sc, v1 * sc); } }
	v_pk_mul_f32 v[106:107], v[92:93], v[96:97]
	v_pk_mul_f32 v[92:93], v[92:93], v[96:97] op_sel:[0,1] op_sel_hi:[1,0]
	v_sub_f32_e32 v106, v106, v107
	v_add_f32_e32 v107, v92, v93
	v_pk_mul_f32 v[92:93], v[94:95], v[98:99]
	s_nop 0
	v_sub_f32_e32 v108, v92, v93
	v_pk_mul_f32 v[92:93], v[94:95], v[98:99] op_sel:[0,1] op_sel_hi:[1,0]
	s_nop 0
	v_add_f32_e32 v94, v92, v93
	v_pk_mul_f32 v[92:93], v[88:89], v[100:101]
	v_pk_mul_f32 v[88:89], v[88:89], v[100:101] op_sel:[0,1] op_sel_hi:[1,0]
	v_sub_f32_e32 v95, v92, v93
	v_add_f32_e32 v109, v88, v89
	v_pk_mul_f32 v[88:89], v[90:91], v[102:103]
	v_lshl_add_u64 v[92:93], v[104:105], 0, s[42:43]
	v_sub_f32_e32 v110, v88, v89
	v_pk_mul_f32 v[88:89], v[90:91], v[102:103] op_sel:[0,1] op_sel_hi:[1,0]
	s_nop 0
	v_add_f32_e32 v91, v88, v89
	v_cvt_pk_bf16_f32 v88, v106, v107
	v_cvt_pk_bf16_f32 v89, v108, v94
	v_cvt_pk_bf16_f32 v90, v95, v109
	v_cvt_pk_bf16_f32 v91, v110, v91
	global_store_dwordx4 v[92:93], v[88:91], off
	s_nop 1
	v_pk_mul_f32 v[88:89], v[84:85], v[96:97]
	v_pk_mul_f32 v[84:85], v[84:85], v[96:97] op_sel:[0,1] op_sel_hi:[1,0]
	v_sub_f32_e32 v88, v88, v89
	v_add_f32_e32 v89, v84, v85
	v_pk_mul_f32 v[84:85], v[86:87], v[98:99]
	s_nop 0
	v_sub_f32_e32 v90, v84, v85
	v_pk_mul_f32 v[84:85], v[86:87], v[98:99] op_sel:[0,1] op_sel_hi:[1,0]
	s_nop 0
	v_add_f32_e32 v86, v84, v85
	v_pk_mul_f32 v[84:85], v[80:81], v[100:101]
	v_pk_mul_f32 v[80:81], v[80:81], v[100:101] op_sel:[0,1] op_sel_hi:[1,0]
	v_sub_f32_e32 v84, v84, v85
	v_add_f32_e32 v85, v80, v81
	v_pk_mul_f32 v[80:81], v[82:83], v[102:103]
	s_nop 0
	v_sub_f32_e32 v87, v80, v81
	v_pk_mul_f32 v[80:81], v[82:83], v[102:103] op_sel:[0,1] op_sel_hi:[1,0]
	s_nop 0
	v_add_f32_e32 v83, v80, v81
	v_cvt_pk_bf16_f32 v80, v88, v89
	v_add_u32_e32 v88, 48, v144
	v_cvt_pk_bf16_f32 v81, v90, v86
	v_cvt_pk_bf16_f32 v82, v84, v85
	v_cvt_pk_bf16_f32 v83, v87, v83
	global_store_dwordx4 v[92:93], v[80:83], off offset:256
	v_ashrrev_i32_e32 v89, 31, v88
	s_nop 0
	v_and_b32_e32 v80, s90, v88
	v_lshlrev_b32_e32 v188, 9, v80
	v_lshl_add_u64 v[80:81], s[96:97], 0, v[188:189]
	v_lshl_add_u64 v[84:85], v[80:81], 0, v[130:131]
	global_load_dwordx4 v[80:83], v[84:85], off
	s_nop 0
	global_load_dwordx4 v[84:87], v[84:85], off offset:16
	v_lshlrev_b64 v[88:89], 10, v[88:89]
	v_lshl_add_u64 v[88:89], v[128:129], 0, v[88:89]
	s_waitcnt vmcnt(0) lgkmcnt(0)
	v_pk_mul_f32 v[90:91], v[76:77], v[80:81]
	v_pk_mul_f32 v[76:77], v[76:77], v[80:81] op_sel:[0,1] op_sel_hi:[1,0]
	v_sub_f32_e32 v90, v90, v91
	v_add_f32_e32 v91, v76, v77
	v_pk_mul_f32 v[76:77], v[78:79], v[82:83]
	s_nop 0
	v_sub_f32_e32 v92, v76, v77
	v_pk_mul_f32 v[76:77], v[78:79], v[82:83] op_sel:[0,1] op_sel_hi:[1,0]
	s_nop 0
	v_add_f32_e32 v78, v76, v77
	v_pk_mul_f32 v[76:77], v[72:73], v[84:85]
	v_pk_mul_f32 v[72:73], v[72:73], v[84:85] op_sel:[0,1] op_sel_hi:[1,0]
	v_sub_f32_e32 v79, v76, v77
	v_add_f32_e32 v93, v72, v73
	v_pk_mul_f32 v[72:73], v[74:75], v[86:87]
	v_lshl_add_u64 v[76:77], v[88:89], 0, s[42:43]
	v_sub_f32_e32 v94, v72, v73
	v_pk_mul_f32 v[72:73], v[74:75], v[86:87] op_sel:[0,1] op_sel_hi:[1,0]
	s_nop 0
	v_add_f32_e32 v75, v72, v73
	v_cvt_pk_bf16_f32 v72, v90, v91
	v_cvt_pk_bf16_f32 v73, v92, v78
	v_cvt_pk_bf16_f32 v74, v79, v93
	v_cvt_pk_bf16_f32 v75, v94, v75
	global_store_dwordx4 v[76:77], v[72:75], off
	s_nop 1
	v_pk_mul_f32 v[72:73], v[68:69], v[80:81]
	v_pk_mul_f32 v[68:69], v[68:69], v[80:81] op_sel:[0,1] op_sel_hi:[1,0]
	v_sub_f32_e32 v72, v72, v73
	v_add_f32_e32 v73, v68, v69
	v_pk_mul_f32 v[68:69], v[70:71], v[82:83]
	s_nop 0
	v_sub_f32_e32 v74, v68, v69
	v_pk_mul_f32 v[68:69], v[70:71], v[82:83] op_sel:[0,1] op_sel_hi:[1,0]
	s_nop 0
	v_add_f32_e32 v70, v68, v69
	v_pk_mul_f32 v[68:69], v[64:65], v[84:85]
	v_pk_mul_f32 v[64:65], v[64:65], v[84:85] op_sel:[0,1] op_sel_hi:[1,0]
	v_sub_f32_e32 v68, v68, v69
	v_add_f32_e32 v69, v64, v65
	v_pk_mul_f32 v[64:65], v[66:67], v[86:87]
	s_nop 0
	v_sub_f32_e32 v71, v64, v65
	v_pk_mul_f32 v[64:65], v[66:67], v[86:87] op_sel:[0,1] op_sel_hi:[1,0]
	s_nop 0
	v_add_f32_e32 v67, v64, v65
	v_cvt_pk_bf16_f32 v64, v72, v73
	v_cvt_pk_bf16_f32 v65, v74, v70
	v_cvt_pk_bf16_f32 v66, v68, v69
	v_cvt_pk_bf16_f32 v67, v71, v67
	global_store_dwordx4 v[76:77], v[64:67], off offset:256
	v_add_u32_e32 v72, 0x80, v144
	s_nop 0
	v_and_b32_e32 v64, s90, v72
	v_lshlrev_b32_e32 v188, 9, v64
	v_lshl_add_u64 v[64:65], s[96:97], 0, v[188:189]
	v_lshl_add_u64 v[68:69], v[64:65], 0, v[130:131]
	global_load_dwordx4 v[64:67], v[68:69], off
	s_nop 0
	global_load_dwordx4 v[68:71], v[68:69], off offset:16
	v_ashrrev_i32_e32 v73, 31, v72
	v_lshlrev_b64 v[72:73], 10, v[72:73]
	v_lshl_add_u64 v[72:73], v[128:129], 0, v[72:73]
	s_waitcnt vmcnt(0) lgkmcnt(0)
; __device__ __forceinline__ void st8(bf16_t* p, f32x4 a, f32x4 b) { u32x4 w = {cvt_pk(a[0], a[1]), cvt_pk(a[2], a[3]), cvt_pk(b[0], b[1]), cvt_pk(b[2], b[3])}; *(u32x4*)p = w; }
; #define FOR_AI_M _Pragma("unroll") for (int ai = 0; ai < 2; ++ai) if ((__builtin_amdgcn_sched_barrier(0), true)) _Pragma("unroll") for (int m = 0; m < 4; ++m)
;   __device__ __forceinline__ void rope_store(const f32x4 (&acc)[2][2][4][2], bf16_t* dst, float sc, int hsel, int rbase, int wc, int fq) const {
;     const int c0 = wc * 32 + fq * 8, i0 = wc * 16 + fq * 4;
;     FOR_AI_M { const int row = rbase + ai * 128 + m * 16, pos = (b.g0 + row) & b.slm;
;       const f32x4* tp = (const f32x4*)(b.rope + ((size_t)pos * 64 + i0) * 2); const f32x4 t0 = tp[0], t1 = tp[1];
; #pragma unroll
;       for (int bj = 0; bj < 2; ++bj) { f32x4 v0 = acc[ai][bj][m][0], v1 = acc[ai][bj][m][1]; rope4(v0, v1, t0, t1);
;         st8(dst + (size_t)row * 512 + (hsel * 2 + bj) * 128 + c0, v0 * sc, v1 * sc); } }
	v_pk_mul_f32 v[74:75], v[60:61], v[64:65]
	v_pk_mul_f32 v[60:61], v[60:61], v[64:65] op_sel:[0,1] op_sel_hi:[1,0]
	v_sub_f32_e32 v74, v74, v75
	v_add_f32_e32 v75, v60, v61
	v_pk_mul_f32 v[60:61], v[62:63], v[66:67]
	s_nop 0
	v_sub_f32_e32 v76, v60, v61
	v_pk_mul_f32 v[60:61], v[62:63], v[66:67] op_sel:[0,1] op_sel_hi:[1,0]
	s_nop 0
	v_add_f32_e32 v62, v60, v61
	v_pk_mul_f32 v[60:61], v[56:57], v[68:69]
	v_pk_mul_f32 v[56:57], v[56:57], v[68:69] op_sel:[0,1] op_sel_hi:[1,0]
	v_sub_f32_e32 v63, v60, v61
	v_add_f32_e32 v77, v56, v57
	v_pk_mul_f32 v[56:57], v[58:59], v[70:71]
	v_lshl_add_u64 v[60:61], v[72:73], 0, s[42:43]
	v_sub_f32_e32 v78, v56, v57
	v_pk_mul_f32 v[56:57], v[58:59], v[70:71] op_sel:[0,1] op_sel_hi:[1,0]
	s_nop 0
	v_add_f32_e32 v59, v56, v57
	v_cvt_pk_bf16_f32 v56, v74, v75
	v_cvt_pk_bf16_f32 v57, v76, v62
	v_cvt_pk_bf16_f32 v58, v63, v77
	v_cvt_pk_bf16_f32 v59, v78, v59
	global_store_dwordx4 v[60:61], v[56:59], off
	s_nop 1
	v_pk_mul_f32 v[56:57], v[52:53], v[64:65]
	v_pk_mul_f32 v[52:53], v[52:53], v[64:65] op_sel:[0,1] op_sel_hi:[1,0]
	v_sub_f32_e32 v56, v56, v57
	v_add_f32_e32 v57, v52, v53
	v_pk_mul_f32 v[52:53], v[54:55], v[66:67]
	s_nop 0
	v_sub_f32_e32 v58, v52, v53
	v_pk_mul_f32 v[52:53], v[54:55], v[66:67] op_sel:[0,1] op_sel_hi:[1,0]
	s_nop 0
	v_add_f32_e32 v54, v52, v53
	v_pk_mul_f32 v[52:53], v[48:49], v[68:69]
	v_pk_mul_f32 v[48:49], v[48:49], v[68:69] op_sel:[0,1] op_sel_hi:[1,0]
	v_sub_f32_e32 v52, v52, v53
	v_add_f32_e32 v53, v48, v49
	v_pk_mul_f32 v[48:49], v[50:51], v[70:71]
	s_nop 0
	v_sub_f32_e32 v55, v48, v49
	v_pk_mul_f32 v[48:49], v[50:51], v[70:71] op_sel:[0,1] op_sel_hi:[1,0]
	s_nop 0
	v_add_f32_e32 v51, v48, v49
	v_cvt_pk_bf16_f32 v48, v56, v57
	v_add_u32_e32 v56, 0x90, v144
	v_cvt_pk_bf16_f32 v49, v58, v54
	v_cvt_pk_bf16_f32 v50, v52, v53
	v_cvt_pk_bf16_f32 v51, v55, v51
	global_store_dwordx4 v[60:61], v[48:51], off offset:256
	v_ashrrev_i32_e32 v57, 31, v56
	s_nop 0
	v_and_b32_e32 v48, s90, v56
	v_lshlrev_b32_e32 v188, 9, v48
	v_lshl_add_u64 v[48:49], s[96:97], 0, v[188:189]
	v_lshl_add_u64 v[52:53], v[48:49], 0, v[130:131]
	global_load_dwordx4 v[48:51], v[52:53], off
	s_nop 0
	global_load_dwordx4 v[52:55], v[52:53], off offset:16
	v_lshlrev_b64 v[56:57], 10, v[56:57]
	v_lshl_add_u64 v[56:57], v[128:129], 0, v[56:57]
	s_waitcnt vmcnt(0) lgkmcnt(0)
	v_pk_mul_f32 v[58:59], v[44:45], v[48:49]
	v_pk_mul_f32 v[44:45], v[44:45], v[48:49] op_sel:[0,1] op_sel_hi:[1,0]
	v_sub_f32_e32 v58, v58, v59
	v_add_f32_e32 v59, v44, v45
	v_pk_mul_f32 v[44:45], v[46:47], v[50:51]
	s_nop 0
	v_sub_f32_e32 v60, v44, v45
	v_pk_mul_f32 v[44:45], v[46:47], v[50:51] op_sel:[0,1] op_sel_hi:[1,0]
	s_nop 0
	v_add_f32_e32 v46, v44, v45
	v_pk_mul_f32 v[44:45], v[40:41], v[52:53]
	v_pk_mul_f32 v[40:41], v[40:41], v[52:53] op_sel:[0,1] op_sel_hi:[1,0]
	v_sub_f32_e32 v47, v44, v45
	v_add_f32_e32 v61, v40, v41
	v_pk_mul_f32 v[40:41], v[42:43], v[54:55]
	v_lshl_add_u64 v[44:45], v[56:57], 0, s[42:43]
	v_sub_f32_e32 v62, v40, v41
	v_pk_mul_f32 v[40:41], v[42:43], v[54:55] op_sel:[0,1] op_sel_hi:[1,0]
	s_nop 0
	v_add_f32_e32 v43, v40, v41
	v_cvt_pk_bf16_f32 v40, v58, v59
	v_cvt_pk_bf16_f32 v41, v60, v46
	v_cvt_pk_bf16_f32 v42, v47, v61
	v_cvt_pk_bf16_f32 v43, v62, v43
	global_store_dwordx4 v[44:45], v[40:43], off
	s_nop 1
	v_pk_mul_f32 v[40:41], v[36:37], v[48:49]
	v_pk_mul_f32 v[36:37], v[36:37], v[48:49] op_sel:[0,1] op_sel_hi:[1,0]
	v_sub_f32_e32 v40, v40, v41
	v_add_f32_e32 v41, v36, v37
	v_pk_mul_f32 v[36:37], v[38:39], v[50:51]
	s_nop 0
	v_sub_f32_e32 v42, v36, v37
	v_pk_mul_f32 v[36:37], v[38:39], v[50:51] op_sel:[0,1] op_sel_hi:[1,0]
	s_nop 0
	v_add_f32_e32 v38, v36, v37
	v_pk_mul_f32 v[36:37], v[32:33], v[52:53]
	v_pk_mul_f32 v[32:33], v[32:33], v[52:53] op_sel:[0,1] op_sel_hi:[1,0]
	v_sub_f32_e32 v36, v36, v37
	v_add_f32_e32 v37, v32, v33
	v_pk_mul_f32 v[32:33], v[34:35], v[54:55]
	s_nop 0
	v_sub_f32_e32 v39, v32, v33
	v_pk_mul_f32 v[32:33], v[34:35], v[54:55] op_sel:[0,1] op_sel_hi:[1,0]
	s_nop 0
	v_add_f32_e32 v35, v32, v33
	v_cvt_pk_bf16_f32 v32, v40, v41
	v_add_u32_e32 v40, 0xa0, v144
	v_cvt_pk_bf16_f32 v33, v42, v38
	v_cvt_pk_bf16_f32 v34, v36, v37
	v_cvt_pk_bf16_f32 v35, v39, v35
	global_store_dwordx4 v[44:45], v[32:35], off offset:256
	v_ashrrev_i32_e32 v41, 31, v40
	s_nop 0
	v_and_b32_e32 v32, s90, v40
	v_lshlrev_b32_e32 v188, 9, v32
	v_lshl_add_u64 v[32:33], s[96:97], 0, v[188:189]
	v_lshl_add_u64 v[36:37], v[32:33], 0, v[130:131]
	global_load_dwordx4 v[32:35], v[36:37], off
	s_nop 0
	global_load_dwordx4 v[36:39], v[36:37], off offset:16
	v_lshlrev_b64 v[40:41], 10, v[40:41]
	v_lshl_add_u64 v[40:41], v[128:129], 0, v[40:41]
	s_waitcnt vmcnt(0) lgkmcnt(0)
; __device__ __forceinline__ void st8(bf16_t* p, f32x4 a, f32x4 b) { u32x4 w = {cvt_pk(a[0], a[1]), cvt_pk(a[2], a[3]), cvt_pk(b[0], b[1]), cvt_pk(b[2], b[3])}; *(u32x4*)p = w; }
; #define FOR_AI_M _Pragma("unroll") for (int ai = 0; ai < 2; ++ai) if ((__builtin_amdgcn_sched_barrier(0), true)) _Pragma("unroll") for (int m = 0; m < 4; ++m)
;   __device__ __forceinline__ void rope_store(const f32x4 (&acc)[2][2][4][2], bf16_t* dst, float sc, int hsel, int rbase, int wc, int fq) const {
;     const int c0 = wc * 32 + fq * 8, i0 = wc * 16 + fq * 4;
;     FOR_AI_M { const int row = rbase + ai * 128 + m * 16, pos = (b.g0 + row) & b.slm;
;       const f32x4* tp = (const f32x4*)(b.rope + ((size_t)pos * 64 + i0) * 2); const f32x4 t0 = tp[0], t1 = tp[1];
; #pragma unroll
;       for (int bj = 0; bj < 2; ++bj) { f32x4 v0 = acc[ai][bj][m][0], v1 = acc[ai][bj][m][1]; rope4(v0, v1, t0, t1);
;         st8(dst + (size_t)row * 512 + (hsel * 2 + bj) * 128 + c0, v0 * sc, v1 * sc); } }
	v_pk_mul_f32 v[42:43], v[28:29], v[32:33]
	v_pk_mul_f32 v[28:29], v[28:29], v[32:33] op_sel:[0,1] op_sel_hi:[1,0]
	v_sub_f32_e32 v42, v42, v43
	v_add_f32_e32 v43, v28, v29
	v_pk_mul_f32 v[28:29], v[30:31], v[34:35]
	s_nop 0
	v_sub_f32_e32 v44, v28, v29
	v_pk_mul_f32 v[28:29], v[30:31], v[34:35] op_sel:[0,1] op_sel_hi:[1,0]
	s_nop 0
	v_add_f32_e32 v30, v28, v29
	v_pk_mul_f32 v[28:29], v[24:25], v[36:37]
	v_pk_mul_f32 v[24:25], v[24:25], v[36:37] op_sel:[0,1] op_sel_hi:[1,0]
	v_sub_f32_e32 v31, v28, v29
	v_add_f32_e32 v45, v24, v25
	v_pk_mul_f32 v[24:25], v[26:27], v[38:39]
	v_lshl_add_u64 v[28:29], v[40:41], 0, s[42:43]
	v_sub_f32_e32 v46, v24, v25
	v_pk_mul_f32 v[24:25], v[26:27], v[38:39] op_sel:[0,1] op_sel_hi:[1,0]
	s_nop 0
	v_add_f32_e32 v27, v24, v25
	v_cvt_pk_bf16_f32 v24, v42, v43
	v_cvt_pk_bf16_f32 v25, v44, v30
	v_cvt_pk_bf16_f32 v26, v31, v45
	v_cvt_pk_bf16_f32 v27, v46, v27
	global_store_dwordx4 v[28:29], v[24:27], off
	s_nop 1
	v_pk_mul_f32 v[24:25], v[20:21], v[32:33]
	v_pk_mul_f32 v[20:21], v[20:21], v[32:33] op_sel:[0,1] op_sel_hi:[1,0]
	v_sub_f32_e32 v24, v24, v25
	v_add_f32_e32 v25, v20, v21
	v_pk_mul_f32 v[20:21], v[22:23], v[34:35]
	s_nop 0
	v_sub_f32_e32 v26, v20, v21
	v_pk_mul_f32 v[20:21], v[22:23], v[34:35] op_sel:[0,1] op_sel_hi:[1,0]
	s_nop 0
	v_add_f32_e32 v22, v20, v21
	v_pk_mul_f32 v[20:21], v[16:17], v[36:37]
	v_pk_mul_f32 v[16:17], v[16:17], v[36:37] op_sel:[0,1] op_sel_hi:[1,0]
	v_sub_f32_e32 v20, v20, v21
	v_add_f32_e32 v21, v16, v17
	v_pk_mul_f32 v[16:17], v[18:19], v[38:39]
	s_nop 0
	v_sub_f32_e32 v23, v16, v17
	v_pk_mul_f32 v[16:17], v[18:19], v[38:39] op_sel:[0,1] op_sel_hi:[1,0]
	s_nop 0
	v_add_f32_e32 v19, v16, v17
	v_cvt_pk_bf16_f32 v16, v24, v25
	v_add_u32_e32 v24, 0xb0, v144
	v_cvt_pk_bf16_f32 v17, v26, v22
	v_cvt_pk_bf16_f32 v18, v20, v21
	v_cvt_pk_bf16_f32 v19, v23, v19
	global_store_dwordx4 v[28:29], v[16:19], off offset:256
	v_ashrrev_i32_e32 v25, 31, v24
	s_nop 0
	v_and_b32_e32 v16, s90, v24
	v_lshlrev_b32_e32 v188, 9, v16
	v_lshl_add_u64 v[16:17], s[96:97], 0, v[188:189]
	v_lshl_add_u64 v[20:21], v[16:17], 0, v[130:131]
	global_load_dwordx4 v[16:19], v[20:21], off
	s_nop 0
	global_load_dwordx4 v[20:23], v[20:21], off offset:16
	v_lshlrev_b64 v[24:25], 10, v[24:25]
	v_lshl_add_u64 v[24:25], v[128:129], 0, v[24:25]
	s_waitcnt vmcnt(0) lgkmcnt(0)
	v_pk_mul_f32 v[26:27], v[12:13], v[16:17]
	v_pk_mul_f32 v[12:13], v[12:13], v[16:17] op_sel:[0,1] op_sel_hi:[1,0]
	v_sub_f32_e32 v26, v26, v27
	v_add_f32_e32 v27, v12, v13
	v_pk_mul_f32 v[12:13], v[14:15], v[18:19]
	s_nop 0
	v_sub_f32_e32 v28, v12, v13
	v_pk_mul_f32 v[12:13], v[14:15], v[18:19] op_sel:[0,1] op_sel_hi:[1,0]
	s_nop 0
	v_add_f32_e32 v14, v12, v13
	v_pk_mul_f32 v[12:13], v[8:9], v[20:21]
	v_pk_mul_f32 v[8:9], v[8:9], v[20:21] op_sel:[0,1] op_sel_hi:[1,0]
	v_sub_f32_e32 v15, v12, v13
	v_add_f32_e32 v29, v8, v9
	v_pk_mul_f32 v[8:9], v[10:11], v[22:23]
	v_lshl_add_u64 v[12:13], v[24:25], 0, s[42:43]
	v_sub_f32_e32 v30, v8, v9
	v_pk_mul_f32 v[8:9], v[10:11], v[22:23] op_sel:[0,1] op_sel_hi:[1,0]
	s_nop 0
	v_add_f32_e32 v11, v8, v9
	v_cvt_pk_bf16_f32 v8, v26, v27
	v_cvt_pk_bf16_f32 v9, v28, v14
	v_cvt_pk_bf16_f32 v10, v15, v29
	v_cvt_pk_bf16_f32 v11, v30, v11
	global_store_dwordx4 v[12:13], v[8:11], off
	s_nop 1
	v_pk_mul_f32 v[8:9], v[4:5], v[16:17]
	v_pk_mul_f32 v[4:5], v[4:5], v[16:17] op_sel:[0,1] op_sel_hi:[1,0]
	v_sub_f32_e32 v8, v8, v9
	v_add_f32_e32 v9, v4, v5
	v_pk_mul_f32 v[4:5], v[6:7], v[18:19]
	s_nop 0
	v_sub_f32_e32 v10, v4, v5
	v_pk_mul_f32 v[4:5], v[6:7], v[18:19] op_sel:[0,1] op_sel_hi:[1,0]
	s_nop 0
	v_add_f32_e32 v6, v4, v5
	v_pk_mul_f32 v[4:5], v[0:1], v[20:21]
	v_pk_mul_f32 v[0:1], v[0:1], v[20:21] op_sel:[0,1] op_sel_hi:[1,0]
	v_sub_f32_e32 v4, v4, v5
	v_add_f32_e32 v5, v0, v1
	v_pk_mul_f32 v[0:1], v[2:3], v[22:23]
	s_nop 0
	v_sub_f32_e32 v7, v0, v1
	v_pk_mul_f32 v[0:1], v[2:3], v[22:23] op_sel:[0,1] op_sel_hi:[1,0]
	s_nop 0
	v_add_f32_e32 v3, v0, v1
	v_cvt_pk_bf16_f32 v0, v8, v9
	v_cvt_pk_bf16_f32 v1, v10, v6
	v_cvt_pk_bf16_f32 v2, v4, v5
	v_cvt_pk_bf16_f32 v3, v7, v3
	global_store_dwordx4 v[12:13], v[0:3], off offset:256
	s_and_b64 vcc, exec, s[40:41]
	s_mov_b64 s[40:41], -1
	s_cbranch_vccnz .LBB0_296

; __device__ __forceinline__ void st8(bf16_t* p, f32x4 a, f32x4 b) { u32x4 w = {cvt_pk(a[0], a[1]), cvt_pk(a[2], a[3]), cvt_pk(b[0], b[1]), cvt_pk(b[2], b[3])}; *(u32x4*)p = w; }
; #define FOR_AI_M _Pragma("unroll") for (int ai = 0; ai < 2; ++ai) if ((__builtin_amdgcn_sched_barrier(0), true)) _Pragma("unroll") for (int m = 0; m < 4; ++m)
;   __device__ __forceinline__ void operator()(EPI_ARGS) const {
;     const int rbase = u.pm * 256 + wr * 64 + fr, c0 = u.pn * 256 + wc * 32 + fq * 8;
;     FOR_AI_M { const int row = rbase + ai * 128 + m * 16; const f32x4* sp = (const f32x4*)(b.ssq_x1 + (size_t)(b.g0 + row) * 16); const f32x4 q0 = sp[0], q1 = sp[1], q2 = sp[2], q3 = sp[3];
;       const float r2 = rsqrtf(((((q0[0] + q0[1]) + (q0[2] + q0[3])) + ((q1[0] + q1[1]) + (q1[2] + q1[3]))) + (((q2[0] + q2[1]) + (q2[2] + q2[3])) + ((q3[0] + q3[1]) + (q3[2] + q3[3])))) * (1.f / 1024.f) + EPS);
; #pragma unroll
;       for (int bj = 0; bj < 2; ++bj) st8(b.UR + (size_t)row * N_UP + c0 + bj * 128, acc[ai][bj][m][0] * r2, acc[ai][bj][m][1] * r2); }
;   }
.LBB0_951:
	s_lshl_b32 s4, s19, 8
	v_mov_b32_e32 v138, v142
	v_mov_b32_e32 v139, v143
	s_add_i32 s4, s4, s77
	s_nop 0
	v_add_u32_e32 v146, s4, v138
	s_lshl_b32 s4, s8, 8
	s_or_b32 s4, s4, s78
	v_lshl_add_u32 v160, v139, 3, s4
	v_ashrrev_i32_e32 v161, 31, v160
	v_add_u32_e32 v138, s68, v146
	v_ashrrev_i32_e32 v139, 31, v138
	v_lshlrev_b64 v[138:139], 6, v[138:139]
	v_lshl_add_u64 v[156:157], s[38:39], 0, v[138:139]
	global_load_dwordx4 v[138:141], v[156:157], off
	global_load_dwordx4 v[148:151], v[156:157], off offset:16
	global_load_dwordx4 v[152:155], v[156:157], off offset:32
	s_nop 0
	global_load_dwordx4 v[156:159], v[156:157], off offset:48
	s_movk_i32 s8, 0x2c00
	v_add_u32_e32 v147, 16, v146
	s_waitcnt vmcnt(0) lgkmcnt(0)
	v_mov_b32_e32 v162, v138
	v_mov_b32_e32 v163, v152
	v_mov_b32_e32 v152, v139
	v_pk_add_f32 v[138:139], v[162:163], v[152:153]
	v_mov_b32_e32 v152, v140
	v_mov_b32_e32 v153, v154
	v_mov_b32_e32 v154, v141
	v_pk_add_f32 v[140:141], v[152:153], v[154:155]
	s_nop 0
	v_pk_add_f32 v[138:139], v[138:139], v[140:141]
	v_mov_b32_e32 v140, v148
	v_mov_b32_e32 v141, v156
	v_mov_b32_e32 v156, v149
	v_mov_b32_e32 v148, v150
	v_mov_b32_e32 v149, v158
	v_mov_b32_e32 v158, v151
	v_pk_add_f32 v[140:141], v[140:141], v[156:157]
	v_pk_add_f32 v[148:149], v[148:149], v[158:159]
	s_nop 0
	v_pk_add_f32 v[140:141], v[140:141], v[148:149]
	s_nop 0
	v_pk_add_f32 v[138:139], v[138:139], v[140:141]
	v_lshlrev_b64 v[140:141], 1, v[160:161]
	v_add_f32_e32 v138, v138, v139
	v_fmamk_f32 v138, v138, 0x3a800000, v234
	v_cmp_gt_f32_e32 vcc, s6, v138
	v_mul_f32_e32 v139, 0x4b800000, v138
	s_nop 0
	v_cndmask_b32_e32 v138, v138, v139, vcc
	v_rsq_f32_e32 v138, v138
	s_nop 0
	v_mul_f32_e32 v139, 0x45800000, v138
	v_cndmask_b32_e32 v148, v138, v139, vcc
	v_mov_b64_e32 v[138:139], s[36:37]
	v_mad_i64_i32 v[150:151], s[4:5], v146, s8, v[138:139]
	v_pk_mul_f32 v[120:121], v[120:121], v[148:149] op_sel_hi:[1,0]
	v_lshl_add_u64 v[150:151], v[150:151], 0, v[140:141]
	v_pk_mul_f32 v[122:123], v[122:123], v[148:149] op_sel_hi:[1,0]
	v_cvt_pk_bf16_f32 v120, v120, v121
	v_pk_mul_f32 v[126:127], v[126:127], v[148:149] op_sel_hi:[1,0]
	v_cvt_pk_bf16_f32 v121, v122, v123
	v_pk_mul_f32 v[124:125], v[124:125], v[148:149] op_sel_hi:[1,0]
	v_pk_mul_f32 v[116:117], v[116:117], v[148:149] op_sel_hi:[1,0]
	v_cvt_pk_bf16_f32 v122, v124, v125
	v_cvt_pk_bf16_f32 v123, v126, v127
	global_store_dwordx4 v[150:151], v[120:123], off
	v_pk_mul_f32 v[118:119], v[118:119], v[148:149] op_sel_hi:[1,0]
	s_nop 0
	v_pk_mul_f32 v[120:121], v[114:115], v[148:149] op_sel_hi:[1,0]
	v_pk_mul_f32 v[114:115], v[112:113], v[148:149] op_sel_hi:[1,0]
	v_cvt_pk_bf16_f32 v112, v116, v117
	v_cvt_pk_bf16_f32 v113, v118, v119
	s_nop 0
	v_cvt_pk_bf16_f32 v114, v114, v115
	v_cvt_pk_bf16_f32 v115, v120, v121
	global_store_dwordx4 v[150:151], v[112:115], off offset:256
	s_nop 1
	v_add_u32_e32 v112, s68, v147
	v_ashrrev_i32_e32 v113, 31, v112
	v_lshlrev_b64 v[112:113], 6, v[112:113]
	v_lshl_add_u64 v[124:125], s[38:39], 0, v[112:113]
	global_load_dwordx4 v[112:115], v[124:125], off
	global_load_dwordx4 v[116:119], v[124:125], off offset:16
	global_load_dwordx4 v[120:123], v[124:125], off offset:32
	s_nop 0
	global_load_dwordx4 v[124:127], v[124:125], off offset:48
	s_waitcnt vmcnt(0) lgkmcnt(0)
	v_mov_b32_e32 v148, v112
	v_mov_b32_e32 v149, v120
	v_mov_b32_e32 v120, v113
	v_pk_add_f32 v[112:113], v[148:149], v[120:121]
	v_mov_b32_e32 v120, v114
	v_mov_b32_e32 v121, v122
	v_mov_b32_e32 v122, v115
	v_pk_add_f32 v[114:115], v[120:121], v[122:123]
	s_nop 0
	v_pk_add_f32 v[112:113], v[112:113], v[114:115]
	v_mov_b32_e32 v114, v116
	v_mov_b32_e32 v115, v124
	v_mov_b32_e32 v124, v117
	v_mov_b32_e32 v116, v118
	v_mov_b32_e32 v117, v126
	v_mov_b32_e32 v126, v119
	v_pk_add_f32 v[114:115], v[114:115], v[124:125]
	v_pk_add_f32 v[116:117], v[116:117], v[126:127]
	s_nop 0
	v_pk_add_f32 v[114:115], v[114:115], v[116:117]
	s_nop 0
	v_pk_add_f32 v[112:113], v[112:113], v[114:115]
	v_mad_i64_i32 v[114:115], s[4:5], v147, s8, v[138:139]
	v_add_f32_e32 v112, v112, v113
	v_fmamk_f32 v112, v112, 0x3a800000, v234
	v_cmp_gt_f32_e32 vcc, s6, v112
	v_mul_f32_e32 v113, 0x4b800000, v112
	v_lshl_add_u64 v[114:115], v[114:115], 0, v[140:141]
	v_cndmask_b32_e32 v112, v112, v113, vcc
	v_rsq_f32_e32 v112, v112
	s_nop 0
	v_mul_f32_e32 v113, 0x45800000, v112
	v_cndmask_b32_e32 v112, v112, v113, vcc
	v_pk_mul_f32 v[110:111], v[110:111], v[112:113] op_sel_hi:[1,0]
	v_pk_mul_f32 v[108:109], v[108:109], v[112:113] op_sel_hi:[1,0]
	v_pk_mul_f32 v[116:117], v[106:107], v[112:113] op_sel_hi:[1,0]
	v_pk_mul_f32 v[106:107], v[104:105], v[112:113] op_sel_hi:[1,0]
	v_cvt_pk_bf16_f32 v104, v108, v109
	v_cvt_pk_bf16_f32 v105, v110, v111
	v_pk_mul_f32 v[102:103], v[102:103], v[112:113] op_sel_hi:[1,0]
	v_cvt_pk_bf16_f32 v106, v106, v107
	v_cvt_pk_bf16_f32 v107, v116, v117
	global_store_dwordx4 v[114:115], v[104:107], off
	v_pk_mul_f32 v[100:101], v[100:101], v[112:113] op_sel_hi:[1,0]
	s_nop 0
	v_pk_mul_f32 v[104:105], v[98:99], v[112:113] op_sel_hi:[1,0]
	v_pk_mul_f32 v[98:99], v[96:97], v[112:113] op_sel_hi:[1,0]
	v_cvt_pk_bf16_f32 v96, v100, v101
	v_cvt_pk_bf16_f32 v97, v102, v103
	s_nop 0
	v_cvt_pk_bf16_f32 v98, v98, v99
	v_cvt_pk_bf16_f32 v99, v104, v105
	global_store_dwordx4 v[114:115], v[96:99], off offset:256
	v_add_u32_e32 v114, 32, v146
	s_nop 0
	v_add_u32_e32 v96, s68, v114
	v_ashrrev_i32_e32 v97, 31, v96
	v_lshlrev_b64 v[96:97], 6, v[96:97]
	v_lshl_add_u64 v[108:109], s[38:39], 0, v[96:97]
	global_load_dwordx4 v[96:99], v[108:109], off
	global_load_dwordx4 v[100:103], v[108:109], off offset:16
	global_load_dwordx4 v[104:107], v[108:109], off offset:32
	s_nop 0
	global_load_dwordx4 v[108:111], v[108:109], off offset:48
	s_waitcnt vmcnt(0) lgkmcnt(0)
; __device__ __forceinline__ void st8(bf16_t* p, f32x4 a, f32x4 b) { u32x4 w = {cvt_pk(a[0], a[1]), cvt_pk(a[2], a[3]), cvt_pk(b[0], b[1]), cvt_pk(b[2], b[3])}; *(u32x4*)p = w; }
; #define FOR_AI_M _Pragma("unroll") for (int ai = 0; ai < 2; ++ai) if ((__builtin_amdgcn_sched_barrier(0), true)) _Pragma("unroll") for (int m = 0; m < 4; ++m)
;   __device__ __forceinline__ void operator()(EPI_ARGS) const {
;     const int rbase = u.pm * 256 + wr * 64 + fr, c0 = u.pn * 256 + wc * 32 + fq * 8;
;     FOR_AI_M { const int row = rbase + ai * 128 + m * 16; const f32x4* sp = (const f32x4*)(b.ssq_x1 + (size_t)(b.g0 + row) * 16); const f32x4 q0 = sp[0], q1 = sp[1], q2 = sp[2], q3 = sp[3];
;       const float r2 = rsqrtf(((((q0[0] + q0[1]) + (q0[2] + q0[3])) + ((q1[0] + q1[1]) + (q1[2] + q1[3]))) + (((q2[0] + q2[1]) + (q2[2] + q2[3])) + ((q3[0] + q3[1]) + (q3[2] + q3[3])))) * (1.f / 1024.f) + EPS);
; #pragma unroll
;       for (int bj = 0; bj < 2; ++bj) st8(b.UR + (size_t)row * N_UP + c0 + bj * 128, acc[ai][bj][m][0] * r2, acc[ai][bj][m][1] * r2); }
;   }
	v_mov_b32_e32 v112, v96
	v_mov_b32_e32 v113, v104
	v_mov_b32_e32 v104, v97
	v_pk_add_f32 v[96:97], v[112:113], v[104:105]
	v_mov_b32_e32 v104, v98
	v_mov_b32_e32 v105, v106
	v_mov_b32_e32 v106, v99
	v_pk_add_f32 v[98:99], v[104:105], v[106:107]
	s_nop 0
	v_pk_add_f32 v[96:97], v[96:97], v[98:99]
	v_mov_b32_e32 v98, v100
	v_mov_b32_e32 v99, v108
	v_mov_b32_e32 v108, v101
	v_mov_b32_e32 v100, v102
	v_mov_b32_e32 v101, v110
	v_mov_b32_e32 v110, v103
	v_pk_add_f32 v[98:99], v[98:99], v[108:109]
	v_pk_add_f32 v[100:101], v[100:101], v[110:111]
	s_nop 0
	v_pk_add_f32 v[98:99], v[98:99], v[100:101]
	s_nop 0
	v_pk_add_f32 v[96:97], v[96:97], v[98:99]
	v_mad_i64_i32 v[98:99], s[4:5], v114, s8, v[138:139]
	v_add_f32_e32 v96, v96, v97
	v_fmamk_f32 v96, v96, 0x3a800000, v234
	v_cmp_gt_f32_e32 vcc, s6, v96
	v_mul_f32_e32 v97, 0x4b800000, v96
	v_lshl_add_u64 v[98:99], v[98:99], 0, v[140:141]
	v_cndmask_b32_e32 v96, v96, v97, vcc
	v_rsq_f32_e32 v96, v96
	s_nop 0
	v_mul_f32_e32 v97, 0x45800000, v96
	v_cndmask_b32_e32 v96, v96, v97, vcc
	v_pk_mul_f32 v[94:95], v[94:95], v[96:97] op_sel_hi:[1,0]
	v_pk_mul_f32 v[92:93], v[92:93], v[96:97] op_sel_hi:[1,0]
	v_pk_mul_f32 v[100:101], v[90:91], v[96:97] op_sel_hi:[1,0]
	v_pk_mul_f32 v[90:91], v[88:89], v[96:97] op_sel_hi:[1,0]
	v_cvt_pk_bf16_f32 v88, v92, v93
	v_cvt_pk_bf16_f32 v89, v94, v95
	v_pk_mul_f32 v[86:87], v[86:87], v[96:97] op_sel_hi:[1,0]
	v_cvt_pk_bf16_f32 v90, v90, v91
	v_cvt_pk_bf16_f32 v91, v100, v101
	global_store_dwordx4 v[98:99], v[88:91], off
	v_pk_mul_f32 v[84:85], v[84:85], v[96:97] op_sel_hi:[1,0]
	s_nop 0
	v_pk_mul_f32 v[88:89], v[82:83], v[96:97] op_sel_hi:[1,0]
	v_pk_mul_f32 v[82:83], v[80:81], v[96:97] op_sel_hi:[1,0]
	v_cvt_pk_bf16_f32 v80, v84, v85
	v_cvt_pk_bf16_f32 v81, v86, v87
	s_nop 0
	v_cvt_pk_bf16_f32 v82, v82, v83
	v_cvt_pk_bf16_f32 v83, v88, v89
	global_store_dwordx4 v[98:99], v[80:83], off offset:256
	v_add_u32_e32 v98, 48, v146
	s_nop 0
	v_add_u32_e32 v80, s68, v98
	v_ashrrev_i32_e32 v81, 31, v80
	v_lshlrev_b64 v[80:81], 6, v[80:81]
	v_lshl_add_u64 v[92:93], s[38:39], 0, v[80:81]
	global_load_dwordx4 v[80:83], v[92:93], off
	global_load_dwordx4 v[84:87], v[92:93], off offset:16
	global_load_dwordx4 v[88:91], v[92:93], off offset:32
	s_nop 0
	global_load_dwordx4 v[92:95], v[92:93], off offset:48
	s_waitcnt vmcnt(0) lgkmcnt(0)
	v_mov_b32_e32 v96, v80
	v_mov_b32_e32 v97, v88
	v_mov_b32_e32 v88, v81
	v_pk_add_f32 v[80:81], v[96:97], v[88:89]
	v_mov_b32_e32 v88, v82
	v_mov_b32_e32 v89, v90
	v_mov_b32_e32 v90, v83
	v_pk_add_f32 v[82:83], v[88:89], v[90:91]
	s_nop 0
	v_pk_add_f32 v[80:81], v[80:81], v[82:83]
	v_mov_b32_e32 v82, v84
	v_mov_b32_e32 v83, v92
	v_mov_b32_e32 v92, v85
	v_mov_b32_e32 v84, v86
	v_mov_b32_e32 v85, v94
	v_mov_b32_e32 v94, v87
	v_pk_add_f32 v[82:83], v[82:83], v[92:93]
	v_pk_add_f32 v[84:85], v[84:85], v[94:95]
	s_nop 0
	v_pk_add_f32 v[82:83], v[82:83], v[84:85]
	s_nop 0
	v_pk_add_f32 v[80:81], v[80:81], v[82:83]
	v_mad_i64_i32 v[82:83], s[4:5], v98, s8, v[138:139]
	v_add_f32_e32 v80, v80, v81
	v_fmamk_f32 v80, v80, 0x3a800000, v234
	v_cmp_gt_f32_e32 vcc, s6, v80
	v_mul_f32_e32 v81, 0x4b800000, v80
	v_lshl_add_u64 v[82:83], v[82:83], 0, v[140:141]
	v_cndmask_b32_e32 v80, v80, v81, vcc
	v_rsq_f32_e32 v80, v80
	s_nop 0
	v_mul_f32_e32 v81, 0x45800000, v80
	v_cndmask_b32_e32 v80, v80, v81, vcc
	v_pk_mul_f32 v[78:79], v[78:79], v[80:81] op_sel_hi:[1,0]
	v_pk_mul_f32 v[76:77], v[76:77], v[80:81] op_sel_hi:[1,0]
	v_pk_mul_f32 v[84:85], v[74:75], v[80:81] op_sel_hi:[1,0]
	v_pk_mul_f32 v[74:75], v[72:73], v[80:81] op_sel_hi:[1,0]
	v_cvt_pk_bf16_f32 v72, v76, v77
	v_cvt_pk_bf16_f32 v73, v78, v79
	v_pk_mul_f32 v[70:71], v[70:71], v[80:81] op_sel_hi:[1,0]
	v_cvt_pk_bf16_f32 v74, v74, v75
	v_cvt_pk_bf16_f32 v75, v84, v85
	global_store_dwordx4 v[82:83], v[72:75], off
	v_pk_mul_f32 v[68:69], v[68:69], v[80:81] op_sel_hi:[1,0]
	s_nop 0
	v_pk_mul_f32 v[72:73], v[66:67], v[80:81] op_sel_hi:[1,0]
	v_pk_mul_f32 v[66:67], v[64:65], v[80:81] op_sel_hi:[1,0]
	v_cvt_pk_bf16_f32 v64, v68, v69
	v_cvt_pk_bf16_f32 v65, v70, v71
	s_nop 0
	v_cvt_pk_bf16_f32 v66, v66, v67
	v_cvt_pk_bf16_f32 v67, v72, v73
	global_store_dwordx4 v[82:83], v[64:67], off offset:256
	v_add_u32_e32 v82, 0x80, v146
	s_nop 0
	v_add_u32_e32 v64, s68, v82
	v_ashrrev_i32_e32 v65, 31, v64
	v_lshlrev_b64 v[64:65], 6, v[64:65]
	v_lshl_add_u64 v[76:77], s[38:39], 0, v[64:65]
	global_load_dwordx4 v[64:67], v[76:77], off
	global_load_dwordx4 v[68:71], v[76:77], off offset:16
	global_load_dwordx4 v[72:75], v[76:77], off offset:32
	s_nop 0
	global_load_dwordx4 v[76:79], v[76:77], off offset:48
	s_waitcnt vmcnt(0) lgkmcnt(0)
; __device__ __forceinline__ void st8(bf16_t* p, f32x4 a, f32x4 b) { u32x4 w = {cvt_pk(a[0], a[1]), cvt_pk(a[2], a[3]), cvt_pk(b[0], b[1]), cvt_pk(b[2], b[3])}; *(u32x4*)p = w; }
; #define FOR_AI_M _Pragma("unroll") for (int ai = 0; ai < 2; ++ai) if ((__builtin_amdgcn_sched_barrier(0), true)) _Pragma("unroll") for (int m = 0; m < 4; ++m)
;   __device__ __forceinline__ void operator()(EPI_ARGS) const {
;     const int rbase = u.pm * 256 + wr * 64 + fr, c0 = u.pn * 256 + wc * 32 + fq * 8;
;     FOR_AI_M { const int row = rbase + ai * 128 + m * 16; const f32x4* sp = (const f32x4*)(b.ssq_x1 + (size_t)(b.g0 + row) * 16); const f32x4 q0 = sp[0], q1 = sp[1], q2 = sp[2], q3 = sp[3];
;       const float r2 = rsqrtf(((((q0[0] + q0[1]) + (q0[2] + q0[3])) + ((q1[0] + q1[1]) + (q1[2] + q1[3]))) + (((q2[0] + q2[1]) + (q2[2] + q2[3])) + ((q3[0] + q3[1]) + (q3[2] + q3[3])))) * (1.f / 1024.f) + EPS);
; #pragma unroll
;       for (int bj = 0; bj < 2; ++bj) st8(b.UR + (size_t)row * N_UP + c0 + bj * 128, acc[ai][bj][m][0] * r2, acc[ai][bj][m][1] * r2); }
;   }
	v_mov_b32_e32 v80, v64
	v_mov_b32_e32 v81, v72
	v_mov_b32_e32 v72, v65
	v_pk_add_f32 v[64:65], v[80:81], v[72:73]
	v_mov_b32_e32 v72, v66
	v_mov_b32_e32 v73, v74
	v_mov_b32_e32 v74, v67
	v_pk_add_f32 v[66:67], v[72:73], v[74:75]
	s_nop 0
	v_pk_add_f32 v[64:65], v[64:65], v[66:67]
	v_mov_b32_e32 v66, v68
	v_mov_b32_e32 v67, v76
	v_mov_b32_e32 v76, v69
	v_mov_b32_e32 v68, v70
	v_mov_b32_e32 v69, v78
	v_mov_b32_e32 v78, v71
	v_pk_add_f32 v[66:67], v[66:67], v[76:77]
	v_pk_add_f32 v[68:69], v[68:69], v[78:79]
	s_nop 0
	v_pk_add_f32 v[66:67], v[66:67], v[68:69]
	s_nop 0
	v_pk_add_f32 v[64:65], v[64:65], v[66:67]
	v_mad_i64_i32 v[66:67], s[4:5], v82, s8, v[138:139]
	v_add_f32_e32 v64, v64, v65
	v_fmamk_f32 v64, v64, 0x3a800000, v234
	v_cmp_gt_f32_e32 vcc, s6, v64
	v_mul_f32_e32 v65, 0x4b800000, v64
	v_lshl_add_u64 v[66:67], v[66:67], 0, v[140:141]
	v_cndmask_b32_e32 v64, v64, v65, vcc
	v_rsq_f32_e32 v64, v64
	s_nop 0
	v_mul_f32_e32 v65, 0x45800000, v64
	v_cndmask_b32_e32 v64, v64, v65, vcc
	v_pk_mul_f32 v[62:63], v[62:63], v[64:65] op_sel_hi:[1,0]
	v_pk_mul_f32 v[60:61], v[60:61], v[64:65] op_sel_hi:[1,0]
	v_pk_mul_f32 v[68:69], v[58:59], v[64:65] op_sel_hi:[1,0]
	v_pk_mul_f32 v[58:59], v[56:57], v[64:65] op_sel_hi:[1,0]
	v_cvt_pk_bf16_f32 v56, v60, v61
	v_cvt_pk_bf16_f32 v57, v62, v63
	v_pk_mul_f32 v[54:55], v[54:55], v[64:65] op_sel_hi:[1,0]
	v_cvt_pk_bf16_f32 v58, v58, v59
	v_cvt_pk_bf16_f32 v59, v68, v69
	global_store_dwordx4 v[66:67], v[56:59], off
	v_pk_mul_f32 v[52:53], v[52:53], v[64:65] op_sel_hi:[1,0]
	s_nop 0
	v_pk_mul_f32 v[56:57], v[50:51], v[64:65] op_sel_hi:[1,0]
	v_pk_mul_f32 v[50:51], v[48:49], v[64:65] op_sel_hi:[1,0]
	v_cvt_pk_bf16_f32 v48, v52, v53
	v_cvt_pk_bf16_f32 v49, v54, v55
	s_nop 0
	v_cvt_pk_bf16_f32 v50, v50, v51
	v_cvt_pk_bf16_f32 v51, v56, v57
	global_store_dwordx4 v[66:67], v[48:51], off offset:256
	v_add_u32_e32 v66, 0x90, v146
	s_nop 0
	v_add_u32_e32 v48, s68, v66
	v_ashrrev_i32_e32 v49, 31, v48
	v_lshlrev_b64 v[48:49], 6, v[48:49]
	v_lshl_add_u64 v[60:61], s[38:39], 0, v[48:49]
	global_load_dwordx4 v[48:51], v[60:61], off
	global_load_dwordx4 v[52:55], v[60:61], off offset:16
	global_load_dwordx4 v[56:59], v[60:61], off offset:32
	s_nop 0
	global_load_dwordx4 v[60:63], v[60:61], off offset:48
	s_waitcnt vmcnt(0) lgkmcnt(0)
	v_mov_b32_e32 v64, v48
	v_mov_b32_e32 v65, v56
	v_mov_b32_e32 v56, v49
	v_pk_add_f32 v[48:49], v[64:65], v[56:57]
	v_mov_b32_e32 v56, v50
	v_mov_b32_e32 v57, v58
	v_mov_b32_e32 v58, v51
	v_pk_add_f32 v[50:51], v[56:57], v[58:59]
	s_nop 0
	v_pk_add_f32 v[48:49], v[48:49], v[50:51]
	v_mov_b32_e32 v50, v52
	v_mov_b32_e32 v51, v60
	v_mov_b32_e32 v60, v53
	v_mov_b32_e32 v52, v54
	v_mov_b32_e32 v53, v62
	v_mov_b32_e32 v62, v55
	v_pk_add_f32 v[50:51], v[50:51], v[60:61]
	v_pk_add_f32 v[52:53], v[52:53], v[62:63]
	s_nop 0
	v_pk_add_f32 v[50:51], v[50:51], v[52:53]
	s_nop 0
	v_pk_add_f32 v[48:49], v[48:49], v[50:51]
	v_mad_i64_i32 v[50:51], s[4:5], v66, s8, v[138:139]
	v_add_f32_e32 v48, v48, v49
	v_fmamk_f32 v48, v48, 0x3a800000, v234
	v_cmp_gt_f32_e32 vcc, s6, v48
	v_mul_f32_e32 v49, 0x4b800000, v48
	v_lshl_add_u64 v[50:51], v[50:51], 0, v[140:141]
	v_cndmask_b32_e32 v48, v48, v49, vcc
	v_rsq_f32_e32 v48, v48
	s_nop 0
	v_mul_f32_e32 v49, 0x45800000, v48
	v_cndmask_b32_e32 v48, v48, v49, vcc
	v_pk_mul_f32 v[46:47], v[46:47], v[48:49] op_sel_hi:[1,0]
	v_pk_mul_f32 v[44:45], v[44:45], v[48:49] op_sel_hi:[1,0]
	v_pk_mul_f32 v[52:53], v[42:43], v[48:49] op_sel_hi:[1,0]
	v_pk_mul_f32 v[42:43], v[40:41], v[48:49] op_sel_hi:[1,0]
	v_cvt_pk_bf16_f32 v40, v44, v45
	v_cvt_pk_bf16_f32 v41, v46, v47
	v_pk_mul_f32 v[38:39], v[38:39], v[48:49] op_sel_hi:[1,0]
	v_cvt_pk_bf16_f32 v42, v42, v43
	v_cvt_pk_bf16_f32 v43, v52, v53
	global_store_dwordx4 v[50:51], v[40:43], off
	v_pk_mul_f32 v[36:37], v[36:37], v[48:49] op_sel_hi:[1,0]
	s_nop 0
	v_pk_mul_f32 v[40:41], v[34:35], v[48:49] op_sel_hi:[1,0]
	v_pk_mul_f32 v[34:35], v[32:33], v[48:49] op_sel_hi:[1,0]
	v_cvt_pk_bf16_f32 v32, v36, v37
	v_cvt_pk_bf16_f32 v33, v38, v39
	s_nop 0
	v_cvt_pk_bf16_f32 v34, v34, v35
	v_cvt_pk_bf16_f32 v35, v40, v41
	global_store_dwordx4 v[50:51], v[32:35], off offset:256
	v_add_u32_e32 v50, 0xa0, v146
	s_nop 0
	v_add_u32_e32 v32, s68, v50
	v_ashrrev_i32_e32 v33, 31, v32
	v_lshlrev_b64 v[32:33], 6, v[32:33]
	v_lshl_add_u64 v[44:45], s[38:39], 0, v[32:33]
	global_load_dwordx4 v[32:35], v[44:45], off
	global_load_dwordx4 v[36:39], v[44:45], off offset:16
	global_load_dwordx4 v[40:43], v[44:45], off offset:32
	s_nop 0
	global_load_dwordx4 v[44:47], v[44:45], off offset:48
	s_waitcnt vmcnt(0) lgkmcnt(0)
; __device__ __forceinline__ void st8(bf16_t* p, f32x4 a, f32x4 b) { u32x4 w = {cvt_pk(a[0], a[1]), cvt_pk(a[2], a[3]), cvt_pk(b[0], b[1]), cvt_pk(b[2], b[3])}; *(u32x4*)p = w; }
; #define FOR_AI_M _Pragma("unroll") for (int ai = 0; ai < 2; ++ai) if ((__builtin_amdgcn_sched_barrier(0), true)) _Pragma("unroll") for (int m = 0; m < 4; ++m)
;   __device__ __forceinline__ void operator()(EPI_ARGS) const {
;     const int rbase = u.pm * 256 + wr * 64 + fr, c0 = u.pn * 256 + wc * 32 + fq * 8;
;     FOR_AI_M { const int row = rbase + ai * 128 + m * 16; const f32x4* sp = (const f32x4*)(b.ssq_x1 + (size_t)(b.g0 + row) * 16); const f32x4 q0 = sp[0], q1 = sp[1], q2 = sp[2], q3 = sp[3];
;       const float r2 = rsqrtf(((((q0[0] + q0[1]) + (q0[2] + q0[3])) + ((q1[0] + q1[1]) + (q1[2] + q1[3]))) + (((q2[0] + q2[1]) + (q2[2] + q2[3])) + ((q3[0] + q3[1]) + (q3[2] + q3[3])))) * (1.f / 1024.f) + EPS);
; #pragma unroll
;       for (int bj = 0; bj < 2; ++bj) st8(b.UR + (size_t)row * N_UP + c0 + bj * 128, acc[ai][bj][m][0] * r2, acc[ai][bj][m][1] * r2); }
;   }
	v_mov_b32_e32 v48, v32
	v_mov_b32_e32 v49, v40
	v_mov_b32_e32 v40, v33
	v_pk_add_f32 v[32:33], v[48:49], v[40:41]
	v_mov_b32_e32 v40, v34
	v_mov_b32_e32 v41, v42
	v_mov_b32_e32 v42, v35
	v_pk_add_f32 v[34:35], v[40:41], v[42:43]
	s_nop 0
	v_pk_add_f32 v[32:33], v[32:33], v[34:35]
	v_mov_b32_e32 v34, v36
	v_mov_b32_e32 v35, v44
	v_mov_b32_e32 v44, v37
	v_mov_b32_e32 v36, v38
	v_mov_b32_e32 v37, v46
	v_mov_b32_e32 v46, v39
	v_pk_add_f32 v[34:35], v[34:35], v[44:45]
	v_pk_add_f32 v[36:37], v[36:37], v[46:47]
	s_nop 0
	v_pk_add_f32 v[34:35], v[34:35], v[36:37]
	s_nop 0
	v_pk_add_f32 v[32:33], v[32:33], v[34:35]
	v_mad_i64_i32 v[34:35], s[4:5], v50, s8, v[138:139]
	v_add_f32_e32 v32, v32, v33
	v_fmamk_f32 v32, v32, 0x3a800000, v234
	v_cmp_gt_f32_e32 vcc, s6, v32
	v_mul_f32_e32 v33, 0x4b800000, v32
	v_lshl_add_u64 v[34:35], v[34:35], 0, v[140:141]
	v_cndmask_b32_e32 v32, v32, v33, vcc
	v_rsq_f32_e32 v32, v32
	s_nop 0
	v_mul_f32_e32 v33, 0x45800000, v32
	v_cndmask_b32_e32 v32, v32, v33, vcc
	v_pk_mul_f32 v[30:31], v[30:31], v[32:33] op_sel_hi:[1,0]
	v_pk_mul_f32 v[28:29], v[28:29], v[32:33] op_sel_hi:[1,0]
	v_pk_mul_f32 v[36:37], v[26:27], v[32:33] op_sel_hi:[1,0]
	v_pk_mul_f32 v[26:27], v[24:25], v[32:33] op_sel_hi:[1,0]
	v_cvt_pk_bf16_f32 v24, v28, v29
	v_cvt_pk_bf16_f32 v25, v30, v31
	v_pk_mul_f32 v[22:23], v[22:23], v[32:33] op_sel_hi:[1,0]
	v_cvt_pk_bf16_f32 v26, v26, v27
	v_cvt_pk_bf16_f32 v27, v36, v37
	global_store_dwordx4 v[34:35], v[24:27], off
	v_pk_mul_f32 v[20:21], v[20:21], v[32:33] op_sel_hi:[1,0]
	s_nop 0
	v_pk_mul_f32 v[24:25], v[18:19], v[32:33] op_sel_hi:[1,0]
	v_pk_mul_f32 v[18:19], v[16:17], v[32:33] op_sel_hi:[1,0]
	v_cvt_pk_bf16_f32 v16, v20, v21
	v_cvt_pk_bf16_f32 v17, v22, v23
	s_nop 0
	v_cvt_pk_bf16_f32 v18, v18, v19
	v_cvt_pk_bf16_f32 v19, v24, v25
	global_store_dwordx4 v[34:35], v[16:19], off offset:256
	v_add_u32_e32 v34, 0xb0, v146
	s_nop 0
	v_add_u32_e32 v16, s68, v34
	v_ashrrev_i32_e32 v17, 31, v16
	v_lshlrev_b64 v[16:17], 6, v[16:17]
	v_lshl_add_u64 v[28:29], s[38:39], 0, v[16:17]
	global_load_dwordx4 v[16:19], v[28:29], off
	global_load_dwordx4 v[20:23], v[28:29], off offset:16
	global_load_dwordx4 v[24:27], v[28:29], off offset:32
	s_nop 0
	global_load_dwordx4 v[28:31], v[28:29], off offset:48
	s_waitcnt vmcnt(0) lgkmcnt(0)
	v_mov_b32_e32 v32, v16
	v_mov_b32_e32 v33, v24
	v_mov_b32_e32 v24, v17
	v_pk_add_f32 v[16:17], v[32:33], v[24:25]
	v_mov_b32_e32 v24, v18
	v_mov_b32_e32 v25, v26
	v_mov_b32_e32 v26, v19
	v_pk_add_f32 v[18:19], v[24:25], v[26:27]
	s_nop 0
	v_pk_add_f32 v[16:17], v[16:17], v[18:19]
	v_mov_b32_e32 v18, v20
	v_mov_b32_e32 v19, v28
	v_mov_b32_e32 v28, v21
	v_mov_b32_e32 v20, v22
	v_mov_b32_e32 v21, v30
	v_mov_b32_e32 v30, v23
	v_pk_add_f32 v[18:19], v[18:19], v[28:29]
	v_pk_add_f32 v[20:21], v[20:21], v[30:31]
	s_nop 0
	v_pk_add_f32 v[18:19], v[18:19], v[20:21]
	s_nop 0
	v_pk_add_f32 v[16:17], v[16:17], v[18:19]
	v_mad_i64_i32 v[18:19], s[4:5], v34, s8, v[138:139]
	v_add_f32_e32 v16, v16, v17
	v_fmamk_f32 v16, v16, 0x3a800000, v234
	v_cmp_gt_f32_e32 vcc, s6, v16
	v_mul_f32_e32 v17, 0x4b800000, v16
	v_lshl_add_u64 v[18:19], v[18:19], 0, v[140:141]
	v_cndmask_b32_e32 v16, v16, v17, vcc
	v_rsq_f32_e32 v16, v16
	s_mov_b64 s[4:5], -1
	v_mul_f32_e32 v17, 0x45800000, v16
	v_cndmask_b32_e32 v16, v16, v17, vcc
	v_pk_mul_f32 v[14:15], v[14:15], v[16:17] op_sel_hi:[1,0]
	v_pk_mul_f32 v[12:13], v[12:13], v[16:17] op_sel_hi:[1,0]
	v_pk_mul_f32 v[20:21], v[10:11], v[16:17] op_sel_hi:[1,0]
	v_pk_mul_f32 v[10:11], v[8:9], v[16:17] op_sel_hi:[1,0]
	v_cvt_pk_bf16_f32 v8, v12, v13
	v_cvt_pk_bf16_f32 v9, v14, v15
	s_and_b64 vcc, exec, s[42:43]
	v_cvt_pk_bf16_f32 v10, v10, v11
	v_cvt_pk_bf16_f32 v11, v20, v21
	global_store_dwordx4 v[18:19], v[8:11], off
	v_pk_mul_f32 v[6:7], v[6:7], v[16:17] op_sel_hi:[1,0]
	v_pk_mul_f32 v[4:5], v[4:5], v[16:17] op_sel_hi:[1,0]
	v_pk_mul_f32 v[8:9], v[2:3], v[16:17] op_sel_hi:[1,0]
	v_pk_mul_f32 v[2:3], v[0:1], v[16:17] op_sel_hi:[1,0]
	v_cvt_pk_bf16_f32 v0, v4, v5
	v_cvt_pk_bf16_f32 v1, v6, v7
	s_nop 0
	v_cvt_pk_bf16_f32 v2, v2, v3
	v_cvt_pk_bf16_f32 v3, v8, v9
	global_store_dwordx4 v[18:19], v[0:3], off offset:256
	s_cbranch_vccnz .LBB0_941
	s_andn2_b64 vcc, exec, s[34:35]
	s_cbranch_vccnz .LBB0_940
	s_barrier
	s_branch .LBB0_940

; __device__ __forceinline__ float bflo(unsigned w) { return __uint_as_float(w << 16); }
; __device__ __forceinline__ float bfhi(unsigned w) { return __uint_as_float(w & 0xffff0000u); }
; __device__ __forceinline__ void st8(bf16_t* p, f32x4 a, f32x4 b) { u32x4 w = {cvt_pk(a[0], a[1]), cvt_pk(a[2], a[3]), cvt_pk(b[0], b[1]), cvt_pk(b[2], b[3])}; *(u32x4*)p = w; }
; __device__ __forceinline__ float sigm(float x) { return __builtin_amdgcn_rcpf(1.f + __builtin_amdgcn_exp2f(x * -1.4426950408889634f)); }
; __device__ __forceinline__ void conv_gate(const Bufs& b, const float* cw, const float* cbias, int CH, int bid, int nb, int tid) {
;     ...
; #pragma unroll
;     for (int i = 0; i < 8; ++i) {
;       float ua[8], ub[8];
; #pragma unroll
;       for (int e = 0; e < 8; ++e) { ua[e] = bs[0][e]; ub[e] = bs[1][e]; }
; #pragma unroll
;       for (int k = 0; k < 3; ++k) { const u32x4 xa = raw[0][i + k], xb = raw[1][i + k];
;         const float fa[8] = {bflo(xa.x), bfhi(xa.x), bflo(xa.y), bfhi(xa.y), bflo(xa.z), bfhi(xa.z), bflo(xa.w), bfhi(xa.w)};
;         const float fb[8] = {bflo(xb.x), bfhi(xb.x), bflo(xb.y), bfhi(xb.y), bflo(xb.z), bfhi(xb.z), bflo(xb.w), bfhi(xb.w)};
; #pragma unroll
;         for (int e = 0; e < 8; ++e) { ua[e] += fa[e] * w[0][k][e]; ub[e] += fb[e] * w[1][k][e]; } }
;       f32x4 y0, y1;
; #pragma unroll
;       for (int e = 0; e < 4; ++e) { y0[e] = ua[e] * sigm(ua[e]) * ub[e]; y1[e] = ua[4 + e] * sigm(ua[4 + e]) * ub[4 + e]; }
;       st8(b.G + (size_t)(r0 + i) * DFF + c, y0, y1);
.LBB0_1009:
	s_waitcnt vmcnt(0) lgkmcnt(0)
	v_lshlrev_b32_e32 v149, 16, v100
	v_lshlrev_b32_e32 v148, 16, v88
	v_pk_fma_f32 v[148:149], v[142:143], v[148:149], v[140:141]
	v_lshlrev_b32_e32 v157, 16, v108
	v_lshlrev_b32_e32 v156, 16, v96
	v_pk_fma_f32 v[150:151], v[144:145], v[156:157], v[148:149]
	v_lshlrev_b32_e32 v149, 16, v104
	v_lshlrev_b32_e32 v148, 16, v92
	v_pk_fma_f32 v[166:167], v[146:147], v[148:149], v[150:151]
	v_and_b32_e32 v151, 0xffff0000, v100
	v_and_b32_e32 v150, 0xffff0000, v88
	v_pk_fma_f32 v[150:151], v[20:21], v[150:151], v[0:1]
	v_and_b32_e32 v159, 0xffff0000, v108
	v_and_b32_e32 v158, 0xffff0000, v96
	v_pk_fma_f32 v[152:153], v[12:13], v[158:159], v[150:151]
	v_and_b32_e32 v151, 0xffff0000, v104
	v_and_b32_e32 v150, 0xffff0000, v92
	v_pk_fma_f32 v[168:169], v[28:29], v[150:151], v[152:153]
	v_lshlrev_b32_e32 v152, 16, v89
	v_lshlrev_b32_e32 v153, 16, v101
	v_and_b32_e32 v101, 0xffff0000, v101
	v_and_b32_e32 v100, 0xffff0000, v89
	v_pk_fma_f32 v[152:153], v[126:127], v[152:153], v[124:125]
	v_lshlrev_b32_e32 v161, 16, v109
	v_lshlrev_b32_e32 v160, 16, v97
	v_pk_fma_f32 v[88:89], v[22:23], v[100:101], v[2:3]
	v_and_b32_e32 v109, 0xffff0000, v109
	v_and_b32_e32 v108, 0xffff0000, v97
	v_pk_fma_f32 v[154:155], v[138:139], v[160:161], v[152:153]
	v_lshlrev_b32_e32 v152, 16, v93
	v_pk_fma_f32 v[96:97], v[14:15], v[108:109], v[88:89]
	v_and_b32_e32 v88, 0xffff0000, v93
	v_lshlrev_b32_e32 v93, 16, v102
	v_lshlrev_b32_e32 v92, 16, v90
	v_lshlrev_b32_e32 v153, 16, v105
	v_and_b32_e32 v89, 0xffff0000, v105
	v_pk_fma_f32 v[92:93], v[122:123], v[92:93], v[120:121]
	v_lshlrev_b32_e32 v105, 16, v110
	v_lshlrev_b32_e32 v104, 16, v98
	v_pk_fma_f32 v[172:173], v[30:31], v[88:89], v[96:97]
	v_pk_fma_f32 v[96:97], v[134:135], v[104:105], v[92:93]
	v_lshlrev_b32_e32 v93, 16, v106
	v_lshlrev_b32_e32 v92, 16, v94
	v_pk_fma_f32 v[174:175], v[130:131], v[92:93], v[96:97]
	v_and_b32_e32 v97, 0xffff0000, v102
	v_and_b32_e32 v96, 0xffff0000, v90
	v_pk_fma_f32 v[96:97], v[24:25], v[96:97], v[4:5]
	v_and_b32_e32 v163, 0xffff0000, v110
	v_and_b32_e32 v162, 0xffff0000, v98
	v_pk_fma_f32 v[100:101], v[16:17], v[162:163], v[96:97]
	v_and_b32_e32 v97, 0xffff0000, v106
	v_and_b32_e32 v96, 0xffff0000, v94
	v_pk_fma_f32 v[176:177], v[8:9], v[96:97], v[100:101]
	v_lshlrev_b32_e32 v100, 16, v91
	v_lshlrev_b32_e32 v101, 16, v103
	v_pk_fma_f32 v[100:101], v[118:119], v[100:101], v[116:117]
	v_lshlrev_b32_e32 v165, 16, v111
	v_lshlrev_b32_e32 v164, 16, v99
	v_and_b32_e32 v103, 0xffff0000, v103
	v_and_b32_e32 v102, 0xffff0000, v91
	v_pk_fma_f32 v[170:171], v[136:137], v[152:153], v[154:155]
	v_pk_fma_f32 v[154:155], v[132:133], v[164:165], v[100:101]
	v_lshlrev_b32_e32 v101, 16, v107
	v_lshlrev_b32_e32 v100, 16, v95
	v_pk_fma_f32 v[90:91], v[26:27], v[102:103], v[6:7]
	v_and_b32_e32 v103, 0xffff0000, v111
	v_and_b32_e32 v102, 0xffff0000, v99
	v_pk_fma_f32 v[178:179], v[128:129], v[100:101], v[154:155]
	v_pk_fma_f32 v[90:91], v[18:19], v[102:103], v[90:91]
	v_and_b32_e32 v155, 0xffff0000, v107
	v_and_b32_e32 v154, 0xffff0000, v95
	v_pk_fma_f32 v[90:91], v[10:11], v[154:155], v[90:91]
	v_mul_f32_e32 v94, 0xbfb8aa3b, v166
	v_mul_f32_e32 v111, 0xbfb8aa3b, v90
	v_mul_f32_e32 v95, 0xbfb8aa3b, v174
	v_mul_f32_e32 v98, 0xbfb8aa3b, v168
	v_mul_f32_e32 v99, 0xbfb8aa3b, v176
	v_mul_f32_e32 v106, 0xbfb8aa3b, v170
	v_mul_f32_e32 v107, 0xbfb8aa3b, v178
	v_mul_f32_e32 v110, 0xbfb8aa3b, v172
	v_exp_f32_e32 v111, v111
	v_exp_f32_e32 v94, v94
	v_exp_f32_e32 v95, v95
	v_exp_f32_e32 v98, v98
	v_exp_f32_e32 v99, v99
	v_exp_f32_e32 v106, v106
	v_exp_f32_e32 v107, v107
	v_exp_f32_e32 v110, v110
	v_add_f32_e32 v111, 1.0, v111
	v_add_f32_e32 v94, 1.0, v94
	v_add_f32_e32 v95, 1.0, v95
	v_add_f32_e32 v98, 1.0, v98
	v_add_f32_e32 v99, 1.0, v99
	v_add_f32_e32 v106, 1.0, v106
	v_add_f32_e32 v107, 1.0, v107
	v_add_f32_e32 v110, 1.0, v110
	v_rcp_f32_e32 v111, v111
	v_rcp_f32_e32 v94, v94
	v_rcp_f32_e32 v95, v95
	v_rcp_f32_e32 v98, v98
	v_rcp_f32_e32 v99, v99
	v_rcp_f32_e32 v106, v106
	v_rcp_f32_e32 v107, v107
	v_rcp_f32_e32 v110, v110
	v_mul_f32_e32 v90, v90, v111
	v_mul_f32_e32 v94, v166, v94
	v_mul_f32_e32 v95, v174, v95
	v_mul_f32_e32 v98, v168, v98
	v_mul_f32_e32 v99, v176, v99
	v_mul_f32_e32 v106, v170, v106
	v_mul_f32_e32 v107, v178, v107
	v_mul_f32_e32 v110, v172, v110
	v_mul_f32_e32 v111, v90, v91
	v_mad_i64_i32 v[90:91], s[4:5], s19, v240, v[114:115]
	v_mul_f32_e32 v94, v94, v167
	v_mul_f32_e32 v95, v95, v175
	v_mul_f32_e32 v98, v98, v169
	v_mul_f32_e32 v99, v99, v177
	v_mul_f32_e32 v106, v106, v171
	v_mul_f32_e32 v107, v107, v179
	v_mul_f32_e32 v110, v110, v173
	v_cvt_pk_bf16_f32 v166, v94, v98
	v_cvt_pk_bf16_f32 v167, v106, v110
	v_cvt_pk_bf16_f32 v168, v95, v99
	v_cvt_pk_bf16_f32 v169, v107, v111
	global_store_dwordx4 v[90:91], v[166:169], off
	v_pk_fma_f32 v[90:91], v[142:143], v[156:157], v[140:141]
	v_lshlrev_b32_e32 v95, 16, v84
	v_pk_fma_f32 v[90:91], v[144:145], v[148:149], v[90:91]
	v_lshlrev_b32_e32 v94, 16, v80
	v_pk_fma_f32 v[98:99], v[146:147], v[94:95], v[90:91]
	v_pk_fma_f32 v[90:91], v[20:21], v[158:159], v[0:1]
	v_lshlrev_b32_e32 v111, 16, v85
	v_pk_fma_f32 v[106:107], v[12:13], v[150:151], v[90:91]
	v_and_b32_e32 v91, 0xffff0000, v84
	v_and_b32_e32 v90, 0xffff0000, v80
	v_pk_fma_f32 v[156:157], v[28:29], v[90:91], v[106:107]
	v_pk_fma_f32 v[106:107], v[126:127], v[160:161], v[124:125]
	v_lshlrev_b32_e32 v110, 16, v81
	v_pk_fma_f32 v[106:107], v[138:139], v[152:153], v[106:107]
	v_and_b32_e32 v84, 0xffff0000, v81
	v_pk_fma_f32 v[80:81], v[122:123], v[104:105], v[120:121]
	v_pk_fma_f32 v[158:159], v[136:137], v[110:111], v[106:107]
	v_pk_fma_f32 v[106:107], v[22:23], v[108:109], v[2:3]
; __device__ __forceinline__ float bflo(unsigned w) { return __uint_as_float(w << 16); }
; __device__ __forceinline__ float bfhi(unsigned w) { return __uint_as_float(w & 0xffff0000u); }
; __device__ __forceinline__ void st8(bf16_t* p, f32x4 a, f32x4 b) { u32x4 w = {cvt_pk(a[0], a[1]), cvt_pk(a[2], a[3]), cvt_pk(b[0], b[1]), cvt_pk(b[2], b[3])}; *(u32x4*)p = w; }
; __device__ __forceinline__ float sigm(float x) { return __builtin_amdgcn_rcpf(1.f + __builtin_amdgcn_exp2f(x * -1.4426950408889634f)); }
; __device__ __forceinline__ void conv_gate(const Bufs& b, const float* cw, const float* cbias, int CH, int bid, int nb, int tid) {
;     ...
; #pragma unroll
;     for (int i = 0; i < 8; ++i) {
;       float ua[8], ub[8];
; #pragma unroll
;       for (int e = 0; e < 8; ++e) { ua[e] = bs[0][e]; ub[e] = bs[1][e]; }
; #pragma unroll
;       for (int k = 0; k < 3; ++k) { const u32x4 xa = raw[0][i + k], xb = raw[1][i + k];
;         const float fa[8] = {bflo(xa.x), bfhi(xa.x), bflo(xa.y), bfhi(xa.y), bflo(xa.z), bfhi(xa.z), bflo(xa.w), bfhi(xa.w)};
;         const float fb[8] = {bflo(xb.x), bfhi(xb.x), bflo(xb.y), bfhi(xb.y), bflo(xb.z), bfhi(xb.z), bflo(xb.w), bfhi(xb.w)};
; #pragma unroll
;         for (int e = 0; e < 8; ++e) { ua[e] += fa[e] * w[0][k][e]; ub[e] += fb[e] * w[1][k][e]; } }
;       f32x4 y0, y1;
; #pragma unroll
;       for (int e = 0; e < 4; ++e) { y0[e] = ua[e] * sigm(ua[e]) * ub[e]; y1[e] = ua[4 + e] * sigm(ua[4 + e]) * ub[4 + e]; }
;       st8(b.G + (size_t)(r0 + i) * DFF + c, y0, y1);
	v_pk_fma_f32 v[80:81], v[134:135], v[92:93], v[80:81]
	v_lshlrev_b32_e32 v109, 16, v86
	v_lshlrev_b32_e32 v108, 16, v82
	v_pk_fma_f32 v[106:107], v[14:15], v[88:89], v[106:107]
	v_and_b32_e32 v85, 0xffff0000, v85
	v_pk_fma_f32 v[104:105], v[130:131], v[108:109], v[80:81]
	v_pk_fma_f32 v[80:81], v[24:25], v[162:163], v[4:5]
	v_pk_fma_f32 v[160:161], v[30:31], v[84:85], v[106:107]
	v_pk_fma_f32 v[106:107], v[16:17], v[96:97], v[80:81]
	v_and_b32_e32 v81, 0xffff0000, v86
	v_and_b32_e32 v80, 0xffff0000, v82
	v_pk_fma_f32 v[162:163], v[8:9], v[80:81], v[106:107]
	v_pk_fma_f32 v[106:107], v[118:119], v[164:165], v[116:117]
	v_pk_fma_f32 v[102:103], v[26:27], v[102:103], v[6:7]
	v_pk_fma_f32 v[164:165], v[132:133], v[100:101], v[106:107]
	v_lshlrev_b32_e32 v107, 16, v87
	v_pk_fma_f32 v[102:103], v[18:19], v[154:155], v[102:103]
	v_and_b32_e32 v87, 0xffff0000, v87
	v_and_b32_e32 v86, 0xffff0000, v83
	v_lshlrev_b32_e32 v106, 16, v83
	v_pk_fma_f32 v[82:83], v[10:11], v[86:87], v[102:103]
	v_mul_f32_e32 v102, 0xbfb8aa3b, v98
	v_exp_f32_e32 v102, v102
	v_mul_f32_e32 v103, 0xbfb8aa3b, v162
	v_exp_f32_e32 v103, v103
	v_pk_fma_f32 v[164:165], v[128:129], v[106:107], v[164:165]
	v_add_f32_e32 v102, 1.0, v102
	v_rcp_f32_e32 v102, v102
	v_add_f32_e32 v103, 1.0, v103
	v_rcp_f32_e32 v103, v103
	s_add_i32 s4, s19, 1
	v_mul_f32_e32 v98, v98, v102
	v_mul_f32_e32 v98, v98, v99
	v_mul_f32_e32 v99, 0xbfb8aa3b, v104
	v_mul_f32_e32 v102, 0xbfb8aa3b, v156
	v_exp_f32_e32 v99, v99
	v_exp_f32_e32 v102, v102
	v_mul_f32_e32 v103, v162, v103
	v_pk_fma_f32 v[154:155], v[26:27], v[154:155], v[6:7]
	v_add_f32_e32 v99, 1.0, v99
	v_add_f32_e32 v102, 1.0, v102
	v_rcp_f32_e32 v99, v99
	v_rcp_f32_e32 v102, v102
	v_pk_fma_f32 v[154:155], v[18:19], v[86:87], v[154:155]
	v_pk_fma_f32 v[88:89], v[22:23], v[88:89], v[2:3]
	v_mul_f32_e32 v99, v104, v99
	v_mul_f32_e32 v102, v156, v102
	v_mul_f32_e32 v99, v99, v105
	v_mul_f32_e32 v102, v102, v157
	v_mul_f32_e32 v104, v103, v163
	v_mul_f32_e32 v103, 0xbfb8aa3b, v158
	v_mul_f32_e32 v105, 0xbfb8aa3b, v164
	v_mul_f32_e32 v157, 0xbfb8aa3b, v82
	v_exp_f32_e32 v103, v103
	v_exp_f32_e32 v105, v105
	v_mul_f32_e32 v156, 0xbfb8aa3b, v160
	v_exp_f32_e32 v157, v157
	v_exp_f32_e32 v156, v156
	v_add_f32_e32 v103, 1.0, v103
	v_add_f32_e32 v105, 1.0, v105
	v_add_f32_e32 v157, 1.0, v157
	v_rcp_f32_e32 v103, v103
	v_rcp_f32_e32 v105, v105
	v_add_f32_e32 v156, 1.0, v156
	v_rcp_f32_e32 v157, v157
	v_rcp_f32_e32 v156, v156
	v_mul_f32_e32 v103, v158, v103
	v_mul_f32_e32 v105, v164, v105
	v_mul_f32_e32 v82, v82, v157
	v_mul_f32_e32 v103, v103, v159
	v_mul_f32_e32 v105, v105, v165
	v_mul_f32_e32 v156, v160, v156
	v_mul_f32_e32 v157, v82, v83
	v_mad_i64_i32 v[82:83], s[4:5], s4, v240, v[114:115]
	v_mul_f32_e32 v156, v156, v161
	v_cvt_pk_bf16_f32 v102, v98, v102
	v_cvt_pk_bf16_f32 v103, v103, v156
	v_cvt_pk_bf16_f32 v104, v99, v104
	v_cvt_pk_bf16_f32 v105, v105, v157
	global_store_dwordx4 v[82:83], v[102:105], off
	v_pk_fma_f32 v[82:83], v[142:143], v[148:149], v[140:141]
	v_pk_fma_f32 v[88:89], v[14:15], v[84:85], v[88:89]
	v_pk_fma_f32 v[82:83], v[144:145], v[94:95], v[82:83]
	v_lshlrev_b32_e32 v105, 16, v76
	v_lshlrev_b32_e32 v104, 16, v72
	v_pk_fma_f32 v[148:149], v[146:147], v[104:105], v[82:83]
	v_pk_fma_f32 v[82:83], v[20:21], v[150:151], v[0:1]
	v_lshlrev_b32_e32 v103, 16, v77
	v_pk_fma_f32 v[98:99], v[12:13], v[90:91], v[82:83]
	v_and_b32_e32 v83, 0xffff0000, v76
	v_and_b32_e32 v82, 0xffff0000, v72
	v_pk_fma_f32 v[150:151], v[28:29], v[82:83], v[98:99]
	v_pk_fma_f32 v[98:99], v[126:127], v[152:153], v[124:125]
	v_lshlrev_b32_e32 v102, 16, v73
	v_pk_fma_f32 v[98:99], v[138:139], v[110:111], v[98:99]
	v_and_b32_e32 v76, 0xffff0000, v73
	v_pk_fma_f32 v[72:73], v[122:123], v[92:93], v[120:121]
	v_pk_fma_f32 v[152:153], v[136:137], v[102:103], v[98:99]
	v_pk_fma_f32 v[72:73], v[134:135], v[108:109], v[72:73]
	v_lshlrev_b32_e32 v99, 16, v78
	v_lshlrev_b32_e32 v98, 16, v74
	v_pk_fma_f32 v[92:93], v[130:131], v[98:99], v[72:73]
	v_pk_fma_f32 v[72:73], v[24:25], v[96:97], v[4:5]
	v_and_b32_e32 v77, 0xffff0000, v77
	v_pk_fma_f32 v[96:97], v[16:17], v[80:81], v[72:73]
	v_and_b32_e32 v73, 0xffff0000, v78
	v_and_b32_e32 v72, 0xffff0000, v74
	v_pk_fma_f32 v[156:157], v[8:9], v[72:73], v[96:97]
	v_pk_fma_f32 v[96:97], v[118:119], v[100:101], v[116:117]
	v_and_b32_e32 v78, 0xffff0000, v75
	v_pk_fma_f32 v[100:101], v[132:133], v[106:107], v[96:97]
	v_lshlrev_b32_e32 v97, 16, v79
	v_and_b32_e32 v79, 0xffff0000, v79
	v_lshlrev_b32_e32 v96, 16, v75
	v_pk_fma_f32 v[74:75], v[10:11], v[78:79], v[154:155]
	v_mul_f32_e32 v154, 0xbfb8aa3b, v148
	v_exp_f32_e32 v154, v154
	v_pk_fma_f32 v[100:101], v[128:129], v[96:97], v[100:101]
	v_pk_fma_f32 v[88:89], v[30:31], v[76:77], v[88:89]
	s_add_i32 s4, s19, 2
	v_add_f32_e32 v154, 1.0, v154
	v_rcp_f32_e32 v154, v154
	v_pk_fma_f32 v[86:87], v[26:27], v[86:87], v[6:7]
	v_pk_fma_f32 v[84:85], v[22:23], v[84:85], v[2:3]
	v_pk_fma_f32 v[86:87], v[18:19], v[78:79], v[86:87]
	v_mul_f32_e32 v148, v148, v154
	v_mul_f32_e32 v148, v148, v149
	v_mul_f32_e32 v149, 0xbfb8aa3b, v92
	v_exp_f32_e32 v149, v149
	v_pk_fma_f32 v[84:85], v[14:15], v[76:77], v[84:85]
	v_pk_fma_f32 v[78:79], v[26:27], v[78:79], v[6:7]
	v_pk_fma_f32 v[76:77], v[22:23], v[76:77], v[2:3]
	v_add_f32_e32 v149, 1.0, v149
	v_rcp_f32_e32 v149, v149
	s_add_i32 s34, s34, s55
	v_mul_f32_e32 v92, v92, v149
	v_mul_f32_e32 v92, v92, v93
	v_mul_f32_e32 v93, 0xbfb8aa3b, v150
	v_exp_f32_e32 v93, v93
	v_mul_f32_e32 v149, 0xbfb8aa3b, v156
	v_exp_f32_e32 v149, v149
	v_add_f32_e32 v93, 1.0, v93
	v_rcp_f32_e32 v93, v93
	v_add_f32_e32 v149, 1.0, v149
	v_rcp_f32_e32 v149, v149
	v_mul_f32_e32 v93, v150, v93
; __device__ __forceinline__ float bflo(unsigned w) { return __uint_as_float(w << 16); }
; __device__ __forceinline__ float bfhi(unsigned w) { return __uint_as_float(w & 0xffff0000u); }
; __device__ __forceinline__ void st8(bf16_t* p, f32x4 a, f32x4 b) { u32x4 w = {cvt_pk(a[0], a[1]), cvt_pk(a[2], a[3]), cvt_pk(b[0], b[1]), cvt_pk(b[2], b[3])}; *(u32x4*)p = w; }
; __device__ __forceinline__ float sigm(float x) { return __builtin_amdgcn_rcpf(1.f + __builtin_amdgcn_exp2f(x * -1.4426950408889634f)); }
; __device__ __forceinline__ void conv_gate(const Bufs& b, const float* cw, const float* cbias, int CH, int bid, int nb, int tid) {
;     ...
; #pragma unroll
;     for (int i = 0; i < 8; ++i) {
;       float ua[8], ub[8];
; #pragma unroll
;       for (int e = 0; e < 8; ++e) { ua[e] = bs[0][e]; ub[e] = bs[1][e]; }
; #pragma unroll
;       for (int k = 0; k < 3; ++k) { const u32x4 xa = raw[0][i + k], xb = raw[1][i + k];
;         const float fa[8] = {bflo(xa.x), bfhi(xa.x), bflo(xa.y), bfhi(xa.y), bflo(xa.z), bfhi(xa.z), bflo(xa.w), bfhi(xa.w)};
;         const float fb[8] = {bflo(xb.x), bfhi(xb.x), bflo(xb.y), bfhi(xb.y), bflo(xb.z), bfhi(xb.z), bflo(xb.w), bfhi(xb.w)};
; #pragma unroll
;         for (int e = 0; e < 8; ++e) { ua[e] += fa[e] * w[0][k][e]; ub[e] += fb[e] * w[1][k][e]; } }
;       f32x4 y0, y1;
; #pragma unroll
;       for (int e = 0; e < 4; ++e) { y0[e] = ua[e] * sigm(ua[e]) * ub[e]; y1[e] = ua[4 + e] * sigm(ua[4 + e]) * ub[4 + e]; }
;       st8(b.G + (size_t)(r0 + i) * DFF + c, y0, y1);
	v_mul_f32_e32 v93, v93, v151
	v_mul_f32_e32 v151, 0xbfb8aa3b, v100
	v_exp_f32_e32 v151, v151
	v_mul_f32_e32 v149, v156, v149
	v_mul_f32_e32 v150, v149, v157
	v_mul_f32_e32 v149, 0xbfb8aa3b, v152
	v_add_f32_e32 v151, 1.0, v151
	v_rcp_f32_e32 v151, v151
	v_exp_f32_e32 v149, v149
	v_cvt_pk_bf16_f32 v148, v148, v93
	v_lshlrev_b32_e32 v93, 16, v69
	v_mul_f32_e32 v100, v100, v151
	v_mul_f32_e32 v100, v100, v101
	v_mul_f32_e32 v101, 0xbfb8aa3b, v88
	v_exp_f32_e32 v101, v101
	v_add_f32_e32 v149, 1.0, v149
	v_rcp_f32_e32 v149, v149
	v_and_b32_e32 v69, 0xffff0000, v69
	v_add_f32_e32 v101, 1.0, v101
	v_rcp_f32_e32 v101, v101
	v_mul_f32_e32 v149, v152, v149
	v_mul_f32_e32 v149, v149, v153
	v_mul_f32_e32 v88, v88, v101
	v_mul_f32_e32 v88, v88, v89
	v_mul_f32_e32 v89, 0xbfb8aa3b, v74
	v_exp_f32_e32 v89, v89
	v_cvt_pk_bf16_f32 v149, v149, v88
	v_cvt_pk_bf16_f32 v150, v92, v150
	v_lshlrev_b32_e32 v92, 16, v65
	v_add_f32_e32 v89, 1.0, v89
	v_rcp_f32_e32 v89, v89
	s_nop 0
	v_mul_f32_e32 v74, v74, v89
	v_mul_f32_e32 v89, v74, v75
	v_mad_i64_i32 v[74:75], s[4:5], s4, v240, v[114:115]
	v_cvt_pk_bf16_f32 v151, v100, v89
	global_store_dwordx4 v[74:75], v[148:151], off
	v_pk_fma_f32 v[74:75], v[142:143], v[94:95], v[140:141]
	v_lshlrev_b32_e32 v95, 16, v68
	v_pk_fma_f32 v[74:75], v[144:145], v[104:105], v[74:75]
	v_lshlrev_b32_e32 v94, 16, v64
	v_pk_fma_f32 v[100:101], v[146:147], v[94:95], v[74:75]
	v_pk_fma_f32 v[74:75], v[20:21], v[90:91], v[0:1]
	v_lshlrev_b32_e32 v91, 16, v70
	v_pk_fma_f32 v[88:89], v[12:13], v[82:83], v[74:75]
	v_and_b32_e32 v75, 0xffff0000, v68
	v_and_b32_e32 v74, 0xffff0000, v64
	v_pk_fma_f32 v[148:149], v[28:29], v[74:75], v[88:89]
	v_pk_fma_f32 v[88:89], v[126:127], v[110:111], v[124:125]
	v_and_b32_e32 v68, 0xffff0000, v65
	v_pk_fma_f32 v[64:65], v[122:123], v[108:109], v[120:121]
	v_pk_fma_f32 v[88:89], v[138:139], v[102:103], v[88:89]
	v_pk_fma_f32 v[64:65], v[134:135], v[98:99], v[64:65]
	v_lshlrev_b32_e32 v90, 16, v66
	v_pk_fma_f32 v[110:111], v[136:137], v[92:93], v[88:89]
	v_pk_fma_f32 v[108:109], v[130:131], v[90:91], v[64:65]
	v_pk_fma_f32 v[64:65], v[24:25], v[80:81], v[4:5]
	v_pk_fma_f32 v[88:89], v[118:119], v[106:107], v[116:117]
	v_pk_fma_f32 v[80:81], v[16:17], v[72:73], v[64:65]
	v_and_b32_e32 v65, 0xffff0000, v70
	v_pk_fma_f32 v[106:107], v[132:133], v[96:97], v[88:89]
	v_lshlrev_b32_e32 v89, 16, v71
	v_and_b32_e32 v71, 0xffff0000, v71
	v_and_b32_e32 v70, 0xffff0000, v67
	v_and_b32_e32 v64, 0xffff0000, v66
	v_lshlrev_b32_e32 v88, 16, v67
	v_pk_fma_f32 v[66:67], v[10:11], v[70:71], v[86:87]
	v_mul_f32_e32 v86, 0xbfb8aa3b, v100
	v_exp_f32_e32 v86, v86
	v_pk_fma_f32 v[80:81], v[8:9], v[64:65], v[80:81]
	v_pk_fma_f32 v[106:107], v[128:129], v[88:89], v[106:107]
	v_pk_fma_f32 v[84:85], v[30:31], v[68:69], v[84:85]
	v_add_f32_e32 v86, 1.0, v86
	v_rcp_f32_e32 v86, v86
	v_mul_f32_e32 v87, 0xbfb8aa3b, v108
	v_exp_f32_e32 v87, v87
	s_add_i32 s4, s19, 3
	v_mul_f32_e32 v86, v100, v86
	v_mul_f32_e32 v86, v86, v101
	v_mul_f32_e32 v101, 0xbfb8aa3b, v80
	v_exp_f32_e32 v101, v101
	v_mul_f32_e32 v100, 0xbfb8aa3b, v148
	v_exp_f32_e32 v100, v100
	v_add_f32_e32 v87, 1.0, v87
	v_add_f32_e32 v101, 1.0, v101
	v_rcp_f32_e32 v101, v101
	v_rcp_f32_e32 v87, v87
	v_add_f32_e32 v100, 1.0, v100
	v_rcp_f32_e32 v100, v100
	v_mul_f32_e32 v80, v80, v101
	v_mul_f32_e32 v101, 0xbfb8aa3b, v106
	v_exp_f32_e32 v101, v101
	v_mul_f32_e32 v80, v80, v81
	v_mul_f32_e32 v81, 0xbfb8aa3b, v110
	v_exp_f32_e32 v81, v81
	v_add_f32_e32 v101, 1.0, v101
	v_rcp_f32_e32 v101, v101
	v_mul_f32_e32 v87, v108, v87
	v_add_f32_e32 v81, 1.0, v81
	v_rcp_f32_e32 v81, v81
	v_mul_f32_e32 v101, v106, v101
	v_mul_f32_e32 v106, 0xbfb8aa3b, v84
	v_exp_f32_e32 v106, v106
	v_mul_f32_e32 v87, v87, v109
	v_mul_f32_e32 v100, v148, v100
	v_mul_f32_e32 v81, v110, v81
	v_add_f32_e32 v106, 1.0, v106
	v_rcp_f32_e32 v106, v106
	v_mul_f32_e32 v100, v100, v149
	v_mul_f32_e32 v81, v81, v111
	v_mul_f32_e32 v101, v101, v107
	v_mul_f32_e32 v84, v84, v106
	v_mul_f32_e32 v85, v84, v85
	v_mul_f32_e32 v84, 0xbfb8aa3b, v66
	v_exp_f32_e32 v84, v84
	v_pk_fma_f32 v[78:79], v[18:19], v[70:71], v[78:79]
	v_pk_fma_f32 v[76:77], v[14:15], v[68:69], v[76:77]
	v_pk_fma_f32 v[68:69], v[22:23], v[68:69], v[2:3]
	v_add_f32_e32 v84, 1.0, v84
	v_rcp_f32_e32 v84, v84
	s_nop 0
	v_mul_f32_e32 v66, v66, v84
	v_mul_f32_e32 v106, v66, v67
	v_mad_i64_i32 v[66:67], s[4:5], s4, v240, v[114:115]
	v_cvt_pk_bf16_f32 v84, v86, v100
	v_cvt_pk_bf16_f32 v85, v81, v85
	v_cvt_pk_bf16_f32 v86, v87, v80
	v_cvt_pk_bf16_f32 v87, v101, v106
	global_store_dwordx4 v[66:67], v[84:87], off
	v_pk_fma_f32 v[66:67], v[142:143], v[104:105], v[140:141]
	s_add_i32 s4, s19, 4
	v_pk_fma_f32 v[66:67], v[144:145], v[94:95], v[66:67]
	v_lshlrev_b32_e32 v87, 16, v60
	v_lshlrev_b32_e32 v86, 16, v56
	v_pk_fma_f32 v[100:101], v[146:147], v[86:87], v[66:67]
	v_pk_fma_f32 v[66:67], v[20:21], v[82:83], v[0:1]
	v_lshlrev_b32_e32 v84, 16, v57
	v_pk_fma_f32 v[80:81], v[12:13], v[74:75], v[66:67]
	v_and_b32_e32 v67, 0xffff0000, v60
	v_and_b32_e32 v66, 0xffff0000, v56
	v_pk_fma_f32 v[104:105], v[28:29], v[66:67], v[80:81]
	v_pk_fma_f32 v[80:81], v[126:127], v[102:103], v[124:125]
	v_and_b32_e32 v60, 0xffff0000, v57
	v_pk_fma_f32 v[56:57], v[122:123], v[98:99], v[120:121]
	v_pk_fma_f32 v[80:81], v[138:139], v[92:93], v[80:81]
	v_lshlrev_b32_e32 v85, 16, v61
	v_pk_fma_f32 v[56:57], v[134:135], v[90:91], v[56:57]
	v_lshlrev_b32_e32 v83, 16, v62
	v_lshlrev_b32_e32 v82, 16, v58
	v_pk_fma_f32 v[102:103], v[136:137], v[84:85], v[80:81]
	v_pk_fma_f32 v[98:99], v[130:131], v[82:83], v[56:57]
	v_pk_fma_f32 v[56:57], v[24:25], v[72:73], v[4:5]
	v_pk_fma_f32 v[80:81], v[118:119], v[96:97], v[116:117]
; __device__ __forceinline__ float bflo(unsigned w) { return __uint_as_float(w << 16); }
; __device__ __forceinline__ float bfhi(unsigned w) { return __uint_as_float(w & 0xffff0000u); }
; __device__ __forceinline__ void st8(bf16_t* p, f32x4 a, f32x4 b) { u32x4 w = {cvt_pk(a[0], a[1]), cvt_pk(a[2], a[3]), cvt_pk(b[0], b[1]), cvt_pk(b[2], b[3])}; *(u32x4*)p = w; }
; __device__ __forceinline__ float sigm(float x) { return __builtin_amdgcn_rcpf(1.f + __builtin_amdgcn_exp2f(x * -1.4426950408889634f)); }
; __device__ __forceinline__ void conv_gate(const Bufs& b, const float* cw, const float* cbias, int CH, int bid, int nb, int tid) {
;     ...
; #pragma unroll
;     for (int i = 0; i < 8; ++i) {
;       float ua[8], ub[8];
; #pragma unroll
;       for (int e = 0; e < 8; ++e) { ua[e] = bs[0][e]; ub[e] = bs[1][e]; }
; #pragma unroll
;       for (int k = 0; k < 3; ++k) { const u32x4 xa = raw[0][i + k], xb = raw[1][i + k];
;         const float fa[8] = {bflo(xa.x), bfhi(xa.x), bflo(xa.y), bfhi(xa.y), bflo(xa.z), bfhi(xa.z), bflo(xa.w), bfhi(xa.w)};
;         const float fb[8] = {bflo(xb.x), bfhi(xb.x), bflo(xb.y), bfhi(xb.y), bflo(xb.z), bfhi(xb.z), bflo(xb.w), bfhi(xb.w)};
; #pragma unroll
;         for (int e = 0; e < 8; ++e) { ua[e] += fa[e] * w[0][k][e]; ub[e] += fb[e] * w[1][k][e]; } }
;       f32x4 y0, y1;
; #pragma unroll
;       for (int e = 0; e < 4; ++e) { y0[e] = ua[e] * sigm(ua[e]) * ub[e]; y1[e] = ua[4 + e] * sigm(ua[4 + e]) * ub[4 + e]; }
;       st8(b.G + (size_t)(r0 + i) * DFF + c, y0, y1);
	v_pk_fma_f32 v[72:73], v[16:17], v[64:65], v[56:57]
	v_and_b32_e32 v57, 0xffff0000, v62
	v_pk_fma_f32 v[96:97], v[132:133], v[88:89], v[80:81]
	v_lshlrev_b32_e32 v81, 16, v63
	v_and_b32_e32 v63, 0xffff0000, v63
	v_and_b32_e32 v62, 0xffff0000, v59
	v_and_b32_e32 v56, 0xffff0000, v58
	v_lshlrev_b32_e32 v80, 16, v59
	v_pk_fma_f32 v[58:59], v[10:11], v[62:63], v[78:79]
	v_mul_f32_e32 v79, 0xbfb8aa3b, v98
	v_exp_f32_e32 v79, v79
	v_pk_fma_f32 v[72:73], v[8:9], v[56:57], v[72:73]
	v_pk_fma_f32 v[96:97], v[128:129], v[80:81], v[96:97]
	v_and_b32_e32 v61, 0xffff0000, v61
	v_add_f32_e32 v79, 1.0, v79
	v_rcp_f32_e32 v79, v79
	v_pk_fma_f32 v[76:77], v[30:31], v[60:61], v[76:77]
	v_mul_f32_e32 v78, 0xbfb8aa3b, v100
	v_exp_f32_e32 v78, v78
	v_mul_f32_e32 v79, v98, v79
	v_mul_f32_e32 v79, v79, v99
	v_mul_f32_e32 v99, 0xbfb8aa3b, v72
	v_exp_f32_e32 v99, v99
	v_mul_f32_e32 v98, 0xbfb8aa3b, v104
	v_exp_f32_e32 v98, v98
	v_add_f32_e32 v78, 1.0, v78
	v_add_f32_e32 v99, 1.0, v99
	v_rcp_f32_e32 v99, v99
	v_rcp_f32_e32 v78, v78
	v_add_f32_e32 v98, 1.0, v98
	v_rcp_f32_e32 v98, v98
	v_mul_f32_e32 v72, v72, v99
	v_mul_f32_e32 v99, 0xbfb8aa3b, v96
	v_exp_f32_e32 v99, v99
	v_mul_f32_e32 v72, v72, v73
	v_mul_f32_e32 v73, 0xbfb8aa3b, v102
	v_exp_f32_e32 v73, v73
	v_add_f32_e32 v99, 1.0, v99
	v_rcp_f32_e32 v99, v99
	v_mul_f32_e32 v78, v100, v78
	v_add_f32_e32 v73, 1.0, v73
	v_rcp_f32_e32 v73, v73
	v_mul_f32_e32 v96, v96, v99
	v_mul_f32_e32 v96, v96, v97
	v_mul_f32_e32 v97, 0xbfb8aa3b, v76
	v_exp_f32_e32 v97, v97
	v_mul_f32_e32 v78, v78, v101
	v_mul_f32_e32 v98, v104, v98
	v_mul_f32_e32 v73, v102, v73
	v_add_f32_e32 v97, 1.0, v97
	v_rcp_f32_e32 v97, v97
	v_mul_f32_e32 v98, v98, v105
	v_mul_f32_e32 v73, v73, v103
	v_pk_fma_f32 v[68:69], v[14:15], v[60:61], v[68:69]
	v_mul_f32_e32 v76, v76, v97
	v_mul_f32_e32 v77, v76, v77
	v_mul_f32_e32 v76, 0xbfb8aa3b, v58
	v_exp_f32_e32 v76, v76
	s_nop 0
	v_add_f32_e32 v76, 1.0, v76
	v_rcp_f32_e32 v76, v76
	s_nop 0
	v_mul_f32_e32 v58, v58, v76
	v_mul_f32_e32 v97, v58, v59
	v_mad_i64_i32 v[58:59], s[4:5], s4, v240, v[114:115]
	v_cvt_pk_bf16_f32 v76, v78, v98
	v_cvt_pk_bf16_f32 v77, v73, v77
	v_cvt_pk_bf16_f32 v78, v79, v72
	v_cvt_pk_bf16_f32 v79, v96, v97
	global_store_dwordx4 v[58:59], v[76:79], off
	v_pk_fma_f32 v[58:59], v[142:143], v[94:95], v[140:141]
	s_add_i32 s4, s19, 5
	v_pk_fma_f32 v[58:59], v[144:145], v[86:87], v[58:59]
	v_lshlrev_b32_e32 v77, 16, v52
	v_lshlrev_b32_e32 v76, 16, v48
	v_pk_fma_f32 v[78:79], v[146:147], v[76:77], v[58:59]
	v_pk_fma_f32 v[58:59], v[20:21], v[74:75], v[0:1]
	v_lshlrev_b32_e32 v75, 16, v53
	v_pk_fma_f32 v[72:73], v[12:13], v[66:67], v[58:59]
	v_and_b32_e32 v59, 0xffff0000, v52
	v_and_b32_e32 v58, 0xffff0000, v48
	v_pk_fma_f32 v[94:95], v[28:29], v[58:59], v[72:73]
	v_pk_fma_f32 v[72:73], v[126:127], v[92:93], v[124:125]
	v_lshlrev_b32_e32 v74, 16, v49
	v_pk_fma_f32 v[72:73], v[138:139], v[84:85], v[72:73]
	v_and_b32_e32 v52, 0xffff0000, v49
	v_pk_fma_f32 v[48:49], v[122:123], v[90:91], v[120:121]
	v_pk_fma_f32 v[92:93], v[136:137], v[74:75], v[72:73]
	v_pk_fma_f32 v[48:49], v[134:135], v[82:83], v[48:49]
	v_lshlrev_b32_e32 v73, 16, v54
	v_lshlrev_b32_e32 v72, 16, v50
	v_pk_fma_f32 v[90:91], v[130:131], v[72:73], v[48:49]
	v_pk_fma_f32 v[48:49], v[24:25], v[64:65], v[4:5]
	v_and_b32_e32 v65, 0xffff0000, v54
	v_mul_f32_e32 v54, 0xbfb8aa3b, v78
	v_exp_f32_e32 v54, v54
	v_pk_fma_f32 v[48:49], v[16:17], v[56:57], v[48:49]
	v_and_b32_e32 v64, 0xffff0000, v50
	v_and_b32_e32 v53, 0xffff0000, v53
	v_add_f32_e32 v54, 1.0, v54
	v_rcp_f32_e32 v54, v54
	v_pk_fma_f32 v[98:99], v[8:9], v[64:65], v[48:49]
	v_pk_fma_f32 v[48:49], v[118:119], v[88:89], v[116:117]
	v_pk_fma_f32 v[96:97], v[30:31], v[52:53], v[68:69]
	v_pk_fma_f32 v[48:49], v[132:133], v[80:81], v[48:49]
	v_lshlrev_b32_e32 v69, 16, v55
	v_lshlrev_b32_e32 v68, 16, v51
	v_pk_fma_f32 v[88:89], v[128:129], v[68:69], v[48:49]
	v_mul_f32_e32 v54, v78, v54
	v_mul_f32_e32 v54, v54, v79
	v_mul_f32_e32 v79, 0xbfb8aa3b, v88
	v_exp_f32_e32 v79, v79
	v_pk_fma_f32 v[48:49], v[26:27], v[70:71], v[6:7]
	v_mul_f32_e32 v78, 0xbfb8aa3b, v92
	v_pk_fma_f32 v[70:71], v[18:19], v[62:63], v[48:49]
	v_add_f32_e32 v79, 1.0, v79
	v_rcp_f32_e32 v79, v79
	v_and_b32_e32 v49, 0xffff0000, v55
	v_and_b32_e32 v48, 0xffff0000, v51
	v_pk_fma_f32 v[50:51], v[10:11], v[48:49], v[70:71]
	v_mul_f32_e32 v79, v88, v79
	v_mul_f32_e32 v88, 0xbfb8aa3b, v96
	v_exp_f32_e32 v88, v88
	v_mul_f32_e32 v55, 0xbfb8aa3b, v90
	v_mul_f32_e32 v79, v79, v89
	v_exp_f32_e32 v55, v55
	v_add_f32_e32 v88, 1.0, v88
	v_rcp_f32_e32 v88, v88
	v_mul_f32_e32 v70, 0xbfb8aa3b, v94
	v_mul_f32_e32 v71, 0xbfb8aa3b, v98
	v_exp_f32_e32 v70, v70
	v_mul_f32_e32 v88, v96, v88
	v_mul_f32_e32 v89, v88, v97
	v_mul_f32_e32 v88, 0xbfb8aa3b, v50
	v_exp_f32_e32 v88, v88
	v_exp_f32_e32 v71, v71
	v_exp_f32_e32 v78, v78
	v_add_f32_e32 v55, 1.0, v55
	v_add_f32_e32 v88, 1.0, v88
	v_rcp_f32_e32 v55, v55
	v_add_f32_e32 v70, 1.0, v70
	v_add_f32_e32 v71, 1.0, v71
	v_add_f32_e32 v78, 1.0, v78
	v_rcp_f32_e32 v88, v88
	v_rcp_f32_e32 v70, v70
	v_rcp_f32_e32 v71, v71
	v_rcp_f32_e32 v78, v78
	v_mul_f32_e32 v55, v90, v55
	v_mul_f32_e32 v50, v50, v88
	v_mul_f32_e32 v55, v55, v91
	v_mul_f32_e32 v70, v94, v70
	v_mul_f32_e32 v71, v98, v71
	v_mul_f32_e32 v78, v92, v78
	v_mul_f32_e32 v91, v50, v51
	v_mad_i64_i32 v[50:51], s[4:5], s4, v240, v[114:115]
	v_mul_f32_e32 v70, v70, v95
	v_mul_f32_e32 v71, v71, v99
	v_mul_f32_e32 v78, v78, v93
	v_cvt_pk_bf16_f32 v88, v54, v70
	v_cvt_pk_bf16_f32 v89, v78, v89
	v_cvt_pk_bf16_f32 v90, v55, v71
	v_cvt_pk_bf16_f32 v91, v79, v91
	global_store_dwordx4 v[50:51], v[88:91], off
	v_pk_fma_f32 v[50:51], v[142:143], v[86:87], v[140:141]
; __device__ __forceinline__ float bflo(unsigned w) { return __uint_as_float(w << 16); }
; __device__ __forceinline__ float bfhi(unsigned w) { return __uint_as_float(w & 0xffff0000u); }
; __device__ __forceinline__ void st8(bf16_t* p, f32x4 a, f32x4 b) { u32x4 w = {cvt_pk(a[0], a[1]), cvt_pk(a[2], a[3]), cvt_pk(b[0], b[1]), cvt_pk(b[2], b[3])}; *(u32x4*)p = w; }
; __device__ __forceinline__ float sigm(float x) { return __builtin_amdgcn_rcpf(1.f + __builtin_amdgcn_exp2f(x * -1.4426950408889634f)); }
; __device__ __forceinline__ void conv_gate(const Bufs& b, const float* cw, const float* cbias, int CH, int bid, int nb, int tid) {
;     ...
; #pragma unroll
;     for (int i = 0; i < 8; ++i) {
;       float ua[8], ub[8];
; #pragma unroll
;       for (int e = 0; e < 8; ++e) { ua[e] = bs[0][e]; ub[e] = bs[1][e]; }
; #pragma unroll
;       for (int k = 0; k < 3; ++k) { const u32x4 xa = raw[0][i + k], xb = raw[1][i + k];
;         const float fa[8] = {bflo(xa.x), bfhi(xa.x), bflo(xa.y), bfhi(xa.y), bflo(xa.z), bfhi(xa.z), bflo(xa.w), bfhi(xa.w)};
;         const float fb[8] = {bflo(xb.x), bfhi(xb.x), bflo(xb.y), bfhi(xb.y), bflo(xb.z), bfhi(xb.z), bflo(xb.w), bfhi(xb.w)};
; #pragma unroll
;         for (int e = 0; e < 8; ++e) { ua[e] += fa[e] * w[0][k][e]; ub[e] += fb[e] * w[1][k][e]; } }
;       f32x4 y0, y1;
; #pragma unroll
;       for (int e = 0; e < 4; ++e) { y0[e] = ua[e] * sigm(ua[e]) * ub[e]; y1[e] = ua[4 + e] * sigm(ua[4 + e]) * ub[4 + e]; }
;       st8(b.G + (size_t)(r0 + i) * DFF + c, y0, y1);
	v_lshlrev_b32_e32 v71, 16, v44
	v_pk_fma_f32 v[50:51], v[144:145], v[76:77], v[50:51]
	v_lshlrev_b32_e32 v70, 16, v40
	v_pk_fma_f32 v[78:79], v[146:147], v[70:71], v[50:51]
	v_pk_fma_f32 v[50:51], v[20:21], v[66:67], v[0:1]
	v_lshlrev_b32_e32 v67, 16, v45
	v_pk_fma_f32 v[54:55], v[12:13], v[58:59], v[50:51]
	v_and_b32_e32 v51, 0xffff0000, v44
	v_and_b32_e32 v50, 0xffff0000, v40
	v_pk_fma_f32 v[86:87], v[28:29], v[50:51], v[54:55]
	v_pk_fma_f32 v[54:55], v[126:127], v[84:85], v[124:125]
	v_lshlrev_b32_e32 v66, 16, v41
	v_pk_fma_f32 v[54:55], v[138:139], v[74:75], v[54:55]
	v_and_b32_e32 v45, 0xffff0000, v45
	v_pk_fma_f32 v[84:85], v[136:137], v[66:67], v[54:55]
	v_pk_fma_f32 v[54:55], v[22:23], v[60:61], v[2:3]
	v_and_b32_e32 v44, 0xffff0000, v41
	v_pk_fma_f32 v[54:55], v[14:15], v[52:53], v[54:55]
	v_lshlrev_b32_e32 v61, 16, v46
	v_pk_fma_f32 v[88:89], v[30:31], v[44:45], v[54:55]
	v_and_b32_e32 v55, 0xffff0000, v46
	v_mul_f32_e32 v46, 0xbfb8aa3b, v78
	v_exp_f32_e32 v46, v46
	v_pk_fma_f32 v[40:41], v[122:123], v[82:83], v[120:121]
	v_lshlrev_b32_e32 v60, 16, v42
	v_pk_fma_f32 v[40:41], v[134:135], v[72:73], v[40:41]
	v_add_f32_e32 v46, 1.0, v46
	v_rcp_f32_e32 v46, v46
	v_pk_fma_f32 v[82:83], v[130:131], v[60:61], v[40:41]
	v_pk_fma_f32 v[40:41], v[24:25], v[56:57], v[4:5]
	v_and_b32_e32 v54, 0xffff0000, v42
	v_mul_f32_e32 v46, v78, v46
	v_mul_f32_e32 v78, 0xbfb8aa3b, v84
	v_exp_f32_e32 v78, v78
	v_pk_fma_f32 v[40:41], v[16:17], v[64:65], v[40:41]
	v_lshlrev_b32_e32 v57, 16, v47
	v_pk_fma_f32 v[90:91], v[8:9], v[54:55], v[40:41]
	v_add_f32_e32 v78, 1.0, v78
	v_rcp_f32_e32 v78, v78
	v_pk_fma_f32 v[40:41], v[118:119], v[80:81], v[116:117]
	v_lshlrev_b32_e32 v56, 16, v43
	v_pk_fma_f32 v[40:41], v[132:133], v[68:69], v[40:41]
	v_mul_f32_e32 v78, v84, v78
	v_pk_fma_f32 v[80:81], v[128:129], v[56:57], v[40:41]
	v_mul_f32_e32 v46, v46, v79
	v_mul_f32_e32 v79, v78, v85
	v_mul_f32_e32 v78, 0xbfb8aa3b, v80
	v_exp_f32_e32 v78, v78
	v_pk_fma_f32 v[40:41], v[26:27], v[62:63], v[6:7]
	s_add_i32 s4, s19, 6
	v_pk_fma_f32 v[62:63], v[18:19], v[48:49], v[40:41]
	v_add_f32_e32 v78, 1.0, v78
	v_rcp_f32_e32 v78, v78
	v_and_b32_e32 v41, 0xffff0000, v47
	v_and_b32_e32 v40, 0xffff0000, v43
	v_pk_fma_f32 v[42:43], v[10:11], v[40:41], v[62:63]
	v_mul_f32_e32 v78, v80, v78
	v_mul_f32_e32 v81, v78, v81
	v_mul_f32_e32 v78, 0xbfb8aa3b, v88
	v_exp_f32_e32 v78, v78
	v_mul_f32_e32 v47, 0xbfb8aa3b, v82
	v_mul_f32_e32 v62, 0xbfb8aa3b, v86
	v_mul_f32_e32 v63, 0xbfb8aa3b, v90
	v_add_f32_e32 v78, 1.0, v78
	v_rcp_f32_e32 v78, v78
	v_exp_f32_e32 v47, v47
	v_exp_f32_e32 v62, v62
	v_exp_f32_e32 v63, v63
	v_mul_f32_e32 v78, v88, v78
	v_mul_f32_e32 v80, v78, v89
	v_mul_f32_e32 v78, 0xbfb8aa3b, v42
	v_exp_f32_e32 v78, v78
	v_add_f32_e32 v47, 1.0, v47
	v_add_f32_e32 v62, 1.0, v62
	v_add_f32_e32 v63, 1.0, v63
	v_add_f32_e32 v78, 1.0, v78
	v_rcp_f32_e32 v78, v78
	v_rcp_f32_e32 v47, v47
	v_rcp_f32_e32 v62, v62
	v_rcp_f32_e32 v63, v63
	v_mul_f32_e32 v42, v42, v78
	v_mul_f32_e32 v47, v82, v47
	v_mul_f32_e32 v62, v86, v62
	v_mul_f32_e32 v63, v90, v63
	v_mul_f32_e32 v82, v42, v43
	v_mad_i64_i32 v[42:43], s[4:5], s4, v240, v[114:115]
	v_mul_f32_e32 v47, v47, v83
	v_mul_f32_e32 v62, v62, v87
	v_mul_f32_e32 v63, v63, v91
	v_cvt_pk_bf16_f32 v78, v46, v62
	v_cvt_pk_bf16_f32 v79, v79, v80
	v_cvt_pk_bf16_f32 v80, v47, v63
	v_cvt_pk_bf16_f32 v81, v81, v82
	global_store_dwordx4 v[42:43], v[78:81], off
	v_pk_fma_f32 v[42:43], v[142:143], v[76:77], v[140:141]
	v_lshlrev_b32_e32 v47, 16, v36
	v_pk_fma_f32 v[42:43], v[144:145], v[70:71], v[42:43]
	v_lshlrev_b32_e32 v46, 16, v32
	v_pk_fma_f32 v[42:43], v[146:147], v[46:47], v[42:43]
	v_pk_fma_f32 v[46:47], v[20:21], v[58:59], v[0:1]
	v_pk_fma_f32 v[52:53], v[22:23], v[52:53], v[2:3]
	v_pk_fma_f32 v[46:47], v[12:13], v[50:51], v[46:47]
	v_and_b32_e32 v51, 0xffff0000, v36
	v_lshlrev_b32_e32 v59, 16, v37
	v_pk_fma_f32 v[44:45], v[14:15], v[44:45], v[52:53]
	v_and_b32_e32 v37, 0xffff0000, v37
	v_and_b32_e32 v36, 0xffff0000, v33
	v_and_b32_e32 v50, 0xffff0000, v32
	v_lshlrev_b32_e32 v58, 16, v33
	v_pk_fma_f32 v[32:33], v[30:31], v[36:37], v[44:45]
	v_pk_fma_f32 v[36:37], v[122:123], v[72:73], v[120:121]
	v_lshlrev_b32_e32 v45, 16, v38
	v_pk_fma_f32 v[36:37], v[134:135], v[60:61], v[36:37]
	v_lshlrev_b32_e32 v44, 16, v34
	v_pk_fma_f32 v[36:37], v[130:131], v[44:45], v[36:37]
	v_pk_fma_f32 v[44:45], v[24:25], v[64:65], v[4:5]
	v_pk_fma_f32 v[48:49], v[26:27], v[48:49], v[6:7]
	v_pk_fma_f32 v[44:45], v[16:17], v[54:55], v[44:45]
	v_and_b32_e32 v53, 0xffff0000, v38
	v_lshlrev_b32_e32 v55, 16, v39
	v_pk_fma_f32 v[40:41], v[18:19], v[40:41], v[48:49]
	v_and_b32_e32 v39, 0xffff0000, v39
	v_and_b32_e32 v38, 0xffff0000, v35
	v_and_b32_e32 v52, 0xffff0000, v34
	v_lshlrev_b32_e32 v54, 16, v35
	v_pk_fma_f32 v[34:35], v[10:11], v[38:39], v[40:41]
	v_mul_f32_e32 v39, 0xbfb8aa3b, v36
	v_exp_f32_e32 v39, v39
	v_pk_fma_f32 v[46:47], v[28:29], v[50:51], v[46:47]
	v_pk_fma_f32 v[44:45], v[8:9], v[52:53], v[44:45]
	v_pk_fma_f32 v[50:51], v[126:127], v[74:75], v[124:125]
	v_add_f32_e32 v39, 1.0, v39
	v_rcp_f32_e32 v39, v39
	v_pk_fma_f32 v[50:51], v[138:139], v[66:67], v[50:51]
	v_mul_f32_e32 v38, 0xbfb8aa3b, v42
	v_pk_fma_f32 v[50:51], v[136:137], v[58:59], v[50:51]
	v_mul_f32_e32 v36, v36, v39
	v_mul_f32_e32 v39, v36, v37
	v_mul_f32_e32 v36, 0xbfb8aa3b, v46
	v_exp_f32_e32 v36, v36
	v_exp_f32_e32 v38, v38
	v_pk_fma_f32 v[52:53], v[118:119], v[68:69], v[116:117]
	s_add_i32 s4, s19, 7
	v_add_f32_e32 v36, 1.0, v36
	v_rcp_f32_e32 v36, v36
	v_add_f32_e32 v38, 1.0, v38
	v_rcp_f32_e32 v38, v38
	v_pk_fma_f32 v[52:53], v[132:133], v[56:57], v[52:53]
	v_mul_f32_e32 v36, v46, v36
	v_mul_f32_e32 v40, v36, v47
	v_mul_f32_e32 v36, 0xbfb8aa3b, v44
	v_exp_f32_e32 v36, v36
	v_pk_fma_f32 v[52:53], v[128:129], v[54:55], v[52:53]
	v_mul_f32_e32 v38, v42, v38
	v_mul_f32_e32 v38, v38, v43
	v_add_f32_e32 v36, 1.0, v36
	v_rcp_f32_e32 v36, v36
	s_add_i32 s19, s19, s54
	s_cmpk_lt_i32 s34, 0x1000
	v_mul_f32_e32 v36, v44, v36
	v_mul_f32_e32 v41, v36, v45
	v_mul_f32_e32 v36, 0xbfb8aa3b, v50
	v_exp_f32_e32 v36, v36
	s_nop 0
	v_add_f32_e32 v36, 1.0, v36
	v_rcp_f32_e32 v36, v36
	s_nop 0
	v_mul_f32_e32 v36, v50, v36
	v_mul_f32_e32 v42, v36, v51
	v_mul_f32_e32 v36, 0xbfb8aa3b, v52
	v_exp_f32_e32 v36, v36
	s_nop 0
	v_add_f32_e32 v36, 1.0, v36
	v_rcp_f32_e32 v36, v36
	s_nop 0
	v_mul_f32_e32 v36, v52, v36
	v_mul_f32_e32 v43, v36, v53
	v_mul_f32_e32 v36, 0xbfb8aa3b, v32
	v_exp_f32_e32 v36, v36
	s_nop 0
	v_add_f32_e32 v36, 1.0, v36
	v_rcp_f32_e32 v36, v36
	s_nop 0
	v_mul_f32_e32 v32, v32, v36
	v_mul_f32_e32 v33, v32, v33
	v_mul_f32_e32 v32, 0xbfb8aa3b, v34
	v_exp_f32_e32 v32, v32
	v_mad_i64_i32 v[36:37], s[4:5], s4, v240, v[114:115]
	v_add_f32_e32 v32, 1.0, v32
	v_rcp_f32_e32 v32, v32
	s_nop 0
	v_mul_f32_e32 v32, v34, v32
	v_mul_f32_e32 v35, v32, v35
	v_cvt_pk_bf16_f32 v32, v38, v40
	v_cvt_pk_bf16_f32 v33, v42, v33
	v_cvt_pk_bf16_f32 v34, v39, v41
	v_cvt_pk_bf16_f32 v35, v43, v35
	global_store_dwordx4 v[36:37], v[32:35], off
	s_cbranch_scc0 .LBB0_1019
; __device__ __forceinline__ void conv_gate(const Bufs& b, const float* cw, const float* cbias, int CH, int bid, int nb, int tid) {
;     ...
;   for (int strip = bid; strip < CH / 8; strip += nb) {
;     const int r0 = strip * 8; const int pos0 = (b.g0 + r0) & b.slm;
;     u32x4 raw[2][10];
;     const bool hp = pos0 > 0, hn = (pos0 + 8) <= b.slm;
; #pragma unroll
;     for (int hf = 0; hf < 2; ++hf) {
;       const bf16_t* base = b.UR + (size_t)r0 * N_UP + hf * DFF + c;
;       raw[hf][0] = hp ? *(const u32x4*)(base - N_UP) : (u32x4){0u, 0u, 0u, 0u};
; #pragma unroll
;       for (int i = 0; i < 8; ++i) raw[hf][1 + i] = *(const u32x4*)(base + (size_t)i * N_UP);
;       raw[hf][9] = hn ? *(const u32x4*)(base + (size_t)8 * N_UP) : (u32x4){0u, 0u, 0u, 0u};
.LBB0_1010:
	s_and_b32 s8, s19, s90
	s_cmp_lg_u32 s8, 0
	s_cselect_b64 s[4:5], -1, 0
	s_cmp_eq_u32 s8, 0
	v_mad_i64_i32 v[148:149], s[10:11], s19, v239, v[112:113]
	s_cbranch_scc1 .LBB0_1012
	v_add_co_u32_e32 v32, vcc, 0xffffd400, v148
	s_nop 1
	v_addc_co_u32_e32 v33, vcc, -1, v149, vcc
	global_load_dwordx4 v[88:91], v[32:33], off
	s_branch .LBB0_1013

; __device__ __forceinline__ void conv_gate(const Bufs& b, const float* cw, const float* cbias, int CH, int bid, int nb, int tid) {
;     ...
;   for (int strip = bid; strip < CH / 8; strip += nb) {
;     const int r0 = strip * 8; const int pos0 = (b.g0 + r0) & b.slm;
;     u32x4 raw[2][10];
;     const bool hp = pos0 > 0, hn = (pos0 + 8) <= b.slm;
; #pragma unroll
;     for (int hf = 0; hf < 2; ++hf) {
;       const bf16_t* base = b.UR + (size_t)r0 * N_UP + hf * DFF + c;
;       raw[hf][0] = hp ? *(const u32x4*)(base - N_UP) : (u32x4){0u, 0u, 0u, 0u};
; #pragma unroll
;       for (int i = 0; i < 8; ++i) raw[hf][1 + i] = *(const u32x4*)(base + (size_t)i * N_UP);
;       raw[hf][9] = hn ? *(const u32x4*)(base + (size_t)8 * N_UP) : (u32x4){0u, 0u, 0u, 0u};
;     }
.LBB0_1013:
	v_add_co_u32_e32 v32, vcc, 0x2000, v148
	s_cmp_le_u32 s8, s18
	s_nop 0
	v_addc_co_u32_e32 v33, vcc, 0, v149, vcc
	global_load_dwordx4 v[96:99], v[148:149], off
	global_load_dwordx4 v[92:95], v[32:33], off offset:3072
	v_add_co_u32_e32 v32, vcc, 0x5000, v148
	s_cselect_b64 s[30:31], -1, 0
	s_nop 0
	v_addc_co_u32_e32 v33, vcc, 0, v149, vcc
	v_add_co_u32_e32 v34, vcc, 0x8000, v148
	s_cmp_gt_u32 s8, s18
	s_nop 0
	v_addc_co_u32_e32 v35, vcc, 0, v149, vcc
	global_load_dwordx4 v[80:83], v[32:33], off offset:2048
	global_load_dwordx4 v[72:75], v[34:35], off offset:1024
	v_add_co_u32_e32 v32, vcc, 0xb000, v148
	v_mov_b32_e32 v100, 0
	s_nop 0
	v_addc_co_u32_e32 v33, vcc, 0, v149, vcc
	v_add_co_u32_e32 v34, vcc, 0xd000, v148
	s_nop 1
	v_addc_co_u32_e32 v35, vcc, 0, v149, vcc
	global_load_dwordx4 v[64:67], v[32:33], off
	global_load_dwordx4 v[56:59], v[34:35], off offset:3072
	v_add_co_u32_e32 v32, vcc, 0x10000, v148
	s_nop 1
	v_addc_co_u32_e32 v33, vcc, 0, v149, vcc
	v_add_co_u32_e32 v34, vcc, 0x13000, v148
	s_nop 1
	v_addc_co_u32_e32 v35, vcc, 0, v149, vcc
	global_load_dwordx4 v[48:51], v[32:33], off offset:2048
	global_load_dwordx4 v[40:43], v[34:35], off offset:1024
	v_mov_b32_e32 v32, 0
	v_mov_b32_e32 v33, 0
	v_mov_b32_e32 v34, 0
	v_mov_b32_e32 v35, 0
	s_cbranch_scc1 .LBB0_1015
	v_add_co_u32_e32 v32, vcc, 0x16000, v148
	s_nop 1
	v_addc_co_u32_e32 v33, vcc, 0, v149, vcc
	global_load_dwordx4 v[32:35], v[32:33], off
.LBB0_1015:
	s_andn2_b64 vcc, exec, s[4:5]
	v_mov_b32_e32 v101, 0
	v_mov_b32_e32 v102, 0
	v_mov_b32_e32 v103, 0
	s_cbranch_vccnz .LBB0_1017
	v_add_co_u32_e32 v36, vcc, 0xffffea00, v148
	s_nop 1
	v_addc_co_u32_e32 v37, vcc, -1, v149, vcc
	global_load_dwordx4 v[100:103], v[36:37], off
.LBB0_1017:
	v_add_co_u32_e32 v36, vcc, 0x1000, v148
	s_nop 1
	v_addc_co_u32_e32 v37, vcc, 0, v149, vcc
	v_add_co_u32_e32 v38, vcc, 0x4000, v148
	s_nop 1
	v_addc_co_u32_e32 v39, vcc, 0, v149, vcc
	global_load_dwordx4 v[108:111], v[36:37], off offset:1536
	global_load_dwordx4 v[104:107], v[38:39], off offset:512
	v_add_co_u32_e32 v36, vcc, 0x6000, v148
	s_nop 1
	v_addc_co_u32_e32 v37, vcc, 0, v149, vcc
	v_add_co_u32_e32 v38, vcc, 0x9000, v148
	s_nop 1
	v_addc_co_u32_e32 v39, vcc, 0, v149, vcc
	global_load_dwordx4 v[84:87], v[36:37], off offset:3584
	global_load_dwordx4 v[76:79], v[38:39], off offset:2560
	v_add_co_u32_e32 v36, vcc, 0xc000, v148
	s_nop 1
	v_addc_co_u32_e32 v37, vcc, 0, v149, vcc
	v_add_co_u32_e32 v38, vcc, 0xf000, v148
	s_nop 1
	v_addc_co_u32_e32 v39, vcc, 0, v149, vcc
	global_load_dwordx4 v[68:71], v[36:37], off offset:1536
	global_load_dwordx4 v[60:63], v[38:39], off offset:512
	v_add_co_u32_e32 v36, vcc, 0x11000, v148
	s_nop 1
	v_addc_co_u32_e32 v37, vcc, 0, v149, vcc
	v_add_co_u32_e32 v38, vcc, 0x14000, v148
	s_nop 1
	v_addc_co_u32_e32 v39, vcc, 0, v149, vcc
	global_load_dwordx4 v[52:55], v[36:37], off offset:3584
	global_load_dwordx4 v[44:47], v[38:39], off offset:2560
	v_mov_b32_e32 v36, 0
	s_andn2_b64 vcc, exec, s[30:31]
	v_mov_b32_e32 v37, 0
	v_mov_b32_e32 v38, 0
	v_mov_b32_e32 v39, 0
	s_cbranch_vccnz .LBB0_1009
	v_add_co_u32_e32 v36, vcc, 0x17000, v148
	s_nop 1
	v_addc_co_u32_e32 v37, vcc, 0, v149, vcc
	global_load_dwordx4 v[36:39], v[36:37], off offset:1536
	s_branch .LBB0_1009
	s_nop 0
	s_nop 0
	s_nop 0
	s_nop 0
	s_nop 0
	s_nop 0
	s_nop 0
	s_nop 0
	s_nop 0
	s_nop 0
	s_nop 0
	s_nop 0
	s_nop 0
	s_nop 0
	s_nop 0
	s_nop 0
	s_nop 0
	s_nop 0
	s_nop 0
	s_nop 0
	s_nop 0
	s_nop 0
	s_nop 0
	s_nop 0
	s_nop 0
	s_nop 0
	s_nop 0
	s_nop 0
	s_nop 0
	s_nop 0
	s_nop 0
	s_nop 0
	s_nop 0
	s_nop 0
	s_nop 0
	s_nop 0
	s_nop 0
	s_nop 0
	s_nop 0
	s_nop 0
	s_nop 0
	s_nop 0
	s_nop 0
	s_nop 0
	s_nop 0
	s_nop 0

; __device__ __forceinline__ float bflo(unsigned w) { return __uint_as_float(w << 16); }
; __device__ __forceinline__ float bfhi(unsigned w) { return __uint_as_float(w & 0xffff0000u); }
; #define SBAR0() __builtin_amdgcn_sched_barrier(0)
;   __device__ __forceinline__ void operator()(EPI_ARGS) const {
;     const int rbase = u.pm * 256 + wr * 64 + fr, c0 = u.pn * 256 + wc * 32 + fq * 8;
; #pragma unroll
;     for (int ai = 0; ai < 2; ++ai) {
;       SBAR0();
;       u32x4 xv[4][2];
; #pragma unroll
;       for (int m = 0; m < 4; ++m)
; #pragma unroll
;         for (int bj = 0; bj < 2; ++bj) xv[m][bj] = *(const u32x4*)(b.RG + (size_t)(rbase + ai * 128 + m * 16) * 1024 + c0 + bj * 128);
;       if (at) {
; #pragma unroll
;         for (int m = 0; m < 4; ++m) { float* orow = b.out + (size_t)(b.g0 + rbase + ai * 128 + m * 16) * DM;
; #pragma unroll
;           for (int bj = 0; bj < 2; ++bj) { const int c = c0 + bj * 128; const u32x4 p = xv[m][bj];
;             *(f32x4*)(orow + c) = (f32x4){bflo(p.x), bfhi(p.x), bflo(p.y), bfhi(p.y)} + acc[ai][bj][m][0]; *(f32x4*)(orow + c + 4) = (f32x4){bflo(p.z), bfhi(p.z), bflo(p.w), bfhi(p.w)} + acc[ai][bj][m][1]; } }
.LBB0_1092:
	s_lshl_b32 s4, s19, 8
	v_mov_b32_e32 v128, v172
	v_mov_b32_e32 v129, v173
	s_add_i32 s4, s4, s71
	s_nop 0
	v_add_u32_e32 v164, s4, v128
	s_lshl_b32 s4, s8, 8
	s_or_b32 s4, s4, s74
	v_lshl_add_u32 v204, v129, 3, s4
	v_ashrrev_i32_e32 v205, 31, v204
	v_add_u32_e32 v166, 48, v164
	v_add_u32_e32 v168, 32, v164
	v_add_u32_e32 v170, 16, v164
	v_ashrrev_i32_e32 v167, 31, v166
	v_ashrrev_i32_e32 v169, 31, v168
	v_ashrrev_i32_e32 v171, 31, v170
	v_ashrrev_i32_e32 v165, 31, v164
	v_lshl_add_u64 v[162:163], v[204:205], 1, s[38:39]
	v_lshlrev_b64 v[128:129], 11, v[166:167]
	v_lshlrev_b64 v[136:137], 11, v[168:169]
	v_lshlrev_b64 v[144:145], 11, v[170:171]
	v_lshlrev_b64 v[176:177], 11, v[164:165]
	v_lshl_add_u64 v[132:133], v[162:163], 0, v[128:129]
	v_lshl_add_u64 v[140:141], v[162:163], 0, v[136:137]
	v_lshl_add_u64 v[148:149], v[162:163], 0, v[144:145]
	v_lshl_add_u64 v[180:181], v[162:163], 0, v[176:177]
	global_load_dwordx4 v[128:131], v[132:133], off offset:256
	s_nop 0
	global_load_dwordx4 v[132:135], v[132:133], off
	s_nop 0
	global_load_dwordx4 v[136:139], v[140:141], off offset:256
	s_nop 0
	global_load_dwordx4 v[140:143], v[140:141], off
	s_nop 0
	global_load_dwordx4 v[144:147], v[148:149], off offset:256
	s_nop 0
	global_load_dwordx4 v[148:151], v[148:149], off
	s_nop 0
	global_load_dwordx4 v[176:179], v[180:181], off offset:256
	s_nop 0
	global_load_dwordx4 v[180:183], v[180:181], off
	v_add_u32_e32 v184, s68, v164
	v_ashrrev_i32_e32 v185, 31, v184
	v_lshlrev_b64 v[184:185], 12, v[184:185]
	s_waitcnt lgkmcnt(0)
	v_lshl_add_u64 v[206:207], s[28:29], 0, v[184:185]
	s_waitcnt vmcnt(0)
	v_lshlrev_b32_e32 v184, 16, v180
	v_and_b32_e32 v185, 0xffff0000, v180
	v_lshlrev_b32_e32 v180, 16, v181
	v_and_b32_e32 v181, 0xffff0000, v181
	v_pk_add_f32 v[186:187], v[126:127], v[180:181]
	v_pk_add_f32 v[184:185], v[124:125], v[184:185]
	v_lshlrev_b64 v[124:125], 2, v[204:205]
	v_lshlrev_b32_e32 v180, 16, v182
	v_and_b32_e32 v181, 0xffff0000, v182
	v_lshlrev_b32_e32 v182, 16, v183
	v_and_b32_e32 v183, 0xffff0000, v183
	v_lshl_add_u64 v[126:127], v[206:207], 0, v[124:125]
	v_pk_add_f32 v[122:123], v[122:123], v[182:183]
	v_pk_add_f32 v[120:121], v[120:121], v[180:181]
	global_store_dwordx4 v[126:127], v[120:123], off offset:16
	global_store_dwordx4 v[126:127], v[184:187], off
	s_nop 0
	v_lshlrev_b32_e32 v120, 16, v176
	v_and_b32_e32 v121, 0xffff0000, v176
	v_lshlrev_b32_e32 v122, 16, v177
	v_and_b32_e32 v123, 0xffff0000, v177
	v_pk_add_f32 v[118:119], v[118:119], v[122:123]
	v_pk_add_f32 v[116:117], v[116:117], v[120:121]
	global_store_dwordx4 v[126:127], v[116:119], off offset:512
	s_nop 1
	v_lshlrev_b32_e32 v116, 16, v178
	v_and_b32_e32 v117, 0xffff0000, v178
	v_lshlrev_b32_e32 v118, 16, v179
	v_and_b32_e32 v119, 0xffff0000, v179
	v_pk_add_f32 v[114:115], v[114:115], v[118:119]
	v_pk_add_f32 v[112:113], v[112:113], v[116:117]
	global_store_dwordx4 v[126:127], v[112:115], off offset:528
	v_lshlrev_b32_e32 v116, 16, v149
	v_and_b32_e32 v117, 0xffff0000, v149
	v_add_u32_e32 v112, s68, v170
	v_ashrrev_i32_e32 v113, 31, v112
	v_lshlrev_b64 v[112:113], 12, v[112:113]
	v_lshl_add_u64 v[112:113], s[28:29], 0, v[112:113]
	v_lshlrev_b32_e32 v114, 16, v148
	v_and_b32_e32 v115, 0xffff0000, v148
	v_pk_add_f32 v[110:111], v[110:111], v[116:117]
	v_pk_add_f32 v[108:109], v[108:109], v[114:115]
	v_lshl_add_u64 v[112:113], v[112:113], 0, v[124:125]
	global_store_dwordx4 v[112:113], v[108:111], off
	s_nop 1
	v_lshlrev_b32_e32 v108, 16, v150
	v_and_b32_e32 v109, 0xffff0000, v150
	v_lshlrev_b32_e32 v110, 16, v151
	v_and_b32_e32 v111, 0xffff0000, v151
	v_pk_add_f32 v[106:107], v[106:107], v[110:111]
	v_pk_add_f32 v[104:105], v[104:105], v[108:109]
	global_store_dwordx4 v[112:113], v[104:107], off offset:16
	s_nop 1
	v_lshlrev_b32_e32 v104, 16, v144
	v_and_b32_e32 v105, 0xffff0000, v144
	v_lshlrev_b32_e32 v106, 16, v145
	v_and_b32_e32 v107, 0xffff0000, v145
	v_pk_add_f32 v[102:103], v[102:103], v[106:107]
	v_pk_add_f32 v[100:101], v[100:101], v[104:105]
	global_store_dwordx4 v[112:113], v[100:103], off offset:512
	s_nop 1
	v_lshlrev_b32_e32 v100, 16, v146
	v_and_b32_e32 v101, 0xffff0000, v146
	v_lshlrev_b32_e32 v102, 16, v147
	v_and_b32_e32 v103, 0xffff0000, v147
	v_pk_add_f32 v[98:99], v[98:99], v[102:103]
	v_pk_add_f32 v[96:97], v[96:97], v[100:101]
	global_store_dwordx4 v[112:113], v[96:99], off offset:528
	v_lshlrev_b32_e32 v100, 16, v141
	v_and_b32_e32 v101, 0xffff0000, v141
	v_add_u32_e32 v96, s68, v168
	v_ashrrev_i32_e32 v97, 31, v96
	v_lshlrev_b64 v[96:97], 12, v[96:97]
	v_lshl_add_u64 v[96:97], s[28:29], 0, v[96:97]
	v_lshlrev_b32_e32 v98, 16, v140
	v_and_b32_e32 v99, 0xffff0000, v140
	v_pk_add_f32 v[94:95], v[94:95], v[100:101]
	v_pk_add_f32 v[92:93], v[92:93], v[98:99]
	v_lshl_add_u64 v[96:97], v[96:97], 0, v[124:125]
	global_store_dwordx4 v[96:97], v[92:95], off
	s_nop 1
	v_lshlrev_b32_e32 v92, 16, v142
	v_and_b32_e32 v93, 0xffff0000, v142
	v_lshlrev_b32_e32 v94, 16, v143
	v_and_b32_e32 v95, 0xffff0000, v143
	v_pk_add_f32 v[90:91], v[90:91], v[94:95]
	v_pk_add_f32 v[88:89], v[88:89], v[92:93]
	global_store_dwordx4 v[96:97], v[88:91], off offset:16
	s_nop 1
	v_lshlrev_b32_e32 v88, 16, v136
	v_and_b32_e32 v89, 0xffff0000, v136
	v_lshlrev_b32_e32 v90, 16, v137
	v_and_b32_e32 v91, 0xffff0000, v137
	v_pk_add_f32 v[86:87], v[86:87], v[90:91]
	v_pk_add_f32 v[84:85], v[84:85], v[88:89]
	global_store_dwordx4 v[96:97], v[84:87], off offset:512
	s_nop 1
	v_lshlrev_b32_e32 v84, 16, v138
	v_and_b32_e32 v85, 0xffff0000, v138
	v_lshlrev_b32_e32 v86, 16, v139
	v_and_b32_e32 v87, 0xffff0000, v139
	v_pk_add_f32 v[82:83], v[82:83], v[86:87]
	v_pk_add_f32 v[80:81], v[80:81], v[84:85]
; __device__ __forceinline__ float bflo(unsigned w) { return __uint_as_float(w << 16); }
; __device__ __forceinline__ float bfhi(unsigned w) { return __uint_as_float(w & 0xffff0000u); }
;   __device__ __forceinline__ void operator()(EPI_ARGS) const {
;     ...
; #pragma unroll
;       for (int m = 0; m < 4; ++m)
; #pragma unroll
;         for (int bj = 0; bj < 2; ++bj) xv[m][bj] = *(const u32x4*)(b.RG + (size_t)(rbase + ai * 128 + m * 16) * 1024 + c0 + bj * 128);
;       if (at) {
; #pragma unroll
;         for (int m = 0; m < 4; ++m) { float* orow = b.out + (size_t)(b.g0 + rbase + ai * 128 + m * 16) * DM;
; #pragma unroll
;           for (int bj = 0; bj < 2; ++bj) { const int c = c0 + bj * 128; const u32x4 p = xv[m][bj];
;             *(f32x4*)(orow + c) = (f32x4){bflo(p.x), bfhi(p.x), bflo(p.y), bfhi(p.y)} + acc[ai][bj][m][0]; *(f32x4*)(orow + c + 4) = (f32x4){bflo(p.z), bfhi(p.z), bflo(p.w), bfhi(p.w)} + acc[ai][bj][m][1]; } }
	global_store_dwordx4 v[96:97], v[80:83], off offset:528
	v_lshlrev_b32_e32 v84, 16, v133
	v_and_b32_e32 v85, 0xffff0000, v133
	v_add_u32_e32 v80, s68, v166
	v_ashrrev_i32_e32 v81, 31, v80
	v_lshlrev_b64 v[80:81], 12, v[80:81]
	v_lshl_add_u64 v[80:81], s[28:29], 0, v[80:81]
	v_lshlrev_b32_e32 v82, 16, v132
	v_and_b32_e32 v83, 0xffff0000, v132
	v_pk_add_f32 v[78:79], v[78:79], v[84:85]
	v_pk_add_f32 v[76:77], v[76:77], v[82:83]
	v_lshl_add_u64 v[80:81], v[80:81], 0, v[124:125]
	global_store_dwordx4 v[80:81], v[76:79], off
	s_nop 1
	v_lshlrev_b32_e32 v76, 16, v134
	v_and_b32_e32 v77, 0xffff0000, v134
	v_lshlrev_b32_e32 v78, 16, v135
	v_and_b32_e32 v79, 0xffff0000, v135
	v_pk_add_f32 v[74:75], v[74:75], v[78:79]
	v_pk_add_f32 v[72:73], v[72:73], v[76:77]
	global_store_dwordx4 v[80:81], v[72:75], off offset:16
	s_nop 1
	v_lshlrev_b32_e32 v72, 16, v128
	v_and_b32_e32 v73, 0xffff0000, v128
	v_lshlrev_b32_e32 v74, 16, v129
	v_and_b32_e32 v75, 0xffff0000, v129
	v_pk_add_f32 v[70:71], v[70:71], v[74:75]
	v_pk_add_f32 v[68:69], v[68:69], v[72:73]
	global_store_dwordx4 v[80:81], v[68:71], off offset:512
	s_nop 1
	v_lshlrev_b32_e32 v68, 16, v130
	v_and_b32_e32 v69, 0xffff0000, v130
	v_lshlrev_b32_e32 v70, 16, v131
	v_and_b32_e32 v71, 0xffff0000, v131
	v_pk_add_f32 v[66:67], v[66:67], v[70:71]
	v_pk_add_f32 v[64:65], v[64:65], v[68:69]
	global_store_dwordx4 v[80:81], v[64:67], off offset:528
	v_add_u32_e32 v76, 0x80, v164
	v_ashrrev_i32_e32 v77, 31, v76
	v_lshlrev_b64 v[64:65], 11, v[76:77]
	v_add_u32_e32 v78, 0x90, v164
	v_lshl_add_u64 v[64:65], v[162:163], 0, v[64:65]
	v_ashrrev_i32_e32 v79, 31, v78
	global_load_dwordx4 v[92:95], v[64:65], off
	global_load_dwordx4 v[88:91], v[64:65], off offset:256
	v_lshlrev_b64 v[64:65], 11, v[78:79]
	v_lshl_add_u64 v[64:65], v[162:163], 0, v[64:65]
	global_load_dwordx4 v[84:87], v[64:65], off
	global_load_dwordx4 v[72:75], v[64:65], off offset:256
	v_add_u32_e32 v98, 0xa0, v164
	v_ashrrev_i32_e32 v99, 31, v98
	v_lshlrev_b64 v[64:65], 11, v[98:99]
	v_lshl_add_u64 v[64:65], v[162:163], 0, v[64:65]
	global_load_dwordx4 v[68:71], v[64:65], off
	s_nop 0
	global_load_dwordx4 v[64:67], v[64:65], off offset:256
	v_add_u32_e32 v96, 0xb0, v164
	v_ashrrev_i32_e32 v97, 31, v96
	v_add_u32_e32 v76, s68, v76
	v_add_u32_e32 v78, s68, v78
	v_lshlrev_b64 v[80:81], 11, v[96:97]
	v_ashrrev_i32_e32 v77, 31, v76
	v_ashrrev_i32_e32 v79, 31, v78
	v_lshl_add_u64 v[80:81], v[162:163], 0, v[80:81]
	v_lshlrev_b64 v[100:101], 12, v[76:77]
	v_lshlrev_b64 v[102:103], 12, v[78:79]
	global_load_dwordx4 v[76:79], v[80:81], off offset:256
	s_nop 0
	global_load_dwordx4 v[80:83], v[80:81], off
	v_lshl_add_u64 v[100:101], s[28:29], 0, v[100:101]
	v_lshl_add_u64 v[102:103], s[28:29], 0, v[102:103]
	v_lshl_add_u64 v[100:101], v[100:101], 0, v[124:125]
	v_lshl_add_u64 v[102:103], v[102:103], 0, v[124:125]
	s_and_b64 vcc, exec, s[40:41]
	s_mov_b64 s[4:5], -1
	s_waitcnt vmcnt(0) lgkmcnt(0)
; __device__ __forceinline__ float bflo(unsigned w) { return __uint_as_float(w << 16); }
; __device__ __forceinline__ float bfhi(unsigned w) { return __uint_as_float(w & 0xffff0000u); }
;   __device__ __forceinline__ void operator()(EPI_ARGS) const {
;     ...
; #pragma unroll
;       for (int m = 0; m < 4; ++m)
; #pragma unroll
;         for (int bj = 0; bj < 2; ++bj) xv[m][bj] = *(const u32x4*)(b.RG + (size_t)(rbase + ai * 128 + m * 16) * 1024 + c0 + bj * 128);
;       if (at) {
; #pragma unroll
;         for (int m = 0; m < 4; ++m) { float* orow = b.out + (size_t)(b.g0 + rbase + ai * 128 + m * 16) * DM;
; #pragma unroll
;           for (int bj = 0; bj < 2; ++bj) { const int c = c0 + bj * 128; const u32x4 p = xv[m][bj];
;             *(f32x4*)(orow + c) = (f32x4){bflo(p.x), bfhi(p.x), bflo(p.y), bfhi(p.y)} + acc[ai][bj][m][0]; *(f32x4*)(orow + c + 4) = (f32x4){bflo(p.z), bfhi(p.z), bflo(p.w), bfhi(p.w)} + acc[ai][bj][m][1]; } }
;       }
;     }
;   }
	v_lshlrev_b32_e32 v104, 16, v92
	v_and_b32_e32 v105, 0xffff0000, v92
	v_lshlrev_b32_e32 v92, 16, v93
	v_and_b32_e32 v93, 0xffff0000, v93
	v_lshlrev_b32_e32 v118, 16, v74
	v_and_b32_e32 v119, 0xffff0000, v74
	v_lshlrev_b32_e32 v74, 16, v75
	v_and_b32_e32 v75, 0xffff0000, v75
	v_lshlrev_b32_e32 v106, 16, v94
	v_and_b32_e32 v107, 0xffff0000, v94
	v_lshlrev_b32_e32 v94, 16, v95
	v_and_b32_e32 v95, 0xffff0000, v95
	v_lshlrev_b32_e32 v108, 16, v88
	v_and_b32_e32 v109, 0xffff0000, v88
	v_lshlrev_b32_e32 v88, 16, v89
	v_and_b32_e32 v89, 0xffff0000, v89
	v_lshlrev_b32_e32 v110, 16, v90
	v_and_b32_e32 v111, 0xffff0000, v90
	v_lshlrev_b32_e32 v90, 16, v91
	v_and_b32_e32 v91, 0xffff0000, v91
	v_lshlrev_b32_e32 v112, 16, v84
	v_and_b32_e32 v113, 0xffff0000, v84
	v_lshlrev_b32_e32 v84, 16, v85
	v_and_b32_e32 v85, 0xffff0000, v85
	v_lshlrev_b32_e32 v114, 16, v86
	v_and_b32_e32 v115, 0xffff0000, v86
	v_lshlrev_b32_e32 v86, 16, v87
	v_and_b32_e32 v87, 0xffff0000, v87
	v_lshlrev_b32_e32 v116, 16, v72
	v_and_b32_e32 v117, 0xffff0000, v72
	v_lshlrev_b32_e32 v72, 16, v73
	v_and_b32_e32 v73, 0xffff0000, v73
	v_pk_add_f32 v[62:63], v[62:63], v[92:93]
	v_pk_add_f32 v[60:61], v[60:61], v[104:105]
	v_pk_add_f32 v[34:35], v[34:35], v[74:75]
	v_pk_add_f32 v[32:33], v[32:33], v[118:119]
	v_pk_add_f32 v[58:59], v[58:59], v[94:95]
	v_pk_add_f32 v[56:57], v[56:57], v[106:107]
	v_pk_add_f32 v[54:55], v[54:55], v[88:89]
	v_pk_add_f32 v[52:53], v[52:53], v[108:109]
	v_pk_add_f32 v[50:51], v[50:51], v[90:91]
	v_pk_add_f32 v[48:49], v[48:49], v[110:111]
	v_pk_add_f32 v[46:47], v[46:47], v[84:85]
	v_pk_add_f32 v[44:45], v[44:45], v[112:113]
	v_pk_add_f32 v[42:43], v[42:43], v[86:87]
	v_pk_add_f32 v[40:41], v[40:41], v[114:115]
	v_pk_add_f32 v[38:39], v[38:39], v[72:73]
	v_pk_add_f32 v[36:37], v[36:37], v[116:117]
	global_store_dwordx4 v[100:101], v[60:63], off
	global_store_dwordx4 v[100:101], v[56:59], off offset:16
	global_store_dwordx4 v[100:101], v[52:55], off offset:512
	global_store_dwordx4 v[100:101], v[48:51], off offset:528
	global_store_dwordx4 v[102:103], v[44:47], off
	global_store_dwordx4 v[102:103], v[40:43], off offset:16
	global_store_dwordx4 v[102:103], v[36:39], off offset:512
	global_store_dwordx4 v[102:103], v[32:35], off offset:528
	s_nop 0
	v_lshlrev_b32_e32 v36, 16, v69
	v_add_u32_e32 v32, s68, v98
	v_ashrrev_i32_e32 v33, 31, v32
	v_lshlrev_b64 v[32:33], 12, v[32:33]
	v_lshl_add_u64 v[32:33], s[28:29], 0, v[32:33]
	v_lshlrev_b32_e32 v34, 16, v68
	v_and_b32_e32 v35, 0xffff0000, v68
	v_and_b32_e32 v37, 0xffff0000, v69
	v_pk_add_f32 v[30:31], v[30:31], v[36:37]
	v_pk_add_f32 v[28:29], v[28:29], v[34:35]
	v_lshl_add_u64 v[32:33], v[32:33], 0, v[124:125]
	global_store_dwordx4 v[32:33], v[28:31], off
	s_nop 1
	v_lshlrev_b32_e32 v28, 16, v70
	v_and_b32_e32 v29, 0xffff0000, v70
	v_lshlrev_b32_e32 v30, 16, v71
	v_and_b32_e32 v31, 0xffff0000, v71
	v_pk_add_f32 v[26:27], v[26:27], v[30:31]
	v_pk_add_f32 v[24:25], v[24:25], v[28:29]
	global_store_dwordx4 v[32:33], v[24:27], off offset:16
	s_nop 1
	v_lshlrev_b32_e32 v24, 16, v64
	v_and_b32_e32 v25, 0xffff0000, v64
	v_lshlrev_b32_e32 v26, 16, v65
	v_and_b32_e32 v27, 0xffff0000, v65
	v_pk_add_f32 v[22:23], v[22:23], v[26:27]
	v_pk_add_f32 v[20:21], v[20:21], v[24:25]
	global_store_dwordx4 v[32:33], v[20:23], off offset:512
	s_nop 1
	v_lshlrev_b32_e32 v20, 16, v66
	v_and_b32_e32 v21, 0xffff0000, v66
	v_lshlrev_b32_e32 v22, 16, v67
	v_and_b32_e32 v23, 0xffff0000, v67
	v_pk_add_f32 v[18:19], v[18:19], v[22:23]
	v_pk_add_f32 v[16:17], v[16:17], v[20:21]
	global_store_dwordx4 v[32:33], v[16:19], off offset:528
	v_lshlrev_b32_e32 v20, 16, v81
	v_and_b32_e32 v21, 0xffff0000, v81
	v_add_u32_e32 v16, s68, v96
	v_ashrrev_i32_e32 v17, 31, v16
	v_lshlrev_b64 v[16:17], 12, v[16:17]
	v_lshl_add_u64 v[16:17], s[28:29], 0, v[16:17]
	v_lshlrev_b32_e32 v18, 16, v80
	v_and_b32_e32 v19, 0xffff0000, v80
	v_pk_add_f32 v[14:15], v[14:15], v[20:21]
	v_pk_add_f32 v[12:13], v[12:13], v[18:19]
	v_lshl_add_u64 v[16:17], v[16:17], 0, v[124:125]
	global_store_dwordx4 v[16:17], v[12:15], off
	s_nop 1
	v_lshlrev_b32_e32 v12, 16, v82
	v_and_b32_e32 v13, 0xffff0000, v82
	v_lshlrev_b32_e32 v14, 16, v83
	v_and_b32_e32 v15, 0xffff0000, v83
	v_pk_add_f32 v[10:11], v[10:11], v[14:15]
	v_pk_add_f32 v[8:9], v[8:9], v[12:13]
	global_store_dwordx4 v[16:17], v[8:11], off offset:16
	s_nop 1
	v_lshlrev_b32_e32 v8, 16, v76
	v_and_b32_e32 v9, 0xffff0000, v76
	v_lshlrev_b32_e32 v10, 16, v77
	v_and_b32_e32 v11, 0xffff0000, v77
	v_pk_add_f32 v[6:7], v[6:7], v[10:11]
	v_pk_add_f32 v[4:5], v[4:5], v[8:9]
	global_store_dwordx4 v[16:17], v[4:7], off offset:512
	s_nop 1
	v_lshlrev_b32_e32 v4, 16, v78
	v_and_b32_e32 v5, 0xffff0000, v78
	v_lshlrev_b32_e32 v6, 16, v79
	v_and_b32_e32 v7, 0xffff0000, v79
	v_pk_add_f32 v[2:3], v[2:3], v[6:7]
	v_pk_add_f32 v[0:1], v[0:1], v[4:5]
	global_store_dwordx4 v[16:17], v[0:3], off offset:528
	s_cbranch_vccnz .LBB0_1076
	s_andn2_b64 vcc, exec, s[36:37]
	s_cbranch_vccnz .LBB0_1075
	s_barrier
	s_branch .LBB0_1075
